# in-proj plain stores as dword via DPP pair exchange, no per-block vmcnt(0); adaLN parameter loads batched; attention LDS reads issued ahead (counted lgkmcnt)
# speedup vs baseline: 1.0757x; 1.0164x over previous
; DI void phase_adaln(const Params& p, int l, unsigned char* smem) {
;     ...
;   for (int row = gw; row < NTOK; row += nw) {
;     const float* M = (const float*)(WS_ + O_MODS) + ((size_t)l * 5 + mod_vec(row)) * 6144;
;     const f32x4* xr = (const f32x4*)(X + (size_t)row * DM);
;     f32x4 v[8]; float ss = 0.f;
; #pragma unroll
;     for (int j = 0; j < 8; ++j) { v[j] = xr[lane + 64 * j]; ss += v[j][0] * v[j][0] + v[j][1] * v[j][1] + v[j][2] * v[j][2] + v[j][3] * v[j][3]; }
; #pragma unroll
;     for (int o = 1; o < 64; o <<= 1) ss += __shfl_xor(ss, o);
;     const float rs = rsqrtf(ss * (1.f / DM) + EPS);
;     float ab[16];
; #pragma unroll
;     for (int c = 0; c < 16; ++c) ab[c] = 0.f;
; #pragma unroll
;     for (int j = 0; j < 8; ++j) {
;       const int c0 = 4 * (lane + 64 * j);
;       const f32x4 g = *(const f32x4*)(ng + c0), sh = *(const f32x4*)(M + c0), sc = *(const f32x4*)(M + 2048 + c0);
.LBB0_141:
	s_mov_b32 s36, 0x78787879
	v_mul_hi_i32 v0, v48, s36
	s_waitcnt lgkmcnt(0)
	v_lshrrev_b32_e32 v1, 31, v0
	v_ashrrev_i32_e32 v0, 11, v0
	v_add_u32_e32 v0, v0, v1
	s_movk_i32 s36, 0xef00
	v_mad_i32_i24 v1, v0, s36, v48
	s_movk_i32 s36, 0xff
	v_cmp_lt_i32_e64 s[36:37], s36, v1
	s_movk_i32 s44, 0x6000
	v_mov_b32_e32 v75, v209
	v_cndmask_b32_e64 v0, 4, v0, s[36:37]
	v_readlane_b32 s36, v254, 45
	v_ashrrev_i32_e32 v1, 31, v0
	v_readlane_b32 s37, v254, 46
	v_mov_b32_e32 v77, v209
	v_mov_b32_e32 v79, v209
	v_lshl_add_u64 v[32:33], s[36:37], 0, v[0:1]
	v_lshl_add_u64 v[0:1], s[46:47], 0, v[72:73]
	global_load_dwordx4 v[28:31], v[0:1], off
	global_load_dwordx4 v[24:27], v[0:1], off offset:1024
	global_load_dwordx4 v[20:23], v[0:1], off offset:2048
	global_load_dwordx4 v[16:19], v[0:1], off offset:3072
	v_add_co_u32_e64 v0, s[36:37], s41, v0
	v_mov_b32_e32 v81, v209
	s_nop 0
	v_addc_co_u32_e64 v1, s[36:37], 0, v1, s[36:37]
	global_load_dwordx4 v[12:15], v[0:1], off
	global_load_dwordx4 v[8:11], v[0:1], off offset:1024
	v_mov_b32_e32 v83, v209
	v_mov_b32_e32 v85, v209
	v_mov_b32_e32 v87, v209
	s_waitcnt vmcnt(0) lgkmcnt(0)
	v_mul_f32_e32 v2, v29, v29
	v_mul_f32_e32 v3, v25, v25
	v_fmac_f32_e32 v2, v28, v28
	v_fmac_f32_e32 v3, v24, v24
	v_fmac_f32_e32 v2, v30, v30
	v_fmac_f32_e32 v3, v26, v26
	v_fmac_f32_e32 v2, v31, v31
	v_fmac_f32_e32 v3, v27, v27
	v_add_f32_e32 v2, v2, v3
	v_mul_f32_e32 v3, v21, v21
	v_fmac_f32_e32 v3, v20, v20
	v_fmac_f32_e32 v3, v22, v22
	v_fmac_f32_e32 v3, v23, v23
	v_add_f32_e32 v2, v2, v3
	v_mul_f32_e32 v3, v17, v17
	v_fmac_f32_e32 v3, v16, v16
	v_fmac_f32_e32 v3, v18, v18
	v_fmac_f32_e32 v3, v19, v19
	v_mov_b32_e32 v4, v13
	v_mov_b32_e32 v5, v9
	v_add_f32_e32 v6, v2, v3
	v_mov_b32_e32 v2, v12
	v_mov_b32_e32 v3, v8
	v_pk_mul_f32 v[4:5], v[4:5], v[4:5]
	s_nop 0
	v_pk_fma_f32 v[2:3], v[2:3], v[2:3], v[4:5]
	v_mov_b32_e32 v4, v14
	v_mov_b32_e32 v5, v10
	v_pk_fma_f32 v[2:3], v[4:5], v[4:5], v[2:3]
	v_mov_b32_e32 v4, v15
	v_mov_b32_e32 v5, v11
	v_pk_fma_f32 v[2:3], v[4:5], v[4:5], v[2:3]
	s_nop 0
	v_add_f32_e32 v2, v6, v2
	v_add_f32_e32 v38, v2, v3
	global_load_dwordx4 v[4:7], v[0:1], off offset:2048
	s_nop 0
	global_load_dwordx4 v[0:3], v[0:1], off offset:3072
	s_waitcnt vmcnt(0) lgkmcnt(0)
	v_mov_b32_e32 v36, v5
	v_mov_b32_e32 v37, v1
	v_mov_b32_e32 v34, v4
	v_mov_b32_e32 v35, v0
	v_pk_mul_f32 v[36:37], v[36:37], v[36:37]
	s_nop 0
	v_pk_fma_f32 v[34:35], v[34:35], v[34:35], v[36:37]
	v_mov_b32_e32 v36, v6
	v_mov_b32_e32 v37, v2
	v_pk_fma_f32 v[34:35], v[36:37], v[36:37], v[34:35]
	v_mov_b32_e32 v36, v7
	v_mov_b32_e32 v37, v3
	v_pk_fma_f32 v[34:35], v[36:37], v[36:37], v[34:35]
	s_nop 0
	v_add_f32_e32 v34, v38, v34
	v_add_f32_e32 v34, v34, v35
	ds_bpermute_b32 v35, v89, v34
	s_waitcnt lgkmcnt(0)
	v_add_f32_e32 v34, v34, v35
	ds_bpermute_b32 v35, v96, v34
	s_waitcnt lgkmcnt(0)
	v_add_f32_e32 v34, v34, v35
	ds_bpermute_b32 v35, v97, v34
	s_waitcnt lgkmcnt(0)
	v_add_f32_e32 v34, v34, v35
	ds_bpermute_b32 v35, v98, v34
	s_waitcnt lgkmcnt(0)
	v_add_f32_e32 v34, v34, v35
	ds_bpermute_b32 v35, v99, v34
	s_waitcnt lgkmcnt(0)
	v_add_f32_e32 v34, v34, v35
	ds_bpermute_b32 v35, v100, v34
	s_waitcnt lgkmcnt(0)
	v_add_f32_e32 v34, v34, v35
	v_fmamk_f32 v34, v34, 0x3a000000, v217
	v_cmp_gt_f32_e64 s[36:37], s40, v34
	v_mul_f32_e32 v35, 0x4b800000, v34
	s_nop 0
	v_cndmask_b32_e64 v34, v34, v35, s[36:37]
	v_rsq_f32_e32 v36, v34
	v_mov_b64_e32 v[34:35], s[50:51]
	v_mad_u64_u32 v[92:93], s[84:85], v32, s44, v[34:35]
	v_mul_f32_e32 v37, 0x45800000, v36
	v_mad_i32_i24 v93, v33, s44, v93
	v_cndmask_b32_e64 v88, v36, v37, s[36:37]
	s_mov_b64 s[36:37], 0x2000
	v_lshl_add_u64 v[90:91], v[92:93], 0, s[36:37]
	v_lshl_add_u64 v[94:95], v[92:93], 0, v[208:209]
	v_lshl_add_u64 v[102:103], v[90:91], 0, v[208:209]
	global_load_dwordx4 v[166:169], v[42:43], off offset:1024
	global_load_dwordx4 v[170:173], v[94:95], off offset:1024
	v_lshl_add_u64 v[174:175], v[90:91], 0, v[74:75]
	global_load_dwordx4 v[174:177], v[174:175], off
	global_load_dwordx4 v[178:181], v[42:43], off offset:2048
	global_load_dwordx4 v[182:185], v[94:95], off offset:2048
	v_lshl_add_u64 v[186:187], v[90:91], 0, v[76:77]
	global_load_dwordx4 v[186:189], v[186:187], off
	global_load_dwordx4 v[190:193], v[42:43], off offset:3072
	global_load_dwordx4 v[194:197], v[94:95], off offset:3072
	v_lshl_add_u64 v[198:199], v[90:91], 0, v[78:79]
	global_load_dwordx4 v[198:201], v[198:199], off
	global_load_dwordx4 v[202:205], v[44:45], off
	v_lshl_add_u64 v[212:213], v[92:93], 0, v[80:81]
	global_load_dwordx4 v[212:215], v[212:213], off
	v_lshl_add_u64 v[224:225], v[90:91], 0, v[80:81]
	global_load_dwordx4 v[224:227], v[224:225], off
	global_load_dwordx4 v[32:35], v[42:43], off
	global_load_dwordx4 v[36:39], v[94:95], off
	v_pk_mul_f32 v[28:29], v[28:29], v[88:89] op_sel_hi:[1,0]
	global_load_dwordx4 v[102:105], v[102:103], off
	v_pk_mul_f32 v[24:25], v[24:25], v[88:89] op_sel_hi:[1,0]
	v_pk_mul_f32 v[20:21], v[20:21], v[88:89] op_sel_hi:[1,0]
	v_pk_mul_f32 v[16:17], v[16:17], v[88:89] op_sel_hi:[1,0]
	v_pk_mul_f32 v[12:13], v[12:13], v[88:89] op_sel_hi:[1,0]
	v_pk_mul_f32 v[8:9], v[8:9], v[88:89] op_sel_hi:[1,0]
	v_pk_mul_f32 v[4:5], v[4:5], v[88:89] op_sel_hi:[1,0]
	v_pk_mul_f32 v[0:1], v[0:1], v[88:89] op_sel_hi:[1,0]
	s_waitcnt vmcnt(0)
	v_pk_mul_f32 v[28:29], v[32:33], v[28:29]
	s_waitcnt lgkmcnt(0)
; DI float bf2f(bfr v) { return __uint_as_float(((unsigned)v) << 16); }
; DI unsigned pk2(float a, float b) { f2_t v = {a, b}; bf2_t r = __builtin_convertvector(v, bf2_t); return __builtin_bit_cast(unsigned, r); }
; DI void phase_adaln(const Params& p, int l, unsigned char* smem) {
;     ...
;     for (int j = 0; j < 8; ++j) {
;       const int c0 = 4 * (lane + 64 * j);
;       const f32x4 g = *(const f32x4*)(ng + c0), sh = *(const f32x4*)(M + c0), sc = *(const f32x4*)(M + 2048 + c0);
;       float o[4];
;       for (int q = 0; q < 4; ++q) o[q] = v[j][q] * rs * g[q] * (1.f + sc[q]) + sh[q];
;       u32x2 w; w[0] = pk2(o[0], o[1]); w[1] = pk2(o[2], o[3]);
;       *(u32x2*)(H + ((size_t)(c0 >> 5) * NTOK + row) * 32 + (c0 & 31)) = w;
; #pragma unroll
;       for (int q = 0; q < 4; ++q) {
;         const bf16x8 w0 = ld16(sW + ((j * 4 + q) * 64 + lane) * 8), w1 = ld16(sW + 16384 + ((j * 4 + q) * 64 + lane) * 8);
; #pragma unroll
;         for (int c = 0; c < 8; ++c) { ab[c] += o[q] * bf2f((bfr)w0[c]); ab[8 + c] += o[q] * bf2f((bfr)w1[c]); }
;       }
	v_pk_add_f32 v[32:33], v[102:103], 1.0 op_sel_hi:[1,0]
	s_nop 0
	v_pk_fma_f32 v[32:33], v[32:33], v[28:29], v[36:37]
	v_pk_mul_f32 v[28:29], v[30:31], v[88:89] op_sel_hi:[1,0]
	v_pk_add_f32 v[30:31], v[104:105], 1.0 op_sel_hi:[1,0]
	v_pk_mul_f32 v[28:29], v[34:35], v[28:29]
	v_lshl_add_u64 v[34:35], s[46:47], 0, v[70:71]
	v_pk_fma_f32 v[28:29], v[30:31], v[28:29], v[38:39]
	v_cvt_pk_bf16_f32 v30, v32, v33
	v_cvt_pk_bf16_f32 v31, v28, v29
	flat_store_dwordx2 v[34:35], v[30:31]
	ds_read_b128 v[34:37], v40
	ds_read_b128 v[116:119], v40 offset:32768
	s_waitcnt lgkmcnt(0)
	v_lshlrev_b32_e32 v30, 16, v34
	v_fma_f32 v115, v32, v30, 0
	v_lshlrev_b32_e32 v30, 16, v116
	v_fma_f32 v107, v32, v30, 0
	v_and_b32_e32 v30, 0xffff0000, v34
	v_fma_f32 v114, v32, v30, 0
	v_and_b32_e32 v30, 0xffff0000, v116
	v_fma_f32 v106, v32, v30, 0
	v_lshlrev_b32_e32 v30, 16, v35
	v_fma_f32 v113, v32, v30, 0
	v_lshlrev_b32_e32 v30, 16, v117
	v_fma_f32 v105, v32, v30, 0
	v_and_b32_e32 v30, 0xffff0000, v35
	v_fma_f32 v112, v32, v30, 0
	v_and_b32_e32 v30, 0xffff0000, v117
	v_fma_f32 v104, v32, v30, 0
	v_lshlrev_b32_e32 v30, 16, v36
	v_fma_f32 v111, v32, v30, 0
	v_lshlrev_b32_e32 v30, 16, v118
	v_fma_f32 v103, v32, v30, 0
	v_and_b32_e32 v30, 0xffff0000, v36
	v_fma_f32 v110, v32, v30, 0
	v_and_b32_e32 v30, 0xffff0000, v118
	v_fma_f32 v102, v32, v30, 0
	v_lshlrev_b32_e32 v30, 16, v37
	v_fma_f32 v109, v32, v30, 0
	v_lshlrev_b32_e32 v30, 16, v119
	v_fma_f32 v101, v32, v30, 0
	v_and_b32_e32 v30, 0xffff0000, v37
	v_fma_f32 v108, v32, v30, 0
	v_and_b32_e32 v30, 0xffff0000, v119
	ds_read_b128 v[34:37], v40 offset:1024
	ds_read_b128 v[116:119], v40 offset:33792
	v_fma_f32 v49, v32, v30, 0
	s_waitcnt lgkmcnt(0)
	v_lshlrev_b32_e32 v30, 16, v34
	v_fmac_f32_e32 v115, v33, v30
	v_lshlrev_b32_e32 v30, 16, v116
	v_fmac_f32_e32 v107, v33, v30
	v_and_b32_e32 v30, 0xffff0000, v34
	v_fmac_f32_e32 v114, v33, v30
	v_and_b32_e32 v30, 0xffff0000, v116
	v_fmac_f32_e32 v106, v33, v30
	v_lshlrev_b32_e32 v30, 16, v35
	v_fmac_f32_e32 v113, v33, v30
	v_lshlrev_b32_e32 v30, 16, v117
	v_fmac_f32_e32 v105, v33, v30
	v_and_b32_e32 v30, 0xffff0000, v35
	v_fmac_f32_e32 v112, v33, v30
	v_and_b32_e32 v30, 0xffff0000, v117
	v_fmac_f32_e32 v104, v33, v30
	v_lshlrev_b32_e32 v30, 16, v36
	v_fmac_f32_e32 v111, v33, v30
	v_lshlrev_b32_e32 v30, 16, v118
	v_fmac_f32_e32 v103, v33, v30
	v_and_b32_e32 v30, 0xffff0000, v36
	v_fmac_f32_e32 v110, v33, v30
	v_and_b32_e32 v30, 0xffff0000, v118
	v_fmac_f32_e32 v102, v33, v30
	v_lshlrev_b32_e32 v30, 16, v37
	v_fmac_f32_e32 v109, v33, v30
	v_lshlrev_b32_e32 v30, 16, v119
	v_fmac_f32_e32 v101, v33, v30
	v_and_b32_e32 v30, 0xffff0000, v37
	v_fmac_f32_e32 v108, v33, v30
	v_and_b32_e32 v30, 0xffff0000, v119
	v_fmac_f32_e32 v49, v33, v30
	ds_read_b128 v[30:33], v40 offset:2048
	ds_read_b128 v[34:37], v40 offset:34816
	s_waitcnt lgkmcnt(0)
	v_lshlrev_b32_e32 v38, 16, v30
	v_and_b32_e32 v30, 0xffff0000, v30
	v_fmac_f32_e32 v114, v28, v30
	v_and_b32_e32 v30, 0xffff0000, v34
	v_fmac_f32_e32 v106, v28, v30
	v_lshlrev_b32_e32 v30, 16, v31
	v_fmac_f32_e32 v113, v28, v30
	v_lshlrev_b32_e32 v30, 16, v35
	v_fmac_f32_e32 v105, v28, v30
	v_and_b32_e32 v30, 0xffff0000, v31
	v_fmac_f32_e32 v112, v28, v30
	v_and_b32_e32 v30, 0xffff0000, v35
	v_fmac_f32_e32 v104, v28, v30
	v_lshlrev_b32_e32 v30, 16, v32
	v_fmac_f32_e32 v111, v28, v30
	v_lshlrev_b32_e32 v30, 16, v36
	v_fmac_f32_e32 v103, v28, v30
	v_and_b32_e32 v30, 0xffff0000, v32
	v_fmac_f32_e32 v110, v28, v30
	v_and_b32_e32 v30, 0xffff0000, v36
	v_fmac_f32_e32 v102, v28, v30
	v_lshlrev_b32_e32 v30, 16, v33
	v_fmac_f32_e32 v109, v28, v30
	v_lshlrev_b32_e32 v30, 16, v37
	v_fmac_f32_e32 v101, v28, v30
	v_and_b32_e32 v30, 0xffff0000, v33
	v_fmac_f32_e32 v108, v28, v30
	v_and_b32_e32 v30, 0xffff0000, v37
	v_fmac_f32_e32 v115, v28, v38
	v_lshlrev_b32_e32 v38, 16, v34
	v_fmac_f32_e32 v49, v28, v30
	ds_read_b128 v[30:33], v40 offset:3072
	ds_read_b128 v[34:37], v40 offset:35840
	v_fmac_f32_e32 v107, v28, v38
	s_waitcnt lgkmcnt(0)
	v_lshlrev_b32_e32 v28, 16, v30
	v_fmac_f32_e32 v115, v29, v28
	v_lshlrev_b32_e32 v28, 16, v34
	v_fmac_f32_e32 v107, v29, v28
	v_and_b32_e32 v28, 0xffff0000, v30
	v_fmac_f32_e32 v114, v29, v28
	v_and_b32_e32 v28, 0xffff0000, v34
	v_fmac_f32_e32 v106, v29, v28
	v_lshlrev_b32_e32 v28, 16, v31
	v_fmac_f32_e32 v113, v29, v28
	v_lshlrev_b32_e32 v28, 16, v35
	v_fmac_f32_e32 v105, v29, v28
	v_and_b32_e32 v28, 0xffff0000, v31
	v_fmac_f32_e32 v112, v29, v28
	v_and_b32_e32 v28, 0xffff0000, v35
	v_fmac_f32_e32 v104, v29, v28
	v_lshlrev_b32_e32 v28, 16, v32
	v_fmac_f32_e32 v111, v29, v28
	v_lshlrev_b32_e32 v28, 16, v36
	v_fmac_f32_e32 v103, v29, v28
	v_and_b32_e32 v28, 0xffff0000, v32
	v_fmac_f32_e32 v110, v29, v28
	v_and_b32_e32 v28, 0xffff0000, v36
	v_fmac_f32_e32 v102, v29, v28
	v_lshlrev_b32_e32 v28, 16, v33
	v_fmac_f32_e32 v109, v29, v28
	v_lshlrev_b32_e32 v28, 16, v37
	v_fmac_f32_e32 v101, v29, v28
	v_and_b32_e32 v28, 0xffff0000, v33
	v_fmac_f32_e32 v108, v29, v28
	v_and_b32_e32 v28, 0xffff0000, v37
	v_lshl_add_u64 v[36:37], v[90:91], 0, v[74:75]
	v_fmac_f32_e32 v49, v29, v28
	s_waitcnt vmcnt(0)
	v_mov_b32_e32 v32, v166
	v_mov_b32_e32 v33, v167
	v_mov_b32_e32 v34, v168
	v_mov_b32_e32 v35, v169
	v_mov_b32_e32 v28, v170
	v_mov_b32_e32 v29, v171
	v_mov_b32_e32 v30, v172
	v_mov_b32_e32 v31, v173
	s_waitcnt vmcnt(0)
	v_pk_mul_f32 v[24:25], v[32:33], v[24:25]
	v_mov_b32_e32 v36, v174
	v_mov_b32_e32 v37, v175
	v_mov_b32_e32 v38, v176
	v_mov_b32_e32 v39, v177
	s_waitcnt vmcnt(0) lgkmcnt(0)
; DI float bf2f(bfr v) { return __uint_as_float(((unsigned)v) << 16); }
; DI unsigned pk2(float a, float b) { f2_t v = {a, b}; bf2_t r = __builtin_convertvector(v, bf2_t); return __builtin_bit_cast(unsigned, r); }
; DI void phase_adaln(const Params& p, int l, unsigned char* smem) {
;     ...
;     for (int j = 0; j < 8; ++j) {
;       const int c0 = 4 * (lane + 64 * j);
;       const f32x4 g = *(const f32x4*)(ng + c0), sh = *(const f32x4*)(M + c0), sc = *(const f32x4*)(M + 2048 + c0);
;       float o[4];
;       for (int q = 0; q < 4; ++q) o[q] = v[j][q] * rs * g[q] * (1.f + sc[q]) + sh[q];
;       u32x2 w; w[0] = pk2(o[0], o[1]); w[1] = pk2(o[2], o[3]);
;       *(u32x2*)(H + ((size_t)(c0 >> 5) * NTOK + row) * 32 + (c0 & 31)) = w;
; #pragma unroll
;       for (int q = 0; q < 4; ++q) {
;         const bf16x8 w0 = ld16(sW + ((j * 4 + q) * 64 + lane) * 8), w1 = ld16(sW + 16384 + ((j * 4 + q) * 64 + lane) * 8);
; #pragma unroll
;         for (int c = 0; c < 8; ++c) { ab[c] += o[q] * bf2f((bfr)w0[c]); ab[8 + c] += o[q] * bf2f((bfr)w1[c]); }
;       }
	v_pk_add_f32 v[32:33], v[36:37], 1.0 op_sel_hi:[1,0]
	s_nop 0
	v_pk_fma_f32 v[28:29], v[24:25], v[32:33], v[28:29]
	v_pk_mul_f32 v[24:25], v[26:27], v[88:89] op_sel_hi:[1,0]
	v_pk_add_f32 v[26:27], v[38:39], 1.0 op_sel_hi:[1,0]
	v_pk_mul_f32 v[24:25], v[34:35], v[24:25]
	s_nop 0
	v_pk_fma_f32 v[24:25], v[24:25], v[26:27], v[30:31]
	v_cvt_pk_bf16_f32 v26, v28, v29
	v_cvt_pk_bf16_f32 v27, v24, v25
	v_lshl_add_u64 v[30:31], s[46:47], 0, v[68:69]
	flat_store_dwordx2 v[30:31], v[26:27]
	ds_read_b128 v[30:33], v41
	ds_read_b128 v[34:37], v41 offset:32768
	s_waitcnt lgkmcnt(0)
	v_lshlrev_b32_e32 v26, 16, v30
	v_fmac_f32_e32 v115, v28, v26
	v_lshlrev_b32_e32 v26, 16, v34
	v_fmac_f32_e32 v107, v28, v26
	v_and_b32_e32 v26, 0xffff0000, v30
	v_fmac_f32_e32 v114, v28, v26
	v_and_b32_e32 v26, 0xffff0000, v34
	v_fmac_f32_e32 v106, v28, v26
	v_lshlrev_b32_e32 v26, 16, v31
	v_fmac_f32_e32 v113, v28, v26
	v_lshlrev_b32_e32 v26, 16, v35
	v_fmac_f32_e32 v105, v28, v26
	v_and_b32_e32 v26, 0xffff0000, v31
	v_fmac_f32_e32 v112, v28, v26
	v_and_b32_e32 v26, 0xffff0000, v35
	v_fmac_f32_e32 v104, v28, v26
	v_lshlrev_b32_e32 v26, 16, v32
	v_fmac_f32_e32 v111, v28, v26
	v_lshlrev_b32_e32 v26, 16, v36
	v_fmac_f32_e32 v103, v28, v26
	v_and_b32_e32 v26, 0xffff0000, v32
	v_fmac_f32_e32 v110, v28, v26
	v_and_b32_e32 v26, 0xffff0000, v36
	v_fmac_f32_e32 v102, v28, v26
	v_lshlrev_b32_e32 v26, 16, v33
	v_fmac_f32_e32 v109, v28, v26
	v_lshlrev_b32_e32 v26, 16, v37
	v_fmac_f32_e32 v101, v28, v26
	v_and_b32_e32 v26, 0xffff0000, v33
	v_fmac_f32_e32 v108, v28, v26
	v_and_b32_e32 v26, 0xffff0000, v37
	ds_read_b128 v[30:33], v41 offset:1024
	ds_read_b128 v[34:37], v41 offset:33792
	v_fmac_f32_e32 v49, v28, v26
	s_waitcnt lgkmcnt(0)
	v_lshlrev_b32_e32 v26, 16, v30
	v_fmac_f32_e32 v115, v29, v26
	v_lshlrev_b32_e32 v26, 16, v34
	v_fmac_f32_e32 v107, v29, v26
	v_and_b32_e32 v26, 0xffff0000, v30
	v_fmac_f32_e32 v114, v29, v26
	v_and_b32_e32 v26, 0xffff0000, v34
	v_fmac_f32_e32 v106, v29, v26
	v_lshlrev_b32_e32 v26, 16, v31
	v_fmac_f32_e32 v113, v29, v26
	v_lshlrev_b32_e32 v26, 16, v35
	v_fmac_f32_e32 v105, v29, v26
	v_and_b32_e32 v26, 0xffff0000, v31
	v_fmac_f32_e32 v112, v29, v26
	v_and_b32_e32 v26, 0xffff0000, v35
	v_fmac_f32_e32 v104, v29, v26
	v_lshlrev_b32_e32 v26, 16, v32
	v_fmac_f32_e32 v111, v29, v26
	v_lshlrev_b32_e32 v26, 16, v36
	v_fmac_f32_e32 v103, v29, v26
	v_and_b32_e32 v26, 0xffff0000, v32
	v_fmac_f32_e32 v110, v29, v26
	v_and_b32_e32 v26, 0xffff0000, v36
	v_fmac_f32_e32 v102, v29, v26
	v_lshlrev_b32_e32 v26, 16, v33
	v_fmac_f32_e32 v109, v29, v26
	v_lshlrev_b32_e32 v26, 16, v37
	v_fmac_f32_e32 v101, v29, v26
	v_and_b32_e32 v26, 0xffff0000, v33
	v_fmac_f32_e32 v108, v29, v26
	v_and_b32_e32 v26, 0xffff0000, v37
	v_fmac_f32_e32 v49, v29, v26
	ds_read_b128 v[26:29], v41 offset:2048
	ds_read_b128 v[30:33], v41 offset:34816
	s_waitcnt lgkmcnt(0)
	v_lshlrev_b32_e32 v34, 16, v26
	v_and_b32_e32 v26, 0xffff0000, v26
	v_fmac_f32_e32 v114, v24, v26
	v_and_b32_e32 v26, 0xffff0000, v30
	v_fmac_f32_e32 v106, v24, v26
	v_lshlrev_b32_e32 v26, 16, v27
	v_fmac_f32_e32 v113, v24, v26
	v_lshlrev_b32_e32 v26, 16, v31
	v_fmac_f32_e32 v105, v24, v26
	v_and_b32_e32 v26, 0xffff0000, v27
	v_fmac_f32_e32 v112, v24, v26
	v_and_b32_e32 v26, 0xffff0000, v31
	v_fmac_f32_e32 v104, v24, v26
	v_lshlrev_b32_e32 v26, 16, v28
	v_fmac_f32_e32 v111, v24, v26
	v_lshlrev_b32_e32 v26, 16, v32
	v_fmac_f32_e32 v103, v24, v26
	v_and_b32_e32 v26, 0xffff0000, v28
	v_fmac_f32_e32 v110, v24, v26
	v_and_b32_e32 v26, 0xffff0000, v32
	v_fmac_f32_e32 v102, v24, v26
	v_lshlrev_b32_e32 v26, 16, v29
	v_fmac_f32_e32 v109, v24, v26
	v_lshlrev_b32_e32 v26, 16, v33
	v_fmac_f32_e32 v101, v24, v26
	v_and_b32_e32 v26, 0xffff0000, v29
	v_fmac_f32_e32 v108, v24, v26
	v_and_b32_e32 v26, 0xffff0000, v33
	v_fmac_f32_e32 v115, v24, v34
	v_lshlrev_b32_e32 v34, 16, v30
	v_fmac_f32_e32 v49, v24, v26
	ds_read_b128 v[26:29], v41 offset:3072
	ds_read_b128 v[30:33], v41 offset:35840
	v_fmac_f32_e32 v107, v24, v34
	s_waitcnt lgkmcnt(0)
	v_lshlrev_b32_e32 v24, 16, v26
	v_fmac_f32_e32 v115, v25, v24
	v_lshlrev_b32_e32 v24, 16, v30
	v_fmac_f32_e32 v107, v25, v24
	v_and_b32_e32 v24, 0xffff0000, v26
	v_fmac_f32_e32 v114, v25, v24
	v_and_b32_e32 v24, 0xffff0000, v30
	v_fmac_f32_e32 v106, v25, v24
	v_lshlrev_b32_e32 v24, 16, v27
	v_fmac_f32_e32 v113, v25, v24
	v_lshlrev_b32_e32 v24, 16, v31
	v_fmac_f32_e32 v105, v25, v24
	v_and_b32_e32 v24, 0xffff0000, v27
	v_fmac_f32_e32 v112, v25, v24
	v_and_b32_e32 v24, 0xffff0000, v31
	v_fmac_f32_e32 v104, v25, v24
	v_lshlrev_b32_e32 v24, 16, v28
	v_fmac_f32_e32 v111, v25, v24
	v_lshlrev_b32_e32 v24, 16, v32
	v_fmac_f32_e32 v103, v25, v24
	v_and_b32_e32 v24, 0xffff0000, v28
	v_fmac_f32_e32 v110, v25, v24
	v_and_b32_e32 v24, 0xffff0000, v32
	v_fmac_f32_e32 v102, v25, v24
	v_lshlrev_b32_e32 v24, 16, v29
	v_fmac_f32_e32 v109, v25, v24
	v_lshlrev_b32_e32 v24, 16, v33
	v_fmac_f32_e32 v101, v25, v24
	v_and_b32_e32 v24, 0xffff0000, v29
	v_fmac_f32_e32 v108, v25, v24
	v_and_b32_e32 v24, 0xffff0000, v33
	v_lshl_add_u64 v[32:33], v[90:91], 0, v[76:77]
	v_fmac_f32_e32 v49, v25, v24
	s_waitcnt vmcnt(0)
	v_mov_b32_e32 v28, v178
	v_mov_b32_e32 v29, v179
	v_mov_b32_e32 v30, v180
	v_mov_b32_e32 v31, v181
	v_mov_b32_e32 v24, v182
	v_mov_b32_e32 v25, v183
	v_mov_b32_e32 v26, v184
	v_mov_b32_e32 v27, v185
	s_waitcnt vmcnt(0)
	v_pk_mul_f32 v[20:21], v[20:21], v[28:29]
	v_mov_b32_e32 v32, v186
	v_mov_b32_e32 v33, v187
	v_mov_b32_e32 v34, v188
	v_mov_b32_e32 v35, v189
	s_waitcnt vmcnt(0) lgkmcnt(0)
; DI float bf2f(bfr v) { return __uint_as_float(((unsigned)v) << 16); }
; DI unsigned pk2(float a, float b) { f2_t v = {a, b}; bf2_t r = __builtin_convertvector(v, bf2_t); return __builtin_bit_cast(unsigned, r); }
; DI void phase_adaln(const Params& p, int l, unsigned char* smem) {
;     ...
;     for (int j = 0; j < 8; ++j) {
;       const int c0 = 4 * (lane + 64 * j);
;       const f32x4 g = *(const f32x4*)(ng + c0), sh = *(const f32x4*)(M + c0), sc = *(const f32x4*)(M + 2048 + c0);
;       float o[4];
;       for (int q = 0; q < 4; ++q) o[q] = v[j][q] * rs * g[q] * (1.f + sc[q]) + sh[q];
;       u32x2 w; w[0] = pk2(o[0], o[1]); w[1] = pk2(o[2], o[3]);
;       *(u32x2*)(H + ((size_t)(c0 >> 5) * NTOK + row) * 32 + (c0 & 31)) = w;
; #pragma unroll
;       for (int q = 0; q < 4; ++q) {
;         const bf16x8 w0 = ld16(sW + ((j * 4 + q) * 64 + lane) * 8), w1 = ld16(sW + 16384 + ((j * 4 + q) * 64 + lane) * 8);
; #pragma unroll
;         for (int c = 0; c < 8; ++c) { ab[c] += o[q] * bf2f((bfr)w0[c]); ab[8 + c] += o[q] * bf2f((bfr)w1[c]); }
;       }
	v_pk_add_f32 v[28:29], v[32:33], 1.0 op_sel_hi:[1,0]
	s_nop 0
	v_pk_fma_f32 v[24:25], v[20:21], v[28:29], v[24:25]
	v_pk_mul_f32 v[20:21], v[22:23], v[88:89] op_sel_hi:[1,0]
	v_pk_add_f32 v[22:23], v[34:35], 1.0 op_sel_hi:[1,0]
	v_pk_mul_f32 v[20:21], v[20:21], v[30:31]
	s_nop 0
	v_pk_fma_f32 v[20:21], v[20:21], v[22:23], v[26:27]
	v_cvt_pk_bf16_f32 v22, v24, v25
	v_cvt_pk_bf16_f32 v23, v20, v21
	v_lshl_add_u64 v[26:27], s[46:47], 0, v[66:67]
	flat_store_dwordx2 v[26:27], v[22:23]
	ds_read_b128 v[26:29], v40 offset:8192
	ds_read_b128 v[30:33], v40 offset:40960
	s_waitcnt lgkmcnt(0)
	v_lshlrev_b32_e32 v22, 16, v26
	v_fmac_f32_e32 v115, v24, v22
	v_lshlrev_b32_e32 v22, 16, v30
	v_fmac_f32_e32 v107, v24, v22
	v_and_b32_e32 v22, 0xffff0000, v26
	v_fmac_f32_e32 v114, v24, v22
	v_and_b32_e32 v22, 0xffff0000, v30
	v_fmac_f32_e32 v106, v24, v22
	v_lshlrev_b32_e32 v22, 16, v27
	v_fmac_f32_e32 v113, v24, v22
	v_lshlrev_b32_e32 v22, 16, v31
	v_fmac_f32_e32 v105, v24, v22
	v_and_b32_e32 v22, 0xffff0000, v27
	v_fmac_f32_e32 v112, v24, v22
	v_and_b32_e32 v22, 0xffff0000, v31
	v_fmac_f32_e32 v104, v24, v22
	v_lshlrev_b32_e32 v22, 16, v28
	v_fmac_f32_e32 v111, v24, v22
	v_lshlrev_b32_e32 v22, 16, v32
	v_fmac_f32_e32 v103, v24, v22
	v_and_b32_e32 v22, 0xffff0000, v28
	v_fmac_f32_e32 v110, v24, v22
	v_and_b32_e32 v22, 0xffff0000, v32
	v_fmac_f32_e32 v102, v24, v22
	v_lshlrev_b32_e32 v22, 16, v29
	v_fmac_f32_e32 v109, v24, v22
	v_lshlrev_b32_e32 v22, 16, v33
	v_fmac_f32_e32 v101, v24, v22
	v_and_b32_e32 v22, 0xffff0000, v29
	v_fmac_f32_e32 v108, v24, v22
	v_and_b32_e32 v22, 0xffff0000, v33
	ds_read_b128 v[26:29], v40 offset:9216
	ds_read_b128 v[30:33], v40 offset:41984
	v_fmac_f32_e32 v49, v24, v22
	s_waitcnt lgkmcnt(0)
	v_lshlrev_b32_e32 v22, 16, v26
	v_fmac_f32_e32 v115, v25, v22
	v_lshlrev_b32_e32 v22, 16, v30
	v_fmac_f32_e32 v107, v25, v22
	v_and_b32_e32 v22, 0xffff0000, v26
	v_fmac_f32_e32 v114, v25, v22
	v_and_b32_e32 v22, 0xffff0000, v30
	v_fmac_f32_e32 v106, v25, v22
	v_lshlrev_b32_e32 v22, 16, v27
	v_fmac_f32_e32 v113, v25, v22
	v_lshlrev_b32_e32 v22, 16, v31
	v_fmac_f32_e32 v105, v25, v22
	v_and_b32_e32 v22, 0xffff0000, v27
	v_fmac_f32_e32 v112, v25, v22
	v_and_b32_e32 v22, 0xffff0000, v31
	v_fmac_f32_e32 v104, v25, v22
	v_lshlrev_b32_e32 v22, 16, v28
	v_fmac_f32_e32 v111, v25, v22
	v_lshlrev_b32_e32 v22, 16, v32
	v_fmac_f32_e32 v103, v25, v22
	v_and_b32_e32 v22, 0xffff0000, v28
	v_fmac_f32_e32 v110, v25, v22
	v_and_b32_e32 v22, 0xffff0000, v32
	v_fmac_f32_e32 v102, v25, v22
	v_lshlrev_b32_e32 v22, 16, v29
	v_fmac_f32_e32 v109, v25, v22
	v_lshlrev_b32_e32 v22, 16, v33
	v_fmac_f32_e32 v101, v25, v22
	v_and_b32_e32 v22, 0xffff0000, v29
	v_fmac_f32_e32 v108, v25, v22
	v_and_b32_e32 v22, 0xffff0000, v33
	v_fmac_f32_e32 v49, v25, v22
	ds_read_b128 v[22:25], v40 offset:10240
	ds_read_b128 v[26:29], v40 offset:43008
	s_waitcnt lgkmcnt(0)
	v_lshlrev_b32_e32 v30, 16, v22
	v_and_b32_e32 v22, 0xffff0000, v22
	v_fmac_f32_e32 v114, v20, v22
	v_and_b32_e32 v22, 0xffff0000, v26
	v_fmac_f32_e32 v106, v20, v22
	v_lshlrev_b32_e32 v22, 16, v23
	v_fmac_f32_e32 v113, v20, v22
	v_lshlrev_b32_e32 v22, 16, v27
	v_fmac_f32_e32 v105, v20, v22
	v_and_b32_e32 v22, 0xffff0000, v23
	v_fmac_f32_e32 v112, v20, v22
	v_and_b32_e32 v22, 0xffff0000, v27
	v_fmac_f32_e32 v104, v20, v22
	v_lshlrev_b32_e32 v22, 16, v24
	v_fmac_f32_e32 v111, v20, v22
	v_lshlrev_b32_e32 v22, 16, v28
	v_fmac_f32_e32 v103, v20, v22
	v_and_b32_e32 v22, 0xffff0000, v24
	v_fmac_f32_e32 v110, v20, v22
	v_and_b32_e32 v22, 0xffff0000, v28
	v_fmac_f32_e32 v102, v20, v22
	v_lshlrev_b32_e32 v22, 16, v25
	v_fmac_f32_e32 v109, v20, v22
	v_lshlrev_b32_e32 v22, 16, v29
	v_fmac_f32_e32 v101, v20, v22
	v_and_b32_e32 v22, 0xffff0000, v25
	v_fmac_f32_e32 v108, v20, v22
	v_and_b32_e32 v22, 0xffff0000, v29
	v_fmac_f32_e32 v115, v20, v30
	v_lshlrev_b32_e32 v30, 16, v26
	v_fmac_f32_e32 v49, v20, v22
	ds_read_b128 v[22:25], v40 offset:11264
	ds_read_b128 v[26:29], v40 offset:44032
	v_fmac_f32_e32 v107, v20, v30
	s_waitcnt lgkmcnt(0)
	v_lshlrev_b32_e32 v20, 16, v22
	v_fmac_f32_e32 v115, v21, v20
	v_lshlrev_b32_e32 v20, 16, v26
	v_fmac_f32_e32 v107, v21, v20
	v_and_b32_e32 v20, 0xffff0000, v22
	v_fmac_f32_e32 v114, v21, v20
	v_and_b32_e32 v20, 0xffff0000, v26
	v_fmac_f32_e32 v106, v21, v20
	v_lshlrev_b32_e32 v20, 16, v23
	v_fmac_f32_e32 v113, v21, v20
	v_lshlrev_b32_e32 v20, 16, v27
	v_fmac_f32_e32 v105, v21, v20
	v_and_b32_e32 v20, 0xffff0000, v23
	v_fmac_f32_e32 v112, v21, v20
	v_and_b32_e32 v20, 0xffff0000, v27
	v_fmac_f32_e32 v104, v21, v20
	v_lshlrev_b32_e32 v20, 16, v24
	v_fmac_f32_e32 v111, v21, v20
	v_lshlrev_b32_e32 v20, 16, v28
	v_fmac_f32_e32 v103, v21, v20
	v_and_b32_e32 v20, 0xffff0000, v24
	v_fmac_f32_e32 v110, v21, v20
	v_and_b32_e32 v20, 0xffff0000, v28
	v_fmac_f32_e32 v102, v21, v20
	v_lshlrev_b32_e32 v20, 16, v25
	v_fmac_f32_e32 v109, v21, v20
	v_lshlrev_b32_e32 v20, 16, v29
	v_fmac_f32_e32 v101, v21, v20
	v_and_b32_e32 v20, 0xffff0000, v25
	v_fmac_f32_e32 v108, v21, v20
	v_and_b32_e32 v20, 0xffff0000, v29
	v_lshl_add_u64 v[28:29], v[90:91], 0, v[78:79]
	v_fmac_f32_e32 v49, v21, v20
	s_waitcnt vmcnt(0)
	v_mov_b32_e32 v24, v190
	v_mov_b32_e32 v25, v191
	v_mov_b32_e32 v26, v192
	v_mov_b32_e32 v27, v193
	v_mov_b32_e32 v20, v194
	v_mov_b32_e32 v21, v195
	v_mov_b32_e32 v22, v196
	v_mov_b32_e32 v23, v197
	s_waitcnt vmcnt(0)
; DI float bf2f(bfr v) { return __uint_as_float(((unsigned)v) << 16); }
; DI unsigned pk2(float a, float b) { f2_t v = {a, b}; bf2_t r = __builtin_convertvector(v, bf2_t); return __builtin_bit_cast(unsigned, r); }
; DI void phase_adaln(const Params& p, int l, unsigned char* smem) {
;     ...
;     for (int j = 0; j < 8; ++j) {
;       const int c0 = 4 * (lane + 64 * j);
;       const f32x4 g = *(const f32x4*)(ng + c0), sh = *(const f32x4*)(M + c0), sc = *(const f32x4*)(M + 2048 + c0);
;       float o[4];
;       for (int q = 0; q < 4; ++q) o[q] = v[j][q] * rs * g[q] * (1.f + sc[q]) + sh[q];
;       u32x2 w; w[0] = pk2(o[0], o[1]); w[1] = pk2(o[2], o[3]);
;       *(u32x2*)(H + ((size_t)(c0 >> 5) * NTOK + row) * 32 + (c0 & 31)) = w;
; #pragma unroll
;       for (int q = 0; q < 4; ++q) {
;         const bf16x8 w0 = ld16(sW + ((j * 4 + q) * 64 + lane) * 8), w1 = ld16(sW + 16384 + ((j * 4 + q) * 64 + lane) * 8);
; #pragma unroll
;         for (int c = 0; c < 8; ++c) { ab[c] += o[q] * bf2f((bfr)w0[c]); ab[8 + c] += o[q] * bf2f((bfr)w1[c]); }
;       }
	v_pk_mul_f32 v[16:17], v[16:17], v[24:25]
	v_mov_b32_e32 v28, v198
	v_mov_b32_e32 v29, v199
	v_mov_b32_e32 v30, v200
	v_mov_b32_e32 v31, v201
	global_load_dwordx4 v[228:231], v[46:47], off
	v_lshl_add_u64 v[236:237], v[92:93], 0, v[82:83]
	global_load_dwordx4 v[236:239], v[236:237], off
	v_lshl_add_u64 v[244:245], v[90:91], 0, v[82:83]
	global_load_dwordx4 v[244:247], v[244:245], off
	global_load_dwordx4 v[248:251], v[50:51], off
	v_lshl_add_u64 v[166:167], v[92:93], 0, v[84:85]
	global_load_dwordx4 v[166:169], v[166:167], off
	v_lshl_add_u64 v[170:171], v[90:91], 0, v[84:85]
	global_load_dwordx4 v[170:173], v[170:171], off
	global_load_dwordx4 v[174:177], v[52:53], off
	v_lshl_add_u64 v[178:179], v[92:93], 0, v[86:87]
	global_load_dwordx4 v[178:181], v[178:179], off
	v_lshl_add_u64 v[182:183], v[90:91], 0, v[86:87]
	global_load_dwordx4 v[182:185], v[182:183], off
	s_waitcnt vmcnt(0) lgkmcnt(0)
	v_pk_add_f32 v[24:25], v[28:29], 1.0 op_sel_hi:[1,0]
	s_nop 0
	v_pk_fma_f32 v[20:21], v[16:17], v[24:25], v[20:21]
	v_pk_mul_f32 v[16:17], v[18:19], v[88:89] op_sel_hi:[1,0]
	v_pk_add_f32 v[18:19], v[30:31], 1.0 op_sel_hi:[1,0]
	v_pk_mul_f32 v[16:17], v[16:17], v[26:27]
	s_nop 0
	v_pk_fma_f32 v[16:17], v[16:17], v[18:19], v[22:23]
	v_cvt_pk_bf16_f32 v18, v20, v21
	v_cvt_pk_bf16_f32 v19, v16, v17
	v_lshl_add_u64 v[22:23], s[46:47], 0, v[64:65]
	flat_store_dwordx2 v[22:23], v[18:19]
	ds_read_b128 v[22:25], v40 offset:12288
	ds_read_b128 v[26:29], v40 offset:45056
	s_waitcnt lgkmcnt(0)
	v_lshlrev_b32_e32 v18, 16, v22
	v_fmac_f32_e32 v115, v20, v18
	v_lshlrev_b32_e32 v18, 16, v26
	v_fmac_f32_e32 v107, v20, v18
	v_and_b32_e32 v18, 0xffff0000, v22
	v_fmac_f32_e32 v114, v20, v18
	v_and_b32_e32 v18, 0xffff0000, v26
	v_fmac_f32_e32 v106, v20, v18
	v_lshlrev_b32_e32 v18, 16, v23
	v_fmac_f32_e32 v113, v20, v18
	v_lshlrev_b32_e32 v18, 16, v27
	v_fmac_f32_e32 v105, v20, v18
	v_and_b32_e32 v18, 0xffff0000, v23
	v_fmac_f32_e32 v112, v20, v18
	v_and_b32_e32 v18, 0xffff0000, v27
	v_fmac_f32_e32 v104, v20, v18
	v_lshlrev_b32_e32 v18, 16, v24
	v_fmac_f32_e32 v111, v20, v18
	v_lshlrev_b32_e32 v18, 16, v28
	v_fmac_f32_e32 v103, v20, v18
	v_and_b32_e32 v18, 0xffff0000, v24
	v_fmac_f32_e32 v110, v20, v18
	v_and_b32_e32 v18, 0xffff0000, v28
	v_fmac_f32_e32 v102, v20, v18
	v_lshlrev_b32_e32 v18, 16, v25
	v_fmac_f32_e32 v109, v20, v18
	v_lshlrev_b32_e32 v18, 16, v29
	v_fmac_f32_e32 v101, v20, v18
	v_and_b32_e32 v18, 0xffff0000, v25
	v_fmac_f32_e32 v108, v20, v18
	v_and_b32_e32 v18, 0xffff0000, v29
	ds_read_b128 v[22:25], v40 offset:13312
	ds_read_b128 v[26:29], v40 offset:46080
	v_fmac_f32_e32 v49, v20, v18
	s_waitcnt lgkmcnt(0)
	v_lshlrev_b32_e32 v18, 16, v22
	v_fmac_f32_e32 v115, v21, v18
	v_lshlrev_b32_e32 v18, 16, v26
	v_fmac_f32_e32 v107, v21, v18
	v_and_b32_e32 v18, 0xffff0000, v22
	v_fmac_f32_e32 v114, v21, v18
	v_and_b32_e32 v18, 0xffff0000, v26
	v_fmac_f32_e32 v106, v21, v18
	v_lshlrev_b32_e32 v18, 16, v23
	v_fmac_f32_e32 v113, v21, v18
	v_lshlrev_b32_e32 v18, 16, v27
	v_fmac_f32_e32 v105, v21, v18
	v_and_b32_e32 v18, 0xffff0000, v23
	v_fmac_f32_e32 v112, v21, v18
	v_and_b32_e32 v18, 0xffff0000, v27
	v_fmac_f32_e32 v104, v21, v18
	v_lshlrev_b32_e32 v18, 16, v24
	v_fmac_f32_e32 v111, v21, v18
	v_lshlrev_b32_e32 v18, 16, v28
	v_fmac_f32_e32 v103, v21, v18
	v_and_b32_e32 v18, 0xffff0000, v24
	v_fmac_f32_e32 v110, v21, v18
	v_and_b32_e32 v18, 0xffff0000, v28
	v_fmac_f32_e32 v102, v21, v18
	v_lshlrev_b32_e32 v18, 16, v25
	v_fmac_f32_e32 v109, v21, v18
	v_lshlrev_b32_e32 v18, 16, v29
	v_fmac_f32_e32 v101, v21, v18
	v_and_b32_e32 v18, 0xffff0000, v25
	v_fmac_f32_e32 v108, v21, v18
	v_and_b32_e32 v18, 0xffff0000, v29
	v_fmac_f32_e32 v49, v21, v18
	ds_read_b128 v[18:21], v40 offset:14336
	ds_read_b128 v[22:25], v40 offset:47104
	s_waitcnt lgkmcnt(0)
	v_lshlrev_b32_e32 v26, 16, v18
	v_and_b32_e32 v18, 0xffff0000, v18
	v_fmac_f32_e32 v114, v16, v18
	v_and_b32_e32 v18, 0xffff0000, v22
	v_fmac_f32_e32 v106, v16, v18
	v_lshlrev_b32_e32 v18, 16, v19
	v_fmac_f32_e32 v113, v16, v18
	v_lshlrev_b32_e32 v18, 16, v23
	v_fmac_f32_e32 v105, v16, v18
	v_and_b32_e32 v18, 0xffff0000, v19
	v_fmac_f32_e32 v112, v16, v18
	v_and_b32_e32 v18, 0xffff0000, v23
	v_fmac_f32_e32 v104, v16, v18
	v_lshlrev_b32_e32 v18, 16, v20
	v_fmac_f32_e32 v111, v16, v18
	v_lshlrev_b32_e32 v18, 16, v24
	v_fmac_f32_e32 v103, v16, v18
	v_and_b32_e32 v18, 0xffff0000, v20
	v_fmac_f32_e32 v110, v16, v18
	v_and_b32_e32 v18, 0xffff0000, v24
	v_fmac_f32_e32 v102, v16, v18
	v_lshlrev_b32_e32 v18, 16, v21
	v_fmac_f32_e32 v109, v16, v18
	v_lshlrev_b32_e32 v18, 16, v25
	v_fmac_f32_e32 v101, v16, v18
	v_and_b32_e32 v18, 0xffff0000, v21
	v_fmac_f32_e32 v108, v16, v18
	v_and_b32_e32 v18, 0xffff0000, v25
	v_fmac_f32_e32 v115, v16, v26
	v_lshlrev_b32_e32 v26, 16, v22
	v_fmac_f32_e32 v49, v16, v18
	ds_read_b128 v[18:21], v40 offset:15360
	ds_read_b128 v[22:25], v40 offset:48128
	v_fmac_f32_e32 v107, v16, v26
	s_waitcnt lgkmcnt(0)
	v_lshlrev_b32_e32 v16, 16, v18
	v_fmac_f32_e32 v115, v17, v16
	v_lshlrev_b32_e32 v16, 16, v22
	v_fmac_f32_e32 v107, v17, v16
	v_and_b32_e32 v16, 0xffff0000, v18
	v_fmac_f32_e32 v114, v17, v16
	v_and_b32_e32 v16, 0xffff0000, v22
	v_fmac_f32_e32 v106, v17, v16
	v_lshlrev_b32_e32 v16, 16, v19
	v_fmac_f32_e32 v113, v17, v16
	v_lshlrev_b32_e32 v16, 16, v23
	v_fmac_f32_e32 v105, v17, v16
	v_and_b32_e32 v16, 0xffff0000, v19
	v_fmac_f32_e32 v112, v17, v16
	v_and_b32_e32 v16, 0xffff0000, v23
	v_fmac_f32_e32 v104, v17, v16
	v_lshlrev_b32_e32 v16, 16, v20
	v_fmac_f32_e32 v111, v17, v16
	v_lshlrev_b32_e32 v16, 16, v24
	v_fmac_f32_e32 v103, v17, v16
	v_and_b32_e32 v16, 0xffff0000, v20
	v_fmac_f32_e32 v110, v17, v16
	v_and_b32_e32 v16, 0xffff0000, v24
	v_fmac_f32_e32 v102, v17, v16
	v_lshlrev_b32_e32 v16, 16, v21
	v_fmac_f32_e32 v109, v17, v16
	v_lshlrev_b32_e32 v16, 16, v25
	v_fmac_f32_e32 v101, v17, v16
	v_and_b32_e32 v16, 0xffff0000, v21
	v_fmac_f32_e32 v108, v17, v16
	v_and_b32_e32 v16, 0xffff0000, v25
	v_fmac_f32_e32 v49, v17, v16
	v_lshl_add_u64 v[16:17], v[92:93], 0, v[80:81]
	v_lshl_add_u64 v[24:25], v[90:91], 0, v[80:81]
	s_waitcnt vmcnt(0)
; DI float bf2f(bfr v) { return __uint_as_float(((unsigned)v) << 16); }
; DI unsigned pk2(float a, float b) { f2_t v = {a, b}; bf2_t r = __builtin_convertvector(v, bf2_t); return __builtin_bit_cast(unsigned, r); }
; DI void phase_adaln(const Params& p, int l, unsigned char* smem) {
;     ...
;     for (int j = 0; j < 8; ++j) {
;       const int c0 = 4 * (lane + 64 * j);
;       const f32x4 g = *(const f32x4*)(ng + c0), sh = *(const f32x4*)(M + c0), sc = *(const f32x4*)(M + 2048 + c0);
;       float o[4];
;       for (int q = 0; q < 4; ++q) o[q] = v[j][q] * rs * g[q] * (1.f + sc[q]) + sh[q];
;       u32x2 w; w[0] = pk2(o[0], o[1]); w[1] = pk2(o[2], o[3]);
;       *(u32x2*)(H + ((size_t)(c0 >> 5) * NTOK + row) * 32 + (c0 & 31)) = w;
; #pragma unroll
;       for (int q = 0; q < 4; ++q) {
;         const bf16x8 w0 = ld16(sW + ((j * 4 + q) * 64 + lane) * 8), w1 = ld16(sW + 16384 + ((j * 4 + q) * 64 + lane) * 8);
; #pragma unroll
;         for (int c = 0; c < 8; ++c) { ab[c] += o[q] * bf2f((bfr)w0[c]); ab[8 + c] += o[q] * bf2f((bfr)w1[c]); }
;       }
	v_mov_b32_e32 v20, v202
	v_mov_b32_e32 v21, v203
	v_mov_b32_e32 v22, v204
	v_mov_b32_e32 v23, v205
	s_waitcnt vmcnt(0)
	v_pk_mul_f32 v[12:13], v[12:13], v[20:21]
	v_mov_b32_e32 v16, v212
	v_mov_b32_e32 v17, v213
	v_mov_b32_e32 v18, v214
	v_mov_b32_e32 v19, v215
	s_nop 0
	v_mov_b32_e32 v24, v224
	v_mov_b32_e32 v25, v225
	v_mov_b32_e32 v26, v226
	v_mov_b32_e32 v27, v227
	s_waitcnt vmcnt(0) lgkmcnt(0)
	v_pk_add_f32 v[20:21], v[24:25], 1.0 op_sel_hi:[1,0]
	s_nop 0
	v_pk_fma_f32 v[16:17], v[12:13], v[20:21], v[16:17]
	v_pk_mul_f32 v[12:13], v[14:15], v[88:89] op_sel_hi:[1,0]
	v_pk_add_f32 v[14:15], v[26:27], 1.0 op_sel_hi:[1,0]
	v_pk_mul_f32 v[12:13], v[12:13], v[22:23]
	s_nop 0
	v_pk_fma_f32 v[12:13], v[12:13], v[14:15], v[18:19]
	v_cvt_pk_bf16_f32 v14, v16, v17
	v_cvt_pk_bf16_f32 v15, v12, v13
	v_lshl_add_u64 v[18:19], s[46:47], 0, v[62:63]
	flat_store_dwordx2 v[18:19], v[14:15]
	ds_read_b128 v[18:21], v40 offset:16384
	ds_read_b128 v[22:25], v40 offset:49152
	s_waitcnt lgkmcnt(0)
	v_lshlrev_b32_e32 v14, 16, v18
	v_fmac_f32_e32 v115, v16, v14
	v_lshlrev_b32_e32 v14, 16, v22
	v_fmac_f32_e32 v107, v16, v14
	v_and_b32_e32 v14, 0xffff0000, v18
	v_fmac_f32_e32 v114, v16, v14
	v_and_b32_e32 v14, 0xffff0000, v22
	v_fmac_f32_e32 v106, v16, v14
	v_lshlrev_b32_e32 v14, 16, v19
	v_fmac_f32_e32 v113, v16, v14
	v_lshlrev_b32_e32 v14, 16, v23
	v_fmac_f32_e32 v105, v16, v14
	v_and_b32_e32 v14, 0xffff0000, v19
	v_fmac_f32_e32 v112, v16, v14
	v_and_b32_e32 v14, 0xffff0000, v23
	v_fmac_f32_e32 v104, v16, v14
	v_lshlrev_b32_e32 v14, 16, v20
	v_fmac_f32_e32 v111, v16, v14
	v_lshlrev_b32_e32 v14, 16, v24
	v_fmac_f32_e32 v103, v16, v14
	v_and_b32_e32 v14, 0xffff0000, v20
	v_fmac_f32_e32 v110, v16, v14
	v_and_b32_e32 v14, 0xffff0000, v24
	v_fmac_f32_e32 v102, v16, v14
	v_lshlrev_b32_e32 v14, 16, v21
	v_fmac_f32_e32 v109, v16, v14
	v_lshlrev_b32_e32 v14, 16, v25
	v_fmac_f32_e32 v101, v16, v14
	v_and_b32_e32 v14, 0xffff0000, v21
	v_fmac_f32_e32 v108, v16, v14
	v_and_b32_e32 v14, 0xffff0000, v25
	ds_read_b128 v[18:21], v40 offset:17408
	ds_read_b128 v[22:25], v40 offset:50176
	v_fmac_f32_e32 v49, v16, v14
	s_waitcnt lgkmcnt(0)
	v_lshlrev_b32_e32 v14, 16, v18
	v_fmac_f32_e32 v115, v17, v14
	v_lshlrev_b32_e32 v14, 16, v22
	v_fmac_f32_e32 v107, v17, v14
	v_and_b32_e32 v14, 0xffff0000, v18
	v_fmac_f32_e32 v114, v17, v14
	v_and_b32_e32 v14, 0xffff0000, v22
	v_fmac_f32_e32 v106, v17, v14
	v_lshlrev_b32_e32 v14, 16, v19
	v_fmac_f32_e32 v113, v17, v14
	v_lshlrev_b32_e32 v14, 16, v23
	v_fmac_f32_e32 v105, v17, v14
	v_and_b32_e32 v14, 0xffff0000, v19
	v_fmac_f32_e32 v112, v17, v14
	v_and_b32_e32 v14, 0xffff0000, v23
	v_fmac_f32_e32 v104, v17, v14
	v_lshlrev_b32_e32 v14, 16, v20
	v_fmac_f32_e32 v111, v17, v14
	v_lshlrev_b32_e32 v14, 16, v24
	v_fmac_f32_e32 v103, v17, v14
	v_and_b32_e32 v14, 0xffff0000, v20
	v_fmac_f32_e32 v110, v17, v14
	v_and_b32_e32 v14, 0xffff0000, v24
	v_fmac_f32_e32 v102, v17, v14
	v_lshlrev_b32_e32 v14, 16, v21
	v_fmac_f32_e32 v109, v17, v14
	v_lshlrev_b32_e32 v14, 16, v25
	v_fmac_f32_e32 v101, v17, v14
	v_and_b32_e32 v14, 0xffff0000, v21
	v_fmac_f32_e32 v108, v17, v14
	v_and_b32_e32 v14, 0xffff0000, v25
	v_fmac_f32_e32 v49, v17, v14
	ds_read_b128 v[14:17], v40 offset:18432
	ds_read_b128 v[18:21], v40 offset:51200
	s_waitcnt lgkmcnt(0)
	v_lshlrev_b32_e32 v22, 16, v14
	v_and_b32_e32 v14, 0xffff0000, v14
	v_fmac_f32_e32 v114, v12, v14
	v_and_b32_e32 v14, 0xffff0000, v18
	v_fmac_f32_e32 v106, v12, v14
	v_lshlrev_b32_e32 v14, 16, v15
	v_fmac_f32_e32 v113, v12, v14
	v_lshlrev_b32_e32 v14, 16, v19
	v_fmac_f32_e32 v105, v12, v14
	v_and_b32_e32 v14, 0xffff0000, v15
	v_fmac_f32_e32 v112, v12, v14
	v_and_b32_e32 v14, 0xffff0000, v19
	v_fmac_f32_e32 v104, v12, v14
	v_lshlrev_b32_e32 v14, 16, v16
	v_fmac_f32_e32 v111, v12, v14
	v_lshlrev_b32_e32 v14, 16, v20
	v_fmac_f32_e32 v103, v12, v14
	v_and_b32_e32 v14, 0xffff0000, v16
	v_fmac_f32_e32 v110, v12, v14
	v_and_b32_e32 v14, 0xffff0000, v20
	v_fmac_f32_e32 v102, v12, v14
	v_lshlrev_b32_e32 v14, 16, v17
	v_fmac_f32_e32 v109, v12, v14
	v_lshlrev_b32_e32 v14, 16, v21
	v_fmac_f32_e32 v101, v12, v14
	v_and_b32_e32 v14, 0xffff0000, v17
	v_fmac_f32_e32 v108, v12, v14
	v_and_b32_e32 v14, 0xffff0000, v21
	v_fmac_f32_e32 v115, v12, v22
	v_lshlrev_b32_e32 v22, 16, v18
	v_fmac_f32_e32 v49, v12, v14
	ds_read_b128 v[14:17], v40 offset:19456
	ds_read_b128 v[18:21], v40 offset:52224
	v_fmac_f32_e32 v107, v12, v22
	s_waitcnt lgkmcnt(0)
	v_lshlrev_b32_e32 v12, 16, v14
	v_fmac_f32_e32 v115, v13, v12
	v_lshlrev_b32_e32 v12, 16, v18
	v_fmac_f32_e32 v107, v13, v12
	v_and_b32_e32 v12, 0xffff0000, v14
	v_fmac_f32_e32 v114, v13, v12
	v_and_b32_e32 v12, 0xffff0000, v18
	v_fmac_f32_e32 v106, v13, v12
	v_lshlrev_b32_e32 v12, 16, v15
	v_fmac_f32_e32 v113, v13, v12
	v_lshlrev_b32_e32 v12, 16, v19
	v_fmac_f32_e32 v105, v13, v12
	v_and_b32_e32 v12, 0xffff0000, v15
	v_fmac_f32_e32 v112, v13, v12
	v_and_b32_e32 v12, 0xffff0000, v19
	v_fmac_f32_e32 v104, v13, v12
	v_lshlrev_b32_e32 v12, 16, v16
	v_fmac_f32_e32 v111, v13, v12
	v_lshlrev_b32_e32 v12, 16, v20
	v_fmac_f32_e32 v103, v13, v12
	v_and_b32_e32 v12, 0xffff0000, v16
	v_fmac_f32_e32 v110, v13, v12
	v_and_b32_e32 v12, 0xffff0000, v20
	v_fmac_f32_e32 v102, v13, v12
	v_lshlrev_b32_e32 v12, 16, v17
	v_fmac_f32_e32 v109, v13, v12
	v_lshlrev_b32_e32 v12, 16, v21
	v_fmac_f32_e32 v101, v13, v12
	v_and_b32_e32 v12, 0xffff0000, v17
	v_fmac_f32_e32 v108, v13, v12
	v_and_b32_e32 v12, 0xffff0000, v21
	v_fmac_f32_e32 v49, v13, v12
	v_lshl_add_u64 v[12:13], v[92:93], 0, v[82:83]
	v_lshl_add_u64 v[20:21], v[90:91], 0, v[82:83]
	s_waitcnt vmcnt(0)
	v_mov_b32_e32 v16, v228
	v_mov_b32_e32 v17, v229
	v_mov_b32_e32 v18, v230
	v_mov_b32_e32 v19, v231
	s_waitcnt vmcnt(0)
; DI float bf2f(bfr v) { return __uint_as_float(((unsigned)v) << 16); }
; DI unsigned pk2(float a, float b) { f2_t v = {a, b}; bf2_t r = __builtin_convertvector(v, bf2_t); return __builtin_bit_cast(unsigned, r); }
; DI void phase_adaln(const Params& p, int l, unsigned char* smem) {
;     ...
;     for (int j = 0; j < 8; ++j) {
;       const int c0 = 4 * (lane + 64 * j);
;       const f32x4 g = *(const f32x4*)(ng + c0), sh = *(const f32x4*)(M + c0), sc = *(const f32x4*)(M + 2048 + c0);
;       float o[4];
;       for (int q = 0; q < 4; ++q) o[q] = v[j][q] * rs * g[q] * (1.f + sc[q]) + sh[q];
;       u32x2 w; w[0] = pk2(o[0], o[1]); w[1] = pk2(o[2], o[3]);
;       *(u32x2*)(H + ((size_t)(c0 >> 5) * NTOK + row) * 32 + (c0 & 31)) = w;
; #pragma unroll
;       for (int q = 0; q < 4; ++q) {
;         const bf16x8 w0 = ld16(sW + ((j * 4 + q) * 64 + lane) * 8), w1 = ld16(sW + 16384 + ((j * 4 + q) * 64 + lane) * 8);
; #pragma unroll
;         for (int c = 0; c < 8; ++c) { ab[c] += o[q] * bf2f((bfr)w0[c]); ab[8 + c] += o[q] * bf2f((bfr)w1[c]); }
;       }
	v_pk_mul_f32 v[8:9], v[8:9], v[16:17]
	v_mov_b32_e32 v12, v236
	v_mov_b32_e32 v13, v237
	v_mov_b32_e32 v14, v238
	v_mov_b32_e32 v15, v239
	s_nop 0
	v_mov_b32_e32 v20, v244
	v_mov_b32_e32 v21, v245
	v_mov_b32_e32 v22, v246
	v_mov_b32_e32 v23, v247
	s_waitcnt vmcnt(0) lgkmcnt(0)
	v_pk_add_f32 v[16:17], v[20:21], 1.0 op_sel_hi:[1,0]
	s_nop 0
	v_pk_fma_f32 v[12:13], v[8:9], v[16:17], v[12:13]
	v_pk_mul_f32 v[8:9], v[10:11], v[88:89] op_sel_hi:[1,0]
	v_pk_add_f32 v[10:11], v[22:23], 1.0 op_sel_hi:[1,0]
	v_pk_mul_f32 v[8:9], v[8:9], v[18:19]
	s_nop 0
	v_pk_fma_f32 v[8:9], v[8:9], v[10:11], v[14:15]
	v_cvt_pk_bf16_f32 v10, v12, v13
	v_cvt_pk_bf16_f32 v11, v8, v9
	v_lshl_add_u64 v[14:15], s[46:47], 0, v[60:61]
	flat_store_dwordx2 v[14:15], v[10:11]
	ds_read_b128 v[14:17], v40 offset:20480
	ds_read_b128 v[18:21], v40 offset:53248
	s_waitcnt lgkmcnt(0)
	v_lshlrev_b32_e32 v10, 16, v14
	v_fmac_f32_e32 v115, v12, v10
	v_lshlrev_b32_e32 v10, 16, v18
	v_fmac_f32_e32 v107, v12, v10
	v_and_b32_e32 v10, 0xffff0000, v14
	v_fmac_f32_e32 v114, v12, v10
	v_and_b32_e32 v10, 0xffff0000, v18
	v_fmac_f32_e32 v106, v12, v10
	v_lshlrev_b32_e32 v10, 16, v15
	v_fmac_f32_e32 v113, v12, v10
	v_lshlrev_b32_e32 v10, 16, v19
	v_fmac_f32_e32 v105, v12, v10
	v_and_b32_e32 v10, 0xffff0000, v15
	v_fmac_f32_e32 v112, v12, v10
	v_and_b32_e32 v10, 0xffff0000, v19
	v_fmac_f32_e32 v104, v12, v10
	v_lshlrev_b32_e32 v10, 16, v16
	v_fmac_f32_e32 v111, v12, v10
	v_lshlrev_b32_e32 v10, 16, v20
	v_fmac_f32_e32 v103, v12, v10
	v_and_b32_e32 v10, 0xffff0000, v16
	v_fmac_f32_e32 v110, v12, v10
	v_and_b32_e32 v10, 0xffff0000, v20
	v_fmac_f32_e32 v102, v12, v10
	v_lshlrev_b32_e32 v10, 16, v17
	v_fmac_f32_e32 v109, v12, v10
	v_lshlrev_b32_e32 v10, 16, v21
	v_fmac_f32_e32 v101, v12, v10
	v_and_b32_e32 v10, 0xffff0000, v17
	v_fmac_f32_e32 v108, v12, v10
	v_and_b32_e32 v10, 0xffff0000, v21
	ds_read_b128 v[14:17], v40 offset:21504
	ds_read_b128 v[18:21], v40 offset:54272
	v_fmac_f32_e32 v49, v12, v10
	s_waitcnt lgkmcnt(0)
	v_lshlrev_b32_e32 v10, 16, v14
	v_fmac_f32_e32 v115, v13, v10
	v_lshlrev_b32_e32 v10, 16, v18
	v_fmac_f32_e32 v107, v13, v10
	v_and_b32_e32 v10, 0xffff0000, v14
	v_fmac_f32_e32 v114, v13, v10
	v_and_b32_e32 v10, 0xffff0000, v18
	v_fmac_f32_e32 v106, v13, v10
	v_lshlrev_b32_e32 v10, 16, v15
	v_fmac_f32_e32 v113, v13, v10
	v_lshlrev_b32_e32 v10, 16, v19
	v_fmac_f32_e32 v105, v13, v10
	v_and_b32_e32 v10, 0xffff0000, v15
	v_fmac_f32_e32 v112, v13, v10
	v_and_b32_e32 v10, 0xffff0000, v19
	v_fmac_f32_e32 v104, v13, v10
	v_lshlrev_b32_e32 v10, 16, v16
	v_fmac_f32_e32 v111, v13, v10
	v_lshlrev_b32_e32 v10, 16, v20
	v_fmac_f32_e32 v103, v13, v10
	v_and_b32_e32 v10, 0xffff0000, v16
	v_fmac_f32_e32 v110, v13, v10
	v_and_b32_e32 v10, 0xffff0000, v20
	v_fmac_f32_e32 v102, v13, v10
	v_lshlrev_b32_e32 v10, 16, v17
	v_fmac_f32_e32 v109, v13, v10
	v_lshlrev_b32_e32 v10, 16, v21
	v_fmac_f32_e32 v101, v13, v10
	v_and_b32_e32 v10, 0xffff0000, v17
	v_fmac_f32_e32 v108, v13, v10
	v_and_b32_e32 v10, 0xffff0000, v21
	v_fmac_f32_e32 v49, v13, v10
	ds_read_b128 v[10:13], v40 offset:22528
	ds_read_b128 v[14:17], v40 offset:55296
	s_waitcnt lgkmcnt(0)
	v_lshlrev_b32_e32 v18, 16, v10
	v_and_b32_e32 v10, 0xffff0000, v10
	v_fmac_f32_e32 v114, v8, v10
	v_and_b32_e32 v10, 0xffff0000, v14
	v_fmac_f32_e32 v106, v8, v10
	v_lshlrev_b32_e32 v10, 16, v11
	v_fmac_f32_e32 v113, v8, v10
	v_lshlrev_b32_e32 v10, 16, v15
	v_fmac_f32_e32 v105, v8, v10
	v_and_b32_e32 v10, 0xffff0000, v11
	v_fmac_f32_e32 v112, v8, v10
	v_and_b32_e32 v10, 0xffff0000, v15
	v_fmac_f32_e32 v104, v8, v10
	v_lshlrev_b32_e32 v10, 16, v12
	v_fmac_f32_e32 v111, v8, v10
	v_lshlrev_b32_e32 v10, 16, v16
	v_fmac_f32_e32 v103, v8, v10
	v_and_b32_e32 v10, 0xffff0000, v12
	v_fmac_f32_e32 v110, v8, v10
	v_and_b32_e32 v10, 0xffff0000, v16
	v_fmac_f32_e32 v102, v8, v10
	v_lshlrev_b32_e32 v10, 16, v13
	v_fmac_f32_e32 v109, v8, v10
	v_lshlrev_b32_e32 v10, 16, v17
	v_fmac_f32_e32 v101, v8, v10
	v_and_b32_e32 v10, 0xffff0000, v13
	v_fmac_f32_e32 v108, v8, v10
	v_and_b32_e32 v10, 0xffff0000, v17
	v_fmac_f32_e32 v115, v8, v18
	v_lshlrev_b32_e32 v18, 16, v14
	v_fmac_f32_e32 v49, v8, v10
	ds_read_b128 v[10:13], v40 offset:23552
	ds_read_b128 v[14:17], v40 offset:56320
	v_fmac_f32_e32 v107, v8, v18
	s_waitcnt lgkmcnt(0)
	v_lshlrev_b32_e32 v8, 16, v10
	v_fmac_f32_e32 v115, v9, v8
	v_lshlrev_b32_e32 v8, 16, v14
	v_fmac_f32_e32 v107, v9, v8
	v_and_b32_e32 v8, 0xffff0000, v10
	v_fmac_f32_e32 v114, v9, v8
	v_and_b32_e32 v8, 0xffff0000, v14
	v_fmac_f32_e32 v106, v9, v8
	v_lshlrev_b32_e32 v8, 16, v11
	v_fmac_f32_e32 v113, v9, v8
	v_lshlrev_b32_e32 v8, 16, v15
	v_fmac_f32_e32 v105, v9, v8
	v_and_b32_e32 v8, 0xffff0000, v11
	v_fmac_f32_e32 v112, v9, v8
	v_and_b32_e32 v8, 0xffff0000, v15
	v_fmac_f32_e32 v104, v9, v8
	v_lshlrev_b32_e32 v8, 16, v12
	v_fmac_f32_e32 v111, v9, v8
	v_lshlrev_b32_e32 v8, 16, v16
	v_fmac_f32_e32 v103, v9, v8
	v_and_b32_e32 v8, 0xffff0000, v12
	v_fmac_f32_e32 v110, v9, v8
	v_and_b32_e32 v8, 0xffff0000, v16
	v_fmac_f32_e32 v102, v9, v8
	v_lshlrev_b32_e32 v8, 16, v13
	v_fmac_f32_e32 v109, v9, v8
	v_lshlrev_b32_e32 v8, 16, v17
	v_fmac_f32_e32 v101, v9, v8
	v_and_b32_e32 v8, 0xffff0000, v13
	v_fmac_f32_e32 v108, v9, v8
	v_and_b32_e32 v8, 0xffff0000, v17
	v_fmac_f32_e32 v49, v9, v8
	v_lshl_add_u64 v[8:9], v[92:93], 0, v[84:85]
	v_lshl_add_u64 v[16:17], v[90:91], 0, v[84:85]
	s_waitcnt vmcnt(0)
	v_mov_b32_e32 v12, v248
	v_mov_b32_e32 v13, v249
	v_mov_b32_e32 v14, v250
	v_mov_b32_e32 v15, v251
	s_waitcnt vmcnt(0)
	v_pk_mul_f32 v[4:5], v[4:5], v[12:13]
	v_mov_b32_e32 v8, v166
	v_mov_b32_e32 v9, v167
	v_mov_b32_e32 v10, v168
	v_mov_b32_e32 v11, v169
	s_nop 0
	v_mov_b32_e32 v16, v170
	v_mov_b32_e32 v17, v171
	v_mov_b32_e32 v18, v172
	v_mov_b32_e32 v19, v173
	s_waitcnt vmcnt(0) lgkmcnt(0)
; DI float bf2f(bfr v) { return __uint_as_float(((unsigned)v) << 16); }
; DI unsigned pk2(float a, float b) { f2_t v = {a, b}; bf2_t r = __builtin_convertvector(v, bf2_t); return __builtin_bit_cast(unsigned, r); }
; DI void phase_adaln(const Params& p, int l, unsigned char* smem) {
;     ...
; #pragma unroll
;     for (int j = 0; j < 8; ++j) {
;       const int c0 = 4 * (lane + 64 * j);
;       const f32x4 g = *(const f32x4*)(ng + c0), sh = *(const f32x4*)(M + c0), sc = *(const f32x4*)(M + 2048 + c0);
;       float o[4];
;       for (int q = 0; q < 4; ++q) o[q] = v[j][q] * rs * g[q] * (1.f + sc[q]) + sh[q];
;       u32x2 w; w[0] = pk2(o[0], o[1]); w[1] = pk2(o[2], o[3]);
;       *(u32x2*)(H + ((size_t)(c0 >> 5) * NTOK + row) * 32 + (c0 & 31)) = w;
; #pragma unroll
;       for (int q = 0; q < 4; ++q) {
;         const bf16x8 w0 = ld16(sW + ((j * 4 + q) * 64 + lane) * 8), w1 = ld16(sW + 16384 + ((j * 4 + q) * 64 + lane) * 8);
; #pragma unroll
;         for (int c = 0; c < 8; ++c) { ab[c] += o[q] * bf2f((bfr)w0[c]); ab[8 + c] += o[q] * bf2f((bfr)w1[c]); }
;       }
;     }
	v_pk_add_f32 v[12:13], v[16:17], 1.0 op_sel_hi:[1,0]
	s_nop 0
	v_pk_fma_f32 v[8:9], v[4:5], v[12:13], v[8:9]
	v_pk_mul_f32 v[4:5], v[6:7], v[88:89] op_sel_hi:[1,0]
	v_pk_add_f32 v[6:7], v[18:19], 1.0 op_sel_hi:[1,0]
	v_pk_mul_f32 v[4:5], v[4:5], v[14:15]
	s_nop 0
	v_pk_fma_f32 v[4:5], v[4:5], v[6:7], v[10:11]
	v_cvt_pk_bf16_f32 v6, v8, v9
	v_cvt_pk_bf16_f32 v7, v4, v5
	v_lshl_add_u64 v[10:11], s[46:47], 0, v[58:59]
	flat_store_dwordx2 v[10:11], v[6:7]
	ds_read_b128 v[10:13], v40 offset:24576
	ds_read_b128 v[14:17], v40 offset:57344
	s_waitcnt lgkmcnt(0)
	v_lshlrev_b32_e32 v6, 16, v10
	v_fmac_f32_e32 v115, v8, v6
	v_lshlrev_b32_e32 v6, 16, v14
	v_fmac_f32_e32 v107, v8, v6
	v_and_b32_e32 v6, 0xffff0000, v10
	v_fmac_f32_e32 v114, v8, v6
	v_and_b32_e32 v6, 0xffff0000, v14
	v_fmac_f32_e32 v106, v8, v6
	v_lshlrev_b32_e32 v6, 16, v11
	v_fmac_f32_e32 v113, v8, v6
	v_lshlrev_b32_e32 v6, 16, v15
	v_fmac_f32_e32 v105, v8, v6
	v_and_b32_e32 v6, 0xffff0000, v11
	v_fmac_f32_e32 v112, v8, v6
	v_and_b32_e32 v6, 0xffff0000, v15
	v_fmac_f32_e32 v104, v8, v6
	v_lshlrev_b32_e32 v6, 16, v12
	v_fmac_f32_e32 v111, v8, v6
	v_lshlrev_b32_e32 v6, 16, v16
	v_fmac_f32_e32 v103, v8, v6
	v_and_b32_e32 v6, 0xffff0000, v12
	v_fmac_f32_e32 v110, v8, v6
	v_and_b32_e32 v6, 0xffff0000, v16
	v_fmac_f32_e32 v102, v8, v6
	v_lshlrev_b32_e32 v6, 16, v13
	v_fmac_f32_e32 v109, v8, v6
	v_lshlrev_b32_e32 v6, 16, v17
	v_fmac_f32_e32 v101, v8, v6
	v_and_b32_e32 v6, 0xffff0000, v13
	v_fmac_f32_e32 v108, v8, v6
	v_and_b32_e32 v6, 0xffff0000, v17
	ds_read_b128 v[10:13], v40 offset:25600
	ds_read_b128 v[14:17], v40 offset:58368
	v_fmac_f32_e32 v49, v8, v6
	s_waitcnt lgkmcnt(0)
	v_lshlrev_b32_e32 v6, 16, v10
	v_fmac_f32_e32 v115, v9, v6
	v_lshlrev_b32_e32 v6, 16, v14
	v_fmac_f32_e32 v107, v9, v6
	v_and_b32_e32 v6, 0xffff0000, v10
	v_fmac_f32_e32 v114, v9, v6
	v_and_b32_e32 v6, 0xffff0000, v14
	v_fmac_f32_e32 v106, v9, v6
	v_lshlrev_b32_e32 v6, 16, v11
	v_fmac_f32_e32 v113, v9, v6
	v_lshlrev_b32_e32 v6, 16, v15
	v_fmac_f32_e32 v105, v9, v6
	v_and_b32_e32 v6, 0xffff0000, v11
	v_fmac_f32_e32 v112, v9, v6
	v_and_b32_e32 v6, 0xffff0000, v15
	v_fmac_f32_e32 v104, v9, v6
	v_lshlrev_b32_e32 v6, 16, v12
	v_fmac_f32_e32 v111, v9, v6
	v_lshlrev_b32_e32 v6, 16, v16
	v_fmac_f32_e32 v103, v9, v6
	v_and_b32_e32 v6, 0xffff0000, v12
	v_fmac_f32_e32 v110, v9, v6
	v_and_b32_e32 v6, 0xffff0000, v16
	v_fmac_f32_e32 v102, v9, v6
	v_lshlrev_b32_e32 v6, 16, v13
	v_fmac_f32_e32 v109, v9, v6
	v_lshlrev_b32_e32 v6, 16, v17
	v_fmac_f32_e32 v101, v9, v6
	v_and_b32_e32 v6, 0xffff0000, v13
	v_fmac_f32_e32 v108, v9, v6
	v_and_b32_e32 v6, 0xffff0000, v17
	v_fmac_f32_e32 v49, v9, v6
	ds_read_b128 v[6:9], v40 offset:26624
	ds_read_b128 v[10:13], v40 offset:59392
	s_waitcnt lgkmcnt(0)
	v_lshlrev_b32_e32 v14, 16, v6
	v_and_b32_e32 v6, 0xffff0000, v6
	v_fmac_f32_e32 v114, v4, v6
	v_and_b32_e32 v6, 0xffff0000, v10
	v_fmac_f32_e32 v106, v4, v6
	v_lshlrev_b32_e32 v6, 16, v7
	v_fmac_f32_e32 v113, v4, v6
	v_lshlrev_b32_e32 v6, 16, v11
	v_fmac_f32_e32 v105, v4, v6
	v_and_b32_e32 v6, 0xffff0000, v7
	v_fmac_f32_e32 v112, v4, v6
	v_and_b32_e32 v6, 0xffff0000, v11
	v_fmac_f32_e32 v104, v4, v6
	v_lshlrev_b32_e32 v6, 16, v8
	v_fmac_f32_e32 v111, v4, v6
	v_lshlrev_b32_e32 v6, 16, v12
	v_fmac_f32_e32 v103, v4, v6
	v_and_b32_e32 v6, 0xffff0000, v8
	v_fmac_f32_e32 v110, v4, v6
	v_and_b32_e32 v6, 0xffff0000, v12
	v_fmac_f32_e32 v102, v4, v6
	v_lshlrev_b32_e32 v6, 16, v9
	v_fmac_f32_e32 v109, v4, v6
	v_lshlrev_b32_e32 v6, 16, v13
	v_fmac_f32_e32 v101, v4, v6
	v_and_b32_e32 v6, 0xffff0000, v9
	v_fmac_f32_e32 v108, v4, v6
	v_and_b32_e32 v6, 0xffff0000, v13
	v_fmac_f32_e32 v115, v4, v14
	v_lshlrev_b32_e32 v14, 16, v10
	v_fmac_f32_e32 v49, v4, v6
	ds_read_b128 v[6:9], v40 offset:27648
	ds_read_b128 v[10:13], v40 offset:60416
	v_fmac_f32_e32 v107, v4, v14
	s_waitcnt lgkmcnt(0)
	v_lshlrev_b32_e32 v4, 16, v6
	v_fmac_f32_e32 v115, v5, v4
	v_lshlrev_b32_e32 v4, 16, v10
	v_fmac_f32_e32 v107, v5, v4
	v_and_b32_e32 v4, 0xffff0000, v6
	v_fmac_f32_e32 v114, v5, v4
	v_and_b32_e32 v4, 0xffff0000, v10
	v_fmac_f32_e32 v106, v5, v4
	v_lshlrev_b32_e32 v4, 16, v7
	v_fmac_f32_e32 v113, v5, v4
	v_lshlrev_b32_e32 v4, 16, v11
	v_fmac_f32_e32 v105, v5, v4
	v_and_b32_e32 v4, 0xffff0000, v7
	v_fmac_f32_e32 v112, v5, v4
	v_and_b32_e32 v4, 0xffff0000, v11
	v_fmac_f32_e32 v104, v5, v4
	v_lshlrev_b32_e32 v4, 16, v8
	v_fmac_f32_e32 v111, v5, v4
	v_lshlrev_b32_e32 v4, 16, v12
	v_fmac_f32_e32 v103, v5, v4
	v_and_b32_e32 v4, 0xffff0000, v8
	v_fmac_f32_e32 v110, v5, v4
	v_and_b32_e32 v4, 0xffff0000, v12
	v_fmac_f32_e32 v102, v5, v4
	v_lshlrev_b32_e32 v4, 16, v9
	v_fmac_f32_e32 v109, v5, v4
	v_lshlrev_b32_e32 v4, 16, v13
	v_fmac_f32_e32 v101, v5, v4
	v_and_b32_e32 v4, 0xffff0000, v9
	v_fmac_f32_e32 v108, v5, v4
	v_and_b32_e32 v4, 0xffff0000, v13
	v_fmac_f32_e32 v49, v5, v4
	v_lshl_add_u64 v[4:5], v[92:93], 0, v[86:87]
	v_lshl_add_u64 v[12:13], v[90:91], 0, v[86:87]
	s_waitcnt vmcnt(0)
	v_mov_b32_e32 v8, v174
	v_mov_b32_e32 v9, v175
	v_mov_b32_e32 v10, v176
	v_mov_b32_e32 v11, v177
	s_waitcnt vmcnt(0)
	v_pk_mul_f32 v[0:1], v[0:1], v[8:9]
	v_mov_b32_e32 v4, v178
	v_mov_b32_e32 v5, v179
	v_mov_b32_e32 v6, v180
	v_mov_b32_e32 v7, v181
	s_nop 0
	v_mov_b32_e32 v12, v182
	v_mov_b32_e32 v13, v183
	v_mov_b32_e32 v14, v184
	v_mov_b32_e32 v15, v185
	s_waitcnt vmcnt(0) lgkmcnt(0)
	v_pk_add_f32 v[8:9], v[12:13], 1.0 op_sel_hi:[1,0]
	s_nop 0
	v_pk_fma_f32 v[4:5], v[0:1], v[8:9], v[4:5]
	v_pk_mul_f32 v[0:1], v[2:3], v[88:89] op_sel_hi:[1,0]
	v_pk_add_f32 v[2:3], v[14:15], 1.0 op_sel_hi:[1,0]
	v_pk_mul_f32 v[0:1], v[0:1], v[10:11]
	s_nop 0
	v_pk_fma_f32 v[0:1], v[0:1], v[2:3], v[6:7]
	v_cvt_pk_bf16_f32 v2, v4, v5
	v_cvt_pk_bf16_f32 v3, v0, v1
	v_lshl_add_u64 v[6:7], s[46:47], 0, v[56:57]
	flat_store_dwordx2 v[6:7], v[2:3]
	ds_read_b128 v[6:9], v40 offset:28672
	ds_read_b128 v[10:13], v40 offset:61440
	s_waitcnt lgkmcnt(0)
; DI float bf2f(bfr v) { return __uint_as_float(((unsigned)v) << 16); }
; DI void phase_adaln(const Params& p, int l, unsigned char* smem) {
;     ...
; #pragma unroll
;       for (int q = 0; q < 4; ++q) {
;         const bf16x8 w0 = ld16(sW + ((j * 4 + q) * 64 + lane) * 8), w1 = ld16(sW + 16384 + ((j * 4 + q) * 64 + lane) * 8);
; #pragma unroll
;         for (int c = 0; c < 8; ++c) { ab[c] += o[q] * bf2f((bfr)w0[c]); ab[8 + c] += o[q] * bf2f((bfr)w1[c]); }
;       }
;     }
; #pragma unroll
;     for (int c = 0; c < 16; ++c) {
;       float s = ab[c];
; #pragma unroll
;       for (int o = 1; o < 64; o <<= 1) s += __shfl_xor(s, o);
;       ab[c] = s;
;     }
	v_lshlrev_b32_e32 v2, 16, v6
	v_fmac_f32_e32 v115, v4, v2
	v_lshlrev_b32_e32 v2, 16, v10
	v_fmac_f32_e32 v107, v4, v2
	v_and_b32_e32 v2, 0xffff0000, v6
	v_fmac_f32_e32 v114, v4, v2
	v_and_b32_e32 v2, 0xffff0000, v10
	v_fmac_f32_e32 v106, v4, v2
	v_lshlrev_b32_e32 v2, 16, v7
	v_fmac_f32_e32 v113, v4, v2
	v_lshlrev_b32_e32 v2, 16, v11
	v_fmac_f32_e32 v105, v4, v2
	v_and_b32_e32 v2, 0xffff0000, v7
	v_fmac_f32_e32 v112, v4, v2
	v_and_b32_e32 v2, 0xffff0000, v11
	v_fmac_f32_e32 v104, v4, v2
	v_lshlrev_b32_e32 v2, 16, v8
	v_fmac_f32_e32 v111, v4, v2
	v_lshlrev_b32_e32 v2, 16, v12
	v_fmac_f32_e32 v103, v4, v2
	v_and_b32_e32 v2, 0xffff0000, v8
	v_fmac_f32_e32 v110, v4, v2
	v_and_b32_e32 v2, 0xffff0000, v12
	v_fmac_f32_e32 v102, v4, v2
	v_lshlrev_b32_e32 v2, 16, v9
	v_fmac_f32_e32 v109, v4, v2
	v_lshlrev_b32_e32 v2, 16, v13
	v_fmac_f32_e32 v101, v4, v2
	v_and_b32_e32 v2, 0xffff0000, v9
	v_fmac_f32_e32 v108, v4, v2
	v_and_b32_e32 v2, 0xffff0000, v13
	ds_read_b128 v[6:9], v40 offset:29696
	ds_read_b128 v[10:13], v40 offset:62464
	v_fmac_f32_e32 v49, v4, v2
	s_waitcnt lgkmcnt(0)
	v_lshlrev_b32_e32 v2, 16, v6
	v_fmac_f32_e32 v115, v5, v2
	v_lshlrev_b32_e32 v2, 16, v10
	v_fmac_f32_e32 v107, v5, v2
	v_and_b32_e32 v2, 0xffff0000, v6
	v_fmac_f32_e32 v114, v5, v2
	v_and_b32_e32 v2, 0xffff0000, v10
	v_fmac_f32_e32 v106, v5, v2
	v_lshlrev_b32_e32 v2, 16, v7
	v_fmac_f32_e32 v113, v5, v2
	v_lshlrev_b32_e32 v2, 16, v11
	v_fmac_f32_e32 v105, v5, v2
	v_and_b32_e32 v2, 0xffff0000, v7
	v_fmac_f32_e32 v112, v5, v2
	v_and_b32_e32 v2, 0xffff0000, v11
	v_fmac_f32_e32 v104, v5, v2
	v_lshlrev_b32_e32 v2, 16, v8
	v_fmac_f32_e32 v111, v5, v2
	v_lshlrev_b32_e32 v2, 16, v12
	v_fmac_f32_e32 v103, v5, v2
	v_and_b32_e32 v2, 0xffff0000, v8
	v_fmac_f32_e32 v110, v5, v2
	v_and_b32_e32 v2, 0xffff0000, v12
	v_fmac_f32_e32 v102, v5, v2
	v_lshlrev_b32_e32 v2, 16, v9
	v_fmac_f32_e32 v109, v5, v2
	v_lshlrev_b32_e32 v2, 16, v13
	v_fmac_f32_e32 v101, v5, v2
	v_and_b32_e32 v2, 0xffff0000, v9
	v_fmac_f32_e32 v108, v5, v2
	v_and_b32_e32 v2, 0xffff0000, v13
	v_fmac_f32_e32 v49, v5, v2
	ds_read_b128 v[2:5], v40 offset:30720
	ds_read_b128 v[6:9], v40 offset:63488
	s_waitcnt lgkmcnt(0)
	v_lshlrev_b32_e32 v10, 16, v2
	v_and_b32_e32 v2, 0xffff0000, v2
	v_fmac_f32_e32 v114, v0, v2
	v_and_b32_e32 v2, 0xffff0000, v6
	v_fmac_f32_e32 v106, v0, v2
	v_lshlrev_b32_e32 v2, 16, v3
	v_fmac_f32_e32 v113, v0, v2
	v_lshlrev_b32_e32 v2, 16, v7
	v_fmac_f32_e32 v105, v0, v2
	v_and_b32_e32 v2, 0xffff0000, v3
	v_fmac_f32_e32 v112, v0, v2
	v_and_b32_e32 v2, 0xffff0000, v7
	v_fmac_f32_e32 v104, v0, v2
	v_lshlrev_b32_e32 v2, 16, v4
	v_fmac_f32_e32 v111, v0, v2
	v_lshlrev_b32_e32 v2, 16, v8
	v_fmac_f32_e32 v103, v0, v2
	v_and_b32_e32 v2, 0xffff0000, v4
	v_fmac_f32_e32 v110, v0, v2
	v_and_b32_e32 v2, 0xffff0000, v8
	v_fmac_f32_e32 v102, v0, v2
	v_lshlrev_b32_e32 v2, 16, v5
	v_fmac_f32_e32 v109, v0, v2
	v_lshlrev_b32_e32 v2, 16, v9
	v_fmac_f32_e32 v101, v0, v2
	v_and_b32_e32 v2, 0xffff0000, v5
	v_fmac_f32_e32 v108, v0, v2
	v_and_b32_e32 v2, 0xffff0000, v9
	v_fmac_f32_e32 v115, v0, v10
	v_lshlrev_b32_e32 v10, 16, v6
	v_fmac_f32_e32 v49, v0, v2
	ds_read_b128 v[2:5], v40 offset:31744
	ds_read_b128 v[6:9], v40 offset:64512
	v_fmac_f32_e32 v107, v0, v10
	s_waitcnt lgkmcnt(0)
	v_lshlrev_b32_e32 v0, 16, v2
	v_fmac_f32_e32 v115, v1, v0
	v_lshlrev_b32_e32 v0, 16, v6
	v_fmac_f32_e32 v107, v1, v0
	v_and_b32_e32 v0, 0xffff0000, v2
	v_fmac_f32_e32 v114, v1, v0
	v_and_b32_e32 v0, 0xffff0000, v6
	v_fmac_f32_e32 v106, v1, v0
	v_lshlrev_b32_e32 v0, 16, v3
	v_fmac_f32_e32 v113, v1, v0
	v_lshlrev_b32_e32 v0, 16, v7
	v_fmac_f32_e32 v105, v1, v0
	v_and_b32_e32 v0, 0xffff0000, v3
	v_fmac_f32_e32 v112, v1, v0
	v_and_b32_e32 v0, 0xffff0000, v7
	v_fmac_f32_e32 v104, v1, v0
	v_lshlrev_b32_e32 v0, 16, v4
	v_fmac_f32_e32 v111, v1, v0
	v_lshlrev_b32_e32 v0, 16, v8
	v_fmac_f32_e32 v103, v1, v0
	v_and_b32_e32 v0, 0xffff0000, v4
	v_fmac_f32_e32 v110, v1, v0
	v_and_b32_e32 v0, 0xffff0000, v8
	v_fmac_f32_e32 v102, v1, v0
	v_lshlrev_b32_e32 v0, 16, v5
	v_fmac_f32_e32 v109, v1, v0
	v_lshlrev_b32_e32 v0, 16, v9
	v_fmac_f32_e32 v101, v1, v0
	v_and_b32_e32 v0, 0xffff0000, v5
	v_fmac_f32_e32 v108, v1, v0
	v_and_b32_e32 v0, 0xffff0000, v9
	v_fmac_f32_e32 v49, v1, v0
	ds_bpermute_b32 v0, v89, v115
	ds_bpermute_b32 v2, v89, v114
	ds_bpermute_b32 v4, v89, v113
	ds_bpermute_b32 v6, v89, v112
	ds_bpermute_b32 v8, v89, v111
	ds_bpermute_b32 v10, v89, v110
	ds_bpermute_b32 v12, v89, v109
	ds_bpermute_b32 v14, v89, v108
	ds_bpermute_b32 v16, v89, v107
	ds_bpermute_b32 v18, v89, v106
	ds_bpermute_b32 v20, v89, v105
	ds_bpermute_b32 v22, v89, v104
	ds_bpermute_b32 v24, v89, v103
	ds_bpermute_b32 v26, v89, v102
	ds_bpermute_b32 v28, v89, v101
	ds_bpermute_b32 v30, v89, v49
	s_waitcnt lgkmcnt(0)
	v_add_f32_e32 v0, v115, v0
	v_add_f32_e32 v2, v114, v2
	v_add_f32_e32 v4, v113, v4
	v_add_f32_e32 v6, v112, v6
	v_add_f32_e32 v8, v111, v8
	v_add_f32_e32 v10, v110, v10
	v_add_f32_e32 v12, v109, v12
	v_add_f32_e32 v14, v108, v14
	v_add_f32_e32 v16, v107, v16
	v_add_f32_e32 v18, v106, v18
	v_add_f32_e32 v20, v105, v20
	v_add_f32_e32 v22, v104, v22
	v_add_f32_e32 v24, v103, v24
	v_add_f32_e32 v26, v102, v26
	v_add_f32_e32 v28, v101, v28
	v_add_f32_e32 v30, v49, v30
	ds_bpermute_b32 v1, v96, v0
	ds_bpermute_b32 v3, v96, v2
	ds_bpermute_b32 v5, v96, v4
	ds_bpermute_b32 v7, v96, v6
	ds_bpermute_b32 v9, v96, v8
	ds_bpermute_b32 v11, v96, v10
	ds_bpermute_b32 v13, v96, v12
	ds_bpermute_b32 v15, v96, v14
	ds_bpermute_b32 v17, v96, v16
	ds_bpermute_b32 v19, v96, v18
	ds_bpermute_b32 v21, v96, v20
	ds_bpermute_b32 v23, v96, v22
	ds_bpermute_b32 v25, v96, v24
	ds_bpermute_b32 v27, v96, v26
	ds_bpermute_b32 v29, v96, v28
	ds_bpermute_b32 v31, v96, v30
	s_waitcnt lgkmcnt(0)
; DI void phase_adaln(const Params& p, int l, unsigned char* smem) {
;     ...
; #pragma unroll
;     for (int c = 0; c < 16; ++c) {
;       float s = ab[c];
; #pragma unroll
;       for (int o = 1; o < 64; o <<= 1) s += __shfl_xor(s, o);
;       ab[c] = s;
;     }
;     float mine = 0.f;
; #pragma unroll
;     for (int c = 0; c < 16; ++c) mine = (lane == c) ? ab[c] : mine;
;     if (lane < 16) AB[(size_t)row * 16 + lane] = mine;
	v_add_f32_e32 v0, v0, v1
	v_add_f32_e32 v2, v2, v3
	v_add_f32_e32 v4, v4, v5
	v_add_f32_e32 v6, v6, v7
	v_add_f32_e32 v8, v8, v9
	v_add_f32_e32 v10, v10, v11
	v_add_f32_e32 v12, v12, v13
	v_add_f32_e32 v14, v14, v15
	v_add_f32_e32 v16, v16, v17
	v_add_f32_e32 v18, v18, v19
	v_add_f32_e32 v20, v20, v21
	v_add_f32_e32 v22, v22, v23
	v_add_f32_e32 v24, v24, v25
	v_add_f32_e32 v26, v26, v27
	v_add_f32_e32 v28, v28, v29
	v_add_f32_e32 v30, v30, v31
	ds_bpermute_b32 v1, v97, v0
	ds_bpermute_b32 v3, v97, v2
	ds_bpermute_b32 v5, v97, v4
	ds_bpermute_b32 v7, v97, v6
	ds_bpermute_b32 v9, v97, v8
	ds_bpermute_b32 v11, v97, v10
	ds_bpermute_b32 v13, v97, v12
	ds_bpermute_b32 v15, v97, v14
	ds_bpermute_b32 v17, v97, v16
	ds_bpermute_b32 v19, v97, v18
	ds_bpermute_b32 v21, v97, v20
	ds_bpermute_b32 v23, v97, v22
	ds_bpermute_b32 v25, v97, v24
	ds_bpermute_b32 v27, v97, v26
	ds_bpermute_b32 v29, v97, v28
	ds_bpermute_b32 v31, v97, v30
	s_waitcnt lgkmcnt(0)
	v_add_f32_e32 v0, v0, v1
	v_add_f32_e32 v2, v2, v3
	v_add_f32_e32 v4, v4, v5
	v_add_f32_e32 v6, v6, v7
	v_add_f32_e32 v8, v8, v9
	v_add_f32_e32 v10, v10, v11
	v_add_f32_e32 v12, v12, v13
	v_add_f32_e32 v14, v14, v15
	v_add_f32_e32 v16, v16, v17
	v_add_f32_e32 v18, v18, v19
	v_add_f32_e32 v20, v20, v21
	v_add_f32_e32 v22, v22, v23
	v_add_f32_e32 v24, v24, v25
	v_add_f32_e32 v26, v26, v27
	v_add_f32_e32 v28, v28, v29
	v_add_f32_e32 v30, v30, v31
	ds_bpermute_b32 v1, v98, v0
	ds_bpermute_b32 v3, v98, v2
	ds_bpermute_b32 v5, v98, v4
	ds_bpermute_b32 v7, v98, v6
	ds_bpermute_b32 v9, v98, v8
	ds_bpermute_b32 v11, v98, v10
	ds_bpermute_b32 v13, v98, v12
	ds_bpermute_b32 v15, v98, v14
	ds_bpermute_b32 v17, v98, v16
	ds_bpermute_b32 v19, v98, v18
	ds_bpermute_b32 v21, v98, v20
	ds_bpermute_b32 v23, v98, v22
	ds_bpermute_b32 v25, v98, v24
	ds_bpermute_b32 v27, v98, v26
	ds_bpermute_b32 v29, v98, v28
	ds_bpermute_b32 v31, v98, v30
	s_waitcnt lgkmcnt(0)
	v_add_f32_e32 v0, v0, v1
	v_add_f32_e32 v2, v2, v3
	v_add_f32_e32 v4, v4, v5
	v_add_f32_e32 v6, v6, v7
	v_add_f32_e32 v8, v8, v9
	v_add_f32_e32 v10, v10, v11
	v_add_f32_e32 v12, v12, v13
	v_add_f32_e32 v14, v14, v15
	v_add_f32_e32 v16, v16, v17
	v_add_f32_e32 v18, v18, v19
	v_add_f32_e32 v20, v20, v21
	v_add_f32_e32 v22, v22, v23
	v_add_f32_e32 v24, v24, v25
	v_add_f32_e32 v26, v26, v27
	v_add_f32_e32 v28, v28, v29
	v_add_f32_e32 v30, v30, v31
	ds_bpermute_b32 v1, v99, v0
	ds_bpermute_b32 v3, v99, v2
	ds_bpermute_b32 v5, v99, v4
	ds_bpermute_b32 v7, v99, v6
	ds_bpermute_b32 v9, v99, v8
	ds_bpermute_b32 v11, v99, v10
	ds_bpermute_b32 v13, v99, v12
	ds_bpermute_b32 v15, v99, v14
	ds_bpermute_b32 v17, v99, v16
	ds_bpermute_b32 v19, v99, v18
	ds_bpermute_b32 v21, v99, v20
	ds_bpermute_b32 v23, v99, v22
	ds_bpermute_b32 v25, v99, v24
	ds_bpermute_b32 v27, v99, v26
	ds_bpermute_b32 v29, v99, v28
	ds_bpermute_b32 v31, v99, v30
	s_waitcnt lgkmcnt(0)
	v_add_f32_e32 v0, v0, v1
	v_add_f32_e32 v2, v2, v3
	v_add_f32_e32 v4, v4, v5
	v_add_f32_e32 v6, v6, v7
	v_add_f32_e32 v8, v8, v9
	v_add_f32_e32 v10, v10, v11
	v_add_f32_e32 v12, v12, v13
	v_add_f32_e32 v14, v14, v15
	v_add_f32_e32 v16, v16, v17
	v_add_f32_e32 v18, v18, v19
	v_add_f32_e32 v20, v20, v21
	v_add_f32_e32 v22, v22, v23
	v_add_f32_e32 v24, v24, v25
	v_add_f32_e32 v26, v26, v27
	v_add_f32_e32 v28, v28, v29
	v_add_f32_e32 v30, v30, v31
	ds_bpermute_b32 v1, v100, v0
	ds_bpermute_b32 v3, v100, v2
	ds_bpermute_b32 v5, v100, v4
	ds_bpermute_b32 v7, v100, v6
	ds_bpermute_b32 v9, v100, v8
	ds_bpermute_b32 v11, v100, v10
	ds_bpermute_b32 v13, v100, v12
	ds_bpermute_b32 v15, v100, v14
	ds_bpermute_b32 v17, v100, v16
	ds_bpermute_b32 v19, v100, v18
	ds_bpermute_b32 v21, v100, v20
	ds_bpermute_b32 v23, v100, v22
	ds_bpermute_b32 v25, v100, v24
	ds_bpermute_b32 v27, v100, v26
	ds_bpermute_b32 v29, v100, v28
	ds_bpermute_b32 v31, v100, v30
	s_and_saveexec_b64 s[36:37], vcc
	s_cbranch_execz .LBB0_140
	s_waitcnt lgkmcnt(0)
	v_add_f32_e32 v0, v0, v1
	v_add_f32_e32 v2, v2, v3
	v_cndmask_b32_e64 v0, 0, v0, s[34:35]
	v_add_f32_e32 v4, v4, v5
	v_cndmask_b32_e64 v0, v0, v2, s[30:31]
	v_add_f32_e32 v6, v6, v7
	v_cndmask_b32_e64 v0, v0, v4, s[28:29]
	v_add_f32_e32 v8, v8, v9
	v_cndmask_b32_e64 v0, v0, v6, s[26:27]
	v_add_f32_e32 v10, v10, v11
	v_cndmask_b32_e64 v0, v0, v8, s[24:25]
	v_add_f32_e32 v12, v12, v13
	v_cndmask_b32_e64 v0, v0, v10, s[22:23]
	v_add_f32_e32 v14, v14, v15
	v_cndmask_b32_e64 v0, v0, v12, s[20:21]
	v_add_f32_e32 v16, v16, v17
	v_cndmask_b32_e64 v0, v0, v14, s[18:19]
	v_add_f32_e32 v18, v18, v19
	v_cndmask_b32_e64 v0, v0, v16, s[16:17]
	v_add_f32_e32 v20, v20, v21
	v_cndmask_b32_e64 v0, v0, v18, s[14:15]
	v_add_f32_e32 v22, v22, v23
	v_cndmask_b32_e64 v0, v0, v20, s[12:13]
	v_add_f32_e32 v24, v24, v25
	v_cndmask_b32_e64 v0, v0, v22, s[10:11]
	v_add_f32_e32 v26, v26, v27
	v_cndmask_b32_e64 v0, v0, v24, s[8:9]
	v_add_f32_e32 v28, v28, v29
	v_cndmask_b32_e64 v0, v0, v26, s[6:7]
	v_add_f32_e32 v30, v30, v31
	v_cndmask_b32_e64 v0, v0, v28, s[4:5]
	v_cndmask_b32_e64 v2, v0, v30, s[38:39]
	v_lshl_add_u64 v[0:1], s[46:47], 0, v[54:55]
	flat_store_dword v[0:1], v2
	s_branch .LBB0_140

; DI bfr f2bf(float a) { return (bfr)(pk2(a, 0.f) & 0xffffu); }
; DI int crow(int r, int h) { return (r & 3) + 8 * (r >> 2) + 4 * h; }
; DI void phase_inproj(const Params& p, int l, unsigned char* smem) {
;     ...
;         const int cb = n0 + wn * 128 + ni * 32, col = cb + l31, rb = wm * 64 + mi * 32;
;         const f32x16& a = acc[mi][ni];
;     ...
;         } else {
; #pragma unroll
;           for (int r = 0; r < 16; ++r) P[(size_t)(m0 + rb + crow(r, h)) * PLD + col] = f2bf(a[r]);
;         }
.LBB0_167:
	s_andn2_b64 vcc, exec, s[10:11]
	s_cbranch_vccnz .LBB0_169
	v_and_b32_e32 v164, 1, v216
	v_add_u32_e32 v163, s44, v176
	v_sub_u32_e32 v164, 0, v164
	v_lshlrev_b32_e32 v162, 1, v128
	v_add_u32_e32 v162, 0xcc00000, v162
	v_lshl_add_u32 v163, v163, 15, v162
	v_and_b32_e32 v162, 0x7ffe, v164
	v_add_u32_e32 v163, v163, v162
	v_and_b32_e32 v162, 0x6060606, v164
	v_xor_b32_e32 v162, 0x5040100, v162
	v_cvt_pk_bf16_f32 v138, v112, v113
	v_cvt_pk_bf16_f32 v139, v114, v115
	v_cvt_pk_bf16_f32 v140, v116, v117
	v_cvt_pk_bf16_f32 v141, v118, v119
	v_cvt_pk_bf16_f32 v142, v120, v121
	v_cvt_pk_bf16_f32 v143, v122, v123
	v_cvt_pk_bf16_f32 v144, v124, v125
	v_cvt_pk_bf16_f32 v145, v126, v127
	v_mov_b32_dpp v146, v138 quad_perm:[1,0,3,2] row_mask:0xf bank_mask:0xf
	v_mov_b32_dpp v147, v139 quad_perm:[1,0,3,2] row_mask:0xf bank_mask:0xf
	v_mov_b32_dpp v148, v140 quad_perm:[1,0,3,2] row_mask:0xf bank_mask:0xf
	v_mov_b32_dpp v149, v141 quad_perm:[1,0,3,2] row_mask:0xf bank_mask:0xf
	v_mov_b32_dpp v150, v142 quad_perm:[1,0,3,2] row_mask:0xf bank_mask:0xf
	v_mov_b32_dpp v151, v143 quad_perm:[1,0,3,2] row_mask:0xf bank_mask:0xf
	v_mov_b32_dpp v152, v144 quad_perm:[1,0,3,2] row_mask:0xf bank_mask:0xf
	v_mov_b32_dpp v153, v145 quad_perm:[1,0,3,2] row_mask:0xf bank_mask:0xf
	v_add_u32_e32 v154, 0x0, v163
	v_add_u32_e32 v155, 0x10000, v163
	v_add_u32_e32 v156, 0x40000, v163
	v_add_u32_e32 v157, 0x50000, v163
	v_add_u32_e32 v158, 0x80000, v163
	v_add_u32_e32 v159, 0x90000, v163
	v_add_u32_e32 v160, 0xc0000, v163
	v_add_u32_e32 v161, 0xd0000, v163
	v_perm_b32 v146, v146, v138, v162
	v_perm_b32 v147, v147, v139, v162
	v_perm_b32 v148, v148, v140, v162
	v_perm_b32 v149, v149, v141, v162
	v_perm_b32 v150, v150, v142, v162
	v_perm_b32 v151, v151, v143, v162
	v_perm_b32 v152, v152, v144, v162
	v_perm_b32 v153, v153, v145, v162
	global_store_dword v154, v146, s[84:85]
	global_store_dword v155, v147, s[84:85]
	global_store_dword v156, v148, s[84:85]
	global_store_dword v157, v149, s[84:85]
	global_store_dword v158, v150, s[84:85]
	global_store_dword v159, v151, s[84:85]
	global_store_dword v160, v152, s[84:85]
	global_store_dword v161, v153, s[84:85]

; DI unsigned pk2(float a, float b) { f2_t v = {a, b}; bf2_t r = __builtin_convertvector(v, bf2_t); return __builtin_bit_cast(unsigned, r); }
; DI void phase_inproj(const Params& p, int l, unsigned char* smem) {
;     ...
;         } else if (n0 >= C_DAV && n0 < C_DAZ) {
;           const int cc = col - C_DAV;
; #pragma unroll
;           for (int g = 0; g < 4; ++g) {
;             const int rr = rb + 8 * g + 4 * h;
;             u32x2 w; w[0] = pk2(a[4 * g], a[4 * g + 1]); w[1] = pk2(a[4 * g + 2], a[4 * g + 3]);
;             *(u32x2*)(VT + ((size_t)(b * 512 + cc)) * SP + s0 + rr) = w;
;           }
.LBB0_170:
	s_andn2_b64 vcc, exec, s[10:11]
	s_cbranch_vccnz .LBB0_172
	v_add_u32_e32 v129, s47, v128
	v_mov_b64_e32 v[132:133], s[22:23]
	v_mad_u64_u32 v[132:133], s[10:11], v129, s42, v[132:133]
	v_cvt_pk_bf16_f32 v134, v112, v113
	v_cvt_pk_bf16_f32 v135, v114, v115
	v_lshl_add_u64 v[132:133], v[176:177], 1, v[132:133]
	flat_store_dwordx2 v[132:133], v[134:135]
	v_cvt_pk_bf16_f32 v134, v116, v117
	v_cvt_pk_bf16_f32 v135, v118, v119
	flat_store_dwordx2 v[132:133], v[134:135] offset:16
	v_cvt_pk_bf16_f32 v134, v120, v121
	v_cvt_pk_bf16_f32 v135, v122, v123
	flat_store_dwordx2 v[132:133], v[134:135] offset:32
	v_cvt_pk_bf16_f32 v134, v124, v125
	v_cvt_pk_bf16_f32 v135, v126, v127
	flat_store_dwordx2 v[132:133], v[134:135] offset:48

; DI unsigned pk2(float a, float b) { f2_t v = {a, b}; bf2_t r = __builtin_convertvector(v, bf2_t); return __builtin_bit_cast(unsigned, r); }
; DI void phase_inproj(const Params& p, int l, unsigned char* smem) {
;     ...
;         if (n0 < 1024) {
;           const int part = n0 >> 9, ch = col & 511;
; #pragma unroll
;           for (int g = 0; g < 4; ++g) {
;             const int rr = rb + 8 * g + 4 * h;
;             u32x2 w; w[0] = pk2(a[4 * g], a[4 * g + 1]); w[1] = pk2(a[4 * g + 2], a[4 * g + 3]);
;             if (isctx) *(u32x2*)(FTC + ((size_t)(b * 512 + ch)) * 512 + part * 256 + s0 + rr) = w;
;             else *(u32x2*)(FTL + ((size_t)(b * 512 + ch)) * 8192 + part * 4096 + (s0 - CTX) + rr) = w;
;           }
.LBB0_173:
	v_and_b32_e32 v129, 0x19f, v128
	v_cndmask_b32_e64 v131, 0, 1, s[6:7]
	s_andn2_b64 vcc, exec, s[10:11]
	v_or_b32_e32 v137, s51, v129
	v_cmp_ne_u32_e64 s[6:7], 1, v131
	s_cbranch_vccnz .LBB0_178
	v_lshlrev_b32_e32 v208, 14, v137
	v_lshl_add_u64 v[132:133], s[18:19], 0, v[208:209]
	v_lshlrev_b32_e32 v208, 10, v137
	v_lshl_add_u64 v[134:135], v[132:133], 0, s[62:63]
	v_lshl_add_u64 v[132:133], s[20:21], 0, v[208:209]
	v_cvt_pk_bf16_f32 v112, v112, v113
	v_cvt_pk_bf16_f32 v113, v114, v115
	v_cndmask_b32_e64 v115, v135, v133, s[4:5]
	v_cndmask_b32_e64 v114, v134, v132, s[4:5]
	v_lshl_add_u64 v[114:115], v[176:177], 1, v[114:115]
	flat_store_dwordx2 v[114:115], v[112:113]
	v_cvt_pk_bf16_f32 v112, v116, v117
	v_cvt_pk_bf16_f32 v113, v118, v119
	flat_store_dwordx2 v[114:115], v[112:113] offset:16
	v_cvt_pk_bf16_f32 v112, v120, v121
	v_cvt_pk_bf16_f32 v113, v122, v123
	flat_store_dwordx2 v[114:115], v[112:113] offset:32
	v_cvt_pk_bf16_f32 v112, v124, v125
	v_cvt_pk_bf16_f32 v113, v126, v127
	s_and_b64 vcc, exec, s[6:7]
	s_mov_b64 s[10:11], -1
	s_cbranch_vccnz .LBB0_176
	v_lshl_add_u64 v[114:115], v[180:181], 1, v[134:135]
	s_mov_b64 s[10:11], 0
	flat_store_dwordx2 v[114:115], v[112:113]

; DI bfr f2bf(float a) { return (bfr)(pk2(a, 0.f) & 0xffffu); }
; DI int crow(int r, int h) { return (r & 3) + 8 * (r >> 2) + 4 * h; }
; DI void phase_inproj(const Params& p, int l, unsigned char* smem) {
;     ...
;         } else {
; #pragma unroll
;           for (int r = 0; r < 16; ++r) P[(size_t)(m0 + rb + crow(r, h)) * PLD + col] = f2bf(a[r]);
;         }
.LBB0_182:
	s_andn2_b64 vcc, exec, s[26:27]
	s_cbranch_vccnz .LBB0_184
	v_and_b32_e32 v164, 1, v216
	v_add_u32_e32 v163, s44, v176
	v_sub_u32_e32 v164, 0, v164
	v_lshlrev_b32_e32 v162, 1, v128
	v_add_u32_e32 v162, 0xcc00000, v162
	v_lshl_add_u32 v163, v163, 15, v162
	v_and_b32_e32 v162, 0x7ffe, v164
	v_add_u32_e32 v163, v163, v162
	v_and_b32_e32 v162, 0x6060606, v164
	v_xor_b32_e32 v162, 0x5040100, v162
	v_cvt_pk_bf16_f32 v138, v96, v97
	v_cvt_pk_bf16_f32 v139, v98, v99
	v_cvt_pk_bf16_f32 v140, v100, v101
	v_cvt_pk_bf16_f32 v141, v102, v103
	v_cvt_pk_bf16_f32 v142, v104, v105
	v_cvt_pk_bf16_f32 v143, v106, v107
	v_cvt_pk_bf16_f32 v144, v108, v109
	v_cvt_pk_bf16_f32 v145, v110, v111
	v_mov_b32_dpp v146, v138 quad_perm:[1,0,3,2] row_mask:0xf bank_mask:0xf
	v_mov_b32_dpp v147, v139 quad_perm:[1,0,3,2] row_mask:0xf bank_mask:0xf
	v_mov_b32_dpp v148, v140 quad_perm:[1,0,3,2] row_mask:0xf bank_mask:0xf
	v_mov_b32_dpp v149, v141 quad_perm:[1,0,3,2] row_mask:0xf bank_mask:0xf
	v_mov_b32_dpp v150, v142 quad_perm:[1,0,3,2] row_mask:0xf bank_mask:0xf
	v_mov_b32_dpp v151, v143 quad_perm:[1,0,3,2] row_mask:0xf bank_mask:0xf
	v_mov_b32_dpp v152, v144 quad_perm:[1,0,3,2] row_mask:0xf bank_mask:0xf
	v_mov_b32_dpp v153, v145 quad_perm:[1,0,3,2] row_mask:0xf bank_mask:0xf
	v_add_u32_e32 v154, 0x0, v163
	v_add_u32_e32 v155, 0x10000, v163
	v_add_u32_e32 v156, 0x40000, v163
	v_add_u32_e32 v157, 0x50000, v163
	v_add_u32_e32 v158, 0x80000, v163
	v_add_u32_e32 v159, 0x90000, v163
	v_add_u32_e32 v160, 0xc0000, v163
	v_add_u32_e32 v161, 0xd0000, v163
	v_perm_b32 v146, v146, v138, v162
	v_perm_b32 v147, v147, v139, v162
	v_perm_b32 v148, v148, v140, v162
	v_perm_b32 v149, v149, v141, v162
	v_perm_b32 v150, v150, v142, v162
	v_perm_b32 v151, v151, v143, v162
	v_perm_b32 v152, v152, v144, v162
	v_perm_b32 v153, v153, v145, v162
	global_store_dword v154, v146, s[84:85] offset:64
	global_store_dword v155, v147, s[84:85] offset:64
	global_store_dword v156, v148, s[84:85] offset:64
	global_store_dword v157, v149, s[84:85] offset:64
	global_store_dword v158, v150, s[84:85] offset:64
	global_store_dword v159, v151, s[84:85] offset:64
	global_store_dword v160, v152, s[84:85] offset:64
	global_store_dword v161, v153, s[84:85] offset:64

; DI unsigned pk2(float a, float b) { f2_t v = {a, b}; bf2_t r = __builtin_convertvector(v, bf2_t); return __builtin_bit_cast(unsigned, r); }
; DI void phase_inproj(const Params& p, int l, unsigned char* smem) {
;     ...
;         } else if (n0 >= C_DAV && n0 < C_DAZ) {
;           const int cc = col - C_DAV;
; #pragma unroll
;           for (int g = 0; g < 4; ++g) {
;             const int rr = rb + 8 * g + 4 * h;
;             u32x2 w; w[0] = pk2(a[4 * g], a[4 * g + 1]); w[1] = pk2(a[4 * g + 2], a[4 * g + 3]);
;             *(u32x2*)(VT + ((size_t)(b * 512 + cc)) * SP + s0 + rr) = w;
;           }
.LBB0_185:
	s_andn2_b64 vcc, exec, s[26:27]
	s_cbranch_vccnz .LBB0_187
	v_add_u32_e32 v113, s47, v112
	v_mov_b64_e32 v[114:115], s[22:23]
	v_mad_u64_u32 v[114:115], s[26:27], v113, s42, v[114:115]
	v_cvt_pk_bf16_f32 v116, v96, v97
	v_cvt_pk_bf16_f32 v117, v98, v99
	v_lshl_add_u64 v[114:115], v[176:177], 1, v[114:115]
	flat_store_dwordx2 v[114:115], v[116:117]
	v_cvt_pk_bf16_f32 v116, v100, v101
	v_cvt_pk_bf16_f32 v117, v102, v103
	flat_store_dwordx2 v[114:115], v[116:117] offset:16
	v_cvt_pk_bf16_f32 v116, v104, v105
	v_cvt_pk_bf16_f32 v117, v106, v107
	flat_store_dwordx2 v[114:115], v[116:117] offset:32
	v_cvt_pk_bf16_f32 v116, v108, v109
	v_cvt_pk_bf16_f32 v117, v110, v111
	flat_store_dwordx2 v[114:115], v[116:117] offset:48

; DI unsigned pk2(float a, float b) { f2_t v = {a, b}; bf2_t r = __builtin_convertvector(v, bf2_t); return __builtin_bit_cast(unsigned, r); }
; DI void phase_inproj(const Params& p, int l, unsigned char* smem) {
;     ...
;         if (n0 < 1024) {
;           const int part = n0 >> 9, ch = col & 511;
; #pragma unroll
;           for (int g = 0; g < 4; ++g) {
;             const int rr = rb + 8 * g + 4 * h;
;             u32x2 w; w[0] = pk2(a[4 * g], a[4 * g + 1]); w[1] = pk2(a[4 * g + 2], a[4 * g + 3]);
;             if (isctx) *(u32x2*)(FTC + ((size_t)(b * 512 + ch)) * 512 + part * 256 + s0 + rr) = w;
;             else *(u32x2*)(FTL + ((size_t)(b * 512 + ch)) * 8192 + part * 4096 + (s0 - CTX) + rr) = w;
;           }
.LBB0_188:
	v_and_b32_e32 v113, 0x1bf, v112
	s_andn2_b64 vcc, exec, s[28:29]
	v_or_b32_e32 v118, s51, v113
	s_cbranch_vccnz .LBB0_193
	v_lshlrev_b32_e32 v208, 14, v118
	v_lshl_add_u64 v[114:115], s[18:19], 0, v[208:209]
	v_lshlrev_b32_e32 v208, 10, v118
	v_lshl_add_u64 v[116:117], v[114:115], 0, s[62:63]
	v_lshl_add_u64 v[114:115], s[20:21], 0, v[208:209]
	v_cvt_pk_bf16_f32 v96, v96, v97
	v_cvt_pk_bf16_f32 v97, v98, v99
	v_cndmask_b32_e64 v99, v117, v115, s[4:5]
	v_cndmask_b32_e64 v98, v116, v114, s[4:5]
	v_lshl_add_u64 v[98:99], v[176:177], 1, v[98:99]
	flat_store_dwordx2 v[98:99], v[96:97]
	v_cvt_pk_bf16_f32 v96, v100, v101
	v_cvt_pk_bf16_f32 v97, v102, v103
	flat_store_dwordx2 v[98:99], v[96:97] offset:16
	v_cvt_pk_bf16_f32 v96, v104, v105
	v_cvt_pk_bf16_f32 v97, v106, v107
	flat_store_dwordx2 v[98:99], v[96:97] offset:32
	v_cvt_pk_bf16_f32 v96, v108, v109
	v_cvt_pk_bf16_f32 v97, v110, v111
	s_and_b64 vcc, exec, s[6:7]
	s_mov_b64 s[26:27], -1
	s_cbranch_vccnz .LBB0_191
	v_lshl_add_u64 v[98:99], v[180:181], 1, v[116:117]
	s_mov_b64 s[26:27], 0
	flat_store_dwordx2 v[98:99], v[96:97]

; DI bfr f2bf(float a) { return (bfr)(pk2(a, 0.f) & 0xffffu); }
; DI int crow(int r, int h) { return (r & 3) + 8 * (r >> 2) + 4 * h; }
; DI void phase_inproj(const Params& p, int l, unsigned char* smem) {
;     ...
;         } else {
; #pragma unroll
;           for (int r = 0; r < 16; ++r) P[(size_t)(m0 + rb + crow(r, h)) * PLD + col] = f2bf(a[r]);
;         }
.LBB0_197:
	s_andn2_b64 vcc, exec, s[26:27]
	s_cbranch_vccnz .LBB0_199
	v_and_b32_e32 v164, 1, v216
	v_add_u32_e32 v163, s44, v176
	v_sub_u32_e32 v164, 0, v164
	v_lshlrev_b32_e32 v162, 1, v128
	v_add_u32_e32 v162, 0xcc00000, v162
	v_lshl_add_u32 v163, v163, 15, v162
	v_and_b32_e32 v162, 0x7ffe, v164
	v_add_u32_e32 v163, v163, v162
	v_and_b32_e32 v162, 0x6060606, v164
	v_xor_b32_e32 v162, 0x5040100, v162
	v_cvt_pk_bf16_f32 v138, v80, v81
	v_cvt_pk_bf16_f32 v139, v82, v83
	v_cvt_pk_bf16_f32 v140, v84, v85
	v_cvt_pk_bf16_f32 v141, v86, v87
	v_cvt_pk_bf16_f32 v142, v88, v89
	v_cvt_pk_bf16_f32 v143, v90, v91
	v_cvt_pk_bf16_f32 v144, v92, v93
	v_cvt_pk_bf16_f32 v145, v94, v95
	v_mov_b32_dpp v146, v138 quad_perm:[1,0,3,2] row_mask:0xf bank_mask:0xf
	v_mov_b32_dpp v147, v139 quad_perm:[1,0,3,2] row_mask:0xf bank_mask:0xf
	v_mov_b32_dpp v148, v140 quad_perm:[1,0,3,2] row_mask:0xf bank_mask:0xf
	v_mov_b32_dpp v149, v141 quad_perm:[1,0,3,2] row_mask:0xf bank_mask:0xf
	v_mov_b32_dpp v150, v142 quad_perm:[1,0,3,2] row_mask:0xf bank_mask:0xf
	v_mov_b32_dpp v151, v143 quad_perm:[1,0,3,2] row_mask:0xf bank_mask:0xf
	v_mov_b32_dpp v152, v144 quad_perm:[1,0,3,2] row_mask:0xf bank_mask:0xf
	v_mov_b32_dpp v153, v145 quad_perm:[1,0,3,2] row_mask:0xf bank_mask:0xf
	v_add_u32_e32 v154, 0x0, v163
	v_add_u32_e32 v155, 0x10000, v163
	v_add_u32_e32 v156, 0x40000, v163
	v_add_u32_e32 v157, 0x50000, v163
	v_add_u32_e32 v158, 0x80000, v163
	v_add_u32_e32 v159, 0x90000, v163
	v_add_u32_e32 v160, 0xc0000, v163
	v_add_u32_e32 v161, 0xd0000, v163
	v_perm_b32 v146, v146, v138, v162
	v_perm_b32 v147, v147, v139, v162
	v_perm_b32 v148, v148, v140, v162
	v_perm_b32 v149, v149, v141, v162
	v_perm_b32 v150, v150, v142, v162
	v_perm_b32 v151, v151, v143, v162
	v_perm_b32 v152, v152, v144, v162
	v_perm_b32 v153, v153, v145, v162
	global_store_dword v154, v146, s[84:85] offset:128
	global_store_dword v155, v147, s[84:85] offset:128
	global_store_dword v156, v148, s[84:85] offset:128
	global_store_dword v157, v149, s[84:85] offset:128
	global_store_dword v158, v150, s[84:85] offset:128
	global_store_dword v159, v151, s[84:85] offset:128
	global_store_dword v160, v152, s[84:85] offset:128
	global_store_dword v161, v153, s[84:85] offset:128

; DI unsigned pk2(float a, float b) { f2_t v = {a, b}; bf2_t r = __builtin_convertvector(v, bf2_t); return __builtin_bit_cast(unsigned, r); }
; DI void phase_inproj(const Params& p, int l, unsigned char* smem) {
;     ...
;         } else if (n0 >= C_DAV && n0 < C_DAZ) {
;           const int cc = col - C_DAV;
; #pragma unroll
;           for (int g = 0; g < 4; ++g) {
;             const int rr = rb + 8 * g + 4 * h;
;             u32x2 w; w[0] = pk2(a[4 * g], a[4 * g + 1]); w[1] = pk2(a[4 * g + 2], a[4 * g + 3]);
;             *(u32x2*)(VT + ((size_t)(b * 512 + cc)) * SP + s0 + rr) = w;
;           }
.LBB0_200:
	s_andn2_b64 vcc, exec, s[26:27]
	s_cbranch_vccnz .LBB0_202
	v_add_u32_e32 v97, s47, v96
	v_mov_b64_e32 v[98:99], s[22:23]
	v_mad_u64_u32 v[98:99], s[26:27], v97, s42, v[98:99]
	v_cvt_pk_bf16_f32 v100, v80, v81
	v_cvt_pk_bf16_f32 v101, v82, v83
	v_lshl_add_u64 v[98:99], v[176:177], 1, v[98:99]
	flat_store_dwordx2 v[98:99], v[100:101]
	v_cvt_pk_bf16_f32 v100, v84, v85
	v_cvt_pk_bf16_f32 v101, v86, v87
	flat_store_dwordx2 v[98:99], v[100:101] offset:16
	v_cvt_pk_bf16_f32 v100, v88, v89
	v_cvt_pk_bf16_f32 v101, v90, v91
	flat_store_dwordx2 v[98:99], v[100:101] offset:32
	v_cvt_pk_bf16_f32 v100, v92, v93
	v_cvt_pk_bf16_f32 v101, v94, v95
	flat_store_dwordx2 v[98:99], v[100:101] offset:48

; DI unsigned pk2(float a, float b) { f2_t v = {a, b}; bf2_t r = __builtin_convertvector(v, bf2_t); return __builtin_bit_cast(unsigned, r); }
; DI void phase_inproj(const Params& p, int l, unsigned char* smem) {
;     ...
;         if (n0 < 1024) {
;           const int part = n0 >> 9, ch = col & 511;
; #pragma unroll
;           for (int g = 0; g < 4; ++g) {
;             const int rr = rb + 8 * g + 4 * h;
;             u32x2 w; w[0] = pk2(a[4 * g], a[4 * g + 1]); w[1] = pk2(a[4 * g + 2], a[4 * g + 3]);
;             if (isctx) *(u32x2*)(FTC + ((size_t)(b * 512 + ch)) * 512 + part * 256 + s0 + rr) = w;
;             else *(u32x2*)(FTL + ((size_t)(b * 512 + ch)) * 8192 + part * 4096 + (s0 - CTX) + rr) = w;
;           }
.LBB0_203:
	v_and_b32_e32 v97, 0x1df, v96
	s_andn2_b64 vcc, exec, s[26:27]
	v_or_b32_e32 v102, s51, v97
	s_cbranch_vccnz .LBB0_208
	v_lshlrev_b32_e32 v208, 14, v102
	v_lshl_add_u64 v[98:99], s[18:19], 0, v[208:209]
	v_lshlrev_b32_e32 v208, 10, v102
	v_lshl_add_u64 v[100:101], v[98:99], 0, s[62:63]
	v_lshl_add_u64 v[98:99], s[20:21], 0, v[208:209]
	v_cvt_pk_bf16_f32 v80, v80, v81
	v_cvt_pk_bf16_f32 v81, v82, v83
	v_cndmask_b32_e64 v83, v101, v99, s[4:5]
	v_cndmask_b32_e64 v82, v100, v98, s[4:5]
	v_lshl_add_u64 v[82:83], v[176:177], 1, v[82:83]
	flat_store_dwordx2 v[82:83], v[80:81]
	v_cvt_pk_bf16_f32 v80, v84, v85
	v_cvt_pk_bf16_f32 v81, v86, v87
	flat_store_dwordx2 v[82:83], v[80:81] offset:16
	v_cvt_pk_bf16_f32 v80, v88, v89
	v_cvt_pk_bf16_f32 v81, v90, v91
	flat_store_dwordx2 v[82:83], v[80:81] offset:32
	v_cvt_pk_bf16_f32 v80, v92, v93
	v_cvt_pk_bf16_f32 v81, v94, v95
	s_and_b64 vcc, exec, s[6:7]
	s_mov_b64 s[26:27], -1
	s_cbranch_vccnz .LBB0_206
	v_lshl_add_u64 v[82:83], v[180:181], 1, v[100:101]
	s_mov_b64 s[26:27], 0
	flat_store_dwordx2 v[82:83], v[80:81]

; DI bfr f2bf(float a) { return (bfr)(pk2(a, 0.f) & 0xffffu); }
; DI int crow(int r, int h) { return (r & 3) + 8 * (r >> 2) + 4 * h; }
; DI void phase_inproj(const Params& p, int l, unsigned char* smem) {
;     ...
;         } else {
; #pragma unroll
;           for (int r = 0; r < 16; ++r) P[(size_t)(m0 + rb + crow(r, h)) * PLD + col] = f2bf(a[r]);
;         }
.LBB0_212:
	s_andn2_b64 vcc, exec, s[26:27]
	s_cbranch_vccnz .LBB0_214
	v_and_b32_e32 v164, 1, v216
	v_add_u32_e32 v163, s44, v176
	v_sub_u32_e32 v164, 0, v164
	v_lshlrev_b32_e32 v162, 1, v128
	v_add_u32_e32 v162, 0xcc00000, v162
	v_lshl_add_u32 v163, v163, 15, v162
	v_and_b32_e32 v162, 0x7ffe, v164
	v_add_u32_e32 v163, v163, v162
	v_and_b32_e32 v162, 0x6060606, v164
	v_xor_b32_e32 v162, 0x5040100, v162
	v_cvt_pk_bf16_f32 v138, v64, v65
	v_cvt_pk_bf16_f32 v139, v66, v67
	v_cvt_pk_bf16_f32 v140, v68, v69
	v_cvt_pk_bf16_f32 v141, v70, v71
	v_cvt_pk_bf16_f32 v142, v72, v73
	v_cvt_pk_bf16_f32 v143, v74, v75
	v_cvt_pk_bf16_f32 v144, v76, v77
	v_cvt_pk_bf16_f32 v145, v78, v79
	v_mov_b32_dpp v146, v138 quad_perm:[1,0,3,2] row_mask:0xf bank_mask:0xf
	v_mov_b32_dpp v147, v139 quad_perm:[1,0,3,2] row_mask:0xf bank_mask:0xf
	v_mov_b32_dpp v148, v140 quad_perm:[1,0,3,2] row_mask:0xf bank_mask:0xf
	v_mov_b32_dpp v149, v141 quad_perm:[1,0,3,2] row_mask:0xf bank_mask:0xf
	v_mov_b32_dpp v150, v142 quad_perm:[1,0,3,2] row_mask:0xf bank_mask:0xf
	v_mov_b32_dpp v151, v143 quad_perm:[1,0,3,2] row_mask:0xf bank_mask:0xf
	v_mov_b32_dpp v152, v144 quad_perm:[1,0,3,2] row_mask:0xf bank_mask:0xf
	v_mov_b32_dpp v153, v145 quad_perm:[1,0,3,2] row_mask:0xf bank_mask:0xf
	v_add_u32_e32 v154, 0x0, v163
	v_add_u32_e32 v155, 0x10000, v163
	v_add_u32_e32 v156, 0x40000, v163
	v_add_u32_e32 v157, 0x50000, v163
	v_add_u32_e32 v158, 0x80000, v163
	v_add_u32_e32 v159, 0x90000, v163
	v_add_u32_e32 v160, 0xc0000, v163
	v_add_u32_e32 v161, 0xd0000, v163
	v_perm_b32 v146, v146, v138, v162
	v_perm_b32 v147, v147, v139, v162
	v_perm_b32 v148, v148, v140, v162
	v_perm_b32 v149, v149, v141, v162
	v_perm_b32 v150, v150, v142, v162
	v_perm_b32 v151, v151, v143, v162
	v_perm_b32 v152, v152, v144, v162
	v_perm_b32 v153, v153, v145, v162
	global_store_dword v154, v146, s[84:85] offset:192
	global_store_dword v155, v147, s[84:85] offset:192
	global_store_dword v156, v148, s[84:85] offset:192
	global_store_dword v157, v149, s[84:85] offset:192
	global_store_dword v158, v150, s[84:85] offset:192
	global_store_dword v159, v151, s[84:85] offset:192
	global_store_dword v160, v152, s[84:85] offset:192
	global_store_dword v161, v153, s[84:85] offset:192

; DI unsigned pk2(float a, float b) { f2_t v = {a, b}; bf2_t r = __builtin_convertvector(v, bf2_t); return __builtin_bit_cast(unsigned, r); }
; DI void phase_inproj(const Params& p, int l, unsigned char* smem) {
;     ...
;         } else if (n0 >= C_DAV && n0 < C_DAZ) {
;           const int cc = col - C_DAV;
; #pragma unroll
;           for (int g = 0; g < 4; ++g) {
;             const int rr = rb + 8 * g + 4 * h;
;             u32x2 w; w[0] = pk2(a[4 * g], a[4 * g + 1]); w[1] = pk2(a[4 * g + 2], a[4 * g + 3]);
;             *(u32x2*)(VT + ((size_t)(b * 512 + cc)) * SP + s0 + rr) = w;
;           }
.LBB0_215:
	s_andn2_b64 vcc, exec, s[26:27]
	s_cbranch_vccnz .LBB0_217
	v_add_u32_e32 v81, s47, v80
	v_mov_b64_e32 v[82:83], s[22:23]
	v_mad_u64_u32 v[82:83], s[26:27], v81, s42, v[82:83]
	v_cvt_pk_bf16_f32 v84, v64, v65
	v_cvt_pk_bf16_f32 v85, v66, v67
	v_lshl_add_u64 v[82:83], v[176:177], 1, v[82:83]
	flat_store_dwordx2 v[82:83], v[84:85]
	v_cvt_pk_bf16_f32 v84, v68, v69
	v_cvt_pk_bf16_f32 v85, v70, v71
	flat_store_dwordx2 v[82:83], v[84:85] offset:16
	v_cvt_pk_bf16_f32 v84, v72, v73
	v_cvt_pk_bf16_f32 v85, v74, v75
	flat_store_dwordx2 v[82:83], v[84:85] offset:32
	v_cvt_pk_bf16_f32 v84, v76, v77
	v_cvt_pk_bf16_f32 v85, v78, v79
	flat_store_dwordx2 v[82:83], v[84:85] offset:48

; DI unsigned pk2(float a, float b) { f2_t v = {a, b}; bf2_t r = __builtin_convertvector(v, bf2_t); return __builtin_bit_cast(unsigned, r); }
; DI void phase_inproj(const Params& p, int l, unsigned char* smem) {
;     ...
;         if (n0 < 1024) {
;           const int part = n0 >> 9, ch = col & 511;
; #pragma unroll
;           for (int g = 0; g < 4; ++g) {
;             const int rr = rb + 8 * g + 4 * h;
;             u32x2 w; w[0] = pk2(a[4 * g], a[4 * g + 1]); w[1] = pk2(a[4 * g + 2], a[4 * g + 3]);
;             if (isctx) *(u32x2*)(FTC + ((size_t)(b * 512 + ch)) * 512 + part * 256 + s0 + rr) = w;
;             else *(u32x2*)(FTL + ((size_t)(b * 512 + ch)) * 8192 + part * 4096 + (s0 - CTX) + rr) = w;
;           }
.LBB0_218:
	v_and_b32_e32 v81, 0x1ff, v80
	s_andn2_b64 vcc, exec, s[26:27]
	v_or_b32_e32 v86, s51, v81
	s_cbranch_vccnz .LBB0_223
	v_lshlrev_b32_e32 v208, 14, v86
	v_lshl_add_u64 v[82:83], s[18:19], 0, v[208:209]
	v_lshlrev_b32_e32 v208, 10, v86
	v_lshl_add_u64 v[84:85], v[82:83], 0, s[62:63]
	v_lshl_add_u64 v[82:83], s[20:21], 0, v[208:209]
	v_cvt_pk_bf16_f32 v64, v64, v65
	v_cvt_pk_bf16_f32 v65, v66, v67
	v_cndmask_b32_e64 v67, v85, v83, s[4:5]
	v_cndmask_b32_e64 v66, v84, v82, s[4:5]
	v_lshl_add_u64 v[66:67], v[176:177], 1, v[66:67]
	flat_store_dwordx2 v[66:67], v[64:65]
	v_cvt_pk_bf16_f32 v64, v68, v69
	v_cvt_pk_bf16_f32 v65, v70, v71
	flat_store_dwordx2 v[66:67], v[64:65] offset:16
	v_cvt_pk_bf16_f32 v64, v72, v73
	v_cvt_pk_bf16_f32 v65, v74, v75
	flat_store_dwordx2 v[66:67], v[64:65] offset:32
	v_cvt_pk_bf16_f32 v64, v76, v77
	v_cvt_pk_bf16_f32 v65, v78, v79
	s_and_b64 vcc, exec, s[6:7]
	s_mov_b64 s[26:27], -1
	s_cbranch_vccnz .LBB0_221
	v_lshl_add_u64 v[66:67], v[180:181], 1, v[84:85]
	s_mov_b64 s[26:27], 0
	flat_store_dwordx2 v[66:67], v[64:65]

; DI bfr f2bf(float a) { return (bfr)(pk2(a, 0.f) & 0xffffu); }
; DI int crow(int r, int h) { return (r & 3) + 8 * (r >> 2) + 4 * h; }
; DI void phase_inproj(const Params& p, int l, unsigned char* smem) {
;     ...
;         } else {
; #pragma unroll
;           for (int r = 0; r < 16; ++r) P[(size_t)(m0 + rb + crow(r, h)) * PLD + col] = f2bf(a[r]);
;         }
.LBB0_227:
	s_andn2_b64 vcc, exec, s[26:27]
	s_cbranch_vccnz .LBB0_229
	v_and_b32_e32 v164, 1, v216
	v_add_u32_e32 v163, s44, v249
	v_sub_u32_e32 v164, 0, v164
	v_lshlrev_b32_e32 v162, 1, v128
	v_add_u32_e32 v162, 0xcc00000, v162
	v_lshl_add_u32 v163, v163, 15, v162
	v_and_b32_e32 v162, 0x7ffe, v164
	v_add_u32_e32 v163, v163, v162
	v_and_b32_e32 v162, 0x6060606, v164
	v_xor_b32_e32 v162, 0x5040100, v162
	v_cvt_pk_bf16_f32 v138, v48, v49
	v_cvt_pk_bf16_f32 v139, v50, v51
	v_cvt_pk_bf16_f32 v140, v52, v53
	v_cvt_pk_bf16_f32 v141, v54, v55
	v_cvt_pk_bf16_f32 v142, v56, v57
	v_cvt_pk_bf16_f32 v143, v58, v59
	v_cvt_pk_bf16_f32 v144, v60, v61
	v_cvt_pk_bf16_f32 v145, v62, v63
	v_mov_b32_dpp v146, v138 quad_perm:[1,0,3,2] row_mask:0xf bank_mask:0xf
	v_mov_b32_dpp v147, v139 quad_perm:[1,0,3,2] row_mask:0xf bank_mask:0xf
	v_mov_b32_dpp v148, v140 quad_perm:[1,0,3,2] row_mask:0xf bank_mask:0xf
	v_mov_b32_dpp v149, v141 quad_perm:[1,0,3,2] row_mask:0xf bank_mask:0xf
	v_mov_b32_dpp v150, v142 quad_perm:[1,0,3,2] row_mask:0xf bank_mask:0xf
	v_mov_b32_dpp v151, v143 quad_perm:[1,0,3,2] row_mask:0xf bank_mask:0xf
	v_mov_b32_dpp v152, v144 quad_perm:[1,0,3,2] row_mask:0xf bank_mask:0xf
	v_mov_b32_dpp v153, v145 quad_perm:[1,0,3,2] row_mask:0xf bank_mask:0xf
	v_add_u32_e32 v154, 0x0, v163
	v_add_u32_e32 v155, 0x10000, v163
	v_add_u32_e32 v156, 0x40000, v163
	v_add_u32_e32 v157, 0x50000, v163
	v_add_u32_e32 v158, 0x80000, v163
	v_add_u32_e32 v159, 0x90000, v163
	v_add_u32_e32 v160, 0xc0000, v163
	v_add_u32_e32 v161, 0xd0000, v163
	v_perm_b32 v146, v146, v138, v162
	v_perm_b32 v147, v147, v139, v162
	v_perm_b32 v148, v148, v140, v162
	v_perm_b32 v149, v149, v141, v162
	v_perm_b32 v150, v150, v142, v162
	v_perm_b32 v151, v151, v143, v162
	v_perm_b32 v152, v152, v144, v162
	v_perm_b32 v153, v153, v145, v162
	global_store_dword v154, v146, s[84:85]
	global_store_dword v155, v147, s[84:85]
	global_store_dword v156, v148, s[84:85]
	global_store_dword v157, v149, s[84:85]
	global_store_dword v158, v150, s[84:85]
	global_store_dword v159, v151, s[84:85]
	global_store_dword v160, v152, s[84:85]
	global_store_dword v161, v153, s[84:85]

; DI unsigned pk2(float a, float b) { f2_t v = {a, b}; bf2_t r = __builtin_convertvector(v, bf2_t); return __builtin_bit_cast(unsigned, r); }
; DI void phase_inproj(const Params& p, int l, unsigned char* smem) {
;     ...
;         } else if (n0 >= C_DAV && n0 < C_DAZ) {
;           const int cc = col - C_DAV;
; #pragma unroll
;           for (int g = 0; g < 4; ++g) {
;             const int rr = rb + 8 * g + 4 * h;
;             u32x2 w; w[0] = pk2(a[4 * g], a[4 * g + 1]); w[1] = pk2(a[4 * g + 2], a[4 * g + 3]);
;             *(u32x2*)(VT + ((size_t)(b * 512 + cc)) * SP + s0 + rr) = w;
;           }
.LBB0_230:
	s_andn2_b64 vcc, exec, s[26:27]
	s_cbranch_vccnz .LBB0_232
	v_add_u32_e32 v65, s47, v128
	v_mov_b64_e32 v[66:67], s[22:23]
	v_mad_u64_u32 v[66:67], s[26:27], v65, s42, v[66:67]
	v_cvt_pk_bf16_f32 v68, v48, v49
	v_cvt_pk_bf16_f32 v69, v50, v51
	v_lshl_add_u64 v[66:67], v[184:185], 1, v[66:67]
	flat_store_dwordx2 v[66:67], v[68:69] offset:64
	v_cvt_pk_bf16_f32 v68, v52, v53
	v_cvt_pk_bf16_f32 v69, v54, v55
	flat_store_dwordx2 v[66:67], v[68:69] offset:80
	v_cvt_pk_bf16_f32 v68, v56, v57
	v_cvt_pk_bf16_f32 v69, v58, v59
	flat_store_dwordx2 v[66:67], v[68:69] offset:96
	v_cvt_pk_bf16_f32 v68, v60, v61
	v_cvt_pk_bf16_f32 v69, v62, v63
	flat_store_dwordx2 v[66:67], v[68:69] offset:112

; DI unsigned pk2(float a, float b) { f2_t v = {a, b}; bf2_t r = __builtin_convertvector(v, bf2_t); return __builtin_bit_cast(unsigned, r); }
; DI void phase_inproj(const Params& p, int l, unsigned char* smem) {
;     ...
;         if (n0 < 1024) {
;           const int part = n0 >> 9, ch = col & 511;
; #pragma unroll
;           for (int g = 0; g < 4; ++g) {
;             const int rr = rb + 8 * g + 4 * h;
;             u32x2 w; w[0] = pk2(a[4 * g], a[4 * g + 1]); w[1] = pk2(a[4 * g + 2], a[4 * g + 3]);
;             if (isctx) *(u32x2*)(FTC + ((size_t)(b * 512 + ch)) * 512 + part * 256 + s0 + rr) = w;
;             else *(u32x2*)(FTL + ((size_t)(b * 512 + ch)) * 8192 + part * 4096 + (s0 - CTX) + rr) = w;
;           }
.LBB0_233:
	s_andn2_b64 vcc, exec, s[26:27]
	s_cbranch_vccnz .LBB0_238
	v_lshlrev_b32_e32 v208, 14, v137
	v_lshl_add_u64 v[66:67], s[18:19], 0, v[208:209]
	v_lshlrev_b32_e32 v208, 10, v137
	v_lshl_add_u64 v[68:69], v[66:67], 0, s[62:63]
	v_lshl_add_u64 v[66:67], s[20:21], 0, v[208:209]
	v_cvt_pk_bf16_f32 v48, v48, v49
	v_cvt_pk_bf16_f32 v49, v50, v51
	v_cndmask_b32_e64 v51, v69, v67, s[4:5]
	v_cndmask_b32_e64 v50, v68, v66, s[4:5]
	v_lshl_add_u64 v[50:51], v[184:185], 1, v[50:51]
	flat_store_dwordx2 v[50:51], v[48:49] offset:64
	v_cvt_pk_bf16_f32 v48, v52, v53
	v_cvt_pk_bf16_f32 v49, v54, v55
	flat_store_dwordx2 v[50:51], v[48:49] offset:80
	v_cvt_pk_bf16_f32 v48, v56, v57
	v_cvt_pk_bf16_f32 v49, v58, v59
	flat_store_dwordx2 v[50:51], v[48:49] offset:96
	v_cvt_pk_bf16_f32 v48, v60, v61
	v_cvt_pk_bf16_f32 v49, v62, v63
	s_and_b64 vcc, exec, s[6:7]
	s_mov_b64 s[26:27], -1
	s_cbranch_vccnz .LBB0_236
	v_lshl_add_u64 v[50:51], v[182:183], 1, v[68:69]
	s_mov_b64 s[26:27], 0
	flat_store_dwordx2 v[50:51], v[48:49]

; DI bfr f2bf(float a) { return (bfr)(pk2(a, 0.f) & 0xffffu); }
; DI int crow(int r, int h) { return (r & 3) + 8 * (r >> 2) + 4 * h; }
; DI void phase_inproj(const Params& p, int l, unsigned char* smem) {
;     ...
;         } else {
; #pragma unroll
;           for (int r = 0; r < 16; ++r) P[(size_t)(m0 + rb + crow(r, h)) * PLD + col] = f2bf(a[r]);
;         }
.LBB0_242:
	s_andn2_b64 vcc, exec, s[26:27]
	s_cbranch_vccnz .LBB0_244
	v_and_b32_e32 v164, 1, v216
	v_add_u32_e32 v163, s44, v249
	v_sub_u32_e32 v164, 0, v164
	v_lshlrev_b32_e32 v162, 1, v128
	v_add_u32_e32 v162, 0xcc00000, v162
	v_lshl_add_u32 v163, v163, 15, v162
	v_and_b32_e32 v162, 0x7ffe, v164
	v_add_u32_e32 v163, v163, v162
	v_and_b32_e32 v162, 0x6060606, v164
	v_xor_b32_e32 v162, 0x5040100, v162
	v_cvt_pk_bf16_f32 v138, v32, v33
	v_cvt_pk_bf16_f32 v139, v34, v35
	v_cvt_pk_bf16_f32 v140, v36, v37
	v_cvt_pk_bf16_f32 v141, v38, v39
	v_cvt_pk_bf16_f32 v142, v40, v41
	v_cvt_pk_bf16_f32 v143, v42, v43
	v_cvt_pk_bf16_f32 v144, v44, v45
	v_cvt_pk_bf16_f32 v145, v46, v47
	v_mov_b32_dpp v146, v138 quad_perm:[1,0,3,2] row_mask:0xf bank_mask:0xf
	v_mov_b32_dpp v147, v139 quad_perm:[1,0,3,2] row_mask:0xf bank_mask:0xf
	v_mov_b32_dpp v148, v140 quad_perm:[1,0,3,2] row_mask:0xf bank_mask:0xf
	v_mov_b32_dpp v149, v141 quad_perm:[1,0,3,2] row_mask:0xf bank_mask:0xf
	v_mov_b32_dpp v150, v142 quad_perm:[1,0,3,2] row_mask:0xf bank_mask:0xf
	v_mov_b32_dpp v151, v143 quad_perm:[1,0,3,2] row_mask:0xf bank_mask:0xf
	v_mov_b32_dpp v152, v144 quad_perm:[1,0,3,2] row_mask:0xf bank_mask:0xf
	v_mov_b32_dpp v153, v145 quad_perm:[1,0,3,2] row_mask:0xf bank_mask:0xf
	v_add_u32_e32 v154, 0x0, v163
	v_add_u32_e32 v155, 0x10000, v163
	v_add_u32_e32 v156, 0x40000, v163
	v_add_u32_e32 v157, 0x50000, v163
	v_add_u32_e32 v158, 0x80000, v163
	v_add_u32_e32 v159, 0x90000, v163
	v_add_u32_e32 v160, 0xc0000, v163
	v_add_u32_e32 v161, 0xd0000, v163
	v_perm_b32 v146, v146, v138, v162
	v_perm_b32 v147, v147, v139, v162
	v_perm_b32 v148, v148, v140, v162
	v_perm_b32 v149, v149, v141, v162
	v_perm_b32 v150, v150, v142, v162
	v_perm_b32 v151, v151, v143, v162
	v_perm_b32 v152, v152, v144, v162
	v_perm_b32 v153, v153, v145, v162
	global_store_dword v154, v146, s[84:85] offset:64
	global_store_dword v155, v147, s[84:85] offset:64
	global_store_dword v156, v148, s[84:85] offset:64
	global_store_dword v157, v149, s[84:85] offset:64
	global_store_dword v158, v150, s[84:85] offset:64
	global_store_dword v159, v151, s[84:85] offset:64
	global_store_dword v160, v152, s[84:85] offset:64
	global_store_dword v161, v153, s[84:85] offset:64

; DI unsigned pk2(float a, float b) { f2_t v = {a, b}; bf2_t r = __builtin_convertvector(v, bf2_t); return __builtin_bit_cast(unsigned, r); }
; DI void phase_inproj(const Params& p, int l, unsigned char* smem) {
;     ...
;         } else if (n0 >= C_DAV && n0 < C_DAZ) {
;           const int cc = col - C_DAV;
; #pragma unroll
;           for (int g = 0; g < 4; ++g) {
;             const int rr = rb + 8 * g + 4 * h;
;             u32x2 w; w[0] = pk2(a[4 * g], a[4 * g + 1]); w[1] = pk2(a[4 * g + 2], a[4 * g + 3]);
;             *(u32x2*)(VT + ((size_t)(b * 512 + cc)) * SP + s0 + rr) = w;
;           }
.LBB0_245:
	s_andn2_b64 vcc, exec, s[26:27]
	s_cbranch_vccnz .LBB0_247
	v_add_u32_e32 v50, s47, v112
	v_mov_b64_e32 v[48:49], s[22:23]
	v_mad_u64_u32 v[48:49], s[26:27], v50, s42, v[48:49]
	v_cvt_pk_bf16_f32 v50, v32, v33
	v_cvt_pk_bf16_f32 v51, v34, v35
	v_lshl_add_u64 v[48:49], v[184:185], 1, v[48:49]
	flat_store_dwordx2 v[48:49], v[50:51] offset:64
	v_cvt_pk_bf16_f32 v50, v36, v37
	v_cvt_pk_bf16_f32 v51, v38, v39
	flat_store_dwordx2 v[48:49], v[50:51] offset:80
	v_cvt_pk_bf16_f32 v50, v40, v41
	v_cvt_pk_bf16_f32 v51, v42, v43
	flat_store_dwordx2 v[48:49], v[50:51] offset:96
	v_cvt_pk_bf16_f32 v50, v44, v45
	v_cvt_pk_bf16_f32 v51, v46, v47
	flat_store_dwordx2 v[48:49], v[50:51] offset:112

; DI unsigned pk2(float a, float b) { f2_t v = {a, b}; bf2_t r = __builtin_convertvector(v, bf2_t); return __builtin_bit_cast(unsigned, r); }
; DI void phase_inproj(const Params& p, int l, unsigned char* smem) {
;     ...
;         if (n0 < 1024) {
;           const int part = n0 >> 9, ch = col & 511;
; #pragma unroll
;           for (int g = 0; g < 4; ++g) {
;             const int rr = rb + 8 * g + 4 * h;
;             u32x2 w; w[0] = pk2(a[4 * g], a[4 * g + 1]); w[1] = pk2(a[4 * g + 2], a[4 * g + 3]);
;             if (isctx) *(u32x2*)(FTC + ((size_t)(b * 512 + ch)) * 512 + part * 256 + s0 + rr) = w;
;             else *(u32x2*)(FTL + ((size_t)(b * 512 + ch)) * 8192 + part * 4096 + (s0 - CTX) + rr) = w;
;           }
.LBB0_248:
	s_andn2_b64 vcc, exec, s[26:27]
	s_cbranch_vccnz .LBB0_253
	v_lshlrev_b32_e32 v208, 14, v118
	v_lshl_add_u64 v[48:49], s[18:19], 0, v[208:209]
	v_lshlrev_b32_e32 v208, 10, v118
	v_lshl_add_u64 v[50:51], v[48:49], 0, s[62:63]
	v_lshl_add_u64 v[48:49], s[20:21], 0, v[208:209]
	v_cvt_pk_bf16_f32 v32, v32, v33
	v_cvt_pk_bf16_f32 v33, v34, v35
	v_cndmask_b32_e64 v35, v51, v49, s[4:5]
	v_cndmask_b32_e64 v34, v50, v48, s[4:5]
	v_lshl_add_u64 v[34:35], v[184:185], 1, v[34:35]
	flat_store_dwordx2 v[34:35], v[32:33] offset:64
	v_cvt_pk_bf16_f32 v32, v36, v37
	v_cvt_pk_bf16_f32 v33, v38, v39
	flat_store_dwordx2 v[34:35], v[32:33] offset:80
	v_cvt_pk_bf16_f32 v32, v40, v41
	v_cvt_pk_bf16_f32 v33, v42, v43
	flat_store_dwordx2 v[34:35], v[32:33] offset:96
	v_cvt_pk_bf16_f32 v32, v44, v45
	v_cvt_pk_bf16_f32 v33, v46, v47
	s_and_b64 vcc, exec, s[6:7]
	s_mov_b64 s[26:27], -1
	s_cbranch_vccnz .LBB0_251
	v_lshl_add_u64 v[34:35], v[182:183], 1, v[50:51]
	s_mov_b64 s[26:27], 0
	flat_store_dwordx2 v[34:35], v[32:33]

; DI bfr f2bf(float a) { return (bfr)(pk2(a, 0.f) & 0xffffu); }
; DI int crow(int r, int h) { return (r & 3) + 8 * (r >> 2) + 4 * h; }
; DI void phase_inproj(const Params& p, int l, unsigned char* smem) {
;     ...
;         } else {
; #pragma unroll
;           for (int r = 0; r < 16; ++r) P[(size_t)(m0 + rb + crow(r, h)) * PLD + col] = f2bf(a[r]);
;         }
.LBB0_257:
	s_andn2_b64 vcc, exec, s[26:27]
	s_cbranch_vccnz .LBB0_259
	v_and_b32_e32 v164, 1, v216
	v_add_u32_e32 v163, s44, v249
	v_sub_u32_e32 v164, 0, v164
	v_lshlrev_b32_e32 v162, 1, v128
	v_add_u32_e32 v162, 0xcc00000, v162
	v_lshl_add_u32 v163, v163, 15, v162
	v_and_b32_e32 v162, 0x7ffe, v164
	v_add_u32_e32 v163, v163, v162
	v_and_b32_e32 v162, 0x6060606, v164
	v_xor_b32_e32 v162, 0x5040100, v162
	v_cvt_pk_bf16_f32 v138, v16, v17
	v_cvt_pk_bf16_f32 v139, v18, v19
	v_cvt_pk_bf16_f32 v140, v20, v21
	v_cvt_pk_bf16_f32 v141, v22, v23
	v_cvt_pk_bf16_f32 v142, v24, v25
	v_cvt_pk_bf16_f32 v143, v26, v27
	v_cvt_pk_bf16_f32 v144, v28, v29
	v_cvt_pk_bf16_f32 v145, v30, v31
	v_mov_b32_dpp v146, v138 quad_perm:[1,0,3,2] row_mask:0xf bank_mask:0xf
	v_mov_b32_dpp v147, v139 quad_perm:[1,0,3,2] row_mask:0xf bank_mask:0xf
	v_mov_b32_dpp v148, v140 quad_perm:[1,0,3,2] row_mask:0xf bank_mask:0xf
	v_mov_b32_dpp v149, v141 quad_perm:[1,0,3,2] row_mask:0xf bank_mask:0xf
	v_mov_b32_dpp v150, v142 quad_perm:[1,0,3,2] row_mask:0xf bank_mask:0xf
	v_mov_b32_dpp v151, v143 quad_perm:[1,0,3,2] row_mask:0xf bank_mask:0xf
	v_mov_b32_dpp v152, v144 quad_perm:[1,0,3,2] row_mask:0xf bank_mask:0xf
	v_mov_b32_dpp v153, v145 quad_perm:[1,0,3,2] row_mask:0xf bank_mask:0xf
	v_add_u32_e32 v154, 0x0, v163
	v_add_u32_e32 v155, 0x10000, v163
	v_add_u32_e32 v156, 0x40000, v163
	v_add_u32_e32 v157, 0x50000, v163
	v_add_u32_e32 v158, 0x80000, v163
	v_add_u32_e32 v159, 0x90000, v163
	v_add_u32_e32 v160, 0xc0000, v163
	v_add_u32_e32 v161, 0xd0000, v163
	v_perm_b32 v146, v146, v138, v162
	v_perm_b32 v147, v147, v139, v162
	v_perm_b32 v148, v148, v140, v162
	v_perm_b32 v149, v149, v141, v162
	v_perm_b32 v150, v150, v142, v162
	v_perm_b32 v151, v151, v143, v162
	v_perm_b32 v152, v152, v144, v162
	v_perm_b32 v153, v153, v145, v162
	global_store_dword v154, v146, s[84:85] offset:128
	global_store_dword v155, v147, s[84:85] offset:128
	global_store_dword v156, v148, s[84:85] offset:128
	global_store_dword v157, v149, s[84:85] offset:128
	global_store_dword v158, v150, s[84:85] offset:128
	global_store_dword v159, v151, s[84:85] offset:128
	global_store_dword v160, v152, s[84:85] offset:128
	global_store_dword v161, v153, s[84:85] offset:128

; DI unsigned pk2(float a, float b) { f2_t v = {a, b}; bf2_t r = __builtin_convertvector(v, bf2_t); return __builtin_bit_cast(unsigned, r); }
; DI void phase_inproj(const Params& p, int l, unsigned char* smem) {
;     ...
;         } else if (n0 >= C_DAV && n0 < C_DAZ) {
;           const int cc = col - C_DAV;
; #pragma unroll
;           for (int g = 0; g < 4; ++g) {
;             const int rr = rb + 8 * g + 4 * h;
;             u32x2 w; w[0] = pk2(a[4 * g], a[4 * g + 1]); w[1] = pk2(a[4 * g + 2], a[4 * g + 3]);
;             *(u32x2*)(VT + ((size_t)(b * 512 + cc)) * SP + s0 + rr) = w;
;           }
.LBB0_260:
	s_andn2_b64 vcc, exec, s[26:27]
	s_cbranch_vccnz .LBB0_262
	v_add_u32_e32 v34, s47, v96
	v_mov_b64_e32 v[32:33], s[22:23]
	v_mad_u64_u32 v[32:33], s[26:27], v34, s42, v[32:33]
	v_cvt_pk_bf16_f32 v34, v16, v17
	v_cvt_pk_bf16_f32 v35, v18, v19
	v_lshl_add_u64 v[32:33], v[184:185], 1, v[32:33]
	flat_store_dwordx2 v[32:33], v[34:35] offset:64
	v_cvt_pk_bf16_f32 v34, v20, v21
	v_cvt_pk_bf16_f32 v35, v22, v23
	flat_store_dwordx2 v[32:33], v[34:35] offset:80
	v_cvt_pk_bf16_f32 v34, v24, v25
	v_cvt_pk_bf16_f32 v35, v26, v27
	flat_store_dwordx2 v[32:33], v[34:35] offset:96
	v_cvt_pk_bf16_f32 v34, v28, v29
	v_cvt_pk_bf16_f32 v35, v30, v31
	flat_store_dwordx2 v[32:33], v[34:35] offset:112

; DI unsigned pk2(float a, float b) { f2_t v = {a, b}; bf2_t r = __builtin_convertvector(v, bf2_t); return __builtin_bit_cast(unsigned, r); }
; DI void phase_inproj(const Params& p, int l, unsigned char* smem) {
;     ...
;         if (n0 < 1024) {
;           const int part = n0 >> 9, ch = col & 511;
; #pragma unroll
;           for (int g = 0; g < 4; ++g) {
;             const int rr = rb + 8 * g + 4 * h;
;             u32x2 w; w[0] = pk2(a[4 * g], a[4 * g + 1]); w[1] = pk2(a[4 * g + 2], a[4 * g + 3]);
;             if (isctx) *(u32x2*)(FTC + ((size_t)(b * 512 + ch)) * 512 + part * 256 + s0 + rr) = w;
;             else *(u32x2*)(FTL + ((size_t)(b * 512 + ch)) * 8192 + part * 4096 + (s0 - CTX) + rr) = w;
;           }
.LBB0_263:
	s_andn2_b64 vcc, exec, s[26:27]
	s_cbranch_vccnz .LBB0_268
	v_lshlrev_b32_e32 v208, 14, v102
	v_lshl_add_u64 v[32:33], s[18:19], 0, v[208:209]
	v_lshlrev_b32_e32 v208, 10, v102
	v_lshl_add_u64 v[34:35], v[32:33], 0, s[62:63]
	v_lshl_add_u64 v[32:33], s[20:21], 0, v[208:209]
	v_cvt_pk_bf16_f32 v16, v16, v17
	v_cvt_pk_bf16_f32 v17, v18, v19
	v_cndmask_b32_e64 v19, v35, v33, s[4:5]
	v_cndmask_b32_e64 v18, v34, v32, s[4:5]
	v_lshl_add_u64 v[18:19], v[184:185], 1, v[18:19]
	flat_store_dwordx2 v[18:19], v[16:17] offset:64
	v_cvt_pk_bf16_f32 v16, v20, v21
	v_cvt_pk_bf16_f32 v17, v22, v23
	flat_store_dwordx2 v[18:19], v[16:17] offset:80
	v_cvt_pk_bf16_f32 v16, v24, v25
	v_cvt_pk_bf16_f32 v17, v26, v27
	flat_store_dwordx2 v[18:19], v[16:17] offset:96
	v_cvt_pk_bf16_f32 v16, v28, v29
	v_cvt_pk_bf16_f32 v17, v30, v31
	s_and_b64 vcc, exec, s[6:7]
	s_mov_b64 s[26:27], -1
	s_cbranch_vccnz .LBB0_266
	v_lshl_add_u64 v[18:19], v[182:183], 1, v[34:35]
	s_mov_b64 s[26:27], 0
	flat_store_dwordx2 v[18:19], v[16:17]

; DI bfr f2bf(float a) { return (bfr)(pk2(a, 0.f) & 0xffffu); }
; DI int crow(int r, int h) { return (r & 3) + 8 * (r >> 2) + 4 * h; }
; DI void phase_inproj(const Params& p, int l, unsigned char* smem) {
;     ...
;         } else {
; #pragma unroll
;           for (int r = 0; r < 16; ++r) P[(size_t)(m0 + rb + crow(r, h)) * PLD + col] = f2bf(a[r]);
;         }
.LBB0_272:
	s_andn2_b64 vcc, exec, s[8:9]
	s_cbranch_vccnz .LBB0_274
	v_and_b32_e32 v164, 1, v216
	v_add_u32_e32 v163, s44, v249
	v_sub_u32_e32 v164, 0, v164
	v_lshlrev_b32_e32 v162, 1, v128
	v_add_u32_e32 v162, 0xcc00000, v162
	v_lshl_add_u32 v163, v163, 15, v162
	v_and_b32_e32 v162, 0x7ffe, v164
	v_add_u32_e32 v163, v163, v162
	v_and_b32_e32 v162, 0x6060606, v164
	v_xor_b32_e32 v162, 0x5040100, v162
	v_cvt_pk_bf16_f32 v138, v0, v1
	v_cvt_pk_bf16_f32 v139, v2, v3
	v_cvt_pk_bf16_f32 v140, v4, v5
	v_cvt_pk_bf16_f32 v141, v6, v7
	v_cvt_pk_bf16_f32 v142, v8, v9
	v_cvt_pk_bf16_f32 v143, v10, v11
	v_cvt_pk_bf16_f32 v144, v12, v13
	v_cvt_pk_bf16_f32 v145, v14, v15
	v_mov_b32_dpp v146, v138 quad_perm:[1,0,3,2] row_mask:0xf bank_mask:0xf
	v_mov_b32_dpp v147, v139 quad_perm:[1,0,3,2] row_mask:0xf bank_mask:0xf
	v_mov_b32_dpp v148, v140 quad_perm:[1,0,3,2] row_mask:0xf bank_mask:0xf
	v_mov_b32_dpp v149, v141 quad_perm:[1,0,3,2] row_mask:0xf bank_mask:0xf
	v_mov_b32_dpp v150, v142 quad_perm:[1,0,3,2] row_mask:0xf bank_mask:0xf
	v_mov_b32_dpp v151, v143 quad_perm:[1,0,3,2] row_mask:0xf bank_mask:0xf
	v_mov_b32_dpp v152, v144 quad_perm:[1,0,3,2] row_mask:0xf bank_mask:0xf
	v_mov_b32_dpp v153, v145 quad_perm:[1,0,3,2] row_mask:0xf bank_mask:0xf
	v_add_u32_e32 v154, 0x0, v163
	v_add_u32_e32 v155, 0x10000, v163
	v_add_u32_e32 v156, 0x40000, v163
	v_add_u32_e32 v157, 0x50000, v163
	v_add_u32_e32 v158, 0x80000, v163
	v_add_u32_e32 v159, 0x90000, v163
	v_add_u32_e32 v160, 0xc0000, v163
	v_add_u32_e32 v161, 0xd0000, v163
	v_perm_b32 v146, v146, v138, v162
	v_perm_b32 v147, v147, v139, v162
	v_perm_b32 v148, v148, v140, v162
	v_perm_b32 v149, v149, v141, v162
	v_perm_b32 v150, v150, v142, v162
	v_perm_b32 v151, v151, v143, v162
	v_perm_b32 v152, v152, v144, v162
	v_perm_b32 v153, v153, v145, v162
	global_store_dword v154, v146, s[84:85] offset:192
	global_store_dword v155, v147, s[84:85] offset:192
	global_store_dword v156, v148, s[84:85] offset:192
	global_store_dword v157, v149, s[84:85] offset:192
	global_store_dword v158, v150, s[84:85] offset:192
	global_store_dword v159, v151, s[84:85] offset:192
	global_store_dword v160, v152, s[84:85] offset:192
	global_store_dword v161, v153, s[84:85] offset:192

; DI unsigned pk2(float a, float b) { f2_t v = {a, b}; bf2_t r = __builtin_convertvector(v, bf2_t); return __builtin_bit_cast(unsigned, r); }
; DI void phase_inproj(const Params& p, int l, unsigned char* smem) {
;     ...
;         } else if (n0 >= C_DAV && n0 < C_DAZ) {
;           const int cc = col - C_DAV;
; #pragma unroll
;           for (int g = 0; g < 4; ++g) {
;             const int rr = rb + 8 * g + 4 * h;
;             u32x2 w; w[0] = pk2(a[4 * g], a[4 * g + 1]); w[1] = pk2(a[4 * g + 2], a[4 * g + 3]);
;             *(u32x2*)(VT + ((size_t)(b * 512 + cc)) * SP + s0 + rr) = w;
;           }
.LBB0_275:
	s_andn2_b64 vcc, exec, s[8:9]
	s_cbranch_vccnz .LBB0_277
	v_add_u32_e32 v18, s47, v80
	v_mov_b64_e32 v[16:17], s[22:23]
	v_mad_u64_u32 v[16:17], s[8:9], v18, s42, v[16:17]
	v_cvt_pk_bf16_f32 v18, v0, v1
	v_cvt_pk_bf16_f32 v19, v2, v3
	v_lshl_add_u64 v[16:17], v[184:185], 1, v[16:17]
	flat_store_dwordx2 v[16:17], v[18:19] offset:64
	v_cvt_pk_bf16_f32 v18, v4, v5
	v_cvt_pk_bf16_f32 v19, v6, v7
	flat_store_dwordx2 v[16:17], v[18:19] offset:80
	v_cvt_pk_bf16_f32 v18, v8, v9
	v_cvt_pk_bf16_f32 v19, v10, v11
	flat_store_dwordx2 v[16:17], v[18:19] offset:96
	v_cvt_pk_bf16_f32 v18, v12, v13
	v_cvt_pk_bf16_f32 v19, v14, v15
	flat_store_dwordx2 v[16:17], v[18:19] offset:112

; DI unsigned pk2(float a, float b) { f2_t v = {a, b}; bf2_t r = __builtin_convertvector(v, bf2_t); return __builtin_bit_cast(unsigned, r); }
; DI void phase_inproj(const Params& p, int l, unsigned char* smem) {
;     ...
;         if (n0 < 1024) {
;           const int part = n0 >> 9, ch = col & 511;
; #pragma unroll
;           for (int g = 0; g < 4; ++g) {
;             const int rr = rb + 8 * g + 4 * h;
;             u32x2 w; w[0] = pk2(a[4 * g], a[4 * g + 1]); w[1] = pk2(a[4 * g + 2], a[4 * g + 3]);
;             if (isctx) *(u32x2*)(FTC + ((size_t)(b * 512 + ch)) * 512 + part * 256 + s0 + rr) = w;
;             else *(u32x2*)(FTL + ((size_t)(b * 512 + ch)) * 8192 + part * 4096 + (s0 - CTX) + rr) = w;
;           }
.LBB0_278:
	s_andn2_b64 vcc, exec, s[10:11]
	s_cbranch_vccnz .LBB0_283
	v_lshlrev_b32_e32 v208, 14, v86
	v_lshl_add_u64 v[16:17], s[18:19], 0, v[208:209]
	v_lshlrev_b32_e32 v208, 10, v86
	v_lshl_add_u64 v[18:19], v[16:17], 0, s[62:63]
	v_lshl_add_u64 v[16:17], s[20:21], 0, v[208:209]
	v_cvt_pk_bf16_f32 v0, v0, v1
	v_cvt_pk_bf16_f32 v1, v2, v3
	v_cndmask_b32_e64 v3, v19, v17, s[4:5]
	v_cndmask_b32_e64 v2, v18, v16, s[4:5]
	v_lshl_add_u64 v[2:3], v[184:185], 1, v[2:3]
	flat_store_dwordx2 v[2:3], v[0:1] offset:64
	v_cvt_pk_bf16_f32 v0, v4, v5
	v_cvt_pk_bf16_f32 v1, v6, v7
	flat_store_dwordx2 v[2:3], v[0:1] offset:80
	v_cvt_pk_bf16_f32 v0, v8, v9
	v_cvt_pk_bf16_f32 v1, v10, v11
	flat_store_dwordx2 v[2:3], v[0:1] offset:96
	v_cvt_pk_bf16_f32 v0, v12, v13
	v_cvt_pk_bf16_f32 v1, v14, v15
	s_and_b64 vcc, exec, s[6:7]
	s_mov_b64 s[4:5], -1
	s_cbranch_vccnz .LBB0_281
	v_lshl_add_u64 v[2:3], v[182:183], 1, v[18:19]
	s_mov_b64 s[4:5], 0
	flat_store_dwordx2 v[2:3], v[0:1]

; #define MFMA(a, b, c) __builtin_amdgcn_mfma_f32_32x32x16_bf16((a), (b), (c), 0, 0, 0)
; DI f32x16 zero16() { f32x16 z; for (int i = 0; i < 16; ++i) z[i] = 0.f; return z; }
; DI void attn_unit(const Params& p, int l, int unit, unsigned char* smem) {
;     ...
;   for (int kt = 0; kt < ntile; ++kt) {
;     __syncthreads();
; #pragma unroll
;     for (int i = 0; i < 4; ++i) { const int c = tid + 256 * i, key = c >> 4, kc = c & 15; *(u32x4*)(sK + key * 136 + 8 * kc) = rk[i]; }
;     __syncthreads();
;     if (kt + 1 < ntile) {
; #pragma unroll
;       for (int i = 0; i < 4; ++i) { const int c = tid + 256 * i, key = c >> 4, kc = c & 15; rk[i] = *(const u32x4*)(Kbase + (size_t)((kt + 1) * 64 + key) * PLD + 8 * kc); }
;     }
; #pragma unroll
;     for (int kb = 0; kb < 2; ++kb)
; #pragma unroll
;       for (int mp = 0; mp < 2; ++mp) {
;         f32x16 st = zero16();
; #pragma unroll
;         for (int s = 0; s < 4; ++s) st = MFMA(ld16(sK + (32 * kb + l31) * 136 + mp * 64 + 16 * s + 8 * h), qf[mp][s], st);
;         float tm = st[0];
; #pragma unroll
;         for (int r = 1; r < 16; ++r) tm = fmaxf(tm, st[r]);
;         const float mn = fmaxf(mx[mp], tm);
;         const float nmc = -mn * cs;
;         float sum = 0.f;
; #pragma unroll
;         for (int r = 0; r < 16; ++r) sum += __builtin_amdgcn_exp2f(fmaf(st[r], cs, nmc));
;         ls[mp] = ls[mp] * __builtin_amdgcn_exp2f((mx[mp] - mn) * cs) + sum;
;         mx[mp] = mn;
;       }
;   }
.LBB0_477:
	v_lshl_add_u64 v[0:1], v[56:57], 0, s[6:7]
	s_waitcnt lgkmcnt(0)
	s_barrier
	s_waitcnt vmcnt(0)
	ds_write_b128 v187, v[16:19]
	ds_write_b128 v186, v[20:23]
	ds_write_b128 v185, v[24:27]
	ds_write_b128 v184, v[28:31]
	s_waitcnt lgkmcnt(0)
	s_barrier
	global_load_dwordx4 v[16:19], v[0:1], off
	v_lshl_add_u64 v[0:1], v[54:55], 0, s[6:7]
	global_load_dwordx4 v[20:23], v[0:1], off
	v_lshl_add_u64 v[0:1], v[52:53], 0, s[6:7]
	global_load_dwordx4 v[24:27], v[0:1], off
	v_lshl_add_u64 v[0:1], v[50:51], 0, s[6:7]
	global_load_dwordx4 v[28:31], v[0:1], off
	ds_read_b128 v[236:239], v149
	ds_read_b128 v[246:249], v149 offset:32
	ds_read_b128 v[250:253], v149 offset:64
	s_waitcnt lgkmcnt(2)
	v_mfma_f32_32x32x16_bf16 v[0:15], v[236:239], v[120:123], 0
	s_add_u32 s6, s6, 0x200000
	s_addc_u32 s7, s7, 0
	s_cmp_eq_u32 s28, s6
	ds_read_b128 v[236:239], v149 offset:96
	s_waitcnt lgkmcnt(2)
	v_mfma_f32_32x32x16_bf16 v[0:15], v[246:249], v[116:119], v[0:15]
	ds_read_b128 v[246:249], v149 offset:128
	s_waitcnt lgkmcnt(2)
	v_mfma_f32_32x32x16_bf16 v[0:15], v[250:253], v[104:107], v[0:15]
	ds_read_b128 v[250:253], v149 offset:160
	s_waitcnt lgkmcnt(2)
	v_mfma_f32_32x32x16_bf16 v[0:15], v[236:239], v[100:103], v[0:15]
	s_nop 11
	v_max3_f32 v58, v0, v1, v2
	v_max3_f32 v58, v58, v3, v4
	v_max3_f32 v58, v58, v5, v6
	v_max3_f32 v58, v58, v7, v8
	v_max3_f32 v58, v58, v9, v10
	v_max3_f32 v58, v58, v11, v12
	v_max3_f32 v58, v58, v13, v14
	v_max3_f32 v93, v151, v58, v15
	v_mul_f32_e32 v58, 0xbe38aa3b, v93
	v_fmamk_f32 v0, v0, 0x3e38aa3b, v58
	v_exp_f32_e32 v76, v0
	v_fmamk_f32 v0, v1, 0x3e38aa3b, v58
	v_exp_f32_e32 v78, v0
	v_fmamk_f32 v0, v2, 0x3e38aa3b, v58
	v_exp_f32_e32 v80, v0
	v_fmamk_f32 v0, v3, 0x3e38aa3b, v58
	v_exp_f32_e32 v82, v0
	v_fmamk_f32 v0, v4, 0x3e38aa3b, v58
	v_exp_f32_e32 v84, v0
	v_fmamk_f32 v0, v5, 0x3e38aa3b, v58
	v_exp_f32_e32 v86, v0
	v_fmamk_f32 v0, v6, 0x3e38aa3b, v58
	v_exp_f32_e32 v88, v0
	v_fmamk_f32 v0, v7, 0x3e38aa3b, v58
	v_exp_f32_e32 v90, v0
	v_fmamk_f32 v0, v8, 0x3e38aa3b, v58
	v_exp_f32_e32 v74, v0
	v_fmamk_f32 v0, v9, 0x3e38aa3b, v58
	v_exp_f32_e32 v72, v0
	v_fmamk_f32 v0, v10, 0x3e38aa3b, v58
	v_exp_f32_e32 v70, v0
	v_fmamk_f32 v0, v11, 0x3e38aa3b, v58
	v_exp_f32_e32 v68, v0
	v_fmamk_f32 v0, v12, 0x3e38aa3b, v58
	v_exp_f32_e32 v66, v0
	v_fmamk_f32 v0, v13, 0x3e38aa3b, v58
	v_exp_f32_e32 v64, v0
	v_fmamk_f32 v0, v14, 0x3e38aa3b, v58
	v_exp_f32_e32 v62, v0
	v_sub_f32_e32 v0, v151, v93
	v_fmac_f32_e32 v58, 0x3e38aa3b, v15
	v_mul_f32_e32 v0, 0x3e38aa3b, v0
	v_exp_f32_e32 v60, v58
	v_exp_f32_e32 v58, v0
	ds_read_b128 v[236:239], v149 offset:192
	s_waitcnt lgkmcnt(2)
	v_mfma_f32_32x32x16_bf16 v[0:15], v[246:249], v[124:127], 0
	ds_read_b128 v[246:249], v149 offset:224
	s_waitcnt lgkmcnt(2)
	v_mfma_f32_32x32x16_bf16 v[0:15], v[250:253], v[112:115], v[0:15]
	ds_read_b128 v[250:253], v149 offset:8704
	s_waitcnt lgkmcnt(2)
	v_mfma_f32_32x32x16_bf16 v[0:15], v[236:239], v[108:111], v[0:15]
	ds_read_b128 v[236:239], v149 offset:8736
	s_waitcnt lgkmcnt(2)
	v_mfma_f32_32x32x16_bf16 v[0:15], v[246:249], v[96:99], v[0:15]
	s_nop 11
	v_max3_f32 v59, v0, v1, v2
	v_max3_f32 v59, v59, v3, v4
	v_max3_f32 v59, v59, v5, v6
	v_max3_f32 v59, v59, v7, v8
	v_max3_f32 v59, v59, v9, v10
	v_max3_f32 v59, v59, v11, v12
	v_max3_f32 v59, v59, v13, v14
	v_max3_f32 v152, v150, v59, v15
	v_mul_f32_e32 v59, 0xbe38aa3b, v152
	v_fmamk_f32 v0, v0, 0x3e38aa3b, v59
	v_exp_f32_e32 v77, v0
	v_fmamk_f32 v0, v1, 0x3e38aa3b, v59
	v_exp_f32_e32 v79, v0
	v_fmamk_f32 v0, v2, 0x3e38aa3b, v59
	v_exp_f32_e32 v81, v0
	v_fmamk_f32 v0, v3, 0x3e38aa3b, v59
	v_exp_f32_e32 v83, v0
	v_fmamk_f32 v0, v4, 0x3e38aa3b, v59
	v_exp_f32_e32 v85, v0
	v_fmamk_f32 v0, v5, 0x3e38aa3b, v59
	v_exp_f32_e32 v87, v0
	v_fmamk_f32 v0, v6, 0x3e38aa3b, v59
	v_exp_f32_e32 v89, v0
	v_fmamk_f32 v0, v7, 0x3e38aa3b, v59
	v_exp_f32_e32 v91, v0
	v_pk_add_f32 v[0:1], v[76:77], 0 op_sel_hi:[1,0]
	s_nop 0
	v_pk_add_f32 v[0:1], v[78:79], v[0:1]
	s_nop 0
	v_pk_add_f32 v[0:1], v[80:81], v[0:1]
	v_pk_add_f32 v[0:1], v[82:83], v[0:1]
	s_nop 0
	v_pk_add_f32 v[0:1], v[84:85], v[0:1]
	s_nop 0
	v_pk_add_f32 v[0:1], v[86:87], v[0:1]
	s_nop 0
	v_pk_add_f32 v[0:1], v[88:89], v[0:1]
	s_nop 0
	v_pk_add_f32 v[76:77], v[90:91], v[0:1]
	v_fmamk_f32 v0, v8, 0x3e38aa3b, v59
	v_exp_f32_e32 v75, v0
	v_fmamk_f32 v0, v9, 0x3e38aa3b, v59
	v_exp_f32_e32 v73, v0
	v_fmamk_f32 v0, v10, 0x3e38aa3b, v59
	v_exp_f32_e32 v71, v0
	v_fmamk_f32 v0, v11, 0x3e38aa3b, v59
	v_exp_f32_e32 v69, v0
	v_fmamk_f32 v0, v12, 0x3e38aa3b, v59
	v_exp_f32_e32 v67, v0
	v_fmamk_f32 v0, v13, 0x3e38aa3b, v59
	v_exp_f32_e32 v65, v0
	v_fmamk_f32 v0, v14, 0x3e38aa3b, v59
	v_exp_f32_e32 v63, v0
	v_sub_f32_e32 v0, v150, v152
	v_fmac_f32_e32 v59, 0x3e38aa3b, v15
	v_mul_f32_e32 v0, 0x3e38aa3b, v0
	v_exp_f32_e32 v61, v59
	v_exp_f32_e32 v59, v0
	ds_read_b128 v[246:249], v149 offset:8768
	s_waitcnt lgkmcnt(2)
	v_mfma_f32_32x32x16_bf16 v[0:15], v[250:253], v[120:123], 0
	ds_read_b128 v[250:253], v149 offset:8800
	s_waitcnt lgkmcnt(2)
	v_mfma_f32_32x32x16_bf16 v[0:15], v[236:239], v[116:119], v[0:15]
	ds_read_b128 v[236:239], v149 offset:8832
	s_waitcnt lgkmcnt(2)
	v_mfma_f32_32x32x16_bf16 v[0:15], v[246:249], v[104:107], v[0:15]
	ds_read_b128 v[246:249], v149 offset:8864
	s_waitcnt lgkmcnt(2)
; #define MFMA(a, b, c) __builtin_amdgcn_mfma_f32_32x32x16_bf16((a), (b), (c), 0, 0, 0)
; DI f32x16 zero16() { f32x16 z; for (int i = 0; i < 16; ++i) z[i] = 0.f; return z; }
; DI void attn_unit(const Params& p, int l, int unit, unsigned char* smem) {
;     ...
;   for (int kt = 0; kt < ntile; ++kt) {
;     __syncthreads();
; #pragma unroll
;     for (int i = 0; i < 4; ++i) { const int c = tid + 256 * i, key = c >> 4, kc = c & 15; *(u32x4*)(sK + key * 136 + 8 * kc) = rk[i]; }
;     __syncthreads();
;     ...
; #pragma unroll
;     for (int kb = 0; kb < 2; ++kb)
; #pragma unroll
;       for (int mp = 0; mp < 2; ++mp) {
;         f32x16 st = zero16();
; #pragma unroll
;         for (int s = 0; s < 4; ++s) st = MFMA(ld16(sK + (32 * kb + l31) * 136 + mp * 64 + 16 * s + 8 * h), qf[mp][s], st);
;         float tm = st[0];
; #pragma unroll
;         for (int r = 1; r < 16; ++r) tm = fmaxf(tm, st[r]);
;         const float mn = fmaxf(mx[mp], tm);
;         const float nmc = -mn * cs;
;         float sum = 0.f;
; #pragma unroll
;         for (int r = 0; r < 16; ++r) sum += __builtin_amdgcn_exp2f(fmaf(st[r], cs, nmc));
;         ls[mp] = ls[mp] * __builtin_amdgcn_exp2f((mx[mp] - mn) * cs) + sum;
;         mx[mp] = mn;
;       }
;   }
	v_mfma_f32_32x32x16_bf16 v[0:15], v[250:253], v[100:103], v[0:15]
	s_nop 11
	v_max3_f32 v78, v0, v1, v2
	v_max3_f32 v78, v78, v3, v4
	v_max3_f32 v78, v78, v5, v6
	v_max3_f32 v78, v78, v7, v8
	v_max3_f32 v78, v78, v9, v10
	v_max3_f32 v78, v78, v11, v12
	v_max3_f32 v78, v78, v13, v14
	v_max3_f32 v151, v93, v78, v15
	v_mul_f32_e32 v78, 0xbe38aa3b, v151
	v_fmamk_f32 v0, v0, 0x3e38aa3b, v78
	v_exp_f32_e32 v142, v0
	v_fmamk_f32 v0, v1, 0x3e38aa3b, v78
	v_exp_f32_e32 v140, v0
	v_fmamk_f32 v0, v2, 0x3e38aa3b, v78
	v_exp_f32_e32 v138, v0
	v_fmamk_f32 v0, v3, 0x3e38aa3b, v78
	v_exp_f32_e32 v136, v0
	v_fmamk_f32 v0, v4, 0x3e38aa3b, v78
	v_exp_f32_e32 v134, v0
	v_fmamk_f32 v0, v5, 0x3e38aa3b, v78
	v_exp_f32_e32 v132, v0
	v_fmamk_f32 v0, v6, 0x3e38aa3b, v78
	v_exp_f32_e32 v130, v0
	v_fmamk_f32 v0, v7, 0x3e38aa3b, v78
	v_exp_f32_e32 v128, v0
	v_fmamk_f32 v0, v8, 0x3e38aa3b, v78
	v_exp_f32_e32 v94, v0
	v_fmamk_f32 v0, v9, 0x3e38aa3b, v78
	v_exp_f32_e32 v92, v0
	v_fmamk_f32 v0, v10, 0x3e38aa3b, v78
	v_exp_f32_e32 v90, v0
	v_fmamk_f32 v0, v11, 0x3e38aa3b, v78
	v_exp_f32_e32 v88, v0
	v_fmamk_f32 v0, v12, 0x3e38aa3b, v78
	v_exp_f32_e32 v86, v0
	v_fmamk_f32 v0, v13, 0x3e38aa3b, v78
	v_exp_f32_e32 v84, v0
	v_fmamk_f32 v0, v14, 0x3e38aa3b, v78
	v_exp_f32_e32 v80, v0
	v_sub_f32_e32 v0, v93, v151
	v_mul_f32_e32 v0, 0x3e38aa3b, v0
	v_exp_f32_e32 v82, v0
	v_fmac_f32_e32 v78, 0x3e38aa3b, v15
	ds_read_b128 v[250:253], v149 offset:8896
	s_waitcnt lgkmcnt(2)
	v_mfma_f32_32x32x16_bf16 v[0:15], v[236:239], v[124:127], 0
	v_exp_f32_e32 v78, v78
	ds_read_b128 v[236:239], v149 offset:8928
	s_waitcnt lgkmcnt(2)
	v_mfma_f32_32x32x16_bf16 v[0:15], v[246:249], v[112:115], v[0:15]
	s_waitcnt lgkmcnt(1)
	v_mfma_f32_32x32x16_bf16 v[0:15], v[250:253], v[108:111], v[0:15]
	s_waitcnt lgkmcnt(0)
	v_mfma_f32_32x32x16_bf16 v[0:15], v[236:239], v[96:99], v[0:15]
	s_nop 11
	v_max3_f32 v79, v0, v1, v2
	v_max3_f32 v79, v79, v3, v4
	v_max3_f32 v79, v79, v5, v6
	v_max3_f32 v79, v79, v7, v8
	v_max3_f32 v79, v79, v9, v10
	v_max3_f32 v79, v79, v11, v12
	v_max3_f32 v79, v79, v13, v14
	v_max3_f32 v150, v152, v79, v15
	v_mul_f32_e32 v79, 0xbe38aa3b, v150
	v_fmamk_f32 v0, v0, 0x3e38aa3b, v79
	v_exp_f32_e32 v143, v0
	v_fmamk_f32 v0, v1, 0x3e38aa3b, v79
	v_exp_f32_e32 v141, v0
	v_fmamk_f32 v0, v2, 0x3e38aa3b, v79
	v_fmamk_f32 v2, v6, 0x3e38aa3b, v79
	v_exp_f32_e32 v139, v0
	v_fmamk_f32 v0, v3, 0x3e38aa3b, v79
	v_exp_f32_e32 v131, v2
	v_fmamk_f32 v2, v7, 0x3e38aa3b, v79
	v_exp_f32_e32 v137, v0
	v_fmamk_f32 v0, v4, 0x3e38aa3b, v79
	v_exp_f32_e32 v129, v2
	v_fmamk_f32 v2, v8, 0x3e38aa3b, v79
	v_exp_f32_e32 v135, v0
	v_fmamk_f32 v0, v5, 0x3e38aa3b, v79
	v_exp_f32_e32 v95, v2
	v_fmamk_f32 v2, v9, 0x3e38aa3b, v79
	v_exp_f32_e32 v133, v0
	v_pk_add_f32 v[0:1], v[142:143], 0 op_sel_hi:[1,0]
	v_exp_f32_e32 v93, v2
	v_fmamk_f32 v2, v10, 0x3e38aa3b, v79
	v_pk_add_f32 v[0:1], v[140:141], v[0:1]
	v_exp_f32_e32 v91, v2
	v_fmamk_f32 v2, v11, 0x3e38aa3b, v79
	v_pk_add_f32 v[0:1], v[138:139], v[0:1]
	v_exp_f32_e32 v89, v2
	v_fmamk_f32 v2, v12, 0x3e38aa3b, v79
	v_pk_add_f32 v[0:1], v[136:137], v[0:1]
	v_exp_f32_e32 v87, v2
	v_fmamk_f32 v2, v13, 0x3e38aa3b, v79
	v_pk_add_f32 v[0:1], v[134:135], v[0:1]
	v_exp_f32_e32 v85, v2
	v_fmamk_f32 v2, v14, 0x3e38aa3b, v79
	v_pk_add_f32 v[0:1], v[132:133], v[0:1]
	v_exp_f32_e32 v81, v2
	v_sub_f32_e32 v2, v152, v150
	v_mul_f32_e32 v2, 0x3e38aa3b, v2
	v_pk_add_f32 v[0:1], v[130:131], v[0:1]
	v_exp_f32_e32 v83, v2
	v_pk_add_f32 v[2:3], v[74:75], v[76:77]
	v_pk_add_f32 v[0:1], v[128:129], v[0:1]
	v_pk_add_f32 v[2:3], v[72:73], v[2:3]
	v_pk_add_f32 v[0:1], v[94:95], v[0:1]
	v_pk_add_f32 v[2:3], v[70:71], v[2:3]
	v_pk_add_f32 v[0:1], v[92:93], v[0:1]
	v_fmac_f32_e32 v79, 0x3e38aa3b, v15
	v_pk_add_f32 v[2:3], v[68:69], v[2:3]
	v_pk_add_f32 v[0:1], v[90:91], v[0:1]
	v_exp_f32_e32 v79, v79
	v_pk_add_f32 v[2:3], v[66:67], v[2:3]
	v_pk_add_f32 v[0:1], v[88:89], v[0:1]
	v_pk_add_f32 v[2:3], v[64:65], v[2:3]
	v_pk_add_f32 v[0:1], v[86:87], v[0:1]
	v_pk_add_f32 v[2:3], v[62:63], v[2:3]
	v_pk_add_f32 v[0:1], v[84:85], v[0:1]
	v_pk_add_f32 v[2:3], v[60:61], v[2:3]
	v_pk_add_f32 v[0:1], v[80:81], v[0:1]
	v_pk_fma_f32 v[2:3], v[48:49], v[58:59], v[2:3]
	v_pk_add_f32 v[0:1], v[78:79], v[0:1]
	s_nop 0
	v_pk_fma_f32 v[48:49], v[82:83], v[2:3], v[0:1]
	s_cbranch_scc0 .LBB0_477
	s_barrier
	s_waitcnt vmcnt(0)
	ds_write_b128 v187, v[16:19]
	ds_write_b128 v186, v[20:23]
	ds_write_b128 v185, v[24:27]
	ds_write_b128 v184, v[28:31]
	s_waitcnt lgkmcnt(0)
	s_barrier
; #define MFMA(a, b, c) __builtin_amdgcn_mfma_f32_32x32x16_bf16((a), (b), (c), 0, 0, 0)
; DI f32x16 zero16() { f32x16 z; for (int i = 0; i < 16; ++i) z[i] = 0.f; return z; }
; DI void attn_unit(const Params& p, int l, int unit, unsigned char* smem) {
;     ...
; #pragma unroll
;     for (int kb = 0; kb < 2; ++kb)
; #pragma unroll
;       for (int mp = 0; mp < 2; ++mp) {
;         f32x16 st = zero16();
; #pragma unroll
;         for (int s = 0; s < 4; ++s) st = MFMA(ld16(sK + (32 * kb + l31) * 136 + mp * 64 + 16 * s + 8 * h), qf[mp][s], st);
;         float tm = st[0];
; #pragma unroll
;         for (int r = 1; r < 16; ++r) tm = fmaxf(tm, st[r]);
;         const float mn = fmaxf(mx[mp], tm);
;         const float nmc = -mn * cs;
;         float sum = 0.f;
; #pragma unroll
;         for (int r = 0; r < 16; ++r) sum += __builtin_amdgcn_exp2f(fmaf(st[r], cs, nmc));
;         ls[mp] = ls[mp] * __builtin_amdgcn_exp2f((mx[mp] - mn) * cs) + sum;
;         mx[mp] = mn;
;       }
;   }
;     ...
; #pragma unroll
;   for (int i = 0; i < 4; ++i) {
;     const int c = tid + 256 * i;
;     { const int key = c >> 4, kc = c & 15; rk[i] = *(const u32x4*)(Kbase + (size_t)key * PLD + 8 * kc); }
;     { const int dv = c >> 3, kc = c & 7; rv[i] = *(const u32x4*)(VT + (size_t)dv * SP + 8 * kc); }
;   }
	ds_read_b128 v[0:3], v149
	ds_read_b128 v[16:19], v149 offset:32
	s_waitcnt lgkmcnt(1)
	v_mfma_f32_32x32x16_bf16 v[0:15], v[0:3], v[120:123], 0
	v_cmp_lt_i32_e32 vcc, v222, v221
	s_lshl_b32 s6, s26, 2
	s_or_b32 s27, s6, s27
	s_mul_hi_i32 s26, s27, 0x110000
	s_mul_i32 s27, s27, 0x110000
	s_add_u32 s6, s4, s27
	s_addc_u32 s7, s5, s26
	s_waitcnt lgkmcnt(0)
	v_mfma_f32_32x32x16_bf16 v[0:15], v[16:19], v[116:119], v[0:15]
	ds_read_b128 v[16:19], v149 offset:64
	flat_load_dwordx4 v[128:131], v[46:47]
	v_or_b32_e32 v50, 32, v165
	v_lshlrev_b32_e32 v188, 2, v167
	s_waitcnt lgkmcnt(0)
	v_mfma_f32_32x32x16_bf16 v[0:15], v[16:19], v[104:107], v[0:15]
	ds_read_b128 v[16:19], v149 offset:96
	s_waitcnt lgkmcnt(0)
	v_mfma_f32_32x32x16_bf16 v[0:15], v[16:19], v[100:103], v[0:15]
	ds_read_b128 v[18:21], v149 offset:160
	s_nop 10
	v_max3_f32 v16, v0, v1, v2
	v_max3_f32 v16, v16, v3, v4
	v_max3_f32 v16, v16, v5, v6
	v_max3_f32 v16, v16, v7, v8
	v_max3_f32 v16, v16, v9, v10
	v_max3_f32 v16, v16, v11, v12
	v_max3_f32 v16, v16, v13, v14
	v_max3_f32 v16, v151, v16, v15
	v_mul_f32_e32 v17, 0xbe38aa3b, v16
	v_fmamk_f32 v0, v0, 0x3e38aa3b, v17
	v_exp_f32_e32 v0, v0
	v_fmamk_f32 v1, v1, 0x3e38aa3b, v17
	v_exp_f32_e32 v1, v1
	v_add_f32_e32 v0, 0, v0
	v_add_f32_e32 v0, v1, v0
	v_fmamk_f32 v1, v2, 0x3e38aa3b, v17
	v_exp_f32_e32 v1, v1
	s_nop 0
	v_add_f32_e32 v0, v1, v0
	v_fmamk_f32 v1, v3, 0x3e38aa3b, v17
	v_exp_f32_e32 v1, v1
	s_nop 0
	v_add_f32_e32 v0, v1, v0
	v_fmamk_f32 v1, v4, 0x3e38aa3b, v17
	v_exp_f32_e32 v1, v1
	s_nop 0
	v_add_f32_e32 v0, v1, v0
	v_fmamk_f32 v1, v5, 0x3e38aa3b, v17
	v_exp_f32_e32 v1, v1
	s_nop 0
	v_add_f32_e32 v0, v1, v0
	v_fmamk_f32 v1, v6, 0x3e38aa3b, v17
	v_exp_f32_e32 v1, v1
	s_nop 0
	v_add_f32_e32 v0, v1, v0
	v_fmamk_f32 v1, v7, 0x3e38aa3b, v17
	v_exp_f32_e32 v1, v1
	s_nop 0
	v_add_f32_e32 v0, v1, v0
	v_fmamk_f32 v1, v8, 0x3e38aa3b, v17
	v_exp_f32_e32 v1, v1
	s_nop 0
	v_add_f32_e32 v0, v1, v0
	v_fmamk_f32 v1, v9, 0x3e38aa3b, v17
	v_exp_f32_e32 v1, v1
	s_nop 0
	v_add_f32_e32 v0, v1, v0
	v_fmamk_f32 v1, v10, 0x3e38aa3b, v17
	v_exp_f32_e32 v1, v1
	s_nop 0
	v_add_f32_e32 v0, v1, v0
	v_fmamk_f32 v1, v11, 0x3e38aa3b, v17
	v_exp_f32_e32 v1, v1
	s_nop 0
	v_add_f32_e32 v0, v1, v0
	v_fmamk_f32 v1, v12, 0x3e38aa3b, v17
	v_exp_f32_e32 v1, v1
	s_nop 0
	v_add_f32_e32 v0, v1, v0
	v_fmamk_f32 v1, v13, 0x3e38aa3b, v17
	v_exp_f32_e32 v1, v1
	s_nop 0
	v_add_f32_e32 v0, v1, v0
	v_fmamk_f32 v1, v14, 0x3e38aa3b, v17
	v_exp_f32_e32 v1, v1
	v_fmac_f32_e32 v17, 0x3e38aa3b, v15
	v_add_f32_e32 v0, v1, v0
	v_exp_f32_e32 v1, v17
	s_nop 0
	v_add_f32_e32 v17, v1, v0
	v_sub_f32_e32 v0, v151, v16
	v_mul_f32_e32 v0, 0x3e38aa3b, v0
	v_exp_f32_e32 v0, v0
	s_nop 0
	v_fmac_f32_e32 v17, v48, v0
	ds_read_b128 v[0:3], v149 offset:128
	s_waitcnt lgkmcnt(0)
	v_mfma_f32_32x32x16_bf16 v[0:15], v[0:3], v[124:127], 0
	v_mfma_f32_32x32x16_bf16 v[0:15], v[18:21], v[112:115], v[0:15]
	ds_read_b128 v[18:21], v149 offset:192
	s_waitcnt lgkmcnt(0)
	v_mfma_f32_32x32x16_bf16 v[0:15], v[18:21], v[108:111], v[0:15]
	ds_read_b128 v[18:21], v149 offset:224
	s_waitcnt lgkmcnt(0)
	v_mfma_f32_32x32x16_bf16 v[0:15], v[18:21], v[96:99], v[0:15]
	ds_read_b128 v[20:23], v149 offset:8736
	s_nop 10
	v_max3_f32 v18, v0, v1, v2
	v_max3_f32 v18, v18, v3, v4
	v_max3_f32 v18, v18, v5, v6
	v_max3_f32 v18, v18, v7, v8
	v_max3_f32 v18, v18, v9, v10
	v_max3_f32 v18, v18, v11, v12
	v_max3_f32 v18, v18, v13, v14
	v_max3_f32 v18, v150, v18, v15
	v_mul_f32_e32 v19, 0xbe38aa3b, v18
	v_fmamk_f32 v0, v0, 0x3e38aa3b, v19
	v_exp_f32_e32 v0, v0
	v_fmamk_f32 v1, v1, 0x3e38aa3b, v19
	v_exp_f32_e32 v1, v1
	v_add_f32_e32 v0, 0, v0
	v_add_f32_e32 v0, v1, v0
	v_fmamk_f32 v1, v2, 0x3e38aa3b, v19
	v_exp_f32_e32 v1, v1
	s_nop 0
	v_add_f32_e32 v0, v1, v0
	v_fmamk_f32 v1, v3, 0x3e38aa3b, v19
	v_exp_f32_e32 v1, v1
	s_nop 0
	v_add_f32_e32 v0, v1, v0
	v_fmamk_f32 v1, v4, 0x3e38aa3b, v19
	v_exp_f32_e32 v1, v1
	s_nop 0
	v_add_f32_e32 v0, v1, v0
	v_fmamk_f32 v1, v5, 0x3e38aa3b, v19
	v_exp_f32_e32 v1, v1
	s_nop 0
	v_add_f32_e32 v0, v1, v0
	v_fmamk_f32 v1, v6, 0x3e38aa3b, v19
	v_exp_f32_e32 v1, v1
	s_nop 0
	v_add_f32_e32 v0, v1, v0
	v_fmamk_f32 v1, v7, 0x3e38aa3b, v19
	v_exp_f32_e32 v1, v1
	s_nop 0
	v_add_f32_e32 v0, v1, v0
	v_fmamk_f32 v1, v8, 0x3e38aa3b, v19
	v_exp_f32_e32 v1, v1
	s_nop 0
	v_add_f32_e32 v0, v1, v0
	v_fmamk_f32 v1, v9, 0x3e38aa3b, v19
	v_exp_f32_e32 v1, v1
	s_nop 0
	v_add_f32_e32 v0, v1, v0
	v_fmamk_f32 v1, v10, 0x3e38aa3b, v19
	v_exp_f32_e32 v1, v1
	s_nop 0
	v_add_f32_e32 v0, v1, v0
	v_fmamk_f32 v1, v11, 0x3e38aa3b, v19
	v_exp_f32_e32 v1, v1
	s_nop 0
	v_add_f32_e32 v0, v1, v0
	v_fmamk_f32 v1, v12, 0x3e38aa3b, v19
	v_exp_f32_e32 v1, v1
	s_nop 0
	v_add_f32_e32 v0, v1, v0
	v_fmamk_f32 v1, v13, 0x3e38aa3b, v19
	v_exp_f32_e32 v1, v1
	s_nop 0
	v_add_f32_e32 v0, v1, v0
	v_fmamk_f32 v1, v14, 0x3e38aa3b, v19
	v_exp_f32_e32 v1, v1
	v_fmac_f32_e32 v19, 0x3e38aa3b, v15
	v_add_f32_e32 v0, v1, v0
	v_exp_f32_e32 v1, v19
	s_nop 0
	v_add_f32_e32 v19, v1, v0
	v_sub_f32_e32 v0, v150, v18
	v_mul_f32_e32 v0, 0x3e38aa3b, v0
	v_exp_f32_e32 v0, v0
	s_nop 0
	v_fmac_f32_e32 v19, v49, v0
	ds_read_b128 v[0:3], v149 offset:8704
	s_waitcnt lgkmcnt(0)
	v_mfma_f32_32x32x16_bf16 v[0:15], v[0:3], v[120:123], 0
	v_mfma_f32_32x32x16_bf16 v[0:15], v[20:23], v[116:119], v[0:15]
	ds_read_b128 v[20:23], v149 offset:8768
	s_waitcnt lgkmcnt(0)
	v_mfma_f32_32x32x16_bf16 v[0:15], v[20:23], v[104:107], v[0:15]
	ds_read_b128 v[20:23], v149 offset:8800
	s_waitcnt lgkmcnt(0)
; #define MFMA(a, b, c) __builtin_amdgcn_mfma_f32_32x32x16_bf16((a), (b), (c), 0, 0, 0)
; DI void attn_unit(const Params& p, int l, int unit, unsigned char* smem) {
;     ...
;         for (int s = 0; s < 4; ++s) st = MFMA(ld16(sK + (32 * kb + l31) * 136 + mp * 64 + 16 * s + 8 * h), qf[mp][s], st);
;         float tm = st[0];
; #pragma unroll
;         for (int r = 1; r < 16; ++r) tm = fmaxf(tm, st[r]);
;         const float mn = fmaxf(mx[mp], tm);
;         const float nmc = -mn * cs;
;         float sum = 0.f;
; #pragma unroll
;         for (int r = 0; r < 16; ++r) sum += __builtin_amdgcn_exp2f(fmaf(st[r], cs, nmc));
;         ls[mp] = ls[mp] * __builtin_amdgcn_exp2f((mx[mp] - mn) * cs) + sum;
;         mx[mp] = mn;
;       }
;   }
;   float nm[2], sc[2];
; #pragma unroll
;   for (int mp = 0; mp < 2; ++mp) {
;     const float mo = __shfl_xor(mx[mp], 32), lo = __shfl_xor(ls[mp], 32);
;     const float M = fmaxf(mx[mp], mo);
;     const float L = ls[mp] * __builtin_amdgcn_exp2f((mx[mp] - M) * cs) + lo * __builtin_amdgcn_exp2f((mo - M) * cs);
;     nm[mp] = -M * cs; sc[mp] = (mp ? lam : 1.f) / L;
;   }
	v_mfma_f32_32x32x16_bf16 v[0:15], v[20:23], v[100:103], v[0:15]
	ds_read_b128 v[22:25], v149 offset:8864
	s_nop 10
	v_max3_f32 v20, v0, v1, v2
	v_max3_f32 v20, v20, v3, v4
	v_max3_f32 v20, v20, v5, v6
	v_max3_f32 v20, v20, v7, v8
	v_max3_f32 v20, v20, v9, v10
	v_max3_f32 v20, v20, v11, v12
	v_max3_f32 v20, v20, v13, v14
	v_max3_f32 v20, v16, v20, v15
	v_mul_f32_e32 v21, 0xbe38aa3b, v20
	v_fmamk_f32 v0, v0, 0x3e38aa3b, v21
	v_exp_f32_e32 v0, v0
	v_fmamk_f32 v1, v1, 0x3e38aa3b, v21
	v_exp_f32_e32 v1, v1
	v_add_f32_e32 v0, 0, v0
	v_add_f32_e32 v0, v1, v0
	v_fmamk_f32 v1, v2, 0x3e38aa3b, v21
	v_exp_f32_e32 v1, v1
	s_nop 0
	v_add_f32_e32 v0, v1, v0
	v_fmamk_f32 v1, v3, 0x3e38aa3b, v21
	v_exp_f32_e32 v1, v1
	s_nop 0
	v_add_f32_e32 v0, v1, v0
	v_fmamk_f32 v1, v4, 0x3e38aa3b, v21
	v_exp_f32_e32 v1, v1
	s_nop 0
	v_add_f32_e32 v0, v1, v0
	v_fmamk_f32 v1, v5, 0x3e38aa3b, v21
	v_exp_f32_e32 v1, v1
	s_nop 0
	v_add_f32_e32 v0, v1, v0
	v_fmamk_f32 v1, v6, 0x3e38aa3b, v21
	v_exp_f32_e32 v1, v1
	s_nop 0
	v_add_f32_e32 v0, v1, v0
	v_fmamk_f32 v1, v7, 0x3e38aa3b, v21
	v_exp_f32_e32 v1, v1
	s_nop 0
	v_add_f32_e32 v0, v1, v0
	v_fmamk_f32 v1, v8, 0x3e38aa3b, v21
	v_exp_f32_e32 v1, v1
	s_nop 0
	v_add_f32_e32 v0, v1, v0
	v_fmamk_f32 v1, v9, 0x3e38aa3b, v21
	v_exp_f32_e32 v1, v1
	s_nop 0
	v_add_f32_e32 v0, v1, v0
	v_fmamk_f32 v1, v10, 0x3e38aa3b, v21
	v_exp_f32_e32 v1, v1
	s_nop 0
	v_add_f32_e32 v0, v1, v0
	v_fmamk_f32 v1, v11, 0x3e38aa3b, v21
	v_exp_f32_e32 v1, v1
	s_nop 0
	v_add_f32_e32 v0, v1, v0
	v_fmamk_f32 v1, v12, 0x3e38aa3b, v21
	v_exp_f32_e32 v1, v1
	s_nop 0
	v_add_f32_e32 v0, v1, v0
	v_fmamk_f32 v1, v13, 0x3e38aa3b, v21
	v_exp_f32_e32 v1, v1
	s_nop 0
	v_add_f32_e32 v0, v1, v0
	v_fmamk_f32 v1, v14, 0x3e38aa3b, v21
	v_exp_f32_e32 v1, v1
	v_fmac_f32_e32 v21, 0x3e38aa3b, v15
	v_add_f32_e32 v0, v1, v0
	v_exp_f32_e32 v1, v21
	s_nop 0
	v_add_f32_e32 v21, v1, v0
	v_sub_f32_e32 v0, v16, v20
	v_mul_f32_e32 v0, 0x3e38aa3b, v0
	v_exp_f32_e32 v0, v0
	s_nop 0
	v_fmac_f32_e32 v21, v0, v17
	ds_read_b128 v[0:3], v149 offset:8832
	s_waitcnt lgkmcnt(0)
	v_mfma_f32_32x32x16_bf16 v[0:15], v[0:3], v[124:127], 0
	v_mfma_f32_32x32x16_bf16 v[0:15], v[22:25], v[112:115], v[0:15]
	ds_read_b128 v[22:25], v149 offset:8896
	s_waitcnt lgkmcnt(0)
	v_mfma_f32_32x32x16_bf16 v[0:15], v[22:25], v[108:111], v[0:15]
	ds_read_b128 v[22:25], v149 offset:8928
	s_waitcnt lgkmcnt(0)
	v_mfma_f32_32x32x16_bf16 v[0:15], v[22:25], v[96:99], v[0:15]
	s_nop 11
	v_max3_f32 v16, v0, v1, v2
	v_max3_f32 v16, v16, v3, v4
	v_max3_f32 v16, v16, v5, v6
	v_max3_f32 v16, v16, v7, v8
	v_max3_f32 v16, v16, v9, v10
	v_max3_f32 v16, v16, v11, v12
	v_max3_f32 v16, v16, v13, v14
	v_max3_f32 v16, v18, v16, v15
	v_mul_f32_e32 v17, 0xbe38aa3b, v16
	v_fmamk_f32 v0, v0, 0x3e38aa3b, v17
	v_exp_f32_e32 v0, v0
	v_fmamk_f32 v1, v1, 0x3e38aa3b, v17
	v_exp_f32_e32 v1, v1
	v_add_f32_e32 v0, 0, v0
	v_add_f32_e32 v0, v1, v0
	v_fmamk_f32 v1, v2, 0x3e38aa3b, v17
	v_exp_f32_e32 v1, v1
	s_nop 0
	v_add_f32_e32 v0, v1, v0
	v_fmamk_f32 v1, v3, 0x3e38aa3b, v17
	v_exp_f32_e32 v1, v1
	s_nop 0
	v_add_f32_e32 v0, v1, v0
	v_fmamk_f32 v1, v4, 0x3e38aa3b, v17
	v_exp_f32_e32 v1, v1
	s_nop 0
	v_add_f32_e32 v0, v1, v0
	v_fmamk_f32 v1, v5, 0x3e38aa3b, v17
	v_exp_f32_e32 v1, v1
	s_nop 0
	v_add_f32_e32 v0, v1, v0
	v_fmamk_f32 v1, v6, 0x3e38aa3b, v17
	v_exp_f32_e32 v1, v1
	s_nop 0
	v_add_f32_e32 v0, v1, v0
	v_fmamk_f32 v1, v7, 0x3e38aa3b, v17
	v_exp_f32_e32 v1, v1
	v_ashrrev_i32_e32 v7, 3, v148
	v_add_f32_e32 v0, v1, v0
	v_fmamk_f32 v1, v8, 0x3e38aa3b, v17
	v_exp_f32_e32 v1, v1
	s_nop 0
	v_add_f32_e32 v0, v1, v0
	v_fmamk_f32 v1, v9, 0x3e38aa3b, v17
	v_exp_f32_e32 v1, v1
	s_nop 0
	v_add_f32_e32 v0, v1, v0
	v_fmamk_f32 v1, v10, 0x3e38aa3b, v17
	v_exp_f32_e32 v1, v1
	s_nop 0
	v_add_f32_e32 v0, v1, v0
	v_fmamk_f32 v1, v11, 0x3e38aa3b, v17
	v_exp_f32_e32 v1, v1
	s_nop 0
	v_add_f32_e32 v0, v1, v0
	v_fmamk_f32 v1, v12, 0x3e38aa3b, v17
	v_exp_f32_e32 v1, v1
	s_nop 0
	v_add_f32_e32 v0, v1, v0
	v_fmamk_f32 v1, v13, 0x3e38aa3b, v17
	v_exp_f32_e32 v1, v1
	s_nop 0
	v_add_f32_e32 v0, v1, v0
	v_fmamk_f32 v1, v14, 0x3e38aa3b, v17
	v_exp_f32_e32 v1, v1
	v_fmac_f32_e32 v17, 0x3e38aa3b, v15
	v_add_f32_e32 v0, v1, v0
	v_exp_f32_e32 v1, v17
	s_nop 0
	v_add_f32_e32 v0, v1, v0
	v_sub_f32_e32 v1, v18, v16
	v_mul_f32_e32 v1, 0x3e38aa3b, v1
	v_exp_f32_e32 v1, v1
	s_nop 0
	v_fmac_f32_e32 v0, v1, v19
	v_cndmask_b32_e32 v1, v220, v222, vcc
	v_lshlrev_b32_e32 v189, 2, v1
	ds_bpermute_b32 v1, v189, v20
	ds_bpermute_b32 v2, v189, v21
	s_waitcnt lgkmcnt(0)
	v_max_f32_e32 v3, v1, v1
	v_max_f32_e32 v3, v20, v3
	v_sub_f32_e32 v4, v20, v3
	v_mul_f32_e32 v4, 0x3e38aa3b, v4
	v_sub_f32_e32 v1, v1, v3
	v_exp_f32_e32 v4, v4
	v_mul_f32_e32 v1, 0x3e38aa3b, v1
	v_exp_f32_e32 v1, v1
	v_mul_f32_e32 v190, 0xbe38aa3b, v3
	v_mul_f32_e32 v4, v4, v21
	v_fmac_f32_e32 v4, v1, v2
	v_div_scale_f32 v1, s[28:29], v4, v4, 1.0
	v_rcp_f32_e32 v2, v1
	s_nop 0
	v_fma_f32 v3, -v1, v2, 1.0
	v_fmac_f32_e32 v2, v3, v2
	v_div_scale_f32 v3, vcc, 1.0, v4, 1.0
	v_mul_f32_e32 v5, v3, v2
	v_fma_f32 v6, -v1, v5, v3
	v_fmac_f32_e32 v5, v6, v2
	v_fma_f32 v1, -v1, v5, v3
	v_div_fmas_f32 v1, v1, v2, v5
	v_div_fixup_f32 v164, v1, v4, 1.0
	ds_bpermute_b32 v1, v189, v16
	ds_bpermute_b32 v2, v189, v0
	v_ashrrev_i32_e32 v6, 3, v146
	s_waitcnt lgkmcnt(0)
; DI f32x16 zero16() { f32x16 z; for (int i = 0; i < 16; ++i) z[i] = 0.f; return z; }
; DI void attn_unit(const Params& p, int l, int unit, unsigned char* smem) {
;     ...
;   float nm[2], sc[2];
; #pragma unroll
;   for (int mp = 0; mp < 2; ++mp) {
;     const float mo = __shfl_xor(mx[mp], 32), lo = __shfl_xor(ls[mp], 32);
;     const float M = fmaxf(mx[mp], mo);
;     const float L = ls[mp] * __builtin_amdgcn_exp2f((mx[mp] - M) * cs) + lo * __builtin_amdgcn_exp2f((mo - M) * cs);
;     nm[mp] = -M * cs; sc[mp] = (mp ? lam : 1.f) / L;
;   }
;   f32x16 oacc[4];
;   for (int i = 0; i < 4; ++i) oacc[i] = zero16();
; #pragma unroll
;   for (int i = 0; i < 4; ++i) {
;     const int c = tid + 256 * i;
;     { const int key = c >> 4, kc = c & 15; rk[i] = *(const u32x4*)(Kbase + (size_t)key * PLD + 8 * kc); }
;     { const int dv = c >> 3, kc = c & 7; rv[i] = *(const u32x4*)(VT + (size_t)dv * SP + 8 * kc); }
;   }
	v_max_f32_e32 v3, v1, v1
	v_max_f32_e32 v3, v16, v3
	v_sub_f32_e32 v4, v16, v3
	v_mul_f32_e32 v4, 0x3e38aa3b, v4
	v_sub_f32_e32 v1, v1, v3
	v_exp_f32_e32 v4, v4
	v_mul_f32_e32 v1, 0x3e38aa3b, v1
	v_exp_f32_e32 v1, v1
	v_mul_f32_e32 v191, 0xbe38aa3b, v3
	v_mul_f32_e32 v0, v4, v0
	v_fmac_f32_e32 v0, v1, v2
	v_div_scale_f32 v1, s[28:29], v0, v0, v145
	v_rcp_f32_e32 v2, v1
	s_nop 0
	v_fma_f32 v3, -v1, v2, 1.0
	v_fmac_f32_e32 v2, v3, v2
	v_div_scale_f32 v3, vcc, v145, v0, v145
	v_mul_f32_e32 v4, v3, v2
	v_fma_f32 v5, -v1, v4, v3
	v_fmac_f32_e32 v4, v5, v2
	v_fma_f32 v1, -v1, v4, v3
	v_div_fmas_f32 v1, v1, v2, v4
	v_div_fixup_f32 v166, v1, v0, v145
	v_lshlrev_b32_e32 v0, 1, v147
	v_and_b32_e32 v2, 0x70, v0
	v_mov_b32_e32 v3, v209
	v_lshl_add_u64 v[0:1], s[6:7], 0, v[2:3]
	s_mov_b64 s[6:7], 0x30f10000
	v_lshl_add_u64 v[0:1], v[0:1], 0, s[6:7]
	v_ashrrev_i32_e32 v3, 3, v144
	v_mad_i64_i32 v[4:5], s[6:7], v3, s42, v[0:1]
	flat_load_dwordx4 v[132:135], v[4:5]
	flat_load_dwordx4 v[136:139], v[42:43]
	v_mad_i64_i32 v[4:5], s[6:7], v6, s42, v[0:1]
	flat_load_dwordx4 v[140:143], v[4:5]
	flat_load_dwordx4 v[144:147], v[44:45]
	v_mad_i64_i32 v[4:5], s[6:7], v7, s42, v[0:1]
	flat_load_dwordx4 v[148:151], v[4:5]
	flat_load_dwordx4 v[152:155], v[40:41]
	v_ashrrev_i32_e32 v4, 3, v156
	v_mad_i64_i32 v[0:1], s[6:7], v4, s42, v[0:1]
	flat_load_dwordx4 v[156:159], v[0:1]
	s_movk_i32 s6, 0x90
	v_mul_lo_u32 v8, v3, s6
	v_mul_lo_u32 v9, v6, s6
	v_mul_lo_u32 v10, v7, s6
	v_mul_lo_u32 v11, v4, s6
	s_add_i32 s6, s9, 1
	s_add_u32 s7, s25, s44
	s_addc_u32 s9, s24, 0
	v_mul_u32_u24_e32 v0, 0x90, v165
	v_lshlrev_b32_e32 v1, 7, v165
	v_lshlrev_b32_e32 v5, 1, v168
	s_add_u32 s24, s7, 0xce03400
	v_or_b32_e32 v198, v0, v168
	v_add3_u32 v197, v0, v1, v5
	v_mul_u32_u24_e32 v0, 0x90, v50
	v_lshlrev_b32_e32 v1, 7, v50
	s_addc_u32 s25, s9, 0
	v_or_b32_e32 v199, v0, v168
	v_add3_u32 v192, v0, v1, v5
	v_lshl_add_u64 v[0:1], s[24:25], 0, v[38:39]
	v_lshl_add_u64 v[168:169], v[0:1], 0, v[208:209]
	v_lshl_add_u64 v[0:1], s[24:25], 0, v[36:37]
	v_lshl_add_u64 v[170:171], v[0:1], 0, v[208:209]
	v_lshl_add_u64 v[0:1], s[24:25], 0, v[34:35]
	v_lshl_add_u64 v[172:173], v[0:1], 0, v[208:209]
	v_lshl_add_u64 v[0:1], s[24:25], 0, v[32:33]
	s_add_u32 s24, s27, 0x30f10080
	s_addc_u32 s25, s26, 0
	v_lshl_add_u64 v[174:175], v[0:1], 0, v[208:209]
	v_mov_b64_e32 v[0:1], s[24:25]
	v_mad_i64_i32 v[176:177], s[24:25], v4, s42, v[0:1]
	v_and_b32_e32 v4, 0x70, v178
	v_mad_i64_i32 v[178:179], s[24:25], v7, s42, v[0:1]
	v_mad_i64_i32 v[180:181], s[24:25], v6, s42, v[0:1]
	v_mad_i64_i32 v[182:183], s[24:25], v3, s42, v[0:1]
	v_mov_b32_e32 v0, 0
	v_mov_b32_e32 v165, v164
	v_mov_b32_e32 v167, v166
	v_or_b32_e32 v176, v176, v4
	v_or_b32_e32 v178, v178, v4
	v_or_b32_e32 v180, v180, v4
	v_or_b32_e32 v182, v182, v4
	v_add_u32_e32 v203, v2, v8
	v_add_u32_e32 v202, v2, v9
	v_add_u32_e32 v201, v2, v10
	v_add_u32_e32 v200, v2, v11
	v_mov_b32_e32 v1, v0
	v_mov_b32_e32 v2, v0
	v_mov_b32_e32 v3, v0
	v_mov_b32_e32 v4, v0
	v_mov_b32_e32 v5, v0
	v_mov_b32_e32 v6, v0
	v_mov_b32_e32 v7, v0
	v_mov_b32_e32 v8, v0
	v_mov_b32_e32 v9, v0
	v_mov_b32_e32 v10, v0
	v_mov_b32_e32 v11, v0
	v_mov_b32_e32 v12, v0
	v_mov_b32_e32 v13, v0
	v_mov_b32_e32 v14, v0
	v_mov_b32_e32 v15, v0
	v_mov_b32_e32 v16, v0
	v_mov_b32_e32 v17, v0
	v_mov_b32_e32 v18, v0
	v_mov_b32_e32 v19, v0
	v_mov_b32_e32 v20, v0
	v_mov_b32_e32 v21, v0
	v_mov_b32_e32 v22, v0
	v_mov_b32_e32 v23, v0
	v_mov_b32_e32 v24, v0
	v_mov_b32_e32 v25, v0
	v_mov_b32_e32 v26, v0
	v_mov_b32_e32 v27, v0
	v_mov_b32_e32 v28, v0
	v_mov_b32_e32 v29, v0
	v_mov_b32_e32 v30, v0
	v_mov_b32_e32 v31, v0
	v_mov_b32_e32 v32, v0
	v_mov_b32_e32 v33, v0
	v_mov_b32_e32 v34, v0
	v_mov_b32_e32 v35, v0
	v_mov_b32_e32 v36, v0
	v_mov_b32_e32 v37, v0
	v_mov_b32_e32 v38, v0
	v_mov_b32_e32 v39, v0
	v_mov_b32_e32 v40, v0
	v_mov_b32_e32 v41, v0
	v_mov_b32_e32 v42, v0
	v_mov_b32_e32 v43, v0
	v_mov_b32_e32 v44, v0
	v_mov_b32_e32 v45, v0
	v_mov_b32_e32 v46, v0
	v_mov_b32_e32 v47, v0
	v_mov_b32_e32 v48, v0
	v_mov_b32_e32 v49, v0
	v_mov_b32_e32 v50, v0
	v_mov_b32_e32 v51, v0
	v_mov_b32_e32 v52, v0
	v_mov_b32_e32 v53, v0
	v_mov_b32_e32 v54, v0
	v_mov_b32_e32 v55, v0
	v_mov_b32_e32 v56, v0
	v_mov_b32_e32 v57, v0
	v_mov_b32_e32 v58, v0
	v_mov_b32_e32 v59, v0
	v_mov_b32_e32 v60, v0
	v_mov_b32_e32 v61, v0
	v_mov_b32_e32 v62, v0
	v_mov_b32_e32 v63, v0
; #define MFMA(a, b, c) __builtin_amdgcn_mfma_f32_32x32x16_bf16((a), (b), (c), 0, 0, 0)
; DI f32x16 zero16() { f32x16 z; for (int i = 0; i < 16; ++i) z[i] = 0.f; return z; }
; DI void attn_unit(const Params& p, int l, int unit, unsigned char* smem) {
;     ...
;   for (int kt = 0; kt < ntile; ++kt) {
;     __syncthreads();
; #pragma unroll
;     for (int i = 0; i < 4; ++i) {
;       const int c = tid + 256 * i;
;       { const int key = c >> 4, kc = c & 15; *(u32x4*)(sK + key * 136 + 8 * kc) = rk[i]; }
;       { const int dv = c >> 3, kc = c & 7; *(u32x4*)(sVT + dv * 72 + 8 * kc) = rv[i]; }
;     }
;     __syncthreads();
;     if (kt + 1 < ntile) {
; #pragma unroll
;       for (int i = 0; i < 4; ++i) {
;         const int c = tid + 256 * i;
;         { const int key = c >> 4, kc = c & 15; rk[i] = *(const u32x4*)(Kbase + (size_t)((kt + 1) * 64 + key) * PLD + 8 * kc); }
;         { const int dv = c >> 3, kc = c & 7; rv[i] = *(const u32x4*)(VT + (size_t)dv * SP + (kt + 1) * 64 + 8 * kc); }
;       }
;     }
; #pragma unroll
;     for (int kb = 0; kb < 2; ++kb) {
;       f32x16 s0 = zero16(), s1 = zero16();
; #pragma unroll
;       for (int s = 0; s < 4; ++s) {
;         s0 = MFMA(ld16(sK + (32 * kb + l31) * 136 + 16 * s + 8 * h), qf[0][s], s0);
;         s1 = MFMA(ld16(sK + (32 * kb + l31) * 136 + 64 + 16 * s + 8 * h), qf[1][s], s1);
;       }
; #pragma unroll
;       for (int r = 0; r < 16; ++r) s0[r] = __builtin_amdgcn_exp2f(fmaf(s0[r], cs, nm[0])) * sc[0] - __builtin_amdgcn_exp2f(fmaf(s1[r], cs, nm[1])) * sc[1];
;       const bf16x8 p0 = pack8<0>(s0), p1 = pack8<1>(s0);
; #pragma unroll
;       for (int dvb = 0; dvb < 4; ++dvb) {
;         oacc[dvb] = MFMA(ld2x8(sVT + (32 * dvb + l31) * 72 + 32 * kb + 4 * h), p0, oacc[dvb]);
;         oacc[dvb] = MFMA(ld2x8(sVT + (32 * dvb + l31) * 72 + 32 * kb + 16 + 4 * h), p1, oacc[dvb]);
;       }
;     }
.LBB0_479:
	v_lshl_add_u64 v[64:65], s[4:5], 0, v[174:175]
	s_waitcnt lgkmcnt(0)
	s_barrier
	s_waitcnt vmcnt(0)
	ds_write_b128 v187, v[128:131]
	ds_write_b128 v203, v[132:135] offset:17408
	ds_write_b128 v186, v[136:139]
	ds_write_b128 v202, v[140:143] offset:17408
	ds_write_b128 v185, v[144:147]
	ds_write_b128 v201, v[148:151] offset:17408
	ds_write_b128 v184, v[152:155]
	ds_write_b128 v200, v[156:159] offset:17408
	s_waitcnt lgkmcnt(0)
	s_barrier
	global_load_dwordx4 v[128:131], v[64:65], off
	v_lshl_add_u64 v[64:65], s[4:5], 0, v[182:183]
	global_load_dwordx4 v[132:135], v[64:65], off
	v_lshl_add_u64 v[64:65], s[4:5], 0, v[172:173]
	global_load_dwordx4 v[136:139], v[64:65], off
	v_lshl_add_u64 v[64:65], s[4:5], 0, v[180:181]
	global_load_dwordx4 v[140:143], v[64:65], off
	v_lshl_add_u64 v[64:65], s[4:5], 0, v[170:171]
	global_load_dwordx4 v[144:147], v[64:65], off
	v_lshl_add_u64 v[64:65], s[4:5], 0, v[178:179]
	global_load_dwordx4 v[148:151], v[64:65], off
	v_lshl_add_u64 v[64:65], s[4:5], 0, v[168:169]
	global_load_dwordx4 v[152:155], v[64:65], off
	v_lshl_add_u64 v[64:65], s[4:5], 0, v[176:177]
	global_load_dwordx4 v[156:159], v[64:65], off
	ds_read_b128 v[236:239], v197
	ds_read_b128 v[246:249], v197 offset:32
	ds_read_b128 v[250:253], v197 offset:128
	s_waitcnt lgkmcnt(2)
	v_mfma_f32_32x32x16_bf16 v[64:79], v[236:239], v[120:123], 0
	v_add_u32_e32 v193, 0x4000, v198
	v_add_u32_e32 v196, 0x4000, v199
	v_add_u32_e32 v195, 0x6800, v198
	v_add_u32_e32 v194, 0x7800, v198
	s_add_i32 s6, s6, -1
	v_lshl_add_u64 v[168:169], v[168:169], 0, s[52:53]
	ds_read_b128 v[236:239], v197 offset:160
	s_waitcnt lgkmcnt(2)
	v_mfma_f32_32x32x16_bf16 v[64:79], v[246:249], v[116:119], v[64:79]
	v_lshl_add_u64 v[170:171], v[170:171], 0, s[52:53]
	v_lshl_add_u64 v[172:173], v[172:173], 0, s[52:53]
	v_lshl_add_u64 v[174:175], v[174:175], 0, s[52:53]
	v_lshl_add_u64 v[176:177], v[176:177], 0, s[80:81]
	v_lshl_add_u64 v[178:179], v[178:179], 0, s[80:81]
	v_lshl_add_u64 v[180:181], v[180:181], 0, s[80:81]
	ds_read_b128 v[246:249], v197 offset:64
	s_waitcnt lgkmcnt(2)
	v_mfma_f32_32x32x16_bf16 v[80:95], v[250:253], v[124:127], 0
	v_lshl_add_u64 v[182:183], v[182:183], 0, s[80:81]
	s_cmp_lg_u32 s6, 0
	ds_read_b128 v[250:253], v197 offset:192
	s_waitcnt lgkmcnt(2)
	v_mfma_f32_32x32x16_bf16 v[80:95], v[236:239], v[112:115], v[80:95]
	ds_read_b128 v[236:239], v197 offset:96
	s_waitcnt lgkmcnt(2)
	v_mfma_f32_32x32x16_bf16 v[64:79], v[246:249], v[104:107], v[64:79]
	ds_read_b128 v[246:249], v197 offset:224
	s_waitcnt lgkmcnt(2)
	v_mfma_f32_32x32x16_bf16 v[80:95], v[250:253], v[108:111], v[80:95]
	ds_read2_b64 v[250:253], v193 offset0:128 offset1:130
	s_waitcnt lgkmcnt(2)
	v_mfma_f32_32x32x16_bf16 v[64:79], v[236:239], v[100:103], v[64:79]
	ds_read2_b64 v[236:239], v193 offset0:132 offset1:134
	s_waitcnt lgkmcnt(2)
	v_mfma_f32_32x32x16_bf16 v[80:95], v[246:249], v[96:99], v[80:95]
	s_nop 8
	v_fmamk_f32 v64, v64, 0x3e38aa3b, v190
	v_fmamk_f32 v65, v65, 0x3e38aa3b, v190
	v_exp_f32_e32 v64, v64
	v_exp_f32_e32 v65, v65
	v_fmamk_f32 v66, v66, 0x3e38aa3b, v190
	v_fmamk_f32 v67, v67, 0x3e38aa3b, v190
	v_exp_f32_e32 v66, v66
	v_fmamk_f32 v80, v80, 0x3e38aa3b, v191
	v_fmamk_f32 v81, v81, 0x3e38aa3b, v191
	v_exp_f32_e32 v80, v80
	v_exp_f32_e32 v81, v81
	v_exp_f32_e32 v67, v67
	v_fmamk_f32 v68, v68, 0x3e38aa3b, v190
	v_fmamk_f32 v69, v69, 0x3e38aa3b, v190
	v_pk_mul_f32 v[80:81], v[166:167], v[80:81]
	v_exp_f32_e32 v68, v68
	v_pk_fma_f32 v[64:65], v[164:165], v[64:65], v[80:81] neg_lo:[0,0,1] neg_hi:[0,0,1]
	v_fmamk_f32 v80, v82, 0x3e38aa3b, v191
	v_fmamk_f32 v81, v83, 0x3e38aa3b, v191
	v_exp_f32_e32 v80, v80
	v_exp_f32_e32 v81, v81
	v_exp_f32_e32 v69, v69
	v_fmamk_f32 v70, v70, 0x3e38aa3b, v190
	v_fmamk_f32 v71, v71, 0x3e38aa3b, v190
	v_pk_mul_f32 v[80:81], v[166:167], v[80:81]
	v_exp_f32_e32 v70, v70
	v_pk_fma_f32 v[66:67], v[164:165], v[66:67], v[80:81] neg_lo:[0,0,1] neg_hi:[0,0,1]
	v_fmamk_f32 v80, v84, 0x3e38aa3b, v191
	v_fmamk_f32 v81, v85, 0x3e38aa3b, v191
	v_exp_f32_e32 v80, v80
	v_exp_f32_e32 v81, v81
	v_exp_f32_e32 v71, v71
	v_fmamk_f32 v72, v72, 0x3e38aa3b, v190
	v_fmamk_f32 v73, v73, 0x3e38aa3b, v190
	v_pk_mul_f32 v[80:81], v[166:167], v[80:81]
	v_exp_f32_e32 v72, v72
	v_pk_fma_f32 v[68:69], v[164:165], v[68:69], v[80:81] neg_lo:[0,0,1] neg_hi:[0,0,1]
	v_fmamk_f32 v80, v86, 0x3e38aa3b, v191
	v_fmamk_f32 v81, v87, 0x3e38aa3b, v191
	v_exp_f32_e32 v80, v80
	v_exp_f32_e32 v81, v81
	v_exp_f32_e32 v73, v73
	v_fmamk_f32 v74, v74, 0x3e38aa3b, v190
	v_fmamk_f32 v75, v75, 0x3e38aa3b, v190
	v_pk_mul_f32 v[80:81], v[166:167], v[80:81]
	v_exp_f32_e32 v74, v74
	v_pk_fma_f32 v[70:71], v[164:165], v[70:71], v[80:81] neg_lo:[0,0,1] neg_hi:[0,0,1]
	v_fmamk_f32 v80, v88, 0x3e38aa3b, v191
	v_fmamk_f32 v81, v89, 0x3e38aa3b, v191
	v_exp_f32_e32 v80, v80
	v_exp_f32_e32 v81, v81
	v_exp_f32_e32 v75, v75
	v_fmamk_f32 v76, v76, 0x3e38aa3b, v190
	v_fmamk_f32 v77, v77, 0x3e38aa3b, v190
	v_pk_mul_f32 v[80:81], v[166:167], v[80:81]
	v_exp_f32_e32 v76, v76
	v_pk_fma_f32 v[72:73], v[164:165], v[72:73], v[80:81] neg_lo:[0,0,1] neg_hi:[0,0,1]
	v_fmamk_f32 v80, v90, 0x3e38aa3b, v191
	v_fmamk_f32 v81, v91, 0x3e38aa3b, v191
	v_exp_f32_e32 v80, v80
	v_exp_f32_e32 v81, v81
	v_exp_f32_e32 v77, v77
	v_fmamk_f32 v78, v78, 0x3e38aa3b, v190
	v_fmamk_f32 v79, v79, 0x3e38aa3b, v190
	v_pk_mul_f32 v[80:81], v[166:167], v[80:81]
	v_exp_f32_e32 v78, v78
	v_pk_fma_f32 v[74:75], v[164:165], v[74:75], v[80:81] neg_lo:[0,0,1] neg_hi:[0,0,1]
	v_fmamk_f32 v80, v92, 0x3e38aa3b, v191
	v_fmamk_f32 v81, v93, 0x3e38aa3b, v191
	v_exp_f32_e32 v80, v80
	v_exp_f32_e32 v81, v81
	v_exp_f32_e32 v79, v79
	v_cvt_pk_bf16_f32 v64, v64, v65
	v_cvt_pk_bf16_f32 v65, v66, v67
	v_pk_mul_f32 v[80:81], v[166:167], v[80:81]
	v_cvt_pk_bf16_f32 v66, v68, v69
	v_pk_fma_f32 v[76:77], v[164:165], v[76:77], v[80:81] neg_lo:[0,0,1] neg_hi:[0,0,1]
	v_fmamk_f32 v80, v94, 0x3e38aa3b, v191
	v_fmamk_f32 v81, v95, 0x3e38aa3b, v191
	v_exp_f32_e32 v80, v80
	v_exp_f32_e32 v81, v81
	v_cvt_pk_bf16_f32 v67, v70, v71
	v_cvt_pk_bf16_f32 v68, v72, v73
	v_cvt_pk_bf16_f32 v69, v74, v75
	v_pk_mul_f32 v[80:81], v[166:167], v[80:81]
	v_cvt_pk_bf16_f32 v70, v76, v77
	v_pk_fma_f32 v[78:79], v[164:165], v[78:79], v[80:81] neg_lo:[0,0,1] neg_hi:[0,0,1]
	s_nop 0
	v_cvt_pk_bf16_f32 v71, v78, v79
	ds_read2_b64 v[246:249], v196 offset0:128 offset1:130
	s_waitcnt lgkmcnt(2)
; #define MFMA(a, b, c) __builtin_amdgcn_mfma_f32_32x32x16_bf16((a), (b), (c), 0, 0, 0)
; DI f32x16 zero16() { f32x16 z; for (int i = 0; i < 16; ++i) z[i] = 0.f; return z; }
; DI void attn_unit(const Params& p, int l, int unit, unsigned char* smem) {
;     ...
; #pragma unroll
;     for (int kb = 0; kb < 2; ++kb) {
;       f32x16 s0 = zero16(), s1 = zero16();
; #pragma unroll
;       for (int s = 0; s < 4; ++s) {
;         s0 = MFMA(ld16(sK + (32 * kb + l31) * 136 + 16 * s + 8 * h), qf[0][s], s0);
;         s1 = MFMA(ld16(sK + (32 * kb + l31) * 136 + 64 + 16 * s + 8 * h), qf[1][s], s1);
;       }
; #pragma unroll
;       for (int r = 0; r < 16; ++r) s0[r] = __builtin_amdgcn_exp2f(fmaf(s0[r], cs, nm[0])) * sc[0] - __builtin_amdgcn_exp2f(fmaf(s1[r], cs, nm[1])) * sc[1];
;       const bf16x8 p0 = pack8<0>(s0), p1 = pack8<1>(s0);
; #pragma unroll
;       for (int dvb = 0; dvb < 4; ++dvb) {
;         oacc[dvb] = MFMA(ld2x8(sVT + (32 * dvb + l31) * 72 + 32 * kb + 4 * h), p0, oacc[dvb]);
;         oacc[dvb] = MFMA(ld2x8(sVT + (32 * dvb + l31) * 72 + 32 * kb + 16 + 4 * h), p1, oacc[dvb]);
;       }
;     }
	v_mfma_f32_32x32x16_bf16 v[48:63], v[250:253], v[64:67], v[48:63]
	ds_read2_b64 v[250:253], v195 offset1:2
	s_waitcnt lgkmcnt(2)
	v_mfma_f32_32x32x16_bf16 v[48:63], v[236:239], v[68:71], v[48:63]
	ds_read2_b64 v[236:239], v195 offset0:4 offset1:6
	s_waitcnt lgkmcnt(2)
	v_mfma_f32_32x32x16_bf16 v[32:47], v[246:249], v[64:67], v[32:47]
	ds_read2_b64 v[246:249], v194 offset0:64 offset1:66
	s_waitcnt lgkmcnt(2)
	v_mfma_f32_32x32x16_bf16 v[16:31], v[250:253], v[64:67], v[16:31]
	ds_read2_b64 v[250:253], v194 offset0:68 offset1:70
	s_waitcnt lgkmcnt(2)
	v_mfma_f32_32x32x16_bf16 v[16:31], v[236:239], v[68:71], v[16:31]
	ds_read2_b64 v[236:239], v196 offset0:132 offset1:134
	s_waitcnt lgkmcnt(2)
	v_mfma_f32_32x32x16_bf16 v[0:15], v[246:249], v[64:67], v[0:15]
	ds_read_b128 v[246:249], v192
	s_waitcnt lgkmcnt(2)
	v_mfma_f32_32x32x16_bf16 v[0:15], v[250:253], v[68:71], v[0:15]
	ds_read_b128 v[250:253], v192 offset:32
	s_waitcnt lgkmcnt(2)
	v_mfma_f32_32x32x16_bf16 v[32:47], v[236:239], v[68:71], v[32:47]
	ds_read_b128 v[236:239], v192 offset:128
	s_waitcnt lgkmcnt(2)
	v_mfma_f32_32x32x16_bf16 v[64:79], v[246:249], v[120:123], 0
	ds_read_b128 v[246:249], v192 offset:160
	s_waitcnt lgkmcnt(2)
	v_mfma_f32_32x32x16_bf16 v[64:79], v[250:253], v[116:119], v[64:79]
	ds_read_b128 v[250:253], v192 offset:64
	s_waitcnt lgkmcnt(2)
	v_mfma_f32_32x32x16_bf16 v[80:95], v[236:239], v[124:127], 0
	ds_read_b128 v[236:239], v192 offset:192
	s_waitcnt lgkmcnt(2)
	v_mfma_f32_32x32x16_bf16 v[80:95], v[246:249], v[112:115], v[80:95]
	ds_read_b128 v[246:249], v192 offset:96
	s_waitcnt lgkmcnt(2)
	v_mfma_f32_32x32x16_bf16 v[64:79], v[250:253], v[104:107], v[64:79]
	ds_read_b128 v[250:253], v192 offset:224
	s_waitcnt lgkmcnt(2)
	v_mfma_f32_32x32x16_bf16 v[80:95], v[236:239], v[108:111], v[80:95]
	ds_read2_b64 v[236:239], v193 offset0:136 offset1:138
	s_waitcnt lgkmcnt(2)
	v_mfma_f32_32x32x16_bf16 v[64:79], v[246:249], v[100:103], v[64:79]
	ds_read2_b64 v[246:249], v193 offset0:140 offset1:142
	s_waitcnt lgkmcnt(2)
	v_mfma_f32_32x32x16_bf16 v[80:95], v[250:253], v[96:99], v[80:95]
	s_nop 8
	v_fmamk_f32 v64, v64, 0x3e38aa3b, v190
	v_fmamk_f32 v65, v65, 0x3e38aa3b, v190
	v_exp_f32_e32 v64, v64
	v_exp_f32_e32 v65, v65
	v_fmamk_f32 v66, v66, 0x3e38aa3b, v190
	v_fmamk_f32 v67, v67, 0x3e38aa3b, v190
	v_exp_f32_e32 v66, v66
	v_fmamk_f32 v80, v80, 0x3e38aa3b, v191
	v_fmamk_f32 v81, v81, 0x3e38aa3b, v191
	v_exp_f32_e32 v80, v80
	v_exp_f32_e32 v81, v81
	v_exp_f32_e32 v67, v67
	v_fmamk_f32 v68, v68, 0x3e38aa3b, v190
	v_fmamk_f32 v69, v69, 0x3e38aa3b, v190
	v_pk_mul_f32 v[80:81], v[166:167], v[80:81]
	v_exp_f32_e32 v68, v68
	v_pk_fma_f32 v[64:65], v[164:165], v[64:65], v[80:81] neg_lo:[0,0,1] neg_hi:[0,0,1]
	v_fmamk_f32 v80, v82, 0x3e38aa3b, v191
	v_fmamk_f32 v81, v83, 0x3e38aa3b, v191
	v_exp_f32_e32 v80, v80
	v_exp_f32_e32 v81, v81
	v_exp_f32_e32 v69, v69
	v_fmamk_f32 v70, v70, 0x3e38aa3b, v190
	v_fmamk_f32 v71, v71, 0x3e38aa3b, v190
	v_pk_mul_f32 v[80:81], v[166:167], v[80:81]
	v_exp_f32_e32 v70, v70
	v_pk_fma_f32 v[66:67], v[164:165], v[66:67], v[80:81] neg_lo:[0,0,1] neg_hi:[0,0,1]
	v_fmamk_f32 v80, v84, 0x3e38aa3b, v191
	v_fmamk_f32 v81, v85, 0x3e38aa3b, v191
	v_exp_f32_e32 v80, v80
	v_exp_f32_e32 v81, v81
	v_exp_f32_e32 v71, v71
	v_fmamk_f32 v72, v72, 0x3e38aa3b, v190
	v_fmamk_f32 v73, v73, 0x3e38aa3b, v190
	v_pk_mul_f32 v[80:81], v[166:167], v[80:81]
	v_exp_f32_e32 v72, v72
	v_pk_fma_f32 v[68:69], v[164:165], v[68:69], v[80:81] neg_lo:[0,0,1] neg_hi:[0,0,1]
	v_fmamk_f32 v80, v86, 0x3e38aa3b, v191
	v_fmamk_f32 v81, v87, 0x3e38aa3b, v191
	v_exp_f32_e32 v80, v80
	v_exp_f32_e32 v81, v81
	v_exp_f32_e32 v73, v73
	v_fmamk_f32 v74, v74, 0x3e38aa3b, v190
	v_fmamk_f32 v75, v75, 0x3e38aa3b, v190
	v_pk_mul_f32 v[80:81], v[166:167], v[80:81]
	v_exp_f32_e32 v74, v74
	v_pk_fma_f32 v[70:71], v[164:165], v[70:71], v[80:81] neg_lo:[0,0,1] neg_hi:[0,0,1]
	v_fmamk_f32 v80, v88, 0x3e38aa3b, v191
	v_fmamk_f32 v81, v89, 0x3e38aa3b, v191
	v_exp_f32_e32 v80, v80
	v_exp_f32_e32 v81, v81
	v_exp_f32_e32 v75, v75
	v_cvt_pk_bf16_f32 v64, v64, v65
	v_cvt_pk_bf16_f32 v65, v66, v67
	v_pk_mul_f32 v[80:81], v[166:167], v[80:81]
	v_cvt_pk_bf16_f32 v66, v68, v69
	v_pk_fma_f32 v[72:73], v[164:165], v[72:73], v[80:81] neg_lo:[0,0,1] neg_hi:[0,0,1]
	v_fmamk_f32 v80, v90, 0x3e38aa3b, v191
	v_fmamk_f32 v81, v91, 0x3e38aa3b, v191
	v_exp_f32_e32 v80, v80
	v_exp_f32_e32 v81, v81
	v_cvt_pk_bf16_f32 v68, v72, v73
	v_fmamk_f32 v76, v76, 0x3e38aa3b, v190
	v_fmamk_f32 v77, v77, 0x3e38aa3b, v190
	v_pk_mul_f32 v[80:81], v[166:167], v[80:81]
	v_exp_f32_e32 v76, v76
	v_pk_fma_f32 v[74:75], v[164:165], v[74:75], v[80:81] neg_lo:[0,0,1] neg_hi:[0,0,1]
	v_fmamk_f32 v80, v92, 0x3e38aa3b, v191
	v_cvt_pk_bf16_f32 v69, v74, v75
	v_fmamk_f32 v81, v93, 0x3e38aa3b, v191
	v_exp_f32_e32 v80, v80
	v_exp_f32_e32 v81, v81
	v_exp_f32_e32 v77, v77
	v_cvt_pk_bf16_f32 v67, v70, v71
	v_fmamk_f32 v78, v78, 0x3e38aa3b, v190
	v_pk_mul_f32 v[80:81], v[166:167], v[80:81]
	ds_read2_b64 v[250:253], v196 offset0:136 offset1:138
	s_waitcnt lgkmcnt(2)
	v_mfma_f32_32x32x16_bf16 v[48:63], v[236:239], v[64:67], v[48:63]
	v_fma_f32 v76, v164, v76, -v80
	v_fma_f32 v77, v165, v77, -v81
	v_fmamk_f32 v80, v94, 0x3e38aa3b, v191
	v_fmamk_f32 v81, v95, 0x3e38aa3b, v191
	v_exp_f32_e32 v80, v80
	v_fmamk_f32 v79, v79, 0x3e38aa3b, v190
	v_exp_f32_e32 v81, v81
	v_exp_f32_e32 v78, v78
	v_exp_f32_e32 v79, v79
	v_cvt_pk_bf16_f32 v70, v76, v77
	v_pk_mul_f32 v[80:81], v[166:167], v[80:81]
	s_nop 0
	v_pk_fma_f32 v[78:79], v[164:165], v[78:79], v[80:81] neg_lo:[0,0,1] neg_hi:[0,0,1]
	s_nop 0
	v_cvt_pk_bf16_f32 v71, v78, v79
	s_nop 0
	ds_read2_b64 v[236:239], v195 offset0:8 offset1:10
	s_waitcnt lgkmcnt(2)
	v_mfma_f32_32x32x16_bf16 v[48:63], v[246:249], v[68:71], v[48:63]
	ds_read2_b64 v[246:249], v195 offset0:12 offset1:14
	s_waitcnt lgkmcnt(2)
	v_mfma_f32_32x32x16_bf16 v[32:47], v[250:253], v[64:67], v[32:47]
	ds_read2_b64 v[250:253], v194 offset0:72 offset1:74
	s_waitcnt lgkmcnt(2)
	v_mfma_f32_32x32x16_bf16 v[16:31], v[236:239], v[64:67], v[16:31]
	ds_read2_b64 v[236:239], v196 offset0:140 offset1:142
	s_waitcnt lgkmcnt(2)
	v_mfma_f32_32x32x16_bf16 v[16:31], v[246:249], v[68:71], v[16:31]
	ds_read2_b64 v[246:249], v194 offset0:76 offset1:78
	s_waitcnt lgkmcnt(2)
	v_mfma_f32_32x32x16_bf16 v[0:15], v[250:253], v[64:67], v[0:15]
	s_waitcnt lgkmcnt(1)
	v_mfma_f32_32x32x16_bf16 v[32:47], v[236:239], v[68:71], v[32:47]
	s_waitcnt lgkmcnt(0)
	v_mfma_f32_32x32x16_bf16 v[0:15], v[246:249], v[68:71], v[0:15]
	s_cbranch_scc1 .LBB0_479
; #define MFMA(a, b, c) __builtin_amdgcn_mfma_f32_32x32x16_bf16((a), (b), (c), 0, 0, 0)
; DI f32x16 zero16() { f32x16 z; for (int i = 0; i < 16; ++i) z[i] = 0.f; return z; }
; DI void attn_unit(const Params& p, int l, int unit, unsigned char* smem) {
;     ...
;     for (int kb = 0; kb < 2; ++kb) {
;       f32x16 s0 = zero16(), s1 = zero16();
; #pragma unroll
;       for (int s = 0; s < 4; ++s) {
;         s0 = MFMA(ld16(sK + (32 * kb + l31) * 136 + 16 * s + 8 * h), qf[0][s], s0);
;         s1 = MFMA(ld16(sK + (32 * kb + l31) * 136 + 64 + 16 * s + 8 * h), qf[1][s], s1);
;       }
; #pragma unroll
;       for (int r = 0; r < 16; ++r) s0[r] = __builtin_amdgcn_exp2f(fmaf(s0[r], cs, nm[0])) * sc[0] - __builtin_amdgcn_exp2f(fmaf(s1[r], cs, nm[1])) * sc[1];
;       const bf16x8 p0 = pack8<0>(s0), p1 = pack8<1>(s0);
; #pragma unroll
;       for (int dvb = 0; dvb < 4; ++dvb) {
;         oacc[dvb] = MFMA(ld2x8(sVT + (32 * dvb + l31) * 72 + 32 * kb + 4 * h), p0, oacc[dvb]);
;         oacc[dvb] = MFMA(ld2x8(sVT + (32 * dvb + l31) * 72 + 32 * kb + 16 + 4 * h), p1, oacc[dvb]);
;       }
;     }
	s_barrier
	s_waitcnt vmcnt(0)
	ds_write_b128 v187, v[128:131]
	ds_write_b128 v203, v[132:135] offset:17408
	ds_write_b128 v186, v[136:139]
	ds_write_b128 v202, v[140:143] offset:17408
	ds_write_b128 v185, v[144:147]
	ds_write_b128 v201, v[148:151] offset:17408
	ds_write_b128 v184, v[152:155]
	ds_write_b128 v200, v[156:159] offset:17408
	s_waitcnt lgkmcnt(0)
	s_barrier
	ds_read_b128 v[64:67], v197
	ds_read_b128 v[128:131], v197 offset:32
	s_waitcnt lgkmcnt(1)
	v_mfma_f32_32x32x16_bf16 v[64:79], v[64:67], v[120:123], 0
	ds_read_b128 v[80:83], v197 offset:128
	s_lshl_b32 s44, s8, 1
	v_lshlrev_b32_e32 v208, 1, v188
	s_mov_b32 s40, 0x800000
	s_waitcnt lgkmcnt(1)
	v_mfma_f32_32x32x16_bf16 v[64:79], v[128:131], v[116:119], v[64:79]
	ds_read_b128 v[128:131], v197 offset:160
	s_waitcnt lgkmcnt(1)
	v_mfma_f32_32x32x16_bf16 v[80:95], v[80:83], v[124:127], 0
	s_waitcnt lgkmcnt(0)
	v_mfma_f32_32x32x16_bf16 v[80:95], v[128:131], v[112:115], v[80:95]
	ds_read_b128 v[128:131], v197 offset:64
	s_waitcnt lgkmcnt(0)
	v_mfma_f32_32x32x16_bf16 v[64:79], v[128:131], v[104:107], v[64:79]
	ds_read_b128 v[128:131], v197 offset:192
	s_waitcnt lgkmcnt(0)
	v_mfma_f32_32x32x16_bf16 v[80:95], v[128:131], v[108:111], v[80:95]
	ds_read_b128 v[128:131], v197 offset:96
	s_waitcnt lgkmcnt(0)
	v_mfma_f32_32x32x16_bf16 v[64:79], v[128:131], v[100:103], v[64:79]
	ds_read_b128 v[128:131], v197 offset:224
	s_waitcnt lgkmcnt(0)
	v_mfma_f32_32x32x16_bf16 v[80:95], v[128:131], v[96:99], v[80:95]
	s_nop 8
	v_fmamk_f32 v64, v64, 0x3e38aa3b, v190
	v_fmamk_f32 v65, v65, 0x3e38aa3b, v190
	v_exp_f32_e32 v64, v64
	v_exp_f32_e32 v65, v65
	v_fmamk_f32 v66, v66, 0x3e38aa3b, v190
	v_fmamk_f32 v67, v67, 0x3e38aa3b, v190
	v_exp_f32_e32 v66, v66
	v_fmamk_f32 v80, v80, 0x3e38aa3b, v191
	v_fmamk_f32 v81, v81, 0x3e38aa3b, v191
	v_exp_f32_e32 v80, v80
	v_exp_f32_e32 v81, v81
	v_exp_f32_e32 v67, v67
	v_fmamk_f32 v68, v68, 0x3e38aa3b, v190
	v_fmamk_f32 v69, v69, 0x3e38aa3b, v190
	v_pk_mul_f32 v[80:81], v[166:167], v[80:81]
	v_exp_f32_e32 v68, v68
	v_pk_fma_f32 v[64:65], v[164:165], v[64:65], v[80:81] neg_lo:[0,0,1] neg_hi:[0,0,1]
	v_fmamk_f32 v80, v82, 0x3e38aa3b, v191
	v_fmamk_f32 v81, v83, 0x3e38aa3b, v191
	v_exp_f32_e32 v80, v80
	v_exp_f32_e32 v81, v81
	v_exp_f32_e32 v69, v69
	v_fmamk_f32 v70, v70, 0x3e38aa3b, v190
	v_fmamk_f32 v71, v71, 0x3e38aa3b, v190
	v_pk_mul_f32 v[80:81], v[166:167], v[80:81]
	v_exp_f32_e32 v70, v70
	v_pk_fma_f32 v[66:67], v[164:165], v[66:67], v[80:81] neg_lo:[0,0,1] neg_hi:[0,0,1]
	v_fmamk_f32 v80, v84, 0x3e38aa3b, v191
	v_fmamk_f32 v81, v85, 0x3e38aa3b, v191
	v_exp_f32_e32 v80, v80
	v_exp_f32_e32 v81, v81
	v_exp_f32_e32 v71, v71
	v_fmamk_f32 v72, v72, 0x3e38aa3b, v190
	v_fmamk_f32 v73, v73, 0x3e38aa3b, v190
	v_pk_mul_f32 v[80:81], v[166:167], v[80:81]
	v_exp_f32_e32 v72, v72
	v_pk_fma_f32 v[68:69], v[164:165], v[68:69], v[80:81] neg_lo:[0,0,1] neg_hi:[0,0,1]
	v_fmamk_f32 v80, v86, 0x3e38aa3b, v191
	v_fmamk_f32 v81, v87, 0x3e38aa3b, v191
	v_exp_f32_e32 v80, v80
	v_exp_f32_e32 v81, v81
	v_exp_f32_e32 v73, v73
	v_fmamk_f32 v74, v74, 0x3e38aa3b, v190
	v_fmamk_f32 v75, v75, 0x3e38aa3b, v190
	v_pk_mul_f32 v[80:81], v[166:167], v[80:81]
	v_exp_f32_e32 v74, v74
	v_pk_fma_f32 v[70:71], v[164:165], v[70:71], v[80:81] neg_lo:[0,0,1] neg_hi:[0,0,1]
	v_fmamk_f32 v80, v88, 0x3e38aa3b, v191
	v_fmamk_f32 v81, v89, 0x3e38aa3b, v191
	v_exp_f32_e32 v80, v80
	v_exp_f32_e32 v81, v81
	v_exp_f32_e32 v75, v75
	v_fmamk_f32 v76, v76, 0x3e38aa3b, v190
	v_fmamk_f32 v77, v77, 0x3e38aa3b, v190
	v_pk_mul_f32 v[80:81], v[166:167], v[80:81]
	v_exp_f32_e32 v76, v76
	v_pk_fma_f32 v[72:73], v[164:165], v[72:73], v[80:81] neg_lo:[0,0,1] neg_hi:[0,0,1]
	v_fmamk_f32 v80, v90, 0x3e38aa3b, v191
	v_fmamk_f32 v81, v91, 0x3e38aa3b, v191
	v_exp_f32_e32 v80, v80
	v_exp_f32_e32 v81, v81
	v_exp_f32_e32 v77, v77
	v_fmamk_f32 v78, v78, 0x3e38aa3b, v190
	v_fmamk_f32 v79, v79, 0x3e38aa3b, v190
	v_pk_mul_f32 v[80:81], v[166:167], v[80:81]
	v_exp_f32_e32 v78, v78
	v_pk_fma_f32 v[74:75], v[164:165], v[74:75], v[80:81] neg_lo:[0,0,1] neg_hi:[0,0,1]
	v_fmamk_f32 v80, v92, 0x3e38aa3b, v191
	v_fmamk_f32 v81, v93, 0x3e38aa3b, v191
	v_exp_f32_e32 v80, v80
	v_exp_f32_e32 v81, v81
	v_exp_f32_e32 v79, v79
	v_cvt_pk_bf16_f32 v64, v64, v65
	v_cvt_pk_bf16_f32 v65, v66, v67
	v_pk_mul_f32 v[80:81], v[166:167], v[80:81]
	v_cvt_pk_bf16_f32 v66, v68, v69
	v_pk_fma_f32 v[76:77], v[164:165], v[76:77], v[80:81] neg_lo:[0,0,1] neg_hi:[0,0,1]
	v_fmamk_f32 v80, v94, 0x3e38aa3b, v191
	v_fmamk_f32 v81, v95, 0x3e38aa3b, v191
	v_exp_f32_e32 v80, v80
	v_exp_f32_e32 v81, v81
	v_cvt_pk_bf16_f32 v67, v70, v71
	v_cvt_pk_bf16_f32 v68, v72, v73
	v_cvt_pk_bf16_f32 v69, v74, v75
	v_pk_mul_f32 v[80:81], v[166:167], v[80:81]
	v_cvt_pk_bf16_f32 v70, v76, v77
	v_pk_fma_f32 v[78:79], v[164:165], v[78:79], v[80:81] neg_lo:[0,0,1] neg_hi:[0,0,1]
	s_nop 0
	v_cvt_pk_bf16_f32 v71, v78, v79
	ds_read2_b64 v[72:75], v193 offset0:128 offset1:130
	ds_read2_b64 v[76:79], v193 offset0:132 offset1:134
	s_waitcnt lgkmcnt(1)
	v_mfma_f32_32x32x16_bf16 v[48:63], v[72:75], v[64:67], v[48:63]
	s_waitcnt lgkmcnt(0)
	v_mfma_f32_32x32x16_bf16 v[48:63], v[76:79], v[68:71], v[48:63]
	ds_read2_b64 v[72:75], v196 offset0:128 offset1:130
	ds_read2_b64 v[76:79], v196 offset0:132 offset1:134
	s_waitcnt lgkmcnt(1)
	v_mfma_f32_32x32x16_bf16 v[32:47], v[72:75], v[64:67], v[32:47]
	ds_read2_b64 v[72:75], v195 offset1:2
	s_waitcnt lgkmcnt(0)
	v_mfma_f32_32x32x16_bf16 v[16:31], v[72:75], v[64:67], v[16:31]
	ds_read2_b64 v[72:75], v195 offset0:4 offset1:6
	s_waitcnt lgkmcnt(0)
	v_mfma_f32_32x32x16_bf16 v[16:31], v[72:75], v[68:71], v[16:31]
	ds_read2_b64 v[72:75], v194 offset0:64 offset1:66
	s_waitcnt lgkmcnt(0)
; #define MFMA(a, b, c) __builtin_amdgcn_mfma_f32_32x32x16_bf16((a), (b), (c), 0, 0, 0)
; DI f32x16 zero16() { f32x16 z; for (int i = 0; i < 16; ++i) z[i] = 0.f; return z; }
; DI void attn_unit(const Params& p, int l, int unit, unsigned char* smem) {
;     ...
;     for (int kb = 0; kb < 2; ++kb) {
;       f32x16 s0 = zero16(), s1 = zero16();
; #pragma unroll
;       for (int s = 0; s < 4; ++s) {
;         s0 = MFMA(ld16(sK + (32 * kb + l31) * 136 + 16 * s + 8 * h), qf[0][s], s0);
;         s1 = MFMA(ld16(sK + (32 * kb + l31) * 136 + 64 + 16 * s + 8 * h), qf[1][s], s1);
;       }
; #pragma unroll
;       for (int r = 0; r < 16; ++r) s0[r] = __builtin_amdgcn_exp2f(fmaf(s0[r], cs, nm[0])) * sc[0] - __builtin_amdgcn_exp2f(fmaf(s1[r], cs, nm[1])) * sc[1];
;       const bf16x8 p0 = pack8<0>(s0), p1 = pack8<1>(s0);
; #pragma unroll
;       for (int dvb = 0; dvb < 4; ++dvb) {
;         oacc[dvb] = MFMA(ld2x8(sVT + (32 * dvb + l31) * 72 + 32 * kb + 4 * h), p0, oacc[dvb]);
;         oacc[dvb] = MFMA(ld2x8(sVT + (32 * dvb + l31) * 72 + 32 * kb + 16 + 4 * h), p1, oacc[dvb]);
;       }
;     }
	v_mfma_f32_32x32x16_bf16 v[0:15], v[72:75], v[64:67], v[0:15]
	ds_read2_b64 v[64:67], v194 offset0:68 offset1:70
	s_waitcnt lgkmcnt(0)
	v_mfma_f32_32x32x16_bf16 v[0:15], v[64:67], v[68:71], v[0:15]
	ds_read_b128 v[64:67], v192
	ds_read_b128 v[128:131], v192 offset:32
	ds_read_b128 v[80:83], v192 offset:128
	v_mfma_f32_32x32x16_bf16 v[32:47], v[76:79], v[68:71], v[32:47]
	s_waitcnt lgkmcnt(2)
	v_mfma_f32_32x32x16_bf16 v[64:79], v[64:67], v[120:123], 0
	s_waitcnt lgkmcnt(1)
	v_mfma_f32_32x32x16_bf16 v[64:79], v[128:131], v[116:119], v[64:79]
	ds_read_b128 v[116:119], v192 offset:160
	s_waitcnt lgkmcnt(1)
	v_mfma_f32_32x32x16_bf16 v[80:95], v[80:83], v[124:127], 0
	s_waitcnt lgkmcnt(0)
	v_mfma_f32_32x32x16_bf16 v[80:95], v[116:119], v[112:115], v[80:95]
	ds_read_b128 v[112:115], v192 offset:64
	s_waitcnt lgkmcnt(0)
	v_mfma_f32_32x32x16_bf16 v[64:79], v[112:115], v[104:107], v[64:79]
	ds_read_b128 v[104:107], v192 offset:192
	s_waitcnt lgkmcnt(0)
	v_mfma_f32_32x32x16_bf16 v[80:95], v[104:107], v[108:111], v[80:95]
	ds_read_b128 v[104:107], v192 offset:96
	s_waitcnt lgkmcnt(0)
	v_mfma_f32_32x32x16_bf16 v[64:79], v[104:107], v[100:103], v[64:79]
	ds_read_b128 v[100:103], v192 offset:224
	s_waitcnt lgkmcnt(0)
	v_mfma_f32_32x32x16_bf16 v[80:95], v[100:103], v[96:99], v[80:95]
	s_nop 8
	v_fmamk_f32 v64, v64, 0x3e38aa3b, v190
	v_fmamk_f32 v65, v65, 0x3e38aa3b, v190
	v_exp_f32_e32 v64, v64
	v_exp_f32_e32 v65, v65
	v_fmamk_f32 v66, v66, 0x3e38aa3b, v190
	v_fmamk_f32 v67, v67, 0x3e38aa3b, v190
	v_exp_f32_e32 v66, v66
	v_fmamk_f32 v80, v80, 0x3e38aa3b, v191
	v_fmamk_f32 v81, v81, 0x3e38aa3b, v191
	v_exp_f32_e32 v80, v80
	v_exp_f32_e32 v81, v81
	v_exp_f32_e32 v67, v67
	v_fmamk_f32 v68, v68, 0x3e38aa3b, v190
	v_fmamk_f32 v69, v69, 0x3e38aa3b, v190
	v_pk_mul_f32 v[80:81], v[166:167], v[80:81]
	v_exp_f32_e32 v68, v68
	v_pk_fma_f32 v[64:65], v[164:165], v[64:65], v[80:81] neg_lo:[0,0,1] neg_hi:[0,0,1]
	v_fmamk_f32 v80, v82, 0x3e38aa3b, v191
	v_fmamk_f32 v81, v83, 0x3e38aa3b, v191
	v_exp_f32_e32 v80, v80
	v_exp_f32_e32 v81, v81
	v_exp_f32_e32 v69, v69
	v_fmamk_f32 v70, v70, 0x3e38aa3b, v190
	v_fmamk_f32 v71, v71, 0x3e38aa3b, v190
	v_pk_mul_f32 v[80:81], v[166:167], v[80:81]
	v_exp_f32_e32 v70, v70
	v_pk_fma_f32 v[66:67], v[164:165], v[66:67], v[80:81] neg_lo:[0,0,1] neg_hi:[0,0,1]
	v_fmamk_f32 v80, v84, 0x3e38aa3b, v191
	v_fmamk_f32 v81, v85, 0x3e38aa3b, v191
	v_exp_f32_e32 v80, v80
	v_exp_f32_e32 v81, v81
	v_exp_f32_e32 v71, v71
	v_fmamk_f32 v72, v72, 0x3e38aa3b, v190
	v_fmamk_f32 v73, v73, 0x3e38aa3b, v190
	v_pk_mul_f32 v[80:81], v[166:167], v[80:81]
	v_exp_f32_e32 v72, v72
	v_pk_fma_f32 v[68:69], v[164:165], v[68:69], v[80:81] neg_lo:[0,0,1] neg_hi:[0,0,1]
	v_fmamk_f32 v80, v86, 0x3e38aa3b, v191
	v_fmamk_f32 v81, v87, 0x3e38aa3b, v191
	v_exp_f32_e32 v80, v80
	v_exp_f32_e32 v81, v81
	v_exp_f32_e32 v73, v73
	v_fmamk_f32 v74, v74, 0x3e38aa3b, v190
	v_fmamk_f32 v75, v75, 0x3e38aa3b, v190
	v_pk_mul_f32 v[80:81], v[166:167], v[80:81]
	v_exp_f32_e32 v74, v74
	v_pk_fma_f32 v[70:71], v[164:165], v[70:71], v[80:81] neg_lo:[0,0,1] neg_hi:[0,0,1]
	v_fmamk_f32 v80, v88, 0x3e38aa3b, v191
	v_fmamk_f32 v81, v89, 0x3e38aa3b, v191
	v_exp_f32_e32 v80, v80
	v_exp_f32_e32 v81, v81
	v_exp_f32_e32 v75, v75
	v_cvt_pk_bf16_f32 v64, v64, v65
	v_cvt_pk_bf16_f32 v65, v66, v67
	v_pk_mul_f32 v[80:81], v[166:167], v[80:81]
	v_cvt_pk_bf16_f32 v66, v68, v69
	v_pk_fma_f32 v[72:73], v[164:165], v[72:73], v[80:81] neg_lo:[0,0,1] neg_hi:[0,0,1]
	v_fmamk_f32 v80, v90, 0x3e38aa3b, v191
	v_fmamk_f32 v81, v91, 0x3e38aa3b, v191
	v_exp_f32_e32 v80, v80
	v_exp_f32_e32 v81, v81
	v_cvt_pk_bf16_f32 v68, v72, v73
	v_fmamk_f32 v76, v76, 0x3e38aa3b, v190
	v_fmamk_f32 v77, v77, 0x3e38aa3b, v190
	v_pk_mul_f32 v[80:81], v[166:167], v[80:81]
	v_exp_f32_e32 v76, v76
	v_pk_fma_f32 v[74:75], v[164:165], v[74:75], v[80:81] neg_lo:[0,0,1] neg_hi:[0,0,1]
	v_fmamk_f32 v80, v92, 0x3e38aa3b, v191
	v_cvt_pk_bf16_f32 v69, v74, v75
	ds_read2_b64 v[72:75], v193 offset0:136 offset1:138
	v_fmamk_f32 v81, v93, 0x3e38aa3b, v191
	v_exp_f32_e32 v80, v80
	v_exp_f32_e32 v81, v81
	v_exp_f32_e32 v77, v77
	v_cvt_pk_bf16_f32 v67, v70, v71
	v_fmamk_f32 v78, v78, 0x3e38aa3b, v190
	v_pk_mul_f32 v[80:81], v[166:167], v[80:81]
	s_waitcnt lgkmcnt(0)
	v_mfma_f32_32x32x16_bf16 v[48:63], v[72:75], v[64:67], v[48:63]
	ds_read2_b64 v[72:75], v193 offset0:140 offset1:142
	v_fma_f32 v76, v164, v76, -v80
	v_fma_f32 v77, v165, v77, -v81
	v_fmamk_f32 v80, v94, 0x3e38aa3b, v191
	v_fmac_f32_e32 v191, 0x3e38aa3b, v95
	v_exp_f32_e32 v80, v80
	v_fmac_f32_e32 v190, 0x3e38aa3b, v79
	v_exp_f32_e32 v81, v191
	v_exp_f32_e32 v78, v78
	v_exp_f32_e32 v79, v190
	v_cvt_pk_bf16_f32 v70, v76, v77
	v_pk_mul_f32 v[80:81], v[166:167], v[80:81]
	s_nop 0
	v_pk_fma_f32 v[78:79], v[164:165], v[78:79], v[80:81] neg_lo:[0,0,1] neg_hi:[0,0,1]
	s_nop 0
	v_cvt_pk_bf16_f32 v71, v78, v79
	s_waitcnt lgkmcnt(0)
	s_nop 0
	v_mfma_f32_32x32x16_bf16 v[48:63], v[72:75], v[68:71], v[48:63]
	ds_read2_b64 v[72:75], v196 offset0:136 offset1:138
	ds_read2_b64 v[76:79], v196 offset0:140 offset1:142
	s_waitcnt lgkmcnt(1)
	v_mfma_f32_32x32x16_bf16 v[32:47], v[72:75], v[64:67], v[32:47]
	ds_read2_b64 v[72:75], v195 offset0:8 offset1:10
	s_waitcnt lgkmcnt(0)
	v_mfma_f32_32x32x16_bf16 v[16:31], v[72:75], v[64:67], v[16:31]
	ds_read2_b64 v[72:75], v195 offset0:12 offset1:14
	s_waitcnt lgkmcnt(0)
	v_mfma_f32_32x32x16_bf16 v[16:31], v[72:75], v[68:71], v[16:31]
	ds_read2_b64 v[72:75], v194 offset0:72 offset1:74
	s_waitcnt lgkmcnt(0)
; DI float bf2f(bfr v) { return __uint_as_float(((unsigned)v) << 16); }
; DI unsigned pk2(float a, float b) { f2_t v = {a, b}; bf2_t r = __builtin_convertvector(v, bf2_t); return __builtin_bit_cast(unsigned, r); }
; DI float siluf_(float x) { return x / (1.f + __expf(-x)); }
; DI void attn_unit(const Params& p, int l, int unit, unsigned char* smem) {
;     ...
;   float ss = 0.f;
; #pragma unroll
;   for (int dvb = 0; dvb < 4; ++dvb)
; #pragma unroll
;     for (int r = 0; r < 16; ++r) ss += oacc[dvb][r] * oacc[dvb][r];
;   ss += __shfl_xor(ss, 32);
;   const float rs = rsqrtf(ss * (1.f / 128.f) + EPS) * (1.f - lam_init);
;   bfr* YS = (bfr*)(WS_ + O_YS);
; #pragma unroll
;   for (int dvb = 0; dvb < 4; ++dvb)
; #pragma unroll
;     for (int g = 0; g < 4; ++g) {
;       const int dv = 32 * dvb + 8 * g + 4 * h;
;       const s16x4 z4 = *(const s16x4*)(P + rowq * PLD + C_DAZ + hd * 128 + dv);
;       const f32x4 gn = *(const f32x4*)(p.da_norm + l * 128 + dv);
;       float y[4];
;       for (int q = 0; q < 4; ++q) y[q] = oacc[dvb][4 * g + q] * rs * gn[q] * siluf_(bf2f((bfr)z4[q]));
;       u32x2 w; w[0] = pk2(y[0], y[1]); w[1] = pk2(y[2], y[3]);
;       *(u32x2*)(YS + rowq * DM + 1536 + hd * 128 + dv) = w;
	v_mfma_f32_32x32x16_bf16 v[0:15], v[72:75], v[64:67], v[0:15]
	v_mul_f32_e32 v74, v49, v49
	v_fmac_f32_e32 v74, v48, v48
	v_fmac_f32_e32 v74, v50, v50
	v_fmac_f32_e32 v74, v51, v51
	v_fmac_f32_e32 v74, v52, v52
	v_fmac_f32_e32 v74, v53, v53
	v_fmac_f32_e32 v74, v54, v54
	v_fmac_f32_e32 v74, v55, v55
	v_mfma_f32_32x32x16_bf16 v[32:47], v[76:79], v[68:71], v[32:47]
	v_fmac_f32_e32 v74, v56, v56
	v_fmac_f32_e32 v74, v57, v57
	v_fmac_f32_e32 v74, v58, v58
	v_fmac_f32_e32 v74, v59, v59
	v_fmac_f32_e32 v74, v60, v60
	v_fmac_f32_e32 v74, v61, v61
	v_fmac_f32_e32 v74, v62, v62
	v_fmac_f32_e32 v74, v63, v63
	s_nop 3
	v_fmac_f32_e32 v74, v32, v32
	v_fmac_f32_e32 v74, v33, v33
	v_fmac_f32_e32 v74, v34, v34
	v_fmac_f32_e32 v74, v35, v35
	v_fmac_f32_e32 v74, v36, v36
	v_fmac_f32_e32 v74, v37, v37
	v_fmac_f32_e32 v74, v38, v38
	v_fmac_f32_e32 v74, v39, v39
	v_fmac_f32_e32 v74, v40, v40
	v_fmac_f32_e32 v74, v41, v41
	v_fmac_f32_e32 v74, v42, v42
	v_fmac_f32_e32 v74, v43, v43
	v_fmac_f32_e32 v74, v44, v44
	v_fmac_f32_e32 v74, v45, v45
	v_fmac_f32_e32 v74, v46, v46
	ds_read2_b64 v[64:67], v194 offset0:76 offset1:78
	v_fmac_f32_e32 v74, v47, v47
	v_fmac_f32_e32 v74, v16, v16
	v_fmac_f32_e32 v74, v17, v17
	v_fmac_f32_e32 v74, v18, v18
	v_fmac_f32_e32 v74, v19, v19
	v_fmac_f32_e32 v74, v20, v20
	v_fmac_f32_e32 v74, v21, v21
	v_fmac_f32_e32 v74, v22, v22
	v_fmac_f32_e32 v74, v23, v23
	s_waitcnt lgkmcnt(0)
	v_mfma_f32_32x32x16_bf16 v[0:15], v[64:67], v[68:71], v[0:15]
	v_fmac_f32_e32 v74, v24, v24
	v_fmac_f32_e32 v74, v25, v25
	v_fmac_f32_e32 v74, v26, v26
	v_fmac_f32_e32 v74, v27, v27
	v_fmac_f32_e32 v74, v28, v28
	v_fmac_f32_e32 v74, v29, v29
	v_fmac_f32_e32 v74, v30, v30
	v_fmac_f32_e32 v74, v31, v31
	s_nop 3
	v_fmac_f32_e32 v74, v0, v0
	v_fmac_f32_e32 v74, v1, v1
	v_fmac_f32_e32 v74, v2, v2
	v_fmac_f32_e32 v74, v3, v3
	v_fmac_f32_e32 v74, v4, v4
	v_fmac_f32_e32 v74, v5, v5
	v_pk_mul_f32 v[72:73], v[6:7], v[6:7]
	v_pk_mul_f32 v[70:71], v[8:9], v[8:9]
	v_add_f32_e32 v72, v72, v74
	v_add_f32_e32 v72, v73, v72
	v_add_f32_e32 v70, v70, v72
	v_pk_mul_f32 v[68:69], v[10:11], v[10:11]
	v_add_f32_e32 v70, v71, v70
	v_add_f32_e32 v68, v68, v70
	v_pk_mul_f32 v[66:67], v[12:13], v[12:13]
	v_add_f32_e32 v68, v69, v68
	v_add_f32_e32 v66, v66, v68
	v_pk_mul_f32 v[64:65], v[14:15], v[14:15]
	v_add_f32_e32 v66, v67, v66
	v_add_f32_e32 v64, v64, v66
	v_add_f32_e32 v64, v65, v64
	ds_bpermute_b32 v65, v189, v64
	v_lshlrev_b64 v[68:69], 12, v[160:161]
	v_lshl_add_u64 v[66:67], v[162:163], 0, s[44:45]
	v_lshl_add_u64 v[68:69], s[4:5], 0, v[68:69]
	v_lshl_add_u64 v[72:73], v[68:69], 0, s[44:45]
	s_waitcnt lgkmcnt(0)
	v_add_f32_e32 v64, v64, v65
	v_fmamk_f32 v64, v64, 0x3c000000, v217
	v_cmp_gt_f32_e32 vcc, s30, v64
	v_mul_f32_e32 v65, 0x4b800000, v64
	v_lshl_add_u64 v[68:69], v[66:67], 0, v[208:209]
	v_cndmask_b32_e32 v64, v64, v65, vcc
	v_rsq_f32_e32 v64, v64
	s_mov_b64 s[4:5], 0x3c00
	v_lshl_add_u64 v[66:67], v[68:69], 0, s[4:5]
	s_movk_i32 s4, 0x3000
	v_mul_f32_e32 v65, 0x45800000, v64
	v_cndmask_b32_e32 v64, v64, v65, vcc
	v_add_co_u32_e32 v68, vcc, s4, v68
	v_lshlrev_b32_e32 v65, 2, v188
	s_nop 0
	v_addc_co_u32_e32 v69, vcc, 0, v69, vcc
	flat_load_dwordx2 v[74:75], v[68:69] offset:3072
	v_mul_f32_e32 v64, v244, v64
	global_load_dwordx4 v[68:71], v65, s[18:19]
	v_pk_mul_f32 v[48:49], v[48:49], v[64:65] op_sel_hi:[1,0]
	v_pk_mul_f32 v[50:51], v[50:51], v[64:65] op_sel_hi:[1,0]
	v_pk_mul_f32 v[52:53], v[52:53], v[64:65] op_sel_hi:[1,0]
	v_pk_mul_f32 v[54:55], v[54:55], v[64:65] op_sel_hi:[1,0]
	v_pk_mul_f32 v[56:57], v[56:57], v[64:65] op_sel_hi:[1,0]
	v_pk_mul_f32 v[32:33], v[32:33], v[64:65] op_sel_hi:[1,0]
	v_pk_mul_f32 v[34:35], v[34:35], v[64:65] op_sel_hi:[1,0]
	v_pk_mul_f32 v[36:37], v[36:37], v[64:65] op_sel_hi:[1,0]
	v_pk_mul_f32 v[38:39], v[38:39], v[64:65] op_sel_hi:[1,0]
	v_pk_mul_f32 v[40:41], v[40:41], v[64:65] op_sel_hi:[1,0]
	v_pk_mul_f32 v[16:17], v[16:17], v[64:65] op_sel_hi:[1,0]
	v_pk_mul_f32 v[18:19], v[18:19], v[64:65] op_sel_hi:[1,0]
	v_pk_mul_f32 v[20:21], v[20:21], v[64:65] op_sel_hi:[1,0]
	v_pk_mul_f32 v[22:23], v[22:23], v[64:65] op_sel_hi:[1,0]
	v_pk_mul_f32 v[24:25], v[24:25], v[64:65] op_sel_hi:[1,0]
	v_pk_mul_f32 v[0:1], v[0:1], v[64:65] op_sel_hi:[1,0]
	v_pk_mul_f32 v[2:3], v[2:3], v[64:65] op_sel_hi:[1,0]
	v_pk_mul_f32 v[4:5], v[4:5], v[64:65] op_sel_hi:[1,0]
	v_pk_mul_f32 v[6:7], v[6:7], v[64:65] op_sel_hi:[1,0]
	v_pk_mul_f32 v[8:9], v[8:9], v[64:65] op_sel_hi:[1,0]
	s_waitcnt vmcnt(0) lgkmcnt(0)
; DI float bf2f(bfr v) { return __uint_as_float(((unsigned)v) << 16); }
; DI unsigned pk2(float a, float b) { f2_t v = {a, b}; bf2_t r = __builtin_convertvector(v, bf2_t); return __builtin_bit_cast(unsigned, r); }
; DI float siluf_(float x) { return x / (1.f + __expf(-x)); }
; DI void attn_unit(const Params& p, int l, int unit, unsigned char* smem) {
;     ...
; #pragma unroll
;   for (int dvb = 0; dvb < 4; ++dvb)
; #pragma unroll
;     for (int g = 0; g < 4; ++g) {
;       const int dv = 32 * dvb + 8 * g + 4 * h;
;       const s16x4 z4 = *(const s16x4*)(P + rowq * PLD + C_DAZ + hd * 128 + dv);
;       const f32x4 gn = *(const f32x4*)(p.da_norm + l * 128 + dv);
;       float y[4];
;       for (int q = 0; q < 4; ++q) y[q] = oacc[dvb][4 * g + q] * rs * gn[q] * siluf_(bf2f((bfr)z4[q]));
;       u32x2 w; w[0] = pk2(y[0], y[1]); w[1] = pk2(y[2], y[3]);
;       *(u32x2*)(YS + rowq * DM + 1536 + hd * 128 + dv) = w;
;     }
	v_and_b32_e32 v78, 0xffff0000, v74
	v_lshlrev_b32_e32 v74, 16, v74
	v_mul_f32_e32 v76, 0xbfb8aa3b, v74
	v_pk_mul_f32 v[48:49], v[68:69], v[48:49]
	v_mul_f32_e32 v68, 0xbfb8aa3b, v78
	v_exp_f32_e32 v76, v76
	v_exp_f32_e32 v77, v68
	v_pk_mul_f32 v[50:51], v[70:71], v[50:51]
	v_pk_add_f32 v[68:69], v[76:77], 1.0 op_sel_hi:[1,0]
	s_nop 0
	v_div_scale_f32 v76, s[4:5], v69, v69, v78
	v_rcp_f32_e32 v77, v76
	s_nop 0
	v_fma_f32 v79, -v76, v77, 1.0
	v_fmac_f32_e32 v77, v79, v77
	v_div_scale_f32 v79, vcc, v78, v69, v78
	v_mul_f32_e32 v80, v79, v77
	v_fma_f32 v81, -v76, v80, v79
	v_fmac_f32_e32 v80, v81, v77
	v_fma_f32 v76, -v76, v80, v79
	v_div_fmas_f32 v76, v76, v77, v80
	v_div_fixup_f32 v69, v76, v69, v78
	v_div_scale_f32 v76, s[4:5], v68, v68, v74
	v_rcp_f32_e32 v77, v76
	s_nop 0
	v_fma_f32 v78, -v76, v77, 1.0
	v_fmac_f32_e32 v77, v78, v77
	v_div_scale_f32 v78, vcc, v74, v68, v74
	v_mul_f32_e32 v79, v78, v77
	v_fma_f32 v80, -v76, v79, v78
	v_fmac_f32_e32 v79, v80, v77
	v_fma_f32 v76, -v76, v79, v78
	v_div_fmas_f32 v76, v76, v77, v79
	v_div_fixup_f32 v68, v76, v68, v74
	v_and_b32_e32 v74, 0xffff0000, v75
	v_lshlrev_b32_e32 v75, 16, v75
	v_pk_mul_f32 v[48:49], v[68:69], v[48:49]
	v_mul_f32_e32 v68, 0xbfb8aa3b, v75
	v_mul_f32_e32 v69, 0xbfb8aa3b, v74
	v_exp_f32_e32 v68, v68
	v_exp_f32_e32 v69, v69
	s_nop 0
	v_pk_add_f32 v[68:69], v[68:69], 1.0 op_sel_hi:[1,0]
	s_nop 0
	v_div_scale_f32 v70, s[4:5], v69, v69, v74
	v_rcp_f32_e32 v71, v70
	s_nop 0
	v_fma_f32 v76, -v70, v71, 1.0
	v_fmac_f32_e32 v71, v76, v71
	v_div_scale_f32 v76, vcc, v74, v69, v74
	v_mul_f32_e32 v77, v76, v71
	v_fma_f32 v78, -v70, v77, v76
	v_fmac_f32_e32 v77, v78, v71
	v_fma_f32 v70, -v70, v77, v76
	v_div_fmas_f32 v70, v70, v71, v77
	v_div_fixup_f32 v69, v70, v69, v74
	v_div_scale_f32 v70, s[4:5], v68, v68, v75
	v_rcp_f32_e32 v71, v70
	s_mov_b64 s[4:5], 0x33110c00
	v_fma_f32 v74, -v70, v71, 1.0
	v_fmac_f32_e32 v71, v74, v71
	v_div_scale_f32 v74, vcc, v75, v68, v75
	v_mul_f32_e32 v76, v74, v71
	v_fma_f32 v77, -v70, v76, v74
	v_fmac_f32_e32 v76, v77, v71
	v_fma_f32 v70, -v70, v76, v74
	v_div_fmas_f32 v70, v70, v71, v76
	v_div_fixup_f32 v68, v70, v68, v75
	v_pk_mul_f32 v[50:51], v[68:69], v[50:51]
	v_cvt_pk_bf16_f32 v68, v48, v49
	v_cvt_pk_bf16_f32 v69, v50, v51
	v_lshl_add_u64 v[50:51], v[72:73], 0, v[208:209]
	v_lshl_add_u64 v[48:49], v[50:51], 0, s[4:5]
	s_mov_b32 s4, 0x33110000
	v_add_co_u32_e32 v50, vcc, s4, v50
	s_nop 1
	v_addc_co_u32_e32 v51, vcc, 0, v51, vcc
	flat_store_dwordx2 v[50:51], v[68:69] offset:3072
	flat_load_dwordx2 v[50:51], v[66:67] offset:16
	s_nop 0
	global_load_dwordx4 v[68:71], v65, s[18:19] offset:32
	s_waitcnt vmcnt(0) lgkmcnt(0)
	v_and_b32_e32 v74, 0xffff0000, v50
	v_lshlrev_b32_e32 v50, 16, v50
	v_mul_f32_e32 v72, 0xbfb8aa3b, v50
	v_pk_mul_f32 v[52:53], v[68:69], v[52:53]
	v_mul_f32_e32 v68, 0xbfb8aa3b, v74
	v_exp_f32_e32 v72, v72
	v_exp_f32_e32 v73, v68
	v_pk_mul_f32 v[54:55], v[70:71], v[54:55]
	v_pk_add_f32 v[68:69], v[72:73], 1.0 op_sel_hi:[1,0]
	s_nop 0
	v_div_scale_f32 v72, s[4:5], v69, v69, v74
	v_rcp_f32_e32 v73, v72
	s_nop 0
	v_fma_f32 v75, -v72, v73, 1.0
	v_fmac_f32_e32 v73, v75, v73
	v_div_scale_f32 v75, vcc, v74, v69, v74
	v_mul_f32_e32 v76, v75, v73
	v_fma_f32 v77, -v72, v76, v75
	v_fmac_f32_e32 v76, v77, v73
	v_fma_f32 v72, -v72, v76, v75
	v_div_fmas_f32 v72, v72, v73, v76
	v_div_fixup_f32 v69, v72, v69, v74
	v_div_scale_f32 v72, s[4:5], v68, v68, v50
	v_rcp_f32_e32 v73, v72
	s_nop 0
	v_fma_f32 v74, -v72, v73, 1.0
	v_fmac_f32_e32 v73, v74, v73
	v_div_scale_f32 v74, vcc, v50, v68, v50
	v_mul_f32_e32 v75, v74, v73
	v_fma_f32 v76, -v72, v75, v74
	v_fmac_f32_e32 v75, v76, v73
	v_fma_f32 v72, -v72, v75, v74
	v_div_fmas_f32 v72, v72, v73, v75
	v_div_fixup_f32 v68, v72, v68, v50
	v_pk_mul_f32 v[52:53], v[68:69], v[52:53]
	v_and_b32_e32 v68, 0xffff0000, v51
	v_lshlrev_b32_e32 v69, 16, v51
	v_mul_f32_e32 v50, 0xbfb8aa3b, v69
	v_mul_f32_e32 v51, 0xbfb8aa3b, v68
	v_exp_f32_e32 v50, v50
	v_exp_f32_e32 v51, v51
	v_cvt_pk_bf16_f32 v52, v52, v53
	v_pk_add_f32 v[50:51], v[50:51], 1.0 op_sel_hi:[1,0]
	s_nop 0
	v_div_scale_f32 v70, s[4:5], v51, v51, v68
	v_rcp_f32_e32 v71, v70
	s_nop 0
	v_fma_f32 v72, -v70, v71, 1.0
	v_fmac_f32_e32 v71, v72, v71
	v_div_scale_f32 v72, vcc, v68, v51, v68
	v_mul_f32_e32 v73, v72, v71
	v_fma_f32 v74, -v70, v73, v72
	v_fmac_f32_e32 v73, v74, v71
	v_fma_f32 v70, -v70, v73, v72
	v_div_fmas_f32 v70, v70, v71, v73
	v_div_fixup_f32 v51, v70, v51, v68
	v_div_scale_f32 v68, s[4:5], v50, v50, v69
	v_rcp_f32_e32 v70, v68
	s_nop 0
	v_fma_f32 v71, -v68, v70, 1.0
	v_fmac_f32_e32 v70, v71, v70
	v_div_scale_f32 v71, vcc, v69, v50, v69
	v_mul_f32_e32 v72, v71, v70
	v_fma_f32 v73, -v68, v72, v71
	v_fmac_f32_e32 v72, v73, v70
	v_fma_f32 v68, -v68, v72, v71
	v_div_fmas_f32 v68, v68, v70, v72
	v_div_fixup_f32 v50, v68, v50, v69
	v_pk_mul_f32 v[50:51], v[50:51], v[54:55]
	s_nop 0
	v_cvt_pk_bf16_f32 v53, v50, v51
	flat_store_dwordx2 v[48:49], v[52:53] offset:16
	flat_load_dwordx2 v[54:55], v[66:67] offset:32
	s_nop 0
	global_load_dwordx4 v[50:53], v65, s[18:19] offset:64
	s_waitcnt vmcnt(0) lgkmcnt(0)
; DI float bf2f(bfr v) { return __uint_as_float(((unsigned)v) << 16); }
; DI unsigned pk2(float a, float b) { f2_t v = {a, b}; bf2_t r = __builtin_convertvector(v, bf2_t); return __builtin_bit_cast(unsigned, r); }
; DI float siluf_(float x) { return x / (1.f + __expf(-x)); }
; DI void attn_unit(const Params& p, int l, int unit, unsigned char* smem) {
;     ...
; #pragma unroll
;   for (int dvb = 0; dvb < 4; ++dvb)
; #pragma unroll
;     for (int g = 0; g < 4; ++g) {
;       const int dv = 32 * dvb + 8 * g + 4 * h;
;       const s16x4 z4 = *(const s16x4*)(P + rowq * PLD + C_DAZ + hd * 128 + dv);
;       const f32x4 gn = *(const f32x4*)(p.da_norm + l * 128 + dv);
;       float y[4];
;       for (int q = 0; q < 4; ++q) y[q] = oacc[dvb][4 * g + q] * rs * gn[q] * siluf_(bf2f((bfr)z4[q]));
;       u32x2 w; w[0] = pk2(y[0], y[1]); w[1] = pk2(y[2], y[3]);
;       *(u32x2*)(YS + rowq * DM + 1536 + hd * 128 + dv) = w;
;     }
	v_and_b32_e32 v70, 0xffff0000, v54
	v_lshlrev_b32_e32 v54, 16, v54
	v_mul_f32_e32 v68, 0xbfb8aa3b, v54
	v_pk_mul_f32 v[50:51], v[50:51], v[56:57]
	v_mul_f32_e32 v56, 0xbfb8aa3b, v70
	v_exp_f32_e32 v68, v68
	v_exp_f32_e32 v69, v56
	s_nop 0
	v_pk_add_f32 v[56:57], v[68:69], 1.0 op_sel_hi:[1,0]
	s_nop 0
	v_div_scale_f32 v68, s[4:5], v57, v57, v70
	v_rcp_f32_e32 v69, v68
	s_nop 0
	v_fma_f32 v71, -v68, v69, 1.0
	v_fmac_f32_e32 v69, v71, v69
	v_div_scale_f32 v71, vcc, v70, v57, v70
	v_mul_f32_e32 v72, v71, v69
	v_fma_f32 v73, -v68, v72, v71
	v_fmac_f32_e32 v72, v73, v69
	v_fma_f32 v68, -v68, v72, v71
	v_div_fmas_f32 v68, v68, v69, v72
	v_div_fixup_f32 v57, v68, v57, v70
	v_div_scale_f32 v68, s[4:5], v56, v56, v54
	v_rcp_f32_e32 v69, v68
	s_nop 0
	v_fma_f32 v70, -v68, v69, 1.0
	v_fmac_f32_e32 v69, v70, v69
	v_div_scale_f32 v70, vcc, v54, v56, v54
	v_mul_f32_e32 v71, v70, v69
	v_fma_f32 v72, -v68, v71, v70
	v_fmac_f32_e32 v71, v72, v69
	v_fma_f32 v68, -v68, v71, v70
	v_div_fmas_f32 v68, v68, v69, v71
	v_div_fixup_f32 v56, v68, v56, v54
	v_and_b32_e32 v68, 0xffff0000, v55
	v_lshlrev_b32_e32 v69, 16, v55
	v_mul_f32_e32 v54, 0xbfb8aa3b, v69
	v_mul_f32_e32 v55, 0xbfb8aa3b, v68
	v_exp_f32_e32 v54, v54
	v_exp_f32_e32 v55, v55
	v_pk_mul_f32 v[50:51], v[56:57], v[50:51]
	v_pk_mul_f32 v[56:57], v[58:59], v[64:65] op_sel_hi:[1,0]
	v_cvt_pk_bf16_f32 v50, v50, v51
	v_pk_add_f32 v[54:55], v[54:55], 1.0 op_sel_hi:[1,0]
	v_pk_mul_f32 v[52:53], v[52:53], v[56:57]
	v_div_scale_f32 v56, s[4:5], v55, v55, v68
	v_rcp_f32_e32 v57, v56
	s_nop 0
	v_fma_f32 v58, -v56, v57, 1.0
	v_fmac_f32_e32 v57, v58, v57
	v_div_scale_f32 v58, vcc, v68, v55, v68
	v_mul_f32_e32 v59, v58, v57
	v_fma_f32 v70, -v56, v59, v58
	v_fmac_f32_e32 v59, v70, v57
	v_fma_f32 v56, -v56, v59, v58
	v_div_fmas_f32 v56, v56, v57, v59
	v_div_fixup_f32 v55, v56, v55, v68
	v_div_scale_f32 v56, s[4:5], v54, v54, v69
	v_rcp_f32_e32 v57, v56
	s_nop 0
	v_fma_f32 v58, -v56, v57, 1.0
	v_fmac_f32_e32 v57, v58, v57
	v_div_scale_f32 v58, vcc, v69, v54, v69
	v_mul_f32_e32 v59, v58, v57
	v_fma_f32 v68, -v56, v59, v58
	v_fmac_f32_e32 v59, v68, v57
	v_fma_f32 v56, -v56, v59, v58
	v_div_fmas_f32 v56, v56, v57, v59
	v_div_fixup_f32 v54, v56, v54, v69
	v_pk_mul_f32 v[52:53], v[54:55], v[52:53]
	v_pk_mul_f32 v[58:59], v[60:61], v[64:65] op_sel_hi:[1,0]
	v_cvt_pk_bf16_f32 v51, v52, v53
	flat_store_dwordx2 v[48:49], v[50:51] offset:32
	flat_load_dwordx2 v[54:55], v[66:67] offset:48
	s_nop 0
	global_load_dwordx4 v[50:53], v65, s[18:19] offset:96
	s_waitcnt vmcnt(0) lgkmcnt(0)
	v_and_b32_e32 v68, 0xffff0000, v54
	v_lshlrev_b32_e32 v54, 16, v54
	v_mul_f32_e32 v56, 0xbfb8aa3b, v54
	v_mul_f32_e32 v57, 0xbfb8aa3b, v68
	v_exp_f32_e32 v56, v56
	v_exp_f32_e32 v57, v57
	v_pk_mul_f32 v[50:51], v[50:51], v[58:59]
	v_pk_add_f32 v[56:57], v[56:57], 1.0 op_sel_hi:[1,0]
	s_nop 0
	v_div_scale_f32 v58, s[4:5], v57, v57, v68
	v_rcp_f32_e32 v59, v58
	s_nop 0
	v_fma_f32 v60, -v58, v59, 1.0
	v_fmac_f32_e32 v59, v60, v59
	v_div_scale_f32 v60, vcc, v68, v57, v68
	v_mul_f32_e32 v61, v60, v59
	v_fma_f32 v69, -v58, v61, v60
	v_fmac_f32_e32 v61, v69, v59
	v_fma_f32 v58, -v58, v61, v60
	v_div_fmas_f32 v58, v58, v59, v61
	v_div_fixup_f32 v57, v58, v57, v68
	v_div_scale_f32 v58, s[4:5], v56, v56, v54
	v_rcp_f32_e32 v59, v58
	s_nop 0
	v_fma_f32 v60, -v58, v59, 1.0
	v_fmac_f32_e32 v59, v60, v59
	v_div_scale_f32 v60, vcc, v54, v56, v54
	v_mul_f32_e32 v61, v60, v59
	v_fma_f32 v68, -v58, v61, v60
	v_fmac_f32_e32 v61, v68, v59
	v_fma_f32 v58, -v58, v61, v60
	v_div_fmas_f32 v58, v58, v59, v61
	v_div_fixup_f32 v56, v58, v56, v54
	v_and_b32_e32 v58, 0xffff0000, v55
	v_lshlrev_b32_e32 v59, 16, v55
	v_mul_f32_e32 v54, 0xbfb8aa3b, v59
	v_mul_f32_e32 v55, 0xbfb8aa3b, v58
	v_exp_f32_e32 v54, v54
	v_exp_f32_e32 v55, v55
	v_pk_mul_f32 v[50:51], v[56:57], v[50:51]
	v_pk_mul_f32 v[56:57], v[62:63], v[64:65] op_sel_hi:[1,0]
	v_cvt_pk_bf16_f32 v50, v50, v51
	v_pk_add_f32 v[54:55], v[54:55], 1.0 op_sel_hi:[1,0]
	v_pk_mul_f32 v[52:53], v[52:53], v[56:57]
	v_div_scale_f32 v56, s[4:5], v55, v55, v58
	v_rcp_f32_e32 v57, v56
	s_nop 0
	v_fma_f32 v60, -v56, v57, 1.0
	v_fmac_f32_e32 v57, v60, v57
	v_div_scale_f32 v60, vcc, v58, v55, v58
	v_mul_f32_e32 v61, v60, v57
	v_fma_f32 v62, -v56, v61, v60
	v_fmac_f32_e32 v61, v62, v57
	v_fma_f32 v56, -v56, v61, v60
	v_div_fmas_f32 v56, v56, v57, v61
	v_div_fixup_f32 v55, v56, v55, v58
	v_div_scale_f32 v56, s[4:5], v54, v54, v59
	v_rcp_f32_e32 v57, v56
	s_nop 0
	v_fma_f32 v58, -v56, v57, 1.0
	v_fmac_f32_e32 v57, v58, v57
	v_div_scale_f32 v58, vcc, v59, v54, v59
	v_mul_f32_e32 v60, v58, v57
	v_fma_f32 v61, -v56, v60, v58
	v_fmac_f32_e32 v60, v61, v57
	v_fma_f32 v56, -v56, v60, v58
	v_div_fmas_f32 v56, v56, v57, v60
	v_div_fixup_f32 v54, v56, v54, v59
	v_pk_mul_f32 v[52:53], v[54:55], v[52:53]
	s_nop 0
	v_cvt_pk_bf16_f32 v51, v52, v53
	flat_store_dwordx2 v[48:49], v[50:51] offset:48
	flat_load_dwordx2 v[54:55], v[66:67] offset:64
	s_nop 0
	global_load_dwordx4 v[50:53], v65, s[18:19] offset:128
	s_waitcnt vmcnt(0) lgkmcnt(0)
; DI float bf2f(bfr v) { return __uint_as_float(((unsigned)v) << 16); }
; DI unsigned pk2(float a, float b) { f2_t v = {a, b}; bf2_t r = __builtin_convertvector(v, bf2_t); return __builtin_bit_cast(unsigned, r); }
; DI float siluf_(float x) { return x / (1.f + __expf(-x)); }
; DI void attn_unit(const Params& p, int l, int unit, unsigned char* smem) {
;     ...
; #pragma unroll
;   for (int dvb = 0; dvb < 4; ++dvb)
; #pragma unroll
;     for (int g = 0; g < 4; ++g) {
;       const int dv = 32 * dvb + 8 * g + 4 * h;
;       const s16x4 z4 = *(const s16x4*)(P + rowq * PLD + C_DAZ + hd * 128 + dv);
;       const f32x4 gn = *(const f32x4*)(p.da_norm + l * 128 + dv);
;       float y[4];
;       for (int q = 0; q < 4; ++q) y[q] = oacc[dvb][4 * g + q] * rs * gn[q] * siluf_(bf2f((bfr)z4[q]));
;       u32x2 w; w[0] = pk2(y[0], y[1]); w[1] = pk2(y[2], y[3]);
;       *(u32x2*)(YS + rowq * DM + 1536 + hd * 128 + dv) = w;
;     }
	v_and_b32_e32 v58, 0xffff0000, v54
	v_lshlrev_b32_e32 v54, 16, v54
	v_mul_f32_e32 v56, 0xbfb8aa3b, v54
	v_pk_mul_f32 v[32:33], v[50:51], v[32:33]
	v_mul_f32_e32 v50, 0xbfb8aa3b, v58
	v_exp_f32_e32 v56, v56
	v_exp_f32_e32 v57, v50
	v_pk_mul_f32 v[34:35], v[52:53], v[34:35]
	v_pk_add_f32 v[50:51], v[56:57], 1.0 op_sel_hi:[1,0]
	s_nop 0
	v_div_scale_f32 v56, s[4:5], v51, v51, v58
	v_rcp_f32_e32 v57, v56
	s_nop 0
	v_fma_f32 v59, -v56, v57, 1.0
	v_fmac_f32_e32 v57, v59, v57
	v_div_scale_f32 v59, vcc, v58, v51, v58
	v_mul_f32_e32 v60, v59, v57
	v_fma_f32 v61, -v56, v60, v59
	v_fmac_f32_e32 v60, v61, v57
	v_fma_f32 v56, -v56, v60, v59
	v_div_fmas_f32 v56, v56, v57, v60
	v_div_fixup_f32 v51, v56, v51, v58
	v_div_scale_f32 v56, s[4:5], v50, v50, v54
	v_rcp_f32_e32 v57, v56
	s_nop 0
	v_fma_f32 v58, -v56, v57, 1.0
	v_fmac_f32_e32 v57, v58, v57
	v_div_scale_f32 v58, vcc, v54, v50, v54
	v_mul_f32_e32 v59, v58, v57
	v_fma_f32 v60, -v56, v59, v58
	v_fmac_f32_e32 v59, v60, v57
	v_fma_f32 v56, -v56, v59, v58
	v_div_fmas_f32 v56, v56, v57, v59
	v_div_fixup_f32 v50, v56, v50, v54
	v_and_b32_e32 v54, 0xffff0000, v55
	v_lshlrev_b32_e32 v55, 16, v55
	v_pk_mul_f32 v[32:33], v[50:51], v[32:33]
	v_mul_f32_e32 v50, 0xbfb8aa3b, v55
	v_mul_f32_e32 v51, 0xbfb8aa3b, v54
	v_exp_f32_e32 v50, v50
	v_exp_f32_e32 v51, v51
	v_cvt_pk_bf16_f32 v32, v32, v33
	v_pk_add_f32 v[50:51], v[50:51], 1.0 op_sel_hi:[1,0]
	s_nop 0
	v_div_scale_f32 v52, s[4:5], v51, v51, v54
	v_rcp_f32_e32 v53, v52
	s_nop 0
	v_fma_f32 v56, -v52, v53, 1.0
	v_fmac_f32_e32 v53, v56, v53
	v_div_scale_f32 v56, vcc, v54, v51, v54
	v_mul_f32_e32 v57, v56, v53
	v_fma_f32 v58, -v52, v57, v56
	v_fmac_f32_e32 v57, v58, v53
	v_fma_f32 v52, -v52, v57, v56
	v_div_fmas_f32 v52, v52, v53, v57
	v_div_fixup_f32 v51, v52, v51, v54
	v_div_scale_f32 v52, s[4:5], v50, v50, v55
	v_rcp_f32_e32 v53, v52
	s_nop 0
	v_fma_f32 v54, -v52, v53, 1.0
	v_fmac_f32_e32 v53, v54, v53
	v_div_scale_f32 v54, vcc, v55, v50, v55
	v_mul_f32_e32 v56, v54, v53
	v_fma_f32 v57, -v52, v56, v54
	v_fmac_f32_e32 v56, v57, v53
	v_fma_f32 v52, -v52, v56, v54
	v_div_fmas_f32 v52, v52, v53, v56
	v_div_fixup_f32 v50, v52, v50, v55
	v_pk_mul_f32 v[34:35], v[50:51], v[34:35]
	s_nop 0
	v_cvt_pk_bf16_f32 v33, v34, v35
	flat_store_dwordx2 v[48:49], v[32:33] offset:64
	flat_load_dwordx2 v[50:51], v[66:67] offset:80
	s_nop 0
	global_load_dwordx4 v[32:35], v65, s[18:19] offset:160
	s_waitcnt vmcnt(0) lgkmcnt(0)
	v_and_b32_e32 v54, 0xffff0000, v50
	v_lshlrev_b32_e32 v50, 16, v50
	v_mul_f32_e32 v52, 0xbfb8aa3b, v50
	v_pk_mul_f32 v[32:33], v[32:33], v[36:37]
	v_mul_f32_e32 v36, 0xbfb8aa3b, v54
	v_exp_f32_e32 v52, v52
	v_exp_f32_e32 v53, v36
	v_pk_mul_f32 v[34:35], v[34:35], v[38:39]
	v_pk_add_f32 v[36:37], v[52:53], 1.0 op_sel_hi:[1,0]
	s_nop 0
	v_div_scale_f32 v52, s[4:5], v37, v37, v54
	v_rcp_f32_e32 v53, v52
	s_nop 0
	v_fma_f32 v55, -v52, v53, 1.0
	v_fmac_f32_e32 v53, v55, v53
	v_div_scale_f32 v55, vcc, v54, v37, v54
	v_mul_f32_e32 v56, v55, v53
	v_fma_f32 v57, -v52, v56, v55
	v_fmac_f32_e32 v56, v57, v53
	v_fma_f32 v52, -v52, v56, v55
	v_div_fmas_f32 v52, v52, v53, v56
	v_div_fixup_f32 v37, v52, v37, v54
	v_div_scale_f32 v52, s[4:5], v36, v36, v50
	v_rcp_f32_e32 v53, v52
	s_nop 0
	v_fma_f32 v54, -v52, v53, 1.0
	v_fmac_f32_e32 v53, v54, v53
	v_div_scale_f32 v54, vcc, v50, v36, v50
	v_mul_f32_e32 v55, v54, v53
	v_fma_f32 v56, -v52, v55, v54
	v_fmac_f32_e32 v55, v56, v53
	v_fma_f32 v52, -v52, v55, v54
	v_div_fmas_f32 v52, v52, v53, v55
	v_div_fixup_f32 v36, v52, v36, v50
	v_and_b32_e32 v50, 0xffff0000, v51
	v_lshlrev_b32_e32 v51, 16, v51
	v_pk_mul_f32 v[32:33], v[36:37], v[32:33]
	v_mul_f32_e32 v36, 0xbfb8aa3b, v51
	v_mul_f32_e32 v37, 0xbfb8aa3b, v50
	v_exp_f32_e32 v36, v36
	v_exp_f32_e32 v37, v37
	v_cvt_pk_bf16_f32 v32, v32, v33
	v_pk_add_f32 v[36:37], v[36:37], 1.0 op_sel_hi:[1,0]
	s_nop 0
	v_div_scale_f32 v38, s[4:5], v37, v37, v50
	v_rcp_f32_e32 v39, v38
	s_nop 0
	v_fma_f32 v52, -v38, v39, 1.0
	v_fmac_f32_e32 v39, v52, v39
	v_div_scale_f32 v52, vcc, v50, v37, v50
	v_mul_f32_e32 v53, v52, v39
	v_fma_f32 v54, -v38, v53, v52
	v_fmac_f32_e32 v53, v54, v39
	v_fma_f32 v38, -v38, v53, v52
	v_div_fmas_f32 v38, v38, v39, v53
	v_div_fixup_f32 v37, v38, v37, v50
	v_div_scale_f32 v38, s[4:5], v36, v36, v51
	v_rcp_f32_e32 v39, v38
	s_nop 0
	v_fma_f32 v50, -v38, v39, 1.0
	v_fmac_f32_e32 v39, v50, v39
	v_div_scale_f32 v50, vcc, v51, v36, v51
	v_mul_f32_e32 v52, v50, v39
	v_fma_f32 v53, -v38, v52, v50
	v_fmac_f32_e32 v52, v53, v39
	v_fma_f32 v38, -v38, v52, v50
	v_div_fmas_f32 v38, v38, v39, v52
	v_div_fixup_f32 v36, v38, v36, v51
	v_pk_mul_f32 v[34:35], v[36:37], v[34:35]
	s_nop 0
	v_cvt_pk_bf16_f32 v33, v34, v35
	flat_store_dwordx2 v[48:49], v[32:33] offset:80
	flat_load_dwordx2 v[36:37], v[66:67] offset:96
	s_nop 0
	global_load_dwordx4 v[32:35], v65, s[18:19] offset:192
	s_waitcnt vmcnt(0) lgkmcnt(0)
; DI float bf2f(bfr v) { return __uint_as_float(((unsigned)v) << 16); }
; DI unsigned pk2(float a, float b) { f2_t v = {a, b}; bf2_t r = __builtin_convertvector(v, bf2_t); return __builtin_bit_cast(unsigned, r); }
; DI float siluf_(float x) { return x / (1.f + __expf(-x)); }
; DI void attn_unit(const Params& p, int l, int unit, unsigned char* smem) {
;     ...
; #pragma unroll
;   for (int dvb = 0; dvb < 4; ++dvb)
; #pragma unroll
;     for (int g = 0; g < 4; ++g) {
;       const int dv = 32 * dvb + 8 * g + 4 * h;
;       const s16x4 z4 = *(const s16x4*)(P + rowq * PLD + C_DAZ + hd * 128 + dv);
;       const f32x4 gn = *(const f32x4*)(p.da_norm + l * 128 + dv);
;       float y[4];
;       for (int q = 0; q < 4; ++q) y[q] = oacc[dvb][4 * g + q] * rs * gn[q] * siluf_(bf2f((bfr)z4[q]));
;       u32x2 w; w[0] = pk2(y[0], y[1]); w[1] = pk2(y[2], y[3]);
;       *(u32x2*)(YS + rowq * DM + 1536 + hd * 128 + dv) = w;
;     }
	v_and_b32_e32 v50, 0xffff0000, v36
	v_lshlrev_b32_e32 v36, 16, v36
	v_mul_f32_e32 v38, 0xbfb8aa3b, v36
	v_mul_f32_e32 v39, 0xbfb8aa3b, v50
	v_exp_f32_e32 v38, v38
	v_exp_f32_e32 v39, v39
	v_pk_mul_f32 v[32:33], v[32:33], v[40:41]
	v_pk_add_f32 v[38:39], v[38:39], 1.0 op_sel_hi:[1,0]
	s_nop 0
	v_div_scale_f32 v40, s[4:5], v39, v39, v50
	v_rcp_f32_e32 v41, v40
	s_nop 0
	v_fma_f32 v51, -v40, v41, 1.0
	v_fmac_f32_e32 v41, v51, v41
	v_div_scale_f32 v51, vcc, v50, v39, v50
	v_mul_f32_e32 v52, v51, v41
	v_fma_f32 v53, -v40, v52, v51
	v_fmac_f32_e32 v52, v53, v41
	v_fma_f32 v40, -v40, v52, v51
	v_div_fmas_f32 v40, v40, v41, v52
	v_div_fixup_f32 v39, v40, v39, v50
	v_div_scale_f32 v40, s[4:5], v38, v38, v36
	v_rcp_f32_e32 v41, v40
	s_nop 0
	v_fma_f32 v50, -v40, v41, 1.0
	v_fmac_f32_e32 v41, v50, v41
	v_div_scale_f32 v50, vcc, v36, v38, v36
	v_mul_f32_e32 v51, v50, v41
	v_fma_f32 v52, -v40, v51, v50
	v_fmac_f32_e32 v51, v52, v41
	v_fma_f32 v40, -v40, v51, v50
	v_div_fmas_f32 v40, v40, v41, v51
	v_div_fixup_f32 v38, v40, v38, v36
	v_and_b32_e32 v40, 0xffff0000, v37
	v_lshlrev_b32_e32 v41, 16, v37
	v_mul_f32_e32 v36, 0xbfb8aa3b, v41
	v_mul_f32_e32 v37, 0xbfb8aa3b, v40
	v_exp_f32_e32 v36, v36
	v_exp_f32_e32 v37, v37
	v_pk_mul_f32 v[32:33], v[38:39], v[32:33]
	v_pk_mul_f32 v[38:39], v[42:43], v[64:65] op_sel_hi:[1,0]
	v_cvt_pk_bf16_f32 v32, v32, v33
	v_pk_add_f32 v[36:37], v[36:37], 1.0 op_sel_hi:[1,0]
	v_pk_mul_f32 v[34:35], v[34:35], v[38:39]
	v_div_scale_f32 v38, s[4:5], v37, v37, v40
	v_rcp_f32_e32 v39, v38
	s_nop 0
	v_fma_f32 v42, -v38, v39, 1.0
	v_fmac_f32_e32 v39, v42, v39
	v_div_scale_f32 v42, vcc, v40, v37, v40
	v_mul_f32_e32 v43, v42, v39
	v_fma_f32 v50, -v38, v43, v42
	v_fmac_f32_e32 v43, v50, v39
	v_fma_f32 v38, -v38, v43, v42
	v_div_fmas_f32 v38, v38, v39, v43
	v_div_fixup_f32 v37, v38, v37, v40
	v_div_scale_f32 v38, s[4:5], v36, v36, v41
	v_rcp_f32_e32 v39, v38
	s_nop 0
	v_fma_f32 v40, -v38, v39, 1.0
	v_fmac_f32_e32 v39, v40, v39
	v_div_scale_f32 v40, vcc, v41, v36, v41
	v_mul_f32_e32 v42, v40, v39
	v_fma_f32 v43, -v38, v42, v40
	v_fmac_f32_e32 v42, v43, v39
	v_fma_f32 v38, -v38, v42, v40
	v_div_fmas_f32 v38, v38, v39, v42
	v_div_fixup_f32 v36, v38, v36, v41
	v_pk_mul_f32 v[34:35], v[36:37], v[34:35]
	v_pk_mul_f32 v[40:41], v[44:45], v[64:65] op_sel_hi:[1,0]
	v_cvt_pk_bf16_f32 v33, v34, v35
	flat_store_dwordx2 v[48:49], v[32:33] offset:96
	flat_load_dwordx2 v[36:37], v[66:67] offset:112
	s_nop 0
	global_load_dwordx4 v[32:35], v65, s[18:19] offset:224
	s_waitcnt vmcnt(0) lgkmcnt(0)
	v_and_b32_e32 v42, 0xffff0000, v36
	v_lshlrev_b32_e32 v36, 16, v36
	v_mul_f32_e32 v38, 0xbfb8aa3b, v36
	v_mul_f32_e32 v39, 0xbfb8aa3b, v42
	v_exp_f32_e32 v38, v38
	v_exp_f32_e32 v39, v39
	v_pk_mul_f32 v[32:33], v[32:33], v[40:41]
	v_pk_add_f32 v[38:39], v[38:39], 1.0 op_sel_hi:[1,0]
	s_nop 0
	v_div_scale_f32 v40, s[4:5], v39, v39, v42
	v_rcp_f32_e32 v41, v40
	s_nop 0
	v_fma_f32 v43, -v40, v41, 1.0
	v_fmac_f32_e32 v41, v43, v41
	v_div_scale_f32 v43, vcc, v42, v39, v42
	v_mul_f32_e32 v44, v43, v41
	v_fma_f32 v45, -v40, v44, v43
	v_fmac_f32_e32 v44, v45, v41
	v_fma_f32 v40, -v40, v44, v43
	v_div_fmas_f32 v40, v40, v41, v44
	v_div_fixup_f32 v39, v40, v39, v42
	v_div_scale_f32 v40, s[4:5], v38, v38, v36
	v_rcp_f32_e32 v41, v40
	s_nop 0
	v_fma_f32 v42, -v40, v41, 1.0
	v_fmac_f32_e32 v41, v42, v41
	v_div_scale_f32 v42, vcc, v36, v38, v36
	v_mul_f32_e32 v43, v42, v41
	v_fma_f32 v44, -v40, v43, v42
	v_fmac_f32_e32 v43, v44, v41
	v_fma_f32 v40, -v40, v43, v42
	v_div_fmas_f32 v40, v40, v41, v43
	v_div_fixup_f32 v38, v40, v38, v36
	v_and_b32_e32 v40, 0xffff0000, v37
	v_lshlrev_b32_e32 v41, 16, v37
	v_mul_f32_e32 v36, 0xbfb8aa3b, v41
	v_mul_f32_e32 v37, 0xbfb8aa3b, v40
	v_exp_f32_e32 v36, v36
	v_exp_f32_e32 v37, v37
	v_pk_mul_f32 v[32:33], v[38:39], v[32:33]
	v_pk_mul_f32 v[38:39], v[46:47], v[64:65] op_sel_hi:[1,0]
	v_cvt_pk_bf16_f32 v32, v32, v33
	v_pk_add_f32 v[36:37], v[36:37], 1.0 op_sel_hi:[1,0]
	v_pk_mul_f32 v[34:35], v[34:35], v[38:39]
	v_div_scale_f32 v38, s[4:5], v37, v37, v40
	v_rcp_f32_e32 v39, v38
	s_nop 0
	v_fma_f32 v42, -v38, v39, 1.0
	v_fmac_f32_e32 v39, v42, v39
	v_div_scale_f32 v42, vcc, v40, v37, v40
	v_mul_f32_e32 v43, v42, v39
	v_fma_f32 v44, -v38, v43, v42
	v_fmac_f32_e32 v43, v44, v39
	v_fma_f32 v38, -v38, v43, v42
	v_div_fmas_f32 v38, v38, v39, v43
	v_div_fixup_f32 v37, v38, v37, v40
	v_div_scale_f32 v38, s[4:5], v36, v36, v41
	v_rcp_f32_e32 v39, v38
	s_nop 0
	v_fma_f32 v40, -v38, v39, 1.0
	v_fmac_f32_e32 v39, v40, v39
	v_div_scale_f32 v40, vcc, v41, v36, v41
	v_mul_f32_e32 v42, v40, v39
	v_fma_f32 v43, -v38, v42, v40
	v_fmac_f32_e32 v42, v43, v39
	v_fma_f32 v38, -v38, v42, v40
	v_div_fmas_f32 v38, v38, v39, v42
	v_div_fixup_f32 v36, v38, v36, v41
	v_pk_mul_f32 v[34:35], v[36:37], v[34:35]
	s_nop 0
	v_cvt_pk_bf16_f32 v33, v34, v35
	flat_store_dwordx2 v[48:49], v[32:33] offset:112
	flat_load_dwordx2 v[36:37], v[66:67] offset:128
	s_nop 0
	global_load_dwordx4 v[32:35], v65, s[18:19] offset:256
	s_waitcnt vmcnt(0) lgkmcnt(0)
; DI float bf2f(bfr v) { return __uint_as_float(((unsigned)v) << 16); }
; DI unsigned pk2(float a, float b) { f2_t v = {a, b}; bf2_t r = __builtin_convertvector(v, bf2_t); return __builtin_bit_cast(unsigned, r); }
; DI float siluf_(float x) { return x / (1.f + __expf(-x)); }
; DI void attn_unit(const Params& p, int l, int unit, unsigned char* smem) {
;     ...
; #pragma unroll
;   for (int dvb = 0; dvb < 4; ++dvb)
; #pragma unroll
;     for (int g = 0; g < 4; ++g) {
;       const int dv = 32 * dvb + 8 * g + 4 * h;
;       const s16x4 z4 = *(const s16x4*)(P + rowq * PLD + C_DAZ + hd * 128 + dv);
;       const f32x4 gn = *(const f32x4*)(p.da_norm + l * 128 + dv);
;       float y[4];
;       for (int q = 0; q < 4; ++q) y[q] = oacc[dvb][4 * g + q] * rs * gn[q] * siluf_(bf2f((bfr)z4[q]));
;       u32x2 w; w[0] = pk2(y[0], y[1]); w[1] = pk2(y[2], y[3]);
;       *(u32x2*)(YS + rowq * DM + 1536 + hd * 128 + dv) = w;
;     }
	v_and_b32_e32 v40, 0xffff0000, v36
	v_lshlrev_b32_e32 v36, 16, v36
	v_mul_f32_e32 v38, 0xbfb8aa3b, v36
	v_pk_mul_f32 v[16:17], v[32:33], v[16:17]
	v_mul_f32_e32 v32, 0xbfb8aa3b, v40
	v_exp_f32_e32 v38, v38
	v_exp_f32_e32 v39, v32
	v_pk_mul_f32 v[18:19], v[34:35], v[18:19]
	v_pk_add_f32 v[32:33], v[38:39], 1.0 op_sel_hi:[1,0]
	s_nop 0
	v_div_scale_f32 v38, s[4:5], v33, v33, v40
	v_rcp_f32_e32 v39, v38
	s_nop 0
	v_fma_f32 v41, -v38, v39, 1.0
	v_fmac_f32_e32 v39, v41, v39
	v_div_scale_f32 v41, vcc, v40, v33, v40
	v_mul_f32_e32 v42, v41, v39
	v_fma_f32 v43, -v38, v42, v41
	v_fmac_f32_e32 v42, v43, v39
	v_fma_f32 v38, -v38, v42, v41
	v_div_fmas_f32 v38, v38, v39, v42
	v_div_fixup_f32 v33, v38, v33, v40
	v_div_scale_f32 v38, s[4:5], v32, v32, v36
	v_rcp_f32_e32 v39, v38
	s_nop 0
	v_fma_f32 v40, -v38, v39, 1.0
	v_fmac_f32_e32 v39, v40, v39
	v_div_scale_f32 v40, vcc, v36, v32, v36
	v_mul_f32_e32 v41, v40, v39
	v_fma_f32 v42, -v38, v41, v40
	v_fmac_f32_e32 v41, v42, v39
	v_fma_f32 v38, -v38, v41, v40
	v_div_fmas_f32 v38, v38, v39, v41
	v_div_fixup_f32 v32, v38, v32, v36
	v_and_b32_e32 v36, 0xffff0000, v37
	v_lshlrev_b32_e32 v37, 16, v37
	v_pk_mul_f32 v[16:17], v[32:33], v[16:17]
	v_mul_f32_e32 v32, 0xbfb8aa3b, v37
	v_mul_f32_e32 v33, 0xbfb8aa3b, v36
	v_exp_f32_e32 v32, v32
	v_exp_f32_e32 v33, v33
	v_cvt_pk_bf16_f32 v16, v16, v17
	v_pk_add_f32 v[32:33], v[32:33], 1.0 op_sel_hi:[1,0]
	s_nop 0
	v_div_scale_f32 v34, s[4:5], v33, v33, v36
	v_rcp_f32_e32 v35, v34
	s_nop 0
	v_fma_f32 v38, -v34, v35, 1.0
	v_fmac_f32_e32 v35, v38, v35
	v_div_scale_f32 v38, vcc, v36, v33, v36
	v_mul_f32_e32 v39, v38, v35
	v_fma_f32 v40, -v34, v39, v38
	v_fmac_f32_e32 v39, v40, v35
	v_fma_f32 v34, -v34, v39, v38
	v_div_fmas_f32 v34, v34, v35, v39
	v_div_fixup_f32 v33, v34, v33, v36
	v_div_scale_f32 v34, s[4:5], v32, v32, v37
	v_rcp_f32_e32 v35, v34
	s_nop 0
	v_fma_f32 v36, -v34, v35, 1.0
	v_fmac_f32_e32 v35, v36, v35
	v_div_scale_f32 v36, vcc, v37, v32, v37
	v_mul_f32_e32 v38, v36, v35
	v_fma_f32 v39, -v34, v38, v36
	v_fmac_f32_e32 v38, v39, v35
	v_fma_f32 v34, -v34, v38, v36
	v_div_fmas_f32 v34, v34, v35, v38
	v_div_fixup_f32 v32, v34, v32, v37
	v_pk_mul_f32 v[18:19], v[32:33], v[18:19]
	s_nop 0
	v_cvt_pk_bf16_f32 v17, v18, v19
	flat_store_dwordx2 v[48:49], v[16:17] offset:128
	flat_load_dwordx2 v[32:33], v[66:67] offset:144
	s_nop 0
	global_load_dwordx4 v[16:19], v65, s[18:19] offset:288
	s_waitcnt vmcnt(0) lgkmcnt(0)
	v_and_b32_e32 v36, 0xffff0000, v32
	v_lshlrev_b32_e32 v32, 16, v32
	v_mul_f32_e32 v34, 0xbfb8aa3b, v32
	v_pk_mul_f32 v[16:17], v[16:17], v[20:21]
	v_mul_f32_e32 v20, 0xbfb8aa3b, v36
	v_exp_f32_e32 v34, v34
	v_exp_f32_e32 v35, v20
	v_pk_mul_f32 v[18:19], v[18:19], v[22:23]
	v_pk_add_f32 v[20:21], v[34:35], 1.0 op_sel_hi:[1,0]
	s_nop 0
	v_div_scale_f32 v34, s[4:5], v21, v21, v36
	v_rcp_f32_e32 v35, v34
	s_nop 0
	v_fma_f32 v37, -v34, v35, 1.0
	v_fmac_f32_e32 v35, v37, v35
	v_div_scale_f32 v37, vcc, v36, v21, v36
	v_mul_f32_e32 v38, v37, v35
	v_fma_f32 v39, -v34, v38, v37
	v_fmac_f32_e32 v38, v39, v35
	v_fma_f32 v34, -v34, v38, v37
	v_div_fmas_f32 v34, v34, v35, v38
	v_div_fixup_f32 v21, v34, v21, v36
	v_div_scale_f32 v34, s[4:5], v20, v20, v32
	v_rcp_f32_e32 v35, v34
	s_nop 0
	v_fma_f32 v36, -v34, v35, 1.0
	v_fmac_f32_e32 v35, v36, v35
	v_div_scale_f32 v36, vcc, v32, v20, v32
	v_mul_f32_e32 v37, v36, v35
	v_fma_f32 v38, -v34, v37, v36
	v_fmac_f32_e32 v37, v38, v35
	v_fma_f32 v34, -v34, v37, v36
	v_div_fmas_f32 v34, v34, v35, v37
	v_div_fixup_f32 v20, v34, v20, v32
	v_and_b32_e32 v32, 0xffff0000, v33
	v_lshlrev_b32_e32 v33, 16, v33
	v_pk_mul_f32 v[16:17], v[20:21], v[16:17]
	v_mul_f32_e32 v20, 0xbfb8aa3b, v33
	v_mul_f32_e32 v21, 0xbfb8aa3b, v32
	v_exp_f32_e32 v20, v20
	v_exp_f32_e32 v21, v21
	v_cvt_pk_bf16_f32 v16, v16, v17
	v_pk_add_f32 v[20:21], v[20:21], 1.0 op_sel_hi:[1,0]
	s_nop 0
	v_div_scale_f32 v22, s[4:5], v21, v21, v32
	v_rcp_f32_e32 v23, v22
	s_nop 0
	v_fma_f32 v34, -v22, v23, 1.0
	v_fmac_f32_e32 v23, v34, v23
	v_div_scale_f32 v34, vcc, v32, v21, v32
	v_mul_f32_e32 v35, v34, v23
	v_fma_f32 v36, -v22, v35, v34
	v_fmac_f32_e32 v35, v36, v23
	v_fma_f32 v22, -v22, v35, v34
	v_div_fmas_f32 v22, v22, v23, v35
	v_div_fixup_f32 v21, v22, v21, v32
	v_div_scale_f32 v22, s[4:5], v20, v20, v33
	v_rcp_f32_e32 v23, v22
	s_nop 0
	v_fma_f32 v32, -v22, v23, 1.0
	v_fmac_f32_e32 v23, v32, v23
	v_div_scale_f32 v32, vcc, v33, v20, v33
	v_mul_f32_e32 v34, v32, v23
	v_fma_f32 v35, -v22, v34, v32
	v_fmac_f32_e32 v34, v35, v23
	v_fma_f32 v22, -v22, v34, v32
	v_div_fmas_f32 v22, v22, v23, v34
	v_div_fixup_f32 v20, v22, v20, v33
	v_pk_mul_f32 v[18:19], v[20:21], v[18:19]
	s_nop 0
	v_cvt_pk_bf16_f32 v17, v18, v19
	flat_store_dwordx2 v[48:49], v[16:17] offset:144
	flat_load_dwordx2 v[20:21], v[66:67] offset:160
	s_nop 0
	global_load_dwordx4 v[16:19], v65, s[18:19] offset:320
	s_waitcnt vmcnt(0) lgkmcnt(0)
; DI float bf2f(bfr v) { return __uint_as_float(((unsigned)v) << 16); }
; DI unsigned pk2(float a, float b) { f2_t v = {a, b}; bf2_t r = __builtin_convertvector(v, bf2_t); return __builtin_bit_cast(unsigned, r); }
; DI float siluf_(float x) { return x / (1.f + __expf(-x)); }
; DI void attn_unit(const Params& p, int l, int unit, unsigned char* smem) {
;     ...
; #pragma unroll
;   for (int dvb = 0; dvb < 4; ++dvb)
; #pragma unroll
;     for (int g = 0; g < 4; ++g) {
;       const int dv = 32 * dvb + 8 * g + 4 * h;
;       const s16x4 z4 = *(const s16x4*)(P + rowq * PLD + C_DAZ + hd * 128 + dv);
;       const f32x4 gn = *(const f32x4*)(p.da_norm + l * 128 + dv);
;       float y[4];
;       for (int q = 0; q < 4; ++q) y[q] = oacc[dvb][4 * g + q] * rs * gn[q] * siluf_(bf2f((bfr)z4[q]));
;       u32x2 w; w[0] = pk2(y[0], y[1]); w[1] = pk2(y[2], y[3]);
;       *(u32x2*)(YS + rowq * DM + 1536 + hd * 128 + dv) = w;
;     }
	v_and_b32_e32 v32, 0xffff0000, v20
	v_lshlrev_b32_e32 v20, 16, v20
	v_mul_f32_e32 v22, 0xbfb8aa3b, v20
	v_mul_f32_e32 v23, 0xbfb8aa3b, v32
	v_exp_f32_e32 v22, v22
	v_exp_f32_e32 v23, v23
	v_pk_mul_f32 v[16:17], v[16:17], v[24:25]
	v_pk_add_f32 v[22:23], v[22:23], 1.0 op_sel_hi:[1,0]
	s_nop 0
	v_div_scale_f32 v24, s[4:5], v23, v23, v32
	v_rcp_f32_e32 v25, v24
	s_nop 0
	v_fma_f32 v33, -v24, v25, 1.0
	v_fmac_f32_e32 v25, v33, v25
	v_div_scale_f32 v33, vcc, v32, v23, v32
	v_mul_f32_e32 v34, v33, v25
	v_fma_f32 v35, -v24, v34, v33
	v_fmac_f32_e32 v34, v35, v25
	v_fma_f32 v24, -v24, v34, v33
	v_div_fmas_f32 v24, v24, v25, v34
	v_div_fixup_f32 v23, v24, v23, v32
	v_div_scale_f32 v24, s[4:5], v22, v22, v20
	v_rcp_f32_e32 v25, v24
	s_nop 0
	v_fma_f32 v32, -v24, v25, 1.0
	v_fmac_f32_e32 v25, v32, v25
	v_div_scale_f32 v32, vcc, v20, v22, v20
	v_mul_f32_e32 v33, v32, v25
	v_fma_f32 v34, -v24, v33, v32
	v_fmac_f32_e32 v33, v34, v25
	v_fma_f32 v24, -v24, v33, v32
	v_div_fmas_f32 v24, v24, v25, v33
	v_div_fixup_f32 v22, v24, v22, v20
	v_and_b32_e32 v24, 0xffff0000, v21
	v_lshlrev_b32_e32 v25, 16, v21
	v_mul_f32_e32 v20, 0xbfb8aa3b, v25
	v_mul_f32_e32 v21, 0xbfb8aa3b, v24
	v_exp_f32_e32 v20, v20
	v_exp_f32_e32 v21, v21
	v_pk_mul_f32 v[16:17], v[22:23], v[16:17]
	v_pk_mul_f32 v[22:23], v[26:27], v[64:65] op_sel_hi:[1,0]
	v_cvt_pk_bf16_f32 v16, v16, v17
	v_pk_add_f32 v[20:21], v[20:21], 1.0 op_sel_hi:[1,0]
	v_pk_mul_f32 v[18:19], v[18:19], v[22:23]
	v_div_scale_f32 v22, s[4:5], v21, v21, v24
	v_rcp_f32_e32 v23, v22
	s_nop 0
	v_fma_f32 v26, -v22, v23, 1.0
	v_fmac_f32_e32 v23, v26, v23
	v_div_scale_f32 v26, vcc, v24, v21, v24
	v_mul_f32_e32 v27, v26, v23
	v_fma_f32 v32, -v22, v27, v26
	v_fmac_f32_e32 v27, v32, v23
	v_fma_f32 v22, -v22, v27, v26
	v_div_fmas_f32 v22, v22, v23, v27
	v_div_fixup_f32 v21, v22, v21, v24
	v_div_scale_f32 v22, s[4:5], v20, v20, v25
	v_rcp_f32_e32 v23, v22
	s_nop 0
	v_fma_f32 v24, -v22, v23, 1.0
	v_fmac_f32_e32 v23, v24, v23
	v_div_scale_f32 v24, vcc, v25, v20, v25
	v_mul_f32_e32 v26, v24, v23
	v_fma_f32 v27, -v22, v26, v24
	v_fmac_f32_e32 v26, v27, v23
	v_fma_f32 v22, -v22, v26, v24
	v_div_fmas_f32 v22, v22, v23, v26
	v_div_fixup_f32 v20, v22, v20, v25
	v_pk_mul_f32 v[18:19], v[20:21], v[18:19]
	v_pk_mul_f32 v[24:25], v[28:29], v[64:65] op_sel_hi:[1,0]
	v_cvt_pk_bf16_f32 v17, v18, v19
	flat_store_dwordx2 v[48:49], v[16:17] offset:160
	flat_load_dwordx2 v[20:21], v[66:67] offset:176
	s_nop 0
	global_load_dwordx4 v[16:19], v65, s[18:19] offset:352
	s_waitcnt vmcnt(0) lgkmcnt(0)
	v_and_b32_e32 v26, 0xffff0000, v20
	v_lshlrev_b32_e32 v20, 16, v20
	v_mul_f32_e32 v22, 0xbfb8aa3b, v20
	v_mul_f32_e32 v23, 0xbfb8aa3b, v26
	v_exp_f32_e32 v22, v22
	v_exp_f32_e32 v23, v23
	v_pk_mul_f32 v[16:17], v[16:17], v[24:25]
	v_pk_add_f32 v[22:23], v[22:23], 1.0 op_sel_hi:[1,0]
	s_nop 0
	v_div_scale_f32 v24, s[4:5], v23, v23, v26
	v_rcp_f32_e32 v25, v24
	s_nop 0
	v_fma_f32 v27, -v24, v25, 1.0
	v_fmac_f32_e32 v25, v27, v25
	v_div_scale_f32 v27, vcc, v26, v23, v26
	v_mul_f32_e32 v28, v27, v25
	v_fma_f32 v29, -v24, v28, v27
	v_fmac_f32_e32 v28, v29, v25
	v_fma_f32 v24, -v24, v28, v27
	v_div_fmas_f32 v24, v24, v25, v28
	v_div_fixup_f32 v23, v24, v23, v26
	v_div_scale_f32 v24, s[4:5], v22, v22, v20
	v_rcp_f32_e32 v25, v24
	s_nop 0
	v_fma_f32 v26, -v24, v25, 1.0
	v_fmac_f32_e32 v25, v26, v25
	v_div_scale_f32 v26, vcc, v20, v22, v20
	v_mul_f32_e32 v27, v26, v25
	v_fma_f32 v28, -v24, v27, v26
	v_fmac_f32_e32 v27, v28, v25
	v_fma_f32 v24, -v24, v27, v26
	v_div_fmas_f32 v24, v24, v25, v27
	v_div_fixup_f32 v22, v24, v22, v20
	v_and_b32_e32 v24, 0xffff0000, v21
	v_lshlrev_b32_e32 v25, 16, v21
	v_mul_f32_e32 v20, 0xbfb8aa3b, v25
	v_mul_f32_e32 v21, 0xbfb8aa3b, v24
	v_exp_f32_e32 v20, v20
	v_exp_f32_e32 v21, v21
	v_pk_mul_f32 v[16:17], v[22:23], v[16:17]
	v_pk_mul_f32 v[22:23], v[30:31], v[64:65] op_sel_hi:[1,0]
	v_cvt_pk_bf16_f32 v16, v16, v17
	v_pk_add_f32 v[20:21], v[20:21], 1.0 op_sel_hi:[1,0]
	v_pk_mul_f32 v[18:19], v[18:19], v[22:23]
	v_div_scale_f32 v22, s[4:5], v21, v21, v24
	v_rcp_f32_e32 v23, v22
	s_nop 0
	v_fma_f32 v26, -v22, v23, 1.0
	v_fmac_f32_e32 v23, v26, v23
	v_div_scale_f32 v26, vcc, v24, v21, v24
	v_mul_f32_e32 v27, v26, v23
	v_fma_f32 v28, -v22, v27, v26
	v_fmac_f32_e32 v27, v28, v23
	v_fma_f32 v22, -v22, v27, v26
	v_div_fmas_f32 v22, v22, v23, v27
	v_div_fixup_f32 v21, v22, v21, v24
	v_div_scale_f32 v22, s[4:5], v20, v20, v25
	v_rcp_f32_e32 v23, v22
	s_nop 0
	v_fma_f32 v24, -v22, v23, 1.0
	v_fmac_f32_e32 v23, v24, v23
	v_div_scale_f32 v24, vcc, v25, v20, v25
	v_mul_f32_e32 v26, v24, v23
	v_fma_f32 v27, -v22, v26, v24
	v_fmac_f32_e32 v26, v27, v23
	v_fma_f32 v22, -v22, v26, v24
	v_div_fmas_f32 v22, v22, v23, v26
	v_div_fixup_f32 v20, v22, v20, v25
	v_pk_mul_f32 v[18:19], v[20:21], v[18:19]
	s_nop 0
	v_cvt_pk_bf16_f32 v17, v18, v19
	flat_store_dwordx2 v[48:49], v[16:17] offset:176
	flat_load_dwordx2 v[20:21], v[66:67] offset:192
	s_nop 0
	global_load_dwordx4 v[16:19], v65, s[18:19] offset:384
	s_waitcnt vmcnt(0) lgkmcnt(0)
; DI float bf2f(bfr v) { return __uint_as_float(((unsigned)v) << 16); }
; DI unsigned pk2(float a, float b) { f2_t v = {a, b}; bf2_t r = __builtin_convertvector(v, bf2_t); return __builtin_bit_cast(unsigned, r); }
; DI float siluf_(float x) { return x / (1.f + __expf(-x)); }
; DI void attn_unit(const Params& p, int l, int unit, unsigned char* smem) {
;     ...
; #pragma unroll
;   for (int dvb = 0; dvb < 4; ++dvb)
; #pragma unroll
;     for (int g = 0; g < 4; ++g) {
;       const int dv = 32 * dvb + 8 * g + 4 * h;
;       const s16x4 z4 = *(const s16x4*)(P + rowq * PLD + C_DAZ + hd * 128 + dv);
;       const f32x4 gn = *(const f32x4*)(p.da_norm + l * 128 + dv);
;       float y[4];
;       for (int q = 0; q < 4; ++q) y[q] = oacc[dvb][4 * g + q] * rs * gn[q] * siluf_(bf2f((bfr)z4[q]));
;       u32x2 w; w[0] = pk2(y[0], y[1]); w[1] = pk2(y[2], y[3]);
;       *(u32x2*)(YS + rowq * DM + 1536 + hd * 128 + dv) = w;
;     }
	v_and_b32_e32 v24, 0xffff0000, v20
	v_lshlrev_b32_e32 v20, 16, v20
	v_mul_f32_e32 v22, 0xbfb8aa3b, v20
	v_pk_mul_f32 v[0:1], v[16:17], v[0:1]
	v_mul_f32_e32 v16, 0xbfb8aa3b, v24
	v_exp_f32_e32 v22, v22
	v_exp_f32_e32 v23, v16
	v_pk_mul_f32 v[2:3], v[18:19], v[2:3]
	v_pk_add_f32 v[16:17], v[22:23], 1.0 op_sel_hi:[1,0]
	s_nop 0
	v_div_scale_f32 v22, s[4:5], v17, v17, v24
	v_rcp_f32_e32 v23, v22
	s_nop 0
	v_fma_f32 v25, -v22, v23, 1.0
	v_fmac_f32_e32 v23, v25, v23
	v_div_scale_f32 v25, vcc, v24, v17, v24
	v_mul_f32_e32 v26, v25, v23
	v_fma_f32 v27, -v22, v26, v25
	v_fmac_f32_e32 v26, v27, v23
	v_fma_f32 v22, -v22, v26, v25
	v_div_fmas_f32 v22, v22, v23, v26
	v_div_fixup_f32 v17, v22, v17, v24
	v_div_scale_f32 v22, s[4:5], v16, v16, v20
	v_rcp_f32_e32 v23, v22
	s_nop 0
	v_fma_f32 v24, -v22, v23, 1.0
	v_fmac_f32_e32 v23, v24, v23
	v_div_scale_f32 v24, vcc, v20, v16, v20
	v_mul_f32_e32 v25, v24, v23
	v_fma_f32 v26, -v22, v25, v24
	v_fmac_f32_e32 v25, v26, v23
	v_fma_f32 v22, -v22, v25, v24
	v_div_fmas_f32 v22, v22, v23, v25
	v_div_fixup_f32 v16, v22, v16, v20
	v_and_b32_e32 v20, 0xffff0000, v21
	v_lshlrev_b32_e32 v21, 16, v21
	v_pk_mul_f32 v[0:1], v[16:17], v[0:1]
	v_mul_f32_e32 v16, 0xbfb8aa3b, v21
	v_mul_f32_e32 v17, 0xbfb8aa3b, v20
	v_exp_f32_e32 v16, v16
	v_exp_f32_e32 v17, v17
	v_cvt_pk_bf16_f32 v0, v0, v1
	v_pk_add_f32 v[16:17], v[16:17], 1.0 op_sel_hi:[1,0]
	s_nop 0
	v_div_scale_f32 v18, s[4:5], v17, v17, v20
	v_rcp_f32_e32 v19, v18
	s_nop 0
	v_fma_f32 v22, -v18, v19, 1.0
	v_fmac_f32_e32 v19, v22, v19
	v_div_scale_f32 v22, vcc, v20, v17, v20
	v_mul_f32_e32 v23, v22, v19
	v_fma_f32 v24, -v18, v23, v22
	v_fmac_f32_e32 v23, v24, v19
	v_fma_f32 v18, -v18, v23, v22
	v_div_fmas_f32 v18, v18, v19, v23
	v_div_fixup_f32 v17, v18, v17, v20
	v_div_scale_f32 v18, s[4:5], v16, v16, v21
	v_rcp_f32_e32 v19, v18
	s_nop 0
	v_fma_f32 v20, -v18, v19, 1.0
	v_fmac_f32_e32 v19, v20, v19
	v_div_scale_f32 v20, vcc, v21, v16, v21
	v_mul_f32_e32 v22, v20, v19
	v_fma_f32 v23, -v18, v22, v20
	v_fmac_f32_e32 v22, v23, v19
	v_fma_f32 v18, -v18, v22, v20
	v_div_fmas_f32 v18, v18, v19, v22
	v_div_fixup_f32 v16, v18, v16, v21
	v_pk_mul_f32 v[2:3], v[16:17], v[2:3]
	s_nop 0
	v_cvt_pk_bf16_f32 v1, v2, v3
	flat_store_dwordx2 v[48:49], v[0:1] offset:192
	flat_load_dwordx2 v[16:17], v[66:67] offset:208
	s_nop 0
	global_load_dwordx4 v[0:3], v65, s[18:19] offset:416
	s_waitcnt vmcnt(0) lgkmcnt(0)
	v_and_b32_e32 v20, 0xffff0000, v16
	v_lshlrev_b32_e32 v16, 16, v16
	v_mul_f32_e32 v18, 0xbfb8aa3b, v16
	v_pk_mul_f32 v[0:1], v[0:1], v[4:5]
	v_mul_f32_e32 v4, 0xbfb8aa3b, v20
	v_exp_f32_e32 v18, v18
	v_exp_f32_e32 v19, v4
	v_pk_mul_f32 v[2:3], v[2:3], v[6:7]
	v_pk_add_f32 v[4:5], v[18:19], 1.0 op_sel_hi:[1,0]
	s_nop 0
	v_div_scale_f32 v18, s[4:5], v5, v5, v20
	v_rcp_f32_e32 v19, v18
	s_nop 0
	v_fma_f32 v21, -v18, v19, 1.0
	v_fmac_f32_e32 v19, v21, v19
	v_div_scale_f32 v21, vcc, v20, v5, v20
	v_mul_f32_e32 v22, v21, v19
	v_fma_f32 v23, -v18, v22, v21
	v_fmac_f32_e32 v22, v23, v19
	v_fma_f32 v18, -v18, v22, v21
	v_div_fmas_f32 v18, v18, v19, v22
	v_div_fixup_f32 v5, v18, v5, v20
	v_div_scale_f32 v18, s[4:5], v4, v4, v16
	v_rcp_f32_e32 v19, v18
	s_nop 0
	v_fma_f32 v20, -v18, v19, 1.0
	v_fmac_f32_e32 v19, v20, v19
	v_div_scale_f32 v20, vcc, v16, v4, v16
	v_mul_f32_e32 v21, v20, v19
	v_fma_f32 v22, -v18, v21, v20
	v_fmac_f32_e32 v21, v22, v19
	v_fma_f32 v18, -v18, v21, v20
	v_div_fmas_f32 v18, v18, v19, v21
	v_div_fixup_f32 v4, v18, v4, v16
	v_and_b32_e32 v16, 0xffff0000, v17
	v_lshlrev_b32_e32 v17, 16, v17
	v_pk_mul_f32 v[0:1], v[4:5], v[0:1]
	v_mul_f32_e32 v4, 0xbfb8aa3b, v17
	v_mul_f32_e32 v5, 0xbfb8aa3b, v16
	v_exp_f32_e32 v4, v4
	v_exp_f32_e32 v5, v5
	v_cvt_pk_bf16_f32 v0, v0, v1
	v_pk_add_f32 v[4:5], v[4:5], 1.0 op_sel_hi:[1,0]
	s_nop 0
	v_div_scale_f32 v6, s[4:5], v5, v5, v16
	v_rcp_f32_e32 v7, v6
	s_nop 0
	v_fma_f32 v18, -v6, v7, 1.0
	v_fmac_f32_e32 v7, v18, v7
	v_div_scale_f32 v18, vcc, v16, v5, v16
	v_mul_f32_e32 v19, v18, v7
	v_fma_f32 v20, -v6, v19, v18
	v_fmac_f32_e32 v19, v20, v7
	v_fma_f32 v6, -v6, v19, v18
	v_div_fmas_f32 v6, v6, v7, v19
	v_div_fixup_f32 v5, v6, v5, v16
	v_div_scale_f32 v6, s[4:5], v4, v4, v17
	v_rcp_f32_e32 v7, v6
	s_nop 0
	v_fma_f32 v16, -v6, v7, 1.0
	v_fmac_f32_e32 v7, v16, v7
	v_div_scale_f32 v16, vcc, v17, v4, v17
	v_mul_f32_e32 v18, v16, v7
	v_fma_f32 v19, -v6, v18, v16
	v_fmac_f32_e32 v18, v19, v7
	v_fma_f32 v6, -v6, v18, v16
	v_div_fmas_f32 v6, v6, v7, v18
	v_div_fixup_f32 v4, v6, v4, v17
	v_pk_mul_f32 v[2:3], v[4:5], v[2:3]
	s_nop 0
	v_cvt_pk_bf16_f32 v1, v2, v3
	flat_store_dwordx2 v[48:49], v[0:1] offset:208
	flat_load_dwordx2 v[4:5], v[66:67] offset:224
	s_nop 0
	global_load_dwordx4 v[0:3], v65, s[18:19] offset:448
	s_waitcnt vmcnt(0) lgkmcnt(0)
; DI float bf2f(bfr v) { return __uint_as_float(((unsigned)v) << 16); }
; DI unsigned pk2(float a, float b) { f2_t v = {a, b}; bf2_t r = __builtin_convertvector(v, bf2_t); return __builtin_bit_cast(unsigned, r); }
; DI float siluf_(float x) { return x / (1.f + __expf(-x)); }
; DI void attn_unit(const Params& p, int l, int unit, unsigned char* smem) {
;     ...
; #pragma unroll
;   for (int dvb = 0; dvb < 4; ++dvb)
; #pragma unroll
;     for (int g = 0; g < 4; ++g) {
;       const int dv = 32 * dvb + 8 * g + 4 * h;
;       const s16x4 z4 = *(const s16x4*)(P + rowq * PLD + C_DAZ + hd * 128 + dv);
;       const f32x4 gn = *(const f32x4*)(p.da_norm + l * 128 + dv);
;       float y[4];
;       for (int q = 0; q < 4; ++q) y[q] = oacc[dvb][4 * g + q] * rs * gn[q] * siluf_(bf2f((bfr)z4[q]));
;       u32x2 w; w[0] = pk2(y[0], y[1]); w[1] = pk2(y[2], y[3]);
;       *(u32x2*)(YS + rowq * DM + 1536 + hd * 128 + dv) = w;
;     }
	v_and_b32_e32 v16, 0xffff0000, v4
	v_lshlrev_b32_e32 v4, 16, v4
	v_mul_f32_e32 v6, 0xbfb8aa3b, v4
	v_mul_f32_e32 v7, 0xbfb8aa3b, v16
	v_exp_f32_e32 v6, v6
	v_exp_f32_e32 v7, v7
	v_pk_mul_f32 v[0:1], v[0:1], v[8:9]
	v_pk_add_f32 v[6:7], v[6:7], 1.0 op_sel_hi:[1,0]
	s_nop 0
	v_div_scale_f32 v8, s[4:5], v7, v7, v16
	v_rcp_f32_e32 v9, v8
	s_nop 0
	v_fma_f32 v17, -v8, v9, 1.0
	v_fmac_f32_e32 v9, v17, v9
	v_div_scale_f32 v17, vcc, v16, v7, v16
	v_mul_f32_e32 v18, v17, v9
	v_fma_f32 v19, -v8, v18, v17
	v_fmac_f32_e32 v18, v19, v9
	v_fma_f32 v8, -v8, v18, v17
	v_div_fmas_f32 v8, v8, v9, v18
	v_div_fixup_f32 v7, v8, v7, v16
	v_div_scale_f32 v8, s[4:5], v6, v6, v4
	v_rcp_f32_e32 v9, v8
	s_nop 0
	v_fma_f32 v16, -v8, v9, 1.0
	v_fmac_f32_e32 v9, v16, v9
	v_div_scale_f32 v16, vcc, v4, v6, v4
	v_mul_f32_e32 v17, v16, v9
	v_fma_f32 v18, -v8, v17, v16
	v_fmac_f32_e32 v17, v18, v9
	v_fma_f32 v8, -v8, v17, v16
	v_div_fmas_f32 v8, v8, v9, v17
	v_div_fixup_f32 v6, v8, v6, v4
	v_and_b32_e32 v8, 0xffff0000, v5
	v_lshlrev_b32_e32 v9, 16, v5
	v_mul_f32_e32 v4, 0xbfb8aa3b, v9
	v_mul_f32_e32 v5, 0xbfb8aa3b, v8
	v_exp_f32_e32 v4, v4
	v_exp_f32_e32 v5, v5
	v_pk_mul_f32 v[0:1], v[6:7], v[0:1]
	v_pk_mul_f32 v[6:7], v[10:11], v[64:65] op_sel_hi:[1,0]
	v_cvt_pk_bf16_f32 v0, v0, v1
	v_pk_add_f32 v[4:5], v[4:5], 1.0 op_sel_hi:[1,0]
	v_pk_mul_f32 v[2:3], v[2:3], v[6:7]
	v_div_scale_f32 v6, s[4:5], v5, v5, v8
	v_rcp_f32_e32 v7, v6
	s_nop 0
	v_fma_f32 v10, -v6, v7, 1.0
	v_fmac_f32_e32 v7, v10, v7
	v_div_scale_f32 v10, vcc, v8, v5, v8
	v_mul_f32_e32 v11, v10, v7
	v_fma_f32 v16, -v6, v11, v10
	v_fmac_f32_e32 v11, v16, v7
	v_fma_f32 v6, -v6, v11, v10
	v_div_fmas_f32 v6, v6, v7, v11
	v_div_fixup_f32 v5, v6, v5, v8
	v_div_scale_f32 v6, s[4:5], v4, v4, v9
	v_rcp_f32_e32 v7, v6
	s_nop 0
	v_fma_f32 v8, -v6, v7, 1.0
	v_fmac_f32_e32 v7, v8, v7
	v_div_scale_f32 v8, vcc, v9, v4, v9
	v_mul_f32_e32 v10, v8, v7
	v_fma_f32 v11, -v6, v10, v8
	v_fmac_f32_e32 v10, v11, v7
	v_fma_f32 v6, -v6, v10, v8
	v_div_fmas_f32 v6, v6, v7, v10
	v_div_fixup_f32 v4, v6, v4, v9
	v_pk_mul_f32 v[2:3], v[4:5], v[2:3]
	v_pk_mul_f32 v[8:9], v[12:13], v[64:65] op_sel_hi:[1,0]
	v_cvt_pk_bf16_f32 v1, v2, v3
	flat_store_dwordx2 v[48:49], v[0:1] offset:224
	flat_load_dwordx2 v[0:1], v[66:67] offset:240
	s_nop 0
	global_load_dwordx4 v[2:5], v65, s[18:19] offset:480
	s_waitcnt vmcnt(0) lgkmcnt(0)
	v_and_b32_e32 v10, 0xffff0000, v0
	v_lshlrev_b32_e32 v0, 16, v0
	v_mul_f32_e32 v6, 0xbfb8aa3b, v0
	v_mul_f32_e32 v7, 0xbfb8aa3b, v10
	v_exp_f32_e32 v6, v6
	v_exp_f32_e32 v7, v7
	v_pk_mul_f32 v[2:3], v[2:3], v[8:9]
	v_pk_add_f32 v[6:7], v[6:7], 1.0 op_sel_hi:[1,0]
	s_nop 0
	v_div_scale_f32 v8, s[4:5], v7, v7, v10
	v_rcp_f32_e32 v9, v8
	s_nop 0
	v_fma_f32 v11, -v8, v9, 1.0
	v_fmac_f32_e32 v9, v11, v9
	v_div_scale_f32 v11, vcc, v10, v7, v10
	v_mul_f32_e32 v12, v11, v9
	v_fma_f32 v13, -v8, v12, v11
	v_fmac_f32_e32 v12, v13, v9
	v_fma_f32 v8, -v8, v12, v11
	v_div_fmas_f32 v8, v8, v9, v12
	v_div_fixup_f32 v7, v8, v7, v10
	v_div_scale_f32 v8, s[4:5], v6, v6, v0
	v_rcp_f32_e32 v9, v8
	s_nop 0
	v_fma_f32 v10, -v8, v9, 1.0
	v_fmac_f32_e32 v9, v10, v9
	v_div_scale_f32 v10, vcc, v0, v6, v0
	v_mul_f32_e32 v11, v10, v9
	v_fma_f32 v12, -v8, v11, v10
	v_fmac_f32_e32 v11, v12, v9
	v_fma_f32 v8, -v8, v11, v10
	v_div_fmas_f32 v8, v8, v9, v11
	v_div_fixup_f32 v6, v8, v6, v0
	v_and_b32_e32 v8, 0xffff0000, v1
	v_lshlrev_b32_e32 v9, 16, v1
	v_mul_f32_e32 v0, 0xbfb8aa3b, v9
	v_mul_f32_e32 v1, 0xbfb8aa3b, v8
	v_exp_f32_e32 v0, v0
	v_exp_f32_e32 v1, v1
	v_pk_mul_f32 v[2:3], v[6:7], v[2:3]
	v_pk_mul_f32 v[6:7], v[14:15], v[64:65] op_sel_hi:[1,0]
	v_cvt_pk_bf16_f32 v2, v2, v3
	v_pk_add_f32 v[0:1], v[0:1], 1.0 op_sel_hi:[1,0]
	v_pk_mul_f32 v[4:5], v[4:5], v[6:7]
	v_div_scale_f32 v6, s[4:5], v1, v1, v8
	v_rcp_f32_e32 v7, v6
	s_nop 0
	v_fma_f32 v10, -v6, v7, 1.0
	v_fmac_f32_e32 v7, v10, v7
	v_div_scale_f32 v10, vcc, v8, v1, v8
	v_mul_f32_e32 v11, v10, v7
	v_fma_f32 v12, -v6, v11, v10
	v_fmac_f32_e32 v11, v12, v7
	v_fma_f32 v6, -v6, v11, v10
	v_div_fmas_f32 v6, v6, v7, v11
	v_div_fixup_f32 v1, v6, v1, v8
	v_div_scale_f32 v6, s[4:5], v0, v0, v9
	v_rcp_f32_e32 v7, v6
	s_nop 0
	v_fma_f32 v8, -v6, v7, 1.0
	v_fmac_f32_e32 v7, v8, v7
	v_div_scale_f32 v8, vcc, v9, v0, v9
	v_mul_f32_e32 v10, v8, v7
	v_fma_f32 v11, -v6, v10, v8
	v_fmac_f32_e32 v10, v11, v7
	v_fma_f32 v6, -v6, v10, v8
	v_div_fmas_f32 v6, v6, v7, v10
	v_div_fixup_f32 v0, v6, v0, v9
	v_pk_mul_f32 v[0:1], v[0:1], v[4:5]
	s_nop 0
	v_cvt_pk_bf16_f32 v3, v0, v1
	flat_store_dwordx2 v[48:49], v[2:3] offset:240
	s_branch .LBB0_309

; #define MFMA(a, b, c) __builtin_amdgcn_mfma_f32_32x32x16_bf16((a), (b), (c), 0, 0, 0)
; DI f32x16 zero16() { f32x16 z; for (int i = 0; i < 16; ++i) z[i] = 0.f; return z; }
; DI void attn_unit(const Params& p, int l, int unit, unsigned char* smem) {
;     ...
;   for (int kt = 0; kt < ntile; ++kt) {
;     __syncthreads();
; #pragma unroll
;     for (int i = 0; i < 4; ++i) { const int c = tid + 256 * i, key = c >> 4, kc = c & 15; *(u32x4*)(sK + key * 136 + 8 * kc) = rk[i]; }
;     __syncthreads();
;     if (kt + 1 < ntile) {
; #pragma unroll
;       for (int i = 0; i < 4; ++i) { const int c = tid + 256 * i, key = c >> 4, kc = c & 15; rk[i] = *(const u32x4*)(Kbase + (size_t)((kt + 1) * 64 + key) * PLD + 8 * kc); }
;     }
; #pragma unroll
;     for (int kb = 0; kb < 2; ++kb)
; #pragma unroll
;       for (int mp = 0; mp < 2; ++mp) {
;         f32x16 st = zero16();
; #pragma unroll
;         for (int s = 0; s < 4; ++s) st = MFMA(ld16(sK + (32 * kb + l31) * 136 + mp * 64 + 16 * s + 8 * h), qf[mp][s], st);
;         float tm = st[0];
; #pragma unroll
;         for (int r = 1; r < 16; ++r) tm = fmaxf(tm, st[r]);
;         const float mn = fmaxf(mx[mp], tm);
;         const float nmc = -mn * cs;
;         float sum = 0.f;
; #pragma unroll
;         for (int r = 0; r < 16; ++r) sum += __builtin_amdgcn_exp2f(fmaf(st[r], cs, nmc));
;         ls[mp] = ls[mp] * __builtin_amdgcn_exp2f((mx[mp] - mn) * cs) + sum;
;         mx[mp] = mn;
;       }
;   }
.LBB0_522:
	v_lshl_add_u64 v[0:1], v[56:57], 0, s[20:21]
	s_waitcnt lgkmcnt(0)
	s_barrier
	s_waitcnt vmcnt(0)
	ds_write_b128 v187, v[16:19]
	ds_write_b128 v186, v[20:23]
	ds_write_b128 v185, v[24:27]
	ds_write_b128 v184, v[28:31]
	s_waitcnt lgkmcnt(0)
	s_barrier
	global_load_dwordx4 v[16:19], v[0:1], off
	v_lshl_add_u64 v[0:1], v[54:55], 0, s[20:21]
	global_load_dwordx4 v[20:23], v[0:1], off
	v_lshl_add_u64 v[0:1], v[52:53], 0, s[20:21]
	global_load_dwordx4 v[24:27], v[0:1], off
	v_lshl_add_u64 v[0:1], v[50:51], 0, s[20:21]
	global_load_dwordx4 v[28:31], v[0:1], off
	ds_read_b128 v[212:215], v149
	ds_read_b128 v[224:227], v149 offset:32
	ds_read_b128 v[228:231], v149 offset:64
	ds_read_b128 v[236:239], v149 offset:96
	ds_read_b128 v[246:249], v149 offset:128
	s_waitcnt lgkmcnt(4)
	v_mfma_f32_32x32x16_bf16 v[0:15], v[212:215], v[120:123], 0
	s_add_u32 s20, s20, 0x200000
	s_addc_u32 s21, s21, 0
	s_cmp_eq_u32 s20, 0x8600000
	ds_read_b128 v[250:253], v149 offset:160
	s_waitcnt lgkmcnt(4)
	v_mfma_f32_32x32x16_bf16 v[0:15], v[224:227], v[116:119], v[0:15]
	ds_read_b128 v[212:215], v149 offset:192
	s_waitcnt lgkmcnt(4)
	v_mfma_f32_32x32x16_bf16 v[0:15], v[228:231], v[104:107], v[0:15]
	ds_read_b128 v[224:227], v149 offset:224
	s_waitcnt lgkmcnt(4)
	v_mfma_f32_32x32x16_bf16 v[0:15], v[236:239], v[100:103], v[0:15]
	s_nop 11
	v_max3_f32 v58, v0, v1, v2
	v_max3_f32 v58, v58, v3, v4
	v_max3_f32 v58, v58, v5, v6
	v_max3_f32 v58, v58, v7, v8
	v_max3_f32 v58, v58, v9, v10
	v_max3_f32 v58, v58, v11, v12
	v_max3_f32 v58, v58, v13, v14
	v_max3_f32 v93, v151, v58, v15
	v_mul_f32_e32 v58, 0xbe38aa3b, v93
	v_fmamk_f32 v0, v0, 0x3e38aa3b, v58
	v_exp_f32_e32 v76, v0
	v_fmamk_f32 v0, v1, 0x3e38aa3b, v58
	v_exp_f32_e32 v78, v0
	v_fmamk_f32 v0, v2, 0x3e38aa3b, v58
	v_exp_f32_e32 v80, v0
	v_fmamk_f32 v0, v3, 0x3e38aa3b, v58
	v_exp_f32_e32 v82, v0
	v_fmamk_f32 v0, v4, 0x3e38aa3b, v58
	v_exp_f32_e32 v84, v0
	v_fmamk_f32 v0, v5, 0x3e38aa3b, v58
	v_exp_f32_e32 v86, v0
	v_fmamk_f32 v0, v6, 0x3e38aa3b, v58
	v_exp_f32_e32 v88, v0
	v_fmamk_f32 v0, v7, 0x3e38aa3b, v58
	v_exp_f32_e32 v90, v0
	v_fmamk_f32 v0, v8, 0x3e38aa3b, v58
	v_exp_f32_e32 v74, v0
	v_fmamk_f32 v0, v9, 0x3e38aa3b, v58
	v_exp_f32_e32 v72, v0
	v_fmamk_f32 v0, v10, 0x3e38aa3b, v58
	v_exp_f32_e32 v70, v0
	v_fmamk_f32 v0, v11, 0x3e38aa3b, v58
	v_exp_f32_e32 v68, v0
	v_fmamk_f32 v0, v12, 0x3e38aa3b, v58
	v_exp_f32_e32 v66, v0
	v_fmamk_f32 v0, v13, 0x3e38aa3b, v58
	v_exp_f32_e32 v64, v0
	v_fmamk_f32 v0, v14, 0x3e38aa3b, v58
	v_exp_f32_e32 v62, v0
	v_sub_f32_e32 v0, v151, v93
	v_fmac_f32_e32 v58, 0x3e38aa3b, v15
	v_mul_f32_e32 v0, 0x3e38aa3b, v0
	v_exp_f32_e32 v60, v58
	v_exp_f32_e32 v58, v0
	ds_read_b128 v[228:231], v149 offset:8704
	s_waitcnt lgkmcnt(4)
	v_mfma_f32_32x32x16_bf16 v[0:15], v[246:249], v[124:127], 0
	ds_read_b128 v[236:239], v149 offset:8736
	s_waitcnt lgkmcnt(4)
	v_mfma_f32_32x32x16_bf16 v[0:15], v[250:253], v[112:115], v[0:15]
	ds_read_b128 v[246:249], v149 offset:8768
	s_waitcnt lgkmcnt(4)
	v_mfma_f32_32x32x16_bf16 v[0:15], v[212:215], v[108:111], v[0:15]
	ds_read_b128 v[250:253], v149 offset:8800
	s_waitcnt lgkmcnt(4)
	v_mfma_f32_32x32x16_bf16 v[0:15], v[224:227], v[96:99], v[0:15]
	s_nop 11
	v_max3_f32 v59, v0, v1, v2
	v_max3_f32 v59, v59, v3, v4
	v_max3_f32 v59, v59, v5, v6
	v_max3_f32 v59, v59, v7, v8
	v_max3_f32 v59, v59, v9, v10
	v_max3_f32 v59, v59, v11, v12
	v_max3_f32 v59, v59, v13, v14
	v_max3_f32 v152, v150, v59, v15
	v_mul_f32_e32 v59, 0xbe38aa3b, v152
	v_fmamk_f32 v0, v0, 0x3e38aa3b, v59
	v_exp_f32_e32 v77, v0
	v_fmamk_f32 v0, v1, 0x3e38aa3b, v59
	v_exp_f32_e32 v79, v0
	v_fmamk_f32 v0, v2, 0x3e38aa3b, v59
	v_exp_f32_e32 v81, v0
	v_fmamk_f32 v0, v3, 0x3e38aa3b, v59
	v_exp_f32_e32 v83, v0
	v_fmamk_f32 v0, v4, 0x3e38aa3b, v59
	v_exp_f32_e32 v85, v0
	v_fmamk_f32 v0, v5, 0x3e38aa3b, v59
	v_exp_f32_e32 v87, v0
	v_fmamk_f32 v0, v6, 0x3e38aa3b, v59
	v_exp_f32_e32 v89, v0
	v_fmamk_f32 v0, v7, 0x3e38aa3b, v59
	v_exp_f32_e32 v91, v0
	v_pk_add_f32 v[0:1], v[76:77], 0 op_sel_hi:[1,0]
	s_nop 0
	v_pk_add_f32 v[0:1], v[78:79], v[0:1]
	s_nop 0
	v_pk_add_f32 v[0:1], v[80:81], v[0:1]
	v_pk_add_f32 v[0:1], v[82:83], v[0:1]
	s_nop 0
	v_pk_add_f32 v[0:1], v[84:85], v[0:1]
	s_nop 0
	v_pk_add_f32 v[0:1], v[86:87], v[0:1]
	s_nop 0
	v_pk_add_f32 v[0:1], v[88:89], v[0:1]
	s_nop 0
	v_pk_add_f32 v[76:77], v[90:91], v[0:1]
	v_fmamk_f32 v0, v8, 0x3e38aa3b, v59
	v_exp_f32_e32 v75, v0
	v_fmamk_f32 v0, v9, 0x3e38aa3b, v59
	v_exp_f32_e32 v73, v0
	v_fmamk_f32 v0, v10, 0x3e38aa3b, v59
	v_exp_f32_e32 v71, v0
	v_fmamk_f32 v0, v11, 0x3e38aa3b, v59
	v_exp_f32_e32 v69, v0
	v_fmamk_f32 v0, v12, 0x3e38aa3b, v59
	v_exp_f32_e32 v67, v0
	v_fmamk_f32 v0, v13, 0x3e38aa3b, v59
	v_exp_f32_e32 v65, v0
	v_fmamk_f32 v0, v14, 0x3e38aa3b, v59
	v_exp_f32_e32 v63, v0
	v_sub_f32_e32 v0, v150, v152
	v_fmac_f32_e32 v59, 0x3e38aa3b, v15
	v_mul_f32_e32 v0, 0x3e38aa3b, v0
	v_exp_f32_e32 v61, v59
	v_exp_f32_e32 v59, v0
	ds_read_b128 v[212:215], v149 offset:8832
	s_waitcnt lgkmcnt(4)
	v_mfma_f32_32x32x16_bf16 v[0:15], v[228:231], v[120:123], 0
	ds_read_b128 v[224:227], v149 offset:8864
	s_waitcnt lgkmcnt(4)
	v_mfma_f32_32x32x16_bf16 v[0:15], v[236:239], v[116:119], v[0:15]
	ds_read_b128 v[228:231], v149 offset:8896
	s_waitcnt lgkmcnt(4)
	v_mfma_f32_32x32x16_bf16 v[0:15], v[246:249], v[104:107], v[0:15]
	ds_read_b128 v[236:239], v149 offset:8928
	s_waitcnt lgkmcnt(4)
; #define MFMA(a, b, c) __builtin_amdgcn_mfma_f32_32x32x16_bf16((a), (b), (c), 0, 0, 0)
; DI f32x16 zero16() { f32x16 z; for (int i = 0; i < 16; ++i) z[i] = 0.f; return z; }
; DI void attn_unit(const Params& p, int l, int unit, unsigned char* smem) {
;     ...
;     __syncthreads();
; #pragma unroll
;     for (int i = 0; i < 4; ++i) { const int c = tid + 256 * i, key = c >> 4, kc = c & 15; *(u32x4*)(sK + key * 136 + 8 * kc) = rk[i]; }
;     __syncthreads();
;     ...
;       for (int mp = 0; mp < 2; ++mp) {
;         f32x16 st = zero16();
; #pragma unroll
;         for (int s = 0; s < 4; ++s) st = MFMA(ld16(sK + (32 * kb + l31) * 136 + mp * 64 + 16 * s + 8 * h), qf[mp][s], st);
;         float tm = st[0];
; #pragma unroll
;         for (int r = 1; r < 16; ++r) tm = fmaxf(tm, st[r]);
;         const float mn = fmaxf(mx[mp], tm);
;         const float nmc = -mn * cs;
;         float sum = 0.f;
; #pragma unroll
;         for (int r = 0; r < 16; ++r) sum += __builtin_amdgcn_exp2f(fmaf(st[r], cs, nmc));
;         ls[mp] = ls[mp] * __builtin_amdgcn_exp2f((mx[mp] - mn) * cs) + sum;
;         mx[mp] = mn;
;       }
;   }
	v_mfma_f32_32x32x16_bf16 v[0:15], v[250:253], v[100:103], v[0:15]
	s_nop 11
	v_max3_f32 v78, v0, v1, v2
	v_max3_f32 v78, v78, v3, v4
	v_max3_f32 v78, v78, v5, v6
	v_max3_f32 v78, v78, v7, v8
	v_max3_f32 v78, v78, v9, v10
	v_max3_f32 v78, v78, v11, v12
	v_max3_f32 v78, v78, v13, v14
	v_max3_f32 v151, v93, v78, v15
	v_mul_f32_e32 v78, 0xbe38aa3b, v151
	v_fmamk_f32 v0, v0, 0x3e38aa3b, v78
	v_exp_f32_e32 v142, v0
	v_fmamk_f32 v0, v1, 0x3e38aa3b, v78
	v_exp_f32_e32 v140, v0
	v_fmamk_f32 v0, v2, 0x3e38aa3b, v78
	v_exp_f32_e32 v138, v0
	v_fmamk_f32 v0, v3, 0x3e38aa3b, v78
	v_exp_f32_e32 v136, v0
	v_fmamk_f32 v0, v4, 0x3e38aa3b, v78
	v_exp_f32_e32 v134, v0
	v_fmamk_f32 v0, v5, 0x3e38aa3b, v78
	v_exp_f32_e32 v132, v0
	v_fmamk_f32 v0, v6, 0x3e38aa3b, v78
	v_exp_f32_e32 v130, v0
	v_fmamk_f32 v0, v7, 0x3e38aa3b, v78
	v_exp_f32_e32 v128, v0
	v_fmamk_f32 v0, v8, 0x3e38aa3b, v78
	v_exp_f32_e32 v94, v0
	v_fmamk_f32 v0, v9, 0x3e38aa3b, v78
	v_exp_f32_e32 v92, v0
	v_fmamk_f32 v0, v10, 0x3e38aa3b, v78
	v_exp_f32_e32 v90, v0
	v_fmamk_f32 v0, v11, 0x3e38aa3b, v78
	v_exp_f32_e32 v88, v0
	v_fmamk_f32 v0, v12, 0x3e38aa3b, v78
	v_exp_f32_e32 v86, v0
	v_fmamk_f32 v0, v13, 0x3e38aa3b, v78
	v_exp_f32_e32 v84, v0
	v_fmamk_f32 v0, v14, 0x3e38aa3b, v78
	v_exp_f32_e32 v80, v0
	v_sub_f32_e32 v0, v93, v151
	v_mul_f32_e32 v0, 0x3e38aa3b, v0
	v_exp_f32_e32 v82, v0
	v_fmac_f32_e32 v78, 0x3e38aa3b, v15
	s_waitcnt lgkmcnt(3)
	v_mfma_f32_32x32x16_bf16 v[0:15], v[212:215], v[124:127], 0
	v_exp_f32_e32 v78, v78
	s_waitcnt lgkmcnt(2)
	v_mfma_f32_32x32x16_bf16 v[0:15], v[224:227], v[112:115], v[0:15]
	s_waitcnt lgkmcnt(1)
	v_mfma_f32_32x32x16_bf16 v[0:15], v[228:231], v[108:111], v[0:15]
	s_waitcnt lgkmcnt(0)
	v_mfma_f32_32x32x16_bf16 v[0:15], v[236:239], v[96:99], v[0:15]
	s_nop 11
	v_max3_f32 v79, v0, v1, v2
	v_max3_f32 v79, v79, v3, v4
	v_max3_f32 v79, v79, v5, v6
	v_max3_f32 v79, v79, v7, v8
	v_max3_f32 v79, v79, v9, v10
	v_max3_f32 v79, v79, v11, v12
	v_max3_f32 v79, v79, v13, v14
	v_max3_f32 v150, v152, v79, v15
	v_mul_f32_e32 v79, 0xbe38aa3b, v150
	v_fmamk_f32 v0, v0, 0x3e38aa3b, v79
	v_exp_f32_e32 v143, v0
	v_fmamk_f32 v0, v1, 0x3e38aa3b, v79
	v_exp_f32_e32 v141, v0
	v_fmamk_f32 v0, v2, 0x3e38aa3b, v79
	v_fmamk_f32 v2, v6, 0x3e38aa3b, v79
	v_exp_f32_e32 v139, v0
	v_fmamk_f32 v0, v3, 0x3e38aa3b, v79
	v_exp_f32_e32 v131, v2
	v_fmamk_f32 v2, v7, 0x3e38aa3b, v79
	v_exp_f32_e32 v137, v0
	v_fmamk_f32 v0, v4, 0x3e38aa3b, v79
	v_exp_f32_e32 v129, v2
	v_fmamk_f32 v2, v8, 0x3e38aa3b, v79
	v_exp_f32_e32 v135, v0
	v_fmamk_f32 v0, v5, 0x3e38aa3b, v79
	v_exp_f32_e32 v95, v2
	v_fmamk_f32 v2, v9, 0x3e38aa3b, v79
	v_exp_f32_e32 v133, v0
	v_pk_add_f32 v[0:1], v[142:143], 0 op_sel_hi:[1,0]
	v_exp_f32_e32 v93, v2
	v_fmamk_f32 v2, v10, 0x3e38aa3b, v79
	v_pk_add_f32 v[0:1], v[140:141], v[0:1]
	v_exp_f32_e32 v91, v2
	v_fmamk_f32 v2, v11, 0x3e38aa3b, v79
	v_pk_add_f32 v[0:1], v[138:139], v[0:1]
	v_exp_f32_e32 v89, v2
	v_fmamk_f32 v2, v12, 0x3e38aa3b, v79
	v_pk_add_f32 v[0:1], v[136:137], v[0:1]
	v_exp_f32_e32 v87, v2
	v_fmamk_f32 v2, v13, 0x3e38aa3b, v79
	v_pk_add_f32 v[0:1], v[134:135], v[0:1]
	v_exp_f32_e32 v85, v2
	v_fmamk_f32 v2, v14, 0x3e38aa3b, v79
	v_pk_add_f32 v[0:1], v[132:133], v[0:1]
	v_exp_f32_e32 v81, v2
	v_sub_f32_e32 v2, v152, v150
	v_mul_f32_e32 v2, 0x3e38aa3b, v2
	v_pk_add_f32 v[0:1], v[130:131], v[0:1]
	v_exp_f32_e32 v83, v2
	v_pk_add_f32 v[2:3], v[74:75], v[76:77]
	v_pk_add_f32 v[0:1], v[128:129], v[0:1]
	v_pk_add_f32 v[2:3], v[72:73], v[2:3]
	v_pk_add_f32 v[0:1], v[94:95], v[0:1]
	v_pk_add_f32 v[2:3], v[70:71], v[2:3]
	v_pk_add_f32 v[0:1], v[92:93], v[0:1]
	v_fmac_f32_e32 v79, 0x3e38aa3b, v15
	v_pk_add_f32 v[2:3], v[68:69], v[2:3]
	v_pk_add_f32 v[0:1], v[90:91], v[0:1]
	v_exp_f32_e32 v79, v79
	v_pk_add_f32 v[2:3], v[66:67], v[2:3]
	v_pk_add_f32 v[0:1], v[88:89], v[0:1]
	v_pk_add_f32 v[2:3], v[64:65], v[2:3]
	v_pk_add_f32 v[0:1], v[86:87], v[0:1]
	v_pk_add_f32 v[2:3], v[62:63], v[2:3]
	v_pk_add_f32 v[0:1], v[84:85], v[0:1]
	v_pk_add_f32 v[2:3], v[60:61], v[2:3]
	v_pk_add_f32 v[0:1], v[80:81], v[0:1]
	v_pk_fma_f32 v[2:3], v[48:49], v[58:59], v[2:3]
	v_pk_add_f32 v[0:1], v[78:79], v[0:1]
	s_nop 0
	v_pk_fma_f32 v[48:49], v[82:83], v[2:3], v[0:1]
	s_cbranch_scc0 .LBB0_522
	s_barrier
	s_waitcnt vmcnt(0)
	ds_write_b128 v187, v[16:19]
	ds_write_b128 v186, v[20:23]
	ds_write_b128 v185, v[24:27]
	ds_write_b128 v184, v[28:31]
	s_waitcnt lgkmcnt(0)
	s_barrier
; #define MFMA(a, b, c) __builtin_amdgcn_mfma_f32_32x32x16_bf16((a), (b), (c), 0, 0, 0)
; DI f32x16 zero16() { f32x16 z; for (int i = 0; i < 16; ++i) z[i] = 0.f; return z; }
; DI void attn_unit(const Params& p, int l, int unit, unsigned char* smem) {
;     ...
; #pragma unroll
;     for (int kb = 0; kb < 2; ++kb)
; #pragma unroll
;       for (int mp = 0; mp < 2; ++mp) {
;         f32x16 st = zero16();
; #pragma unroll
;         for (int s = 0; s < 4; ++s) st = MFMA(ld16(sK + (32 * kb + l31) * 136 + mp * 64 + 16 * s + 8 * h), qf[mp][s], st);
;         float tm = st[0];
; #pragma unroll
;         for (int r = 1; r < 16; ++r) tm = fmaxf(tm, st[r]);
;         const float mn = fmaxf(mx[mp], tm);
;         const float nmc = -mn * cs;
;         float sum = 0.f;
; #pragma unroll
;         for (int r = 0; r < 16; ++r) sum += __builtin_amdgcn_exp2f(fmaf(st[r], cs, nmc));
;         ls[mp] = ls[mp] * __builtin_amdgcn_exp2f((mx[mp] - mn) * cs) + sum;
;         mx[mp] = mn;
;       }
;   }
	ds_read_b128 v[0:3], v149
	ds_read_b128 v[16:19], v149 offset:32
	s_waitcnt lgkmcnt(1)
	v_mfma_f32_32x32x16_bf16 v[0:15], v[0:3], v[120:123], 0
	v_cmp_lt_i32_e32 vcc, v222, v221
	s_lshl_b32 s20, s26, 2
	s_or_b32 s27, s20, s27
	s_mul_hi_i32 s26, s27, 0x110000
	s_mul_i32 s27, s27, 0x110000
	s_add_u32 s20, s10, s27
	s_addc_u32 s21, s11, s26
	s_waitcnt lgkmcnt(0)
	v_mfma_f32_32x32x16_bf16 v[0:15], v[16:19], v[116:119], v[0:15]
	ds_read_b128 v[16:19], v149 offset:64
	flat_load_dwordx4 v[128:131], v[46:47]
	v_or_b32_e32 v50, 32, v165
	v_lshlrev_b32_e32 v188, 2, v167
	s_waitcnt lgkmcnt(0)
	v_mfma_f32_32x32x16_bf16 v[0:15], v[16:19], v[104:107], v[0:15]
	ds_read_b128 v[16:19], v149 offset:96
	s_waitcnt lgkmcnt(0)
	v_mfma_f32_32x32x16_bf16 v[0:15], v[16:19], v[100:103], v[0:15]
	ds_read_b128 v[18:21], v149 offset:160
	s_nop 10
	v_max3_f32 v16, v0, v1, v2
	v_max3_f32 v16, v16, v3, v4
	v_max3_f32 v16, v16, v5, v6
	v_max3_f32 v16, v16, v7, v8
	v_max3_f32 v16, v16, v9, v10
	v_max3_f32 v16, v16, v11, v12
	v_max3_f32 v16, v16, v13, v14
	v_max3_f32 v16, v151, v16, v15
	v_mul_f32_e32 v17, 0xbe38aa3b, v16
	v_fmamk_f32 v0, v0, 0x3e38aa3b, v17
	v_exp_f32_e32 v0, v0
	v_fmamk_f32 v1, v1, 0x3e38aa3b, v17
	v_exp_f32_e32 v1, v1
	v_add_f32_e32 v0, 0, v0
	v_add_f32_e32 v0, v1, v0
	v_fmamk_f32 v1, v2, 0x3e38aa3b, v17
	v_exp_f32_e32 v1, v1
	s_nop 0
	v_add_f32_e32 v0, v1, v0
	v_fmamk_f32 v1, v3, 0x3e38aa3b, v17
	v_exp_f32_e32 v1, v1
	s_nop 0
	v_add_f32_e32 v0, v1, v0
	v_fmamk_f32 v1, v4, 0x3e38aa3b, v17
	v_exp_f32_e32 v1, v1
	s_nop 0
	v_add_f32_e32 v0, v1, v0
	v_fmamk_f32 v1, v5, 0x3e38aa3b, v17
	v_exp_f32_e32 v1, v1
	s_nop 0
	v_add_f32_e32 v0, v1, v0
	v_fmamk_f32 v1, v6, 0x3e38aa3b, v17
	v_exp_f32_e32 v1, v1
	s_nop 0
	v_add_f32_e32 v0, v1, v0
	v_fmamk_f32 v1, v7, 0x3e38aa3b, v17
	v_exp_f32_e32 v1, v1
	s_nop 0
	v_add_f32_e32 v0, v1, v0
	v_fmamk_f32 v1, v8, 0x3e38aa3b, v17
	v_exp_f32_e32 v1, v1
	s_nop 0
	v_add_f32_e32 v0, v1, v0
	v_fmamk_f32 v1, v9, 0x3e38aa3b, v17
	v_exp_f32_e32 v1, v1
	s_nop 0
	v_add_f32_e32 v0, v1, v0
	v_fmamk_f32 v1, v10, 0x3e38aa3b, v17
	v_exp_f32_e32 v1, v1
	s_nop 0
	v_add_f32_e32 v0, v1, v0
	v_fmamk_f32 v1, v11, 0x3e38aa3b, v17
	v_exp_f32_e32 v1, v1
	s_nop 0
	v_add_f32_e32 v0, v1, v0
	v_fmamk_f32 v1, v12, 0x3e38aa3b, v17
	v_exp_f32_e32 v1, v1
	s_nop 0
	v_add_f32_e32 v0, v1, v0
	v_fmamk_f32 v1, v13, 0x3e38aa3b, v17
	v_exp_f32_e32 v1, v1
	s_nop 0
	v_add_f32_e32 v0, v1, v0
	v_fmamk_f32 v1, v14, 0x3e38aa3b, v17
	v_exp_f32_e32 v1, v1
	v_fmac_f32_e32 v17, 0x3e38aa3b, v15
	v_add_f32_e32 v0, v1, v0
	v_exp_f32_e32 v1, v17
	s_nop 0
	v_add_f32_e32 v17, v1, v0
	v_sub_f32_e32 v0, v151, v16
	v_mul_f32_e32 v0, 0x3e38aa3b, v0
	v_exp_f32_e32 v0, v0
	s_nop 0
	v_fmac_f32_e32 v17, v48, v0
	ds_read_b128 v[0:3], v149 offset:128
	s_waitcnt lgkmcnt(0)
	v_mfma_f32_32x32x16_bf16 v[0:15], v[0:3], v[124:127], 0
	v_mfma_f32_32x32x16_bf16 v[0:15], v[18:21], v[112:115], v[0:15]
	ds_read_b128 v[18:21], v149 offset:192
	s_waitcnt lgkmcnt(0)
	v_mfma_f32_32x32x16_bf16 v[0:15], v[18:21], v[108:111], v[0:15]
	ds_read_b128 v[18:21], v149 offset:224
	s_waitcnt lgkmcnt(0)
	v_mfma_f32_32x32x16_bf16 v[0:15], v[18:21], v[96:99], v[0:15]
	ds_read_b128 v[20:23], v149 offset:8736
	s_nop 10
	v_max3_f32 v18, v0, v1, v2
	v_max3_f32 v18, v18, v3, v4
	v_max3_f32 v18, v18, v5, v6
	v_max3_f32 v18, v18, v7, v8
	v_max3_f32 v18, v18, v9, v10
	v_max3_f32 v18, v18, v11, v12
	v_max3_f32 v18, v18, v13, v14
	v_max3_f32 v18, v150, v18, v15
	v_mul_f32_e32 v19, 0xbe38aa3b, v18
	v_fmamk_f32 v0, v0, 0x3e38aa3b, v19
	v_exp_f32_e32 v0, v0
	v_fmamk_f32 v1, v1, 0x3e38aa3b, v19
	v_exp_f32_e32 v1, v1
	v_add_f32_e32 v0, 0, v0
	v_add_f32_e32 v0, v1, v0
	v_fmamk_f32 v1, v2, 0x3e38aa3b, v19
	v_exp_f32_e32 v1, v1
	s_nop 0
	v_add_f32_e32 v0, v1, v0
	v_fmamk_f32 v1, v3, 0x3e38aa3b, v19
	v_exp_f32_e32 v1, v1
	s_nop 0
	v_add_f32_e32 v0, v1, v0
	v_fmamk_f32 v1, v4, 0x3e38aa3b, v19
	v_exp_f32_e32 v1, v1
	s_nop 0
	v_add_f32_e32 v0, v1, v0
	v_fmamk_f32 v1, v5, 0x3e38aa3b, v19
	v_exp_f32_e32 v1, v1
	s_nop 0
	v_add_f32_e32 v0, v1, v0
	v_fmamk_f32 v1, v6, 0x3e38aa3b, v19
	v_exp_f32_e32 v1, v1
	s_nop 0
	v_add_f32_e32 v0, v1, v0
	v_fmamk_f32 v1, v7, 0x3e38aa3b, v19
	v_exp_f32_e32 v1, v1
	s_nop 0
	v_add_f32_e32 v0, v1, v0
	v_fmamk_f32 v1, v8, 0x3e38aa3b, v19
	v_exp_f32_e32 v1, v1
	s_nop 0
	v_add_f32_e32 v0, v1, v0
	v_fmamk_f32 v1, v9, 0x3e38aa3b, v19
	v_exp_f32_e32 v1, v1
	s_nop 0
	v_add_f32_e32 v0, v1, v0
	v_fmamk_f32 v1, v10, 0x3e38aa3b, v19
	v_exp_f32_e32 v1, v1
	s_nop 0
	v_add_f32_e32 v0, v1, v0
	v_fmamk_f32 v1, v11, 0x3e38aa3b, v19
	v_exp_f32_e32 v1, v1
	s_nop 0
	v_add_f32_e32 v0, v1, v0
	v_fmamk_f32 v1, v12, 0x3e38aa3b, v19
	v_exp_f32_e32 v1, v1
	s_nop 0
	v_add_f32_e32 v0, v1, v0
	v_fmamk_f32 v1, v13, 0x3e38aa3b, v19
	v_exp_f32_e32 v1, v1
	s_nop 0
	v_add_f32_e32 v0, v1, v0
	v_fmamk_f32 v1, v14, 0x3e38aa3b, v19
	v_exp_f32_e32 v1, v1
	v_fmac_f32_e32 v19, 0x3e38aa3b, v15
	v_add_f32_e32 v0, v1, v0
	v_exp_f32_e32 v1, v19
	s_nop 0
	v_add_f32_e32 v19, v1, v0
	v_sub_f32_e32 v0, v150, v18
	v_mul_f32_e32 v0, 0x3e38aa3b, v0
	v_exp_f32_e32 v0, v0
	s_nop 0
	v_fmac_f32_e32 v19, v49, v0
	ds_read_b128 v[0:3], v149 offset:8704
	s_waitcnt lgkmcnt(0)
	v_mfma_f32_32x32x16_bf16 v[0:15], v[0:3], v[120:123], 0
	v_mfma_f32_32x32x16_bf16 v[0:15], v[20:23], v[116:119], v[0:15]
	ds_read_b128 v[20:23], v149 offset:8768
	s_waitcnt lgkmcnt(0)
	v_mfma_f32_32x32x16_bf16 v[0:15], v[20:23], v[104:107], v[0:15]
	ds_read_b128 v[20:23], v149 offset:8800
	s_waitcnt lgkmcnt(0)
; #define MFMA(a, b, c) __builtin_amdgcn_mfma_f32_32x32x16_bf16((a), (b), (c), 0, 0, 0)
; DI f32x16 zero16() { f32x16 z; for (int i = 0; i < 16; ++i) z[i] = 0.f; return z; }
; DI void attn_unit(const Params& p, int l, int unit, unsigned char* smem) {
;     ...
; #pragma unroll
;     for (int kb = 0; kb < 2; ++kb)
; #pragma unroll
;       for (int mp = 0; mp < 2; ++mp) {
;         f32x16 st = zero16();
; #pragma unroll
;         for (int s = 0; s < 4; ++s) st = MFMA(ld16(sK + (32 * kb + l31) * 136 + mp * 64 + 16 * s + 8 * h), qf[mp][s], st);
;         float tm = st[0];
; #pragma unroll
;         for (int r = 1; r < 16; ++r) tm = fmaxf(tm, st[r]);
;         const float mn = fmaxf(mx[mp], tm);
;         const float nmc = -mn * cs;
;         float sum = 0.f;
; #pragma unroll
;         for (int r = 0; r < 16; ++r) sum += __builtin_amdgcn_exp2f(fmaf(st[r], cs, nmc));
;         ls[mp] = ls[mp] * __builtin_amdgcn_exp2f((mx[mp] - mn) * cs) + sum;
;         mx[mp] = mn;
;       }
;   }
;   float nm[2], sc[2];
; #pragma unroll
;   for (int mp = 0; mp < 2; ++mp) {
;     const float mo = __shfl_xor(mx[mp], 32), lo = __shfl_xor(ls[mp], 32);
;     const float M = fmaxf(mx[mp], mo);
;     const float L = ls[mp] * __builtin_amdgcn_exp2f((mx[mp] - M) * cs) + lo * __builtin_amdgcn_exp2f((mo - M) * cs);
;     nm[mp] = -M * cs; sc[mp] = (mp ? lam : 1.f) / L;
;   }
	v_mfma_f32_32x32x16_bf16 v[0:15], v[20:23], v[100:103], v[0:15]
	ds_read_b128 v[22:25], v149 offset:8864
	s_nop 10
	v_max3_f32 v20, v0, v1, v2
	v_max3_f32 v20, v20, v3, v4
	v_max3_f32 v20, v20, v5, v6
	v_max3_f32 v20, v20, v7, v8
	v_max3_f32 v20, v20, v9, v10
	v_max3_f32 v20, v20, v11, v12
	v_max3_f32 v20, v20, v13, v14
	v_max3_f32 v20, v16, v20, v15
	v_mul_f32_e32 v21, 0xbe38aa3b, v20
	v_fmamk_f32 v0, v0, 0x3e38aa3b, v21
	v_exp_f32_e32 v0, v0
	v_fmamk_f32 v1, v1, 0x3e38aa3b, v21
	v_exp_f32_e32 v1, v1
	v_add_f32_e32 v0, 0, v0
	v_add_f32_e32 v0, v1, v0
	v_fmamk_f32 v1, v2, 0x3e38aa3b, v21
	v_exp_f32_e32 v1, v1
	s_nop 0
	v_add_f32_e32 v0, v1, v0
	v_fmamk_f32 v1, v3, 0x3e38aa3b, v21
	v_exp_f32_e32 v1, v1
	s_nop 0
	v_add_f32_e32 v0, v1, v0
	v_fmamk_f32 v1, v4, 0x3e38aa3b, v21
	v_exp_f32_e32 v1, v1
	s_nop 0
	v_add_f32_e32 v0, v1, v0
	v_fmamk_f32 v1, v5, 0x3e38aa3b, v21
	v_exp_f32_e32 v1, v1
	s_nop 0
	v_add_f32_e32 v0, v1, v0
	v_fmamk_f32 v1, v6, 0x3e38aa3b, v21
	v_exp_f32_e32 v1, v1
	s_nop 0
	v_add_f32_e32 v0, v1, v0
	v_fmamk_f32 v1, v7, 0x3e38aa3b, v21
	v_exp_f32_e32 v1, v1
	s_nop 0
	v_add_f32_e32 v0, v1, v0
	v_fmamk_f32 v1, v8, 0x3e38aa3b, v21
	v_exp_f32_e32 v1, v1
	s_nop 0
	v_add_f32_e32 v0, v1, v0
	v_fmamk_f32 v1, v9, 0x3e38aa3b, v21
	v_exp_f32_e32 v1, v1
	s_nop 0
	v_add_f32_e32 v0, v1, v0
	v_fmamk_f32 v1, v10, 0x3e38aa3b, v21
	v_exp_f32_e32 v1, v1
	s_nop 0
	v_add_f32_e32 v0, v1, v0
	v_fmamk_f32 v1, v11, 0x3e38aa3b, v21
	v_exp_f32_e32 v1, v1
	s_nop 0
	v_add_f32_e32 v0, v1, v0
	v_fmamk_f32 v1, v12, 0x3e38aa3b, v21
	v_exp_f32_e32 v1, v1
	s_nop 0
	v_add_f32_e32 v0, v1, v0
	v_fmamk_f32 v1, v13, 0x3e38aa3b, v21
	v_exp_f32_e32 v1, v1
	s_nop 0
	v_add_f32_e32 v0, v1, v0
	v_fmamk_f32 v1, v14, 0x3e38aa3b, v21
	v_exp_f32_e32 v1, v1
	v_fmac_f32_e32 v21, 0x3e38aa3b, v15
	v_add_f32_e32 v0, v1, v0
	v_exp_f32_e32 v1, v21
	s_nop 0
	v_add_f32_e32 v21, v1, v0
	v_sub_f32_e32 v0, v16, v20
	v_mul_f32_e32 v0, 0x3e38aa3b, v0
	v_exp_f32_e32 v0, v0
	s_nop 0
	v_fmac_f32_e32 v21, v0, v17
	ds_read_b128 v[0:3], v149 offset:8832
	s_waitcnt lgkmcnt(0)
	v_mfma_f32_32x32x16_bf16 v[0:15], v[0:3], v[124:127], 0
	v_mfma_f32_32x32x16_bf16 v[0:15], v[22:25], v[112:115], v[0:15]
	ds_read_b128 v[22:25], v149 offset:8896
	s_waitcnt lgkmcnt(0)
	v_mfma_f32_32x32x16_bf16 v[0:15], v[22:25], v[108:111], v[0:15]
	ds_read_b128 v[22:25], v149 offset:8928
	s_waitcnt lgkmcnt(0)
	v_mfma_f32_32x32x16_bf16 v[0:15], v[22:25], v[96:99], v[0:15]
	s_nop 11
	v_max3_f32 v16, v0, v1, v2
	v_max3_f32 v16, v16, v3, v4
	v_max3_f32 v16, v16, v5, v6
	v_max3_f32 v16, v16, v7, v8
	v_max3_f32 v16, v16, v9, v10
	v_max3_f32 v16, v16, v11, v12
	v_max3_f32 v16, v16, v13, v14
	v_max3_f32 v16, v18, v16, v15
	v_mul_f32_e32 v17, 0xbe38aa3b, v16
	v_fmamk_f32 v0, v0, 0x3e38aa3b, v17
	v_exp_f32_e32 v0, v0
	v_fmamk_f32 v1, v1, 0x3e38aa3b, v17
	v_exp_f32_e32 v1, v1
	v_add_f32_e32 v0, 0, v0
	v_add_f32_e32 v0, v1, v0
	v_fmamk_f32 v1, v2, 0x3e38aa3b, v17
	v_exp_f32_e32 v1, v1
	s_nop 0
	v_add_f32_e32 v0, v1, v0
	v_fmamk_f32 v1, v3, 0x3e38aa3b, v17
	v_exp_f32_e32 v1, v1
	s_nop 0
	v_add_f32_e32 v0, v1, v0
	v_fmamk_f32 v1, v4, 0x3e38aa3b, v17
	v_exp_f32_e32 v1, v1
	s_nop 0
	v_add_f32_e32 v0, v1, v0
	v_fmamk_f32 v1, v5, 0x3e38aa3b, v17
	v_exp_f32_e32 v1, v1
	s_nop 0
	v_add_f32_e32 v0, v1, v0
	v_fmamk_f32 v1, v6, 0x3e38aa3b, v17
	v_exp_f32_e32 v1, v1
	s_nop 0
	v_add_f32_e32 v0, v1, v0
	v_fmamk_f32 v1, v7, 0x3e38aa3b, v17
	v_exp_f32_e32 v1, v1
	v_ashrrev_i32_e32 v7, 3, v148
	v_add_f32_e32 v0, v1, v0
	v_fmamk_f32 v1, v8, 0x3e38aa3b, v17
	v_exp_f32_e32 v1, v1
	s_nop 0
	v_add_f32_e32 v0, v1, v0
	v_fmamk_f32 v1, v9, 0x3e38aa3b, v17
	v_exp_f32_e32 v1, v1
	s_nop 0
	v_add_f32_e32 v0, v1, v0
	v_fmamk_f32 v1, v10, 0x3e38aa3b, v17
	v_exp_f32_e32 v1, v1
	s_nop 0
	v_add_f32_e32 v0, v1, v0
	v_fmamk_f32 v1, v11, 0x3e38aa3b, v17
	v_exp_f32_e32 v1, v1
	s_nop 0
	v_add_f32_e32 v0, v1, v0
	v_fmamk_f32 v1, v12, 0x3e38aa3b, v17
	v_exp_f32_e32 v1, v1
	s_nop 0
	v_add_f32_e32 v0, v1, v0
	v_fmamk_f32 v1, v13, 0x3e38aa3b, v17
	v_exp_f32_e32 v1, v1
	s_nop 0
	v_add_f32_e32 v0, v1, v0
	v_fmamk_f32 v1, v14, 0x3e38aa3b, v17
	v_exp_f32_e32 v1, v1
	v_fmac_f32_e32 v17, 0x3e38aa3b, v15
	v_add_f32_e32 v0, v1, v0
	v_exp_f32_e32 v1, v17
	s_nop 0
	v_add_f32_e32 v0, v1, v0
	v_sub_f32_e32 v1, v18, v16
	v_mul_f32_e32 v1, 0x3e38aa3b, v1
	v_exp_f32_e32 v1, v1
	s_nop 0
	v_fmac_f32_e32 v0, v1, v19
	v_cndmask_b32_e32 v1, v220, v222, vcc
	v_lshlrev_b32_e32 v189, 2, v1
	ds_bpermute_b32 v1, v189, v20
	ds_bpermute_b32 v2, v189, v21
	s_waitcnt lgkmcnt(0)
	v_max_f32_e32 v3, v1, v1
	v_max_f32_e32 v3, v20, v3
	v_sub_f32_e32 v4, v20, v3
	v_mul_f32_e32 v4, 0x3e38aa3b, v4
	v_sub_f32_e32 v1, v1, v3
	v_exp_f32_e32 v4, v4
	v_mul_f32_e32 v1, 0x3e38aa3b, v1
	v_exp_f32_e32 v1, v1
	v_mul_f32_e32 v190, 0xbe38aa3b, v3
	v_mul_f32_e32 v4, v4, v21
	v_fmac_f32_e32 v4, v1, v2
	v_div_scale_f32 v1, s[28:29], v4, v4, 1.0
	v_rcp_f32_e32 v2, v1
	s_nop 0
	v_fma_f32 v3, -v1, v2, 1.0
	v_fmac_f32_e32 v2, v3, v2
	v_div_scale_f32 v3, vcc, 1.0, v4, 1.0
	v_mul_f32_e32 v5, v3, v2
	v_fma_f32 v6, -v1, v5, v3
	v_fmac_f32_e32 v5, v6, v2
	v_fma_f32 v1, -v1, v5, v3
	v_div_fmas_f32 v1, v1, v2, v5
	v_div_fixup_f32 v164, v1, v4, 1.0
	ds_bpermute_b32 v1, v189, v16
	ds_bpermute_b32 v2, v189, v0
	v_ashrrev_i32_e32 v6, 3, v146
	s_waitcnt lgkmcnt(0)
; DI f32x16 zero16() { f32x16 z; for (int i = 0; i < 16; ++i) z[i] = 0.f; return z; }
; DI void attn_unit(const Params& p, int l, int unit, unsigned char* smem) {
;     ...
;   float nm[2], sc[2];
; #pragma unroll
;   for (int mp = 0; mp < 2; ++mp) {
;     const float mo = __shfl_xor(mx[mp], 32), lo = __shfl_xor(ls[mp], 32);
;     const float M = fmaxf(mx[mp], mo);
;     const float L = ls[mp] * __builtin_amdgcn_exp2f((mx[mp] - M) * cs) + lo * __builtin_amdgcn_exp2f((mo - M) * cs);
;     nm[mp] = -M * cs; sc[mp] = (mp ? lam : 1.f) / L;
;   }
;   f32x16 oacc[4];
;   for (int i = 0; i < 4; ++i) oacc[i] = zero16();
; #pragma unroll
;   for (int i = 0; i < 4; ++i) {
;     const int c = tid + 256 * i;
;     { const int key = c >> 4, kc = c & 15; rk[i] = *(const u32x4*)(Kbase + (size_t)key * PLD + 8 * kc); }
;     { const int dv = c >> 3, kc = c & 7; rv[i] = *(const u32x4*)(VT + (size_t)dv * SP + 8 * kc); }
;   }
	v_max_f32_e32 v3, v1, v1
	v_max_f32_e32 v3, v16, v3
	v_sub_f32_e32 v4, v16, v3
	v_mul_f32_e32 v4, 0x3e38aa3b, v4
	v_sub_f32_e32 v1, v1, v3
	v_exp_f32_e32 v4, v4
	v_mul_f32_e32 v1, 0x3e38aa3b, v1
	v_exp_f32_e32 v1, v1
	v_mul_f32_e32 v191, 0xbe38aa3b, v3
	v_mul_f32_e32 v0, v4, v0
	v_fmac_f32_e32 v0, v1, v2
	v_div_scale_f32 v1, s[28:29], v0, v0, v145
	v_rcp_f32_e32 v2, v1
	s_nop 0
	v_fma_f32 v3, -v1, v2, 1.0
	v_fmac_f32_e32 v2, v3, v2
	v_div_scale_f32 v3, vcc, v145, v0, v145
	v_mul_f32_e32 v4, v3, v2
	v_fma_f32 v5, -v1, v4, v3
	v_fmac_f32_e32 v4, v5, v2
	v_fma_f32 v1, -v1, v4, v3
	v_div_fmas_f32 v1, v1, v2, v4
	v_div_fixup_f32 v166, v1, v0, v145
	v_lshlrev_b32_e32 v0, 1, v147
	v_and_b32_e32 v2, 0x70, v0
	v_mov_b32_e32 v3, v209
	v_lshl_add_u64 v[0:1], s[20:21], 0, v[2:3]
	s_mov_b64 s[20:21], 0x30f10000
	v_lshl_add_u64 v[0:1], v[0:1], 0, s[20:21]
	v_ashrrev_i32_e32 v3, 3, v144
	v_mad_i64_i32 v[4:5], s[20:21], v3, s42, v[0:1]
	flat_load_dwordx4 v[132:135], v[4:5]
	flat_load_dwordx4 v[136:139], v[42:43]
	v_mad_i64_i32 v[4:5], s[20:21], v6, s42, v[0:1]
	flat_load_dwordx4 v[140:143], v[4:5]
	flat_load_dwordx4 v[144:147], v[44:45]
	v_mad_i64_i32 v[4:5], s[20:21], v7, s42, v[0:1]
	flat_load_dwordx4 v[148:151], v[4:5]
	flat_load_dwordx4 v[152:155], v[40:41]
	v_ashrrev_i32_e32 v4, 3, v156
	v_mad_i64_i32 v[0:1], s[20:21], v4, s42, v[0:1]
	flat_load_dwordx4 v[156:159], v[0:1]
	s_movk_i32 s20, 0x90
	v_mul_lo_u32 v8, v3, s20
	v_mul_lo_u32 v9, v6, s20
	v_mul_lo_u32 v10, v7, s20
	v_mul_lo_u32 v11, v4, s20
	s_add_u32 s20, s25, s44
	s_addc_u32 s21, s23, 0
	v_mul_u32_u24_e32 v0, 0x90, v165
	v_lshlrev_b32_e32 v1, 7, v165
	v_lshlrev_b32_e32 v5, 1, v168
	s_add_u32 s20, s20, 0xce03400
	v_or_b32_e32 v198, v0, v168
	v_add3_u32 v197, v0, v1, v5
	v_mul_u32_u24_e32 v0, 0x90, v50
	v_lshlrev_b32_e32 v1, 7, v50
	s_addc_u32 s21, s21, 0
	v_or_b32_e32 v199, v0, v168
	v_add3_u32 v192, v0, v1, v5
	v_lshl_add_u64 v[0:1], s[20:21], 0, v[38:39]
	v_lshl_add_u64 v[168:169], v[0:1], 0, v[208:209]
	v_lshl_add_u64 v[0:1], s[20:21], 0, v[36:37]
	v_lshl_add_u64 v[170:171], v[0:1], 0, v[208:209]
	v_lshl_add_u64 v[0:1], s[20:21], 0, v[34:35]
	v_lshl_add_u64 v[172:173], v[0:1], 0, v[208:209]
	v_lshl_add_u64 v[0:1], s[20:21], 0, v[32:33]
	s_add_u32 s20, s27, 0x30f10080
	s_addc_u32 s21, s26, 0
	v_lshl_add_u64 v[174:175], v[0:1], 0, v[208:209]
	v_mov_b64_e32 v[0:1], s[20:21]
	v_mad_i64_i32 v[176:177], s[20:21], v4, s42, v[0:1]
	v_and_b32_e32 v4, 0x70, v178
	v_mad_i64_i32 v[178:179], s[20:21], v7, s42, v[0:1]
	v_mad_i64_i32 v[180:181], s[20:21], v6, s42, v[0:1]
	v_mad_i64_i32 v[182:183], s[20:21], v3, s42, v[0:1]
	v_mov_b32_e32 v0, 0
	v_mov_b32_e32 v165, v164
	v_mov_b32_e32 v167, v166
	v_or_b32_e32 v176, v176, v4
	v_or_b32_e32 v178, v178, v4
	v_or_b32_e32 v180, v180, v4
	v_or_b32_e32 v182, v182, v4
	s_movk_i32 s20, 0x43
	v_add_u32_e32 v203, v2, v8
	v_add_u32_e32 v202, v2, v9
	v_add_u32_e32 v201, v2, v10
	v_add_u32_e32 v200, v2, v11
	v_mov_b32_e32 v1, v0
	v_mov_b32_e32 v2, v0
	v_mov_b32_e32 v3, v0
	v_mov_b32_e32 v4, v0
	v_mov_b32_e32 v5, v0
	v_mov_b32_e32 v6, v0
	v_mov_b32_e32 v7, v0
	v_mov_b32_e32 v8, v0
	v_mov_b32_e32 v9, v0
	v_mov_b32_e32 v10, v0
	v_mov_b32_e32 v11, v0
	v_mov_b32_e32 v12, v0
	v_mov_b32_e32 v13, v0
	v_mov_b32_e32 v14, v0
	v_mov_b32_e32 v15, v0
	v_mov_b32_e32 v16, v0
	v_mov_b32_e32 v17, v0
	v_mov_b32_e32 v18, v0
	v_mov_b32_e32 v19, v0
	v_mov_b32_e32 v20, v0
	v_mov_b32_e32 v21, v0
	v_mov_b32_e32 v22, v0
	v_mov_b32_e32 v23, v0
	v_mov_b32_e32 v24, v0
	v_mov_b32_e32 v25, v0
	v_mov_b32_e32 v26, v0
	v_mov_b32_e32 v27, v0
	v_mov_b32_e32 v28, v0
	v_mov_b32_e32 v29, v0
	v_mov_b32_e32 v30, v0
	v_mov_b32_e32 v31, v0
	v_mov_b32_e32 v32, v0
	v_mov_b32_e32 v33, v0
	v_mov_b32_e32 v34, v0
	v_mov_b32_e32 v35, v0
	v_mov_b32_e32 v36, v0
	v_mov_b32_e32 v37, v0
	v_mov_b32_e32 v38, v0
	v_mov_b32_e32 v39, v0
	v_mov_b32_e32 v40, v0
	v_mov_b32_e32 v41, v0
	v_mov_b32_e32 v42, v0
	v_mov_b32_e32 v43, v0
	v_mov_b32_e32 v44, v0
	v_mov_b32_e32 v45, v0
	v_mov_b32_e32 v46, v0
	v_mov_b32_e32 v47, v0
	v_mov_b32_e32 v48, v0
	v_mov_b32_e32 v49, v0
	v_mov_b32_e32 v50, v0
	v_mov_b32_e32 v51, v0
	v_mov_b32_e32 v52, v0
	v_mov_b32_e32 v53, v0
	v_mov_b32_e32 v54, v0
	v_mov_b32_e32 v55, v0
	v_mov_b32_e32 v56, v0
	v_mov_b32_e32 v57, v0
	v_mov_b32_e32 v58, v0
	v_mov_b32_e32 v59, v0
	v_mov_b32_e32 v60, v0
	v_mov_b32_e32 v61, v0
	v_mov_b32_e32 v62, v0
	v_mov_b32_e32 v63, v0
; #define MFMA(a, b, c) __builtin_amdgcn_mfma_f32_32x32x16_bf16((a), (b), (c), 0, 0, 0)
; DI f32x16 zero16() { f32x16 z; for (int i = 0; i < 16; ++i) z[i] = 0.f; return z; }
; DI void attn_unit(const Params& p, int l, int unit, unsigned char* smem) {
;     ...
;   for (int kt = 0; kt < ntile; ++kt) {
;     __syncthreads();
; #pragma unroll
;     for (int i = 0; i < 4; ++i) {
;       const int c = tid + 256 * i;
;       { const int key = c >> 4, kc = c & 15; *(u32x4*)(sK + key * 136 + 8 * kc) = rk[i]; }
;       { const int dv = c >> 3, kc = c & 7; *(u32x4*)(sVT + dv * 72 + 8 * kc) = rv[i]; }
;     }
;     __syncthreads();
;     if (kt + 1 < ntile) {
; #pragma unroll
;       for (int i = 0; i < 4; ++i) {
;         const int c = tid + 256 * i;
;         { const int key = c >> 4, kc = c & 15; rk[i] = *(const u32x4*)(Kbase + (size_t)((kt + 1) * 64 + key) * PLD + 8 * kc); }
;         { const int dv = c >> 3, kc = c & 7; rv[i] = *(const u32x4*)(VT + (size_t)dv * SP + (kt + 1) * 64 + 8 * kc); }
;       }
;     }
; #pragma unroll
;     for (int kb = 0; kb < 2; ++kb) {
;       f32x16 s0 = zero16(), s1 = zero16();
; #pragma unroll
;       for (int s = 0; s < 4; ++s) {
;         s0 = MFMA(ld16(sK + (32 * kb + l31) * 136 + 16 * s + 8 * h), qf[0][s], s0);
;         s1 = MFMA(ld16(sK + (32 * kb + l31) * 136 + 64 + 16 * s + 8 * h), qf[1][s], s1);
;       }
; #pragma unroll
;       for (int r = 0; r < 16; ++r) s0[r] = __builtin_amdgcn_exp2f(fmaf(s0[r], cs, nm[0])) * sc[0] - __builtin_amdgcn_exp2f(fmaf(s1[r], cs, nm[1])) * sc[1];
;       const bf16x8 p0 = pack8<0>(s0), p1 = pack8<1>(s0);
; #pragma unroll
;       for (int dvb = 0; dvb < 4; ++dvb) {
;         oacc[dvb] = MFMA(ld2x8(sVT + (32 * dvb + l31) * 72 + 32 * kb + 4 * h), p0, oacc[dvb]);
;         oacc[dvb] = MFMA(ld2x8(sVT + (32 * dvb + l31) * 72 + 32 * kb + 16 + 4 * h), p1, oacc[dvb]);
;       }
.LBB0_524:
	v_lshl_add_u64 v[64:65], s[10:11], 0, v[174:175]
	s_waitcnt lgkmcnt(0)
	s_barrier
	s_waitcnt vmcnt(0)
	ds_write_b128 v187, v[128:131]
	ds_write_b128 v203, v[132:135] offset:17408
	ds_write_b128 v186, v[136:139]
	ds_write_b128 v202, v[140:143] offset:17408
	ds_write_b128 v185, v[144:147]
	ds_write_b128 v201, v[148:151] offset:17408
	ds_write_b128 v184, v[152:155]
	ds_write_b128 v200, v[156:159] offset:17408
	s_waitcnt lgkmcnt(0)
	s_barrier
	global_load_dwordx4 v[128:131], v[64:65], off
	v_lshl_add_u64 v[64:65], s[10:11], 0, v[182:183]
	global_load_dwordx4 v[132:135], v[64:65], off
	v_lshl_add_u64 v[64:65], s[10:11], 0, v[172:173]
	global_load_dwordx4 v[136:139], v[64:65], off
	v_lshl_add_u64 v[64:65], s[10:11], 0, v[180:181]
	global_load_dwordx4 v[140:143], v[64:65], off
	v_lshl_add_u64 v[64:65], s[10:11], 0, v[170:171]
	global_load_dwordx4 v[144:147], v[64:65], off
	v_lshl_add_u64 v[64:65], s[10:11], 0, v[178:179]
	global_load_dwordx4 v[148:151], v[64:65], off
	v_lshl_add_u64 v[64:65], s[10:11], 0, v[168:169]
	global_load_dwordx4 v[152:155], v[64:65], off
	v_lshl_add_u64 v[64:65], s[10:11], 0, v[176:177]
	global_load_dwordx4 v[156:159], v[64:65], off
	ds_read_b128 v[212:215], v197
	ds_read_b128 v[224:227], v197 offset:32
	ds_read_b128 v[228:231], v197 offset:128
	ds_read_b128 v[236:239], v197 offset:160
	ds_read_b128 v[246:249], v197 offset:64
	s_waitcnt lgkmcnt(4)
	v_mfma_f32_32x32x16_bf16 v[64:79], v[212:215], v[120:123], 0
	v_add_u32_e32 v193, 0x4000, v198
	v_add_u32_e32 v196, 0x4000, v199
	v_add_u32_e32 v195, 0x6800, v198
	v_add_u32_e32 v194, 0x7800, v198
	s_add_i32 s20, s20, -1
	v_lshl_add_u64 v[168:169], v[168:169], 0, s[52:53]
	ds_read_b128 v[250:253], v197 offset:192
	s_waitcnt lgkmcnt(4)
	v_mfma_f32_32x32x16_bf16 v[64:79], v[224:227], v[116:119], v[64:79]
	v_lshl_add_u64 v[170:171], v[170:171], 0, s[52:53]
	v_lshl_add_u64 v[172:173], v[172:173], 0, s[52:53]
	v_lshl_add_u64 v[174:175], v[174:175], 0, s[52:53]
	v_lshl_add_u64 v[176:177], v[176:177], 0, s[80:81]
	v_lshl_add_u64 v[178:179], v[178:179], 0, s[80:81]
	v_lshl_add_u64 v[180:181], v[180:181], 0, s[80:81]
	ds_read_b128 v[212:215], v197 offset:96
	s_waitcnt lgkmcnt(4)
	v_mfma_f32_32x32x16_bf16 v[80:95], v[228:231], v[124:127], 0
	v_lshl_add_u64 v[182:183], v[182:183], 0, s[80:81]
	s_cmp_lg_u32 s20, 0
	ds_read_b128 v[224:227], v197 offset:224
	s_waitcnt lgkmcnt(4)
	v_mfma_f32_32x32x16_bf16 v[80:95], v[236:239], v[112:115], v[80:95]
	ds_read2_b64 v[228:231], v193 offset0:128 offset1:130
	s_waitcnt lgkmcnt(4)
	v_mfma_f32_32x32x16_bf16 v[64:79], v[246:249], v[104:107], v[64:79]
	ds_read2_b64 v[236:239], v193 offset0:132 offset1:134
	s_waitcnt lgkmcnt(4)
	v_mfma_f32_32x32x16_bf16 v[80:95], v[250:253], v[108:111], v[80:95]
	ds_read2_b64 v[246:249], v196 offset0:128 offset1:130
	s_waitcnt lgkmcnt(4)
	v_mfma_f32_32x32x16_bf16 v[64:79], v[212:215], v[100:103], v[64:79]
	ds_read2_b64 v[250:253], v195 offset1:2
	s_waitcnt lgkmcnt(4)
	v_mfma_f32_32x32x16_bf16 v[80:95], v[224:227], v[96:99], v[80:95]
	s_nop 8
	v_fmamk_f32 v64, v64, 0x3e38aa3b, v190
	v_fmamk_f32 v65, v65, 0x3e38aa3b, v190
	v_exp_f32_e32 v64, v64
	v_exp_f32_e32 v65, v65
	v_fmamk_f32 v66, v66, 0x3e38aa3b, v190
	v_fmamk_f32 v67, v67, 0x3e38aa3b, v190
	v_exp_f32_e32 v66, v66
	v_fmamk_f32 v80, v80, 0x3e38aa3b, v191
	v_fmamk_f32 v81, v81, 0x3e38aa3b, v191
	v_exp_f32_e32 v80, v80
	v_exp_f32_e32 v81, v81
	v_exp_f32_e32 v67, v67
	v_fmamk_f32 v68, v68, 0x3e38aa3b, v190
	v_fmamk_f32 v69, v69, 0x3e38aa3b, v190
	v_pk_mul_f32 v[80:81], v[166:167], v[80:81]
	v_exp_f32_e32 v68, v68
	v_pk_fma_f32 v[64:65], v[164:165], v[64:65], v[80:81] neg_lo:[0,0,1] neg_hi:[0,0,1]
	v_fmamk_f32 v80, v82, 0x3e38aa3b, v191
	v_fmamk_f32 v81, v83, 0x3e38aa3b, v191
	v_exp_f32_e32 v80, v80
	v_exp_f32_e32 v81, v81
	v_exp_f32_e32 v69, v69
	v_fmamk_f32 v70, v70, 0x3e38aa3b, v190
	v_fmamk_f32 v71, v71, 0x3e38aa3b, v190
	v_pk_mul_f32 v[80:81], v[166:167], v[80:81]
	v_exp_f32_e32 v70, v70
	v_pk_fma_f32 v[66:67], v[164:165], v[66:67], v[80:81] neg_lo:[0,0,1] neg_hi:[0,0,1]
	v_fmamk_f32 v80, v84, 0x3e38aa3b, v191
	v_fmamk_f32 v81, v85, 0x3e38aa3b, v191
	v_exp_f32_e32 v80, v80
	v_exp_f32_e32 v81, v81
	v_exp_f32_e32 v71, v71
	v_fmamk_f32 v72, v72, 0x3e38aa3b, v190
	v_fmamk_f32 v73, v73, 0x3e38aa3b, v190
	v_pk_mul_f32 v[80:81], v[166:167], v[80:81]
	v_exp_f32_e32 v72, v72
	v_pk_fma_f32 v[68:69], v[164:165], v[68:69], v[80:81] neg_lo:[0,0,1] neg_hi:[0,0,1]
	v_fmamk_f32 v80, v86, 0x3e38aa3b, v191
	v_fmamk_f32 v81, v87, 0x3e38aa3b, v191
	v_exp_f32_e32 v80, v80
	v_exp_f32_e32 v81, v81
	v_exp_f32_e32 v73, v73
	v_fmamk_f32 v74, v74, 0x3e38aa3b, v190
	v_fmamk_f32 v75, v75, 0x3e38aa3b, v190
	v_pk_mul_f32 v[80:81], v[166:167], v[80:81]
	v_exp_f32_e32 v74, v74
	v_pk_fma_f32 v[70:71], v[164:165], v[70:71], v[80:81] neg_lo:[0,0,1] neg_hi:[0,0,1]
	v_fmamk_f32 v80, v88, 0x3e38aa3b, v191
	v_fmamk_f32 v81, v89, 0x3e38aa3b, v191
	v_exp_f32_e32 v80, v80
	v_exp_f32_e32 v81, v81
	v_exp_f32_e32 v75, v75
	v_fmamk_f32 v76, v76, 0x3e38aa3b, v190
	v_fmamk_f32 v77, v77, 0x3e38aa3b, v190
	v_pk_mul_f32 v[80:81], v[166:167], v[80:81]
	v_exp_f32_e32 v76, v76
	v_pk_fma_f32 v[72:73], v[164:165], v[72:73], v[80:81] neg_lo:[0,0,1] neg_hi:[0,0,1]
	v_fmamk_f32 v80, v90, 0x3e38aa3b, v191
	v_fmamk_f32 v81, v91, 0x3e38aa3b, v191
	v_exp_f32_e32 v80, v80
	v_exp_f32_e32 v81, v81
	v_exp_f32_e32 v77, v77
	v_fmamk_f32 v78, v78, 0x3e38aa3b, v190
	v_fmamk_f32 v79, v79, 0x3e38aa3b, v190
	v_pk_mul_f32 v[80:81], v[166:167], v[80:81]
	v_exp_f32_e32 v78, v78
	v_pk_fma_f32 v[74:75], v[164:165], v[74:75], v[80:81] neg_lo:[0,0,1] neg_hi:[0,0,1]
	v_fmamk_f32 v80, v92, 0x3e38aa3b, v191
	v_fmamk_f32 v81, v93, 0x3e38aa3b, v191
	v_exp_f32_e32 v80, v80
	v_exp_f32_e32 v81, v81
	v_exp_f32_e32 v79, v79
	v_cvt_pk_bf16_f32 v64, v64, v65
	v_cvt_pk_bf16_f32 v65, v66, v67
	v_pk_mul_f32 v[80:81], v[166:167], v[80:81]
	v_cvt_pk_bf16_f32 v66, v68, v69
	v_pk_fma_f32 v[76:77], v[164:165], v[76:77], v[80:81] neg_lo:[0,0,1] neg_hi:[0,0,1]
	v_fmamk_f32 v80, v94, 0x3e38aa3b, v191
	v_fmamk_f32 v81, v95, 0x3e38aa3b, v191
	v_exp_f32_e32 v80, v80
	v_exp_f32_e32 v81, v81
	v_cvt_pk_bf16_f32 v67, v70, v71
	v_cvt_pk_bf16_f32 v68, v72, v73
	v_cvt_pk_bf16_f32 v69, v74, v75
	v_pk_mul_f32 v[80:81], v[166:167], v[80:81]
	v_cvt_pk_bf16_f32 v70, v76, v77
	v_pk_fma_f32 v[78:79], v[164:165], v[78:79], v[80:81] neg_lo:[0,0,1] neg_hi:[0,0,1]
	s_nop 0
	v_cvt_pk_bf16_f32 v71, v78, v79
	ds_read2_b64 v[212:215], v195 offset0:4 offset1:6
	s_waitcnt lgkmcnt(4)
; #define MFMA(a, b, c) __builtin_amdgcn_mfma_f32_32x32x16_bf16((a), (b), (c), 0, 0, 0)
; DI f32x16 zero16() { f32x16 z; for (int i = 0; i < 16; ++i) z[i] = 0.f; return z; }
; DI void attn_unit(const Params& p, int l, int unit, unsigned char* smem) {
;     ...
; #pragma unroll
;     for (int kb = 0; kb < 2; ++kb) {
;       f32x16 s0 = zero16(), s1 = zero16();
; #pragma unroll
;       for (int s = 0; s < 4; ++s) {
;         s0 = MFMA(ld16(sK + (32 * kb + l31) * 136 + 16 * s + 8 * h), qf[0][s], s0);
;         s1 = MFMA(ld16(sK + (32 * kb + l31) * 136 + 64 + 16 * s + 8 * h), qf[1][s], s1);
;       }
; #pragma unroll
;       for (int r = 0; r < 16; ++r) s0[r] = __builtin_amdgcn_exp2f(fmaf(s0[r], cs, nm[0])) * sc[0] - __builtin_amdgcn_exp2f(fmaf(s1[r], cs, nm[1])) * sc[1];
;       const bf16x8 p0 = pack8<0>(s0), p1 = pack8<1>(s0);
; #pragma unroll
;       for (int dvb = 0; dvb < 4; ++dvb) {
;         oacc[dvb] = MFMA(ld2x8(sVT + (32 * dvb + l31) * 72 + 32 * kb + 4 * h), p0, oacc[dvb]);
;         oacc[dvb] = MFMA(ld2x8(sVT + (32 * dvb + l31) * 72 + 32 * kb + 16 + 4 * h), p1, oacc[dvb]);
;       }
	v_mfma_f32_32x32x16_bf16 v[48:63], v[228:231], v[64:67], v[48:63]
	ds_read2_b64 v[224:227], v194 offset0:64 offset1:66
	s_waitcnt lgkmcnt(4)
	v_mfma_f32_32x32x16_bf16 v[48:63], v[236:239], v[68:71], v[48:63]
	ds_read2_b64 v[228:231], v194 offset0:68 offset1:70
	s_waitcnt lgkmcnt(4)
	v_mfma_f32_32x32x16_bf16 v[32:47], v[246:249], v[64:67], v[32:47]
	ds_read2_b64 v[236:239], v196 offset0:132 offset1:134
	s_waitcnt lgkmcnt(4)
	v_mfma_f32_32x32x16_bf16 v[16:31], v[250:253], v[64:67], v[16:31]
	ds_read_b128 v[246:249], v192
	s_waitcnt lgkmcnt(4)
	v_mfma_f32_32x32x16_bf16 v[16:31], v[212:215], v[68:71], v[16:31]
	ds_read_b128 v[250:253], v192 offset:32
	s_waitcnt lgkmcnt(4)
	v_mfma_f32_32x32x16_bf16 v[0:15], v[224:227], v[64:67], v[0:15]
	ds_read_b128 v[212:215], v192 offset:128
	s_waitcnt lgkmcnt(4)
	v_mfma_f32_32x32x16_bf16 v[0:15], v[228:231], v[68:71], v[0:15]
	ds_read_b128 v[224:227], v192 offset:160
	s_waitcnt lgkmcnt(4)
	v_mfma_f32_32x32x16_bf16 v[32:47], v[236:239], v[68:71], v[32:47]
	ds_read_b128 v[228:231], v192 offset:64
	s_waitcnt lgkmcnt(4)
	v_mfma_f32_32x32x16_bf16 v[64:79], v[246:249], v[120:123], 0
	ds_read_b128 v[236:239], v192 offset:192
	s_waitcnt lgkmcnt(4)
	v_mfma_f32_32x32x16_bf16 v[64:79], v[250:253], v[116:119], v[64:79]
	ds_read_b128 v[246:249], v192 offset:96
	s_waitcnt lgkmcnt(4)
	v_mfma_f32_32x32x16_bf16 v[80:95], v[212:215], v[124:127], 0
	ds_read_b128 v[250:253], v192 offset:224
	s_waitcnt lgkmcnt(4)
	v_mfma_f32_32x32x16_bf16 v[80:95], v[224:227], v[112:115], v[80:95]
	ds_read2_b64 v[212:215], v193 offset0:136 offset1:138
	s_waitcnt lgkmcnt(4)
	v_mfma_f32_32x32x16_bf16 v[64:79], v[228:231], v[104:107], v[64:79]
	ds_read2_b64 v[224:227], v193 offset0:140 offset1:142
	s_waitcnt lgkmcnt(4)
	v_mfma_f32_32x32x16_bf16 v[80:95], v[236:239], v[108:111], v[80:95]
	ds_read2_b64 v[228:231], v196 offset0:136 offset1:138
	s_waitcnt lgkmcnt(4)
	v_mfma_f32_32x32x16_bf16 v[64:79], v[246:249], v[100:103], v[64:79]
	ds_read2_b64 v[236:239], v195 offset0:8 offset1:10
	s_waitcnt lgkmcnt(4)
	v_mfma_f32_32x32x16_bf16 v[80:95], v[250:253], v[96:99], v[80:95]
	s_nop 8
	v_fmamk_f32 v64, v64, 0x3e38aa3b, v190
	v_fmamk_f32 v65, v65, 0x3e38aa3b, v190
	v_exp_f32_e32 v64, v64
	v_exp_f32_e32 v65, v65
	v_fmamk_f32 v66, v66, 0x3e38aa3b, v190
	v_fmamk_f32 v67, v67, 0x3e38aa3b, v190
	v_exp_f32_e32 v66, v66
	v_fmamk_f32 v80, v80, 0x3e38aa3b, v191
	v_fmamk_f32 v81, v81, 0x3e38aa3b, v191
	v_exp_f32_e32 v80, v80
	v_exp_f32_e32 v81, v81
	v_exp_f32_e32 v67, v67
	v_fmamk_f32 v68, v68, 0x3e38aa3b, v190
	v_fmamk_f32 v69, v69, 0x3e38aa3b, v190
	v_pk_mul_f32 v[80:81], v[166:167], v[80:81]
	v_exp_f32_e32 v68, v68
	v_pk_fma_f32 v[64:65], v[164:165], v[64:65], v[80:81] neg_lo:[0,0,1] neg_hi:[0,0,1]
	v_fmamk_f32 v80, v82, 0x3e38aa3b, v191
	v_fmamk_f32 v81, v83, 0x3e38aa3b, v191
	v_exp_f32_e32 v80, v80
	v_exp_f32_e32 v81, v81
	v_exp_f32_e32 v69, v69
	v_fmamk_f32 v70, v70, 0x3e38aa3b, v190
	v_fmamk_f32 v71, v71, 0x3e38aa3b, v190
	v_pk_mul_f32 v[80:81], v[166:167], v[80:81]
	v_exp_f32_e32 v70, v70
	v_pk_fma_f32 v[66:67], v[164:165], v[66:67], v[80:81] neg_lo:[0,0,1] neg_hi:[0,0,1]
	v_fmamk_f32 v80, v84, 0x3e38aa3b, v191
	v_fmamk_f32 v81, v85, 0x3e38aa3b, v191
	v_exp_f32_e32 v80, v80
	v_exp_f32_e32 v81, v81
	v_exp_f32_e32 v71, v71
	v_fmamk_f32 v72, v72, 0x3e38aa3b, v190
	v_fmamk_f32 v73, v73, 0x3e38aa3b, v190
	v_pk_mul_f32 v[80:81], v[166:167], v[80:81]
	v_exp_f32_e32 v72, v72
	v_pk_fma_f32 v[68:69], v[164:165], v[68:69], v[80:81] neg_lo:[0,0,1] neg_hi:[0,0,1]
	v_fmamk_f32 v80, v86, 0x3e38aa3b, v191
	v_fmamk_f32 v81, v87, 0x3e38aa3b, v191
	v_exp_f32_e32 v80, v80
	v_exp_f32_e32 v81, v81
	v_exp_f32_e32 v73, v73
	v_fmamk_f32 v74, v74, 0x3e38aa3b, v190
	v_fmamk_f32 v75, v75, 0x3e38aa3b, v190
	v_pk_mul_f32 v[80:81], v[166:167], v[80:81]
	v_exp_f32_e32 v74, v74
	v_pk_fma_f32 v[70:71], v[164:165], v[70:71], v[80:81] neg_lo:[0,0,1] neg_hi:[0,0,1]
	v_fmamk_f32 v80, v88, 0x3e38aa3b, v191
	v_fmamk_f32 v81, v89, 0x3e38aa3b, v191
	v_exp_f32_e32 v80, v80
	v_exp_f32_e32 v81, v81
	v_exp_f32_e32 v75, v75
	v_cvt_pk_bf16_f32 v64, v64, v65
	v_cvt_pk_bf16_f32 v65, v66, v67
	v_pk_mul_f32 v[80:81], v[166:167], v[80:81]
	v_cvt_pk_bf16_f32 v66, v68, v69
	v_pk_fma_f32 v[72:73], v[164:165], v[72:73], v[80:81] neg_lo:[0,0,1] neg_hi:[0,0,1]
	v_fmamk_f32 v80, v90, 0x3e38aa3b, v191
	v_fmamk_f32 v81, v91, 0x3e38aa3b, v191
	v_exp_f32_e32 v80, v80
	v_exp_f32_e32 v81, v81
	v_cvt_pk_bf16_f32 v68, v72, v73
	v_fmamk_f32 v76, v76, 0x3e38aa3b, v190
	v_fmamk_f32 v77, v77, 0x3e38aa3b, v190
	v_pk_mul_f32 v[80:81], v[166:167], v[80:81]
	v_exp_f32_e32 v76, v76
	v_pk_fma_f32 v[74:75], v[164:165], v[74:75], v[80:81] neg_lo:[0,0,1] neg_hi:[0,0,1]
	v_fmamk_f32 v80, v92, 0x3e38aa3b, v191
	v_cvt_pk_bf16_f32 v69, v74, v75
	v_fmamk_f32 v81, v93, 0x3e38aa3b, v191
	v_exp_f32_e32 v80, v80
	v_exp_f32_e32 v81, v81
	v_exp_f32_e32 v77, v77
	v_cvt_pk_bf16_f32 v67, v70, v71
	v_fmamk_f32 v78, v78, 0x3e38aa3b, v190
	v_pk_mul_f32 v[80:81], v[166:167], v[80:81]
	ds_read2_b64 v[246:249], v195 offset0:12 offset1:14
	s_waitcnt lgkmcnt(4)
	v_mfma_f32_32x32x16_bf16 v[48:63], v[212:215], v[64:67], v[48:63]
	v_fma_f32 v76, v164, v76, -v80
	v_fma_f32 v77, v165, v77, -v81
	v_fmamk_f32 v80, v94, 0x3e38aa3b, v191
	v_fmamk_f32 v81, v95, 0x3e38aa3b, v191
	v_exp_f32_e32 v80, v80
	v_fmamk_f32 v79, v79, 0x3e38aa3b, v190
	v_exp_f32_e32 v81, v81
	v_exp_f32_e32 v78, v78
	v_exp_f32_e32 v79, v79
	v_cvt_pk_bf16_f32 v70, v76, v77
	v_pk_mul_f32 v[80:81], v[166:167], v[80:81]
	s_nop 0
	v_pk_fma_f32 v[78:79], v[164:165], v[78:79], v[80:81] neg_lo:[0,0,1] neg_hi:[0,0,1]
	s_nop 0
	v_cvt_pk_bf16_f32 v71, v78, v79
	s_nop 0
	ds_read2_b64 v[250:253], v194 offset0:72 offset1:74
	s_waitcnt lgkmcnt(4)
	v_mfma_f32_32x32x16_bf16 v[48:63], v[224:227], v[68:71], v[48:63]
	ds_read2_b64 v[212:215], v196 offset0:140 offset1:142
	s_waitcnt lgkmcnt(4)
	v_mfma_f32_32x32x16_bf16 v[32:47], v[228:231], v[64:67], v[32:47]
	ds_read2_b64 v[224:227], v194 offset0:76 offset1:78
	s_waitcnt lgkmcnt(4)
	v_mfma_f32_32x32x16_bf16 v[16:31], v[236:239], v[64:67], v[16:31]
	s_waitcnt lgkmcnt(3)
	v_mfma_f32_32x32x16_bf16 v[16:31], v[246:249], v[68:71], v[16:31]
	s_waitcnt lgkmcnt(2)
	v_mfma_f32_32x32x16_bf16 v[0:15], v[250:253], v[64:67], v[0:15]
	s_waitcnt lgkmcnt(1)
	v_mfma_f32_32x32x16_bf16 v[32:47], v[212:215], v[68:71], v[32:47]
	s_waitcnt lgkmcnt(0)
	v_mfma_f32_32x32x16_bf16 v[0:15], v[224:227], v[68:71], v[0:15]
	s_cbranch_scc1 .LBB0_524
; #define MFMA(a, b, c) __builtin_amdgcn_mfma_f32_32x32x16_bf16((a), (b), (c), 0, 0, 0)
; DI f32x16 zero16() { f32x16 z; for (int i = 0; i < 16; ++i) z[i] = 0.f; return z; }
; DI void attn_unit(const Params& p, int l, int unit, unsigned char* smem) {
;     ...
;     __syncthreads();
; #pragma unroll
;     for (int i = 0; i < 4; ++i) {
;       const int c = tid + 256 * i;
;       { const int key = c >> 4, kc = c & 15; *(u32x4*)(sK + key * 136 + 8 * kc) = rk[i]; }
;       { const int dv = c >> 3, kc = c & 7; *(u32x4*)(sVT + dv * 72 + 8 * kc) = rv[i]; }
;     }
;     __syncthreads();
;     if (kt + 1 < ntile) {
; #pragma unroll
;       for (int i = 0; i < 4; ++i) {
;         const int c = tid + 256 * i;
;         { const int key = c >> 4, kc = c & 15; rk[i] = *(const u32x4*)(Kbase + (size_t)((kt + 1) * 64 + key) * PLD + 8 * kc); }
;         { const int dv = c >> 3, kc = c & 7; rv[i] = *(const u32x4*)(VT + (size_t)dv * SP + (kt + 1) * 64 + 8 * kc); }
;       }
;     }
; #pragma unroll
;     for (int kb = 0; kb < 2; ++kb) {
;       f32x16 s0 = zero16(), s1 = zero16();
; #pragma unroll
;       for (int s = 0; s < 4; ++s) {
;         s0 = MFMA(ld16(sK + (32 * kb + l31) * 136 + 16 * s + 8 * h), qf[0][s], s0);
;         s1 = MFMA(ld16(sK + (32 * kb + l31) * 136 + 64 + 16 * s + 8 * h), qf[1][s], s1);
;       }
; #pragma unroll
;       for (int r = 0; r < 16; ++r) s0[r] = __builtin_amdgcn_exp2f(fmaf(s0[r], cs, nm[0])) * sc[0] - __builtin_amdgcn_exp2f(fmaf(s1[r], cs, nm[1])) * sc[1];
;       const bf16x8 p0 = pack8<0>(s0), p1 = pack8<1>(s0);
; #pragma unroll
;       for (int dvb = 0; dvb < 4; ++dvb) {
;         oacc[dvb] = MFMA(ld2x8(sVT + (32 * dvb + l31) * 72 + 32 * kb + 4 * h), p0, oacc[dvb]);
;         oacc[dvb] = MFMA(ld2x8(sVT + (32 * dvb + l31) * 72 + 32 * kb + 16 + 4 * h), p1, oacc[dvb]);
;       }
	s_barrier
	s_waitcnt vmcnt(0)
	ds_write_b128 v187, v[128:131]
	ds_write_b128 v203, v[132:135] offset:17408
	ds_write_b128 v186, v[136:139]
	ds_write_b128 v202, v[140:143] offset:17408
	ds_write_b128 v185, v[144:147]
	ds_write_b128 v201, v[148:151] offset:17408
	ds_write_b128 v184, v[152:155]
	ds_write_b128 v200, v[156:159] offset:17408
	s_waitcnt lgkmcnt(0)
	s_barrier
	ds_read_b128 v[64:67], v197
	ds_read_b128 v[128:131], v197 offset:32
	s_waitcnt lgkmcnt(1)
	v_mfma_f32_32x32x16_bf16 v[64:79], v[64:67], v[120:123], 0
	ds_read_b128 v[80:83], v197 offset:128
	s_lshl_b32 s44, s22, 1
	v_lshlrev_b32_e32 v208, 1, v188
	s_waitcnt lgkmcnt(1)
	v_mfma_f32_32x32x16_bf16 v[64:79], v[128:131], v[116:119], v[64:79]
	ds_read_b128 v[128:131], v197 offset:160
	s_waitcnt lgkmcnt(1)
	v_mfma_f32_32x32x16_bf16 v[80:95], v[80:83], v[124:127], 0
	s_waitcnt lgkmcnt(0)
	v_mfma_f32_32x32x16_bf16 v[80:95], v[128:131], v[112:115], v[80:95]
	ds_read_b128 v[128:131], v197 offset:64
	s_waitcnt lgkmcnt(0)
	v_mfma_f32_32x32x16_bf16 v[64:79], v[128:131], v[104:107], v[64:79]
	ds_read_b128 v[128:131], v197 offset:192
	s_waitcnt lgkmcnt(0)
	v_mfma_f32_32x32x16_bf16 v[80:95], v[128:131], v[108:111], v[80:95]
	ds_read_b128 v[128:131], v197 offset:96
	s_waitcnt lgkmcnt(0)
	v_mfma_f32_32x32x16_bf16 v[64:79], v[128:131], v[100:103], v[64:79]
	ds_read_b128 v[128:131], v197 offset:224
	s_waitcnt lgkmcnt(0)
	v_mfma_f32_32x32x16_bf16 v[80:95], v[128:131], v[96:99], v[80:95]
	s_nop 8
	v_fmamk_f32 v64, v64, 0x3e38aa3b, v190
	v_fmamk_f32 v65, v65, 0x3e38aa3b, v190
	v_exp_f32_e32 v64, v64
	v_exp_f32_e32 v65, v65
	v_fmamk_f32 v66, v66, 0x3e38aa3b, v190
	v_fmamk_f32 v67, v67, 0x3e38aa3b, v190
	v_exp_f32_e32 v66, v66
	v_fmamk_f32 v80, v80, 0x3e38aa3b, v191
	v_fmamk_f32 v81, v81, 0x3e38aa3b, v191
	v_exp_f32_e32 v80, v80
	v_exp_f32_e32 v81, v81
	v_exp_f32_e32 v67, v67
	v_fmamk_f32 v68, v68, 0x3e38aa3b, v190
	v_fmamk_f32 v69, v69, 0x3e38aa3b, v190
	v_pk_mul_f32 v[80:81], v[166:167], v[80:81]
	v_exp_f32_e32 v68, v68
	v_pk_fma_f32 v[64:65], v[164:165], v[64:65], v[80:81] neg_lo:[0,0,1] neg_hi:[0,0,1]
	v_fmamk_f32 v80, v82, 0x3e38aa3b, v191
	v_fmamk_f32 v81, v83, 0x3e38aa3b, v191
	v_exp_f32_e32 v80, v80
	v_exp_f32_e32 v81, v81
	v_exp_f32_e32 v69, v69
	v_fmamk_f32 v70, v70, 0x3e38aa3b, v190
	v_fmamk_f32 v71, v71, 0x3e38aa3b, v190
	v_pk_mul_f32 v[80:81], v[166:167], v[80:81]
	v_exp_f32_e32 v70, v70
	v_pk_fma_f32 v[66:67], v[164:165], v[66:67], v[80:81] neg_lo:[0,0,1] neg_hi:[0,0,1]
	v_fmamk_f32 v80, v84, 0x3e38aa3b, v191
	v_fmamk_f32 v81, v85, 0x3e38aa3b, v191
	v_exp_f32_e32 v80, v80
	v_exp_f32_e32 v81, v81
	v_exp_f32_e32 v71, v71
	v_fmamk_f32 v72, v72, 0x3e38aa3b, v190
	v_fmamk_f32 v73, v73, 0x3e38aa3b, v190
	v_pk_mul_f32 v[80:81], v[166:167], v[80:81]
	v_exp_f32_e32 v72, v72
	v_pk_fma_f32 v[68:69], v[164:165], v[68:69], v[80:81] neg_lo:[0,0,1] neg_hi:[0,0,1]
	v_fmamk_f32 v80, v86, 0x3e38aa3b, v191
	v_fmamk_f32 v81, v87, 0x3e38aa3b, v191
	v_exp_f32_e32 v80, v80
	v_exp_f32_e32 v81, v81
	v_exp_f32_e32 v73, v73
	v_fmamk_f32 v74, v74, 0x3e38aa3b, v190
	v_fmamk_f32 v75, v75, 0x3e38aa3b, v190
	v_pk_mul_f32 v[80:81], v[166:167], v[80:81]
	v_exp_f32_e32 v74, v74
	v_pk_fma_f32 v[70:71], v[164:165], v[70:71], v[80:81] neg_lo:[0,0,1] neg_hi:[0,0,1]
	v_fmamk_f32 v80, v88, 0x3e38aa3b, v191
	v_fmamk_f32 v81, v89, 0x3e38aa3b, v191
	v_exp_f32_e32 v80, v80
	v_exp_f32_e32 v81, v81
	v_exp_f32_e32 v75, v75
	v_fmamk_f32 v76, v76, 0x3e38aa3b, v190
	v_fmamk_f32 v77, v77, 0x3e38aa3b, v190
	v_pk_mul_f32 v[80:81], v[166:167], v[80:81]
	v_exp_f32_e32 v76, v76
	v_pk_fma_f32 v[72:73], v[164:165], v[72:73], v[80:81] neg_lo:[0,0,1] neg_hi:[0,0,1]
	v_fmamk_f32 v80, v90, 0x3e38aa3b, v191
	v_fmamk_f32 v81, v91, 0x3e38aa3b, v191
	v_exp_f32_e32 v80, v80
	v_exp_f32_e32 v81, v81
	v_exp_f32_e32 v77, v77
	v_fmamk_f32 v78, v78, 0x3e38aa3b, v190
	v_fmamk_f32 v79, v79, 0x3e38aa3b, v190
	v_pk_mul_f32 v[80:81], v[166:167], v[80:81]
	v_exp_f32_e32 v78, v78
	v_pk_fma_f32 v[74:75], v[164:165], v[74:75], v[80:81] neg_lo:[0,0,1] neg_hi:[0,0,1]
	v_fmamk_f32 v80, v92, 0x3e38aa3b, v191
	v_fmamk_f32 v81, v93, 0x3e38aa3b, v191
	v_exp_f32_e32 v80, v80
	v_exp_f32_e32 v81, v81
	v_exp_f32_e32 v79, v79
	v_cvt_pk_bf16_f32 v64, v64, v65
	v_cvt_pk_bf16_f32 v65, v66, v67
	v_pk_mul_f32 v[80:81], v[166:167], v[80:81]
	v_cvt_pk_bf16_f32 v66, v68, v69
	v_pk_fma_f32 v[76:77], v[164:165], v[76:77], v[80:81] neg_lo:[0,0,1] neg_hi:[0,0,1]
	v_fmamk_f32 v80, v94, 0x3e38aa3b, v191
	v_fmamk_f32 v81, v95, 0x3e38aa3b, v191
	v_exp_f32_e32 v80, v80
	v_exp_f32_e32 v81, v81
	v_cvt_pk_bf16_f32 v67, v70, v71
	v_cvt_pk_bf16_f32 v68, v72, v73
	v_cvt_pk_bf16_f32 v69, v74, v75
	v_pk_mul_f32 v[80:81], v[166:167], v[80:81]
	v_cvt_pk_bf16_f32 v70, v76, v77
	v_pk_fma_f32 v[78:79], v[164:165], v[78:79], v[80:81] neg_lo:[0,0,1] neg_hi:[0,0,1]
	s_nop 0
	v_cvt_pk_bf16_f32 v71, v78, v79
	ds_read2_b64 v[72:75], v193 offset0:128 offset1:130
	ds_read2_b64 v[76:79], v193 offset0:132 offset1:134
	s_waitcnt lgkmcnt(1)
	v_mfma_f32_32x32x16_bf16 v[48:63], v[72:75], v[64:67], v[48:63]
	s_waitcnt lgkmcnt(0)
	v_mfma_f32_32x32x16_bf16 v[48:63], v[76:79], v[68:71], v[48:63]
	ds_read2_b64 v[72:75], v196 offset0:128 offset1:130
	ds_read2_b64 v[76:79], v196 offset0:132 offset1:134
	s_waitcnt lgkmcnt(1)
	v_mfma_f32_32x32x16_bf16 v[32:47], v[72:75], v[64:67], v[32:47]
	ds_read2_b64 v[72:75], v195 offset1:2
	s_waitcnt lgkmcnt(0)
	v_mfma_f32_32x32x16_bf16 v[16:31], v[72:75], v[64:67], v[16:31]
	ds_read2_b64 v[72:75], v195 offset0:4 offset1:6
	s_waitcnt lgkmcnt(0)
	v_mfma_f32_32x32x16_bf16 v[16:31], v[72:75], v[68:71], v[16:31]
	ds_read2_b64 v[72:75], v194 offset0:64 offset1:66
	s_waitcnt lgkmcnt(0)
; #define MFMA(a, b, c) __builtin_amdgcn_mfma_f32_32x32x16_bf16((a), (b), (c), 0, 0, 0)
; DI f32x16 zero16() { f32x16 z; for (int i = 0; i < 16; ++i) z[i] = 0.f; return z; }
; DI void attn_unit(const Params& p, int l, int unit, unsigned char* smem) {
;     ...
;     for (int kb = 0; kb < 2; ++kb) {
;       f32x16 s0 = zero16(), s1 = zero16();
; #pragma unroll
;       for (int s = 0; s < 4; ++s) {
;         s0 = MFMA(ld16(sK + (32 * kb + l31) * 136 + 16 * s + 8 * h), qf[0][s], s0);
;         s1 = MFMA(ld16(sK + (32 * kb + l31) * 136 + 64 + 16 * s + 8 * h), qf[1][s], s1);
;       }
; #pragma unroll
;       for (int r = 0; r < 16; ++r) s0[r] = __builtin_amdgcn_exp2f(fmaf(s0[r], cs, nm[0])) * sc[0] - __builtin_amdgcn_exp2f(fmaf(s1[r], cs, nm[1])) * sc[1];
;       const bf16x8 p0 = pack8<0>(s0), p1 = pack8<1>(s0);
; #pragma unroll
;       for (int dvb = 0; dvb < 4; ++dvb) {
;         oacc[dvb] = MFMA(ld2x8(sVT + (32 * dvb + l31) * 72 + 32 * kb + 4 * h), p0, oacc[dvb]);
;         oacc[dvb] = MFMA(ld2x8(sVT + (32 * dvb + l31) * 72 + 32 * kb + 16 + 4 * h), p1, oacc[dvb]);
;       }
	v_mfma_f32_32x32x16_bf16 v[0:15], v[72:75], v[64:67], v[0:15]
	ds_read2_b64 v[64:67], v194 offset0:68 offset1:70
	s_waitcnt lgkmcnt(0)
	v_mfma_f32_32x32x16_bf16 v[0:15], v[64:67], v[68:71], v[0:15]
	ds_read_b128 v[64:67], v192
	ds_read_b128 v[128:131], v192 offset:32
	ds_read_b128 v[80:83], v192 offset:128
	v_mfma_f32_32x32x16_bf16 v[32:47], v[76:79], v[68:71], v[32:47]
	s_waitcnt lgkmcnt(2)
	v_mfma_f32_32x32x16_bf16 v[64:79], v[64:67], v[120:123], 0
	s_waitcnt lgkmcnt(1)
	v_mfma_f32_32x32x16_bf16 v[64:79], v[128:131], v[116:119], v[64:79]
	ds_read_b128 v[116:119], v192 offset:160
	s_waitcnt lgkmcnt(1)
	v_mfma_f32_32x32x16_bf16 v[80:95], v[80:83], v[124:127], 0
	s_waitcnt lgkmcnt(0)
	v_mfma_f32_32x32x16_bf16 v[80:95], v[116:119], v[112:115], v[80:95]
	ds_read_b128 v[112:115], v192 offset:64
	s_waitcnt lgkmcnt(0)
	v_mfma_f32_32x32x16_bf16 v[64:79], v[112:115], v[104:107], v[64:79]
	ds_read_b128 v[104:107], v192 offset:192
	s_waitcnt lgkmcnt(0)
	v_mfma_f32_32x32x16_bf16 v[80:95], v[104:107], v[108:111], v[80:95]
	ds_read_b128 v[104:107], v192 offset:96
	s_waitcnt lgkmcnt(0)
	v_mfma_f32_32x32x16_bf16 v[64:79], v[104:107], v[100:103], v[64:79]
	ds_read_b128 v[100:103], v192 offset:224
	s_waitcnt lgkmcnt(0)
	v_mfma_f32_32x32x16_bf16 v[80:95], v[100:103], v[96:99], v[80:95]
	s_nop 8
	v_fmamk_f32 v64, v64, 0x3e38aa3b, v190
	v_fmamk_f32 v65, v65, 0x3e38aa3b, v190
	v_exp_f32_e32 v64, v64
	v_exp_f32_e32 v65, v65
	v_fmamk_f32 v66, v66, 0x3e38aa3b, v190
	v_fmamk_f32 v67, v67, 0x3e38aa3b, v190
	v_exp_f32_e32 v66, v66
	v_fmamk_f32 v80, v80, 0x3e38aa3b, v191
	v_fmamk_f32 v81, v81, 0x3e38aa3b, v191
	v_exp_f32_e32 v80, v80
	v_exp_f32_e32 v81, v81
	v_exp_f32_e32 v67, v67
	v_fmamk_f32 v68, v68, 0x3e38aa3b, v190
	v_fmamk_f32 v69, v69, 0x3e38aa3b, v190
	v_pk_mul_f32 v[80:81], v[166:167], v[80:81]
	v_exp_f32_e32 v68, v68
	v_pk_fma_f32 v[64:65], v[164:165], v[64:65], v[80:81] neg_lo:[0,0,1] neg_hi:[0,0,1]
	v_fmamk_f32 v80, v82, 0x3e38aa3b, v191
	v_fmamk_f32 v81, v83, 0x3e38aa3b, v191
	v_exp_f32_e32 v80, v80
	v_exp_f32_e32 v81, v81
	v_exp_f32_e32 v69, v69
	v_fmamk_f32 v70, v70, 0x3e38aa3b, v190
	v_fmamk_f32 v71, v71, 0x3e38aa3b, v190
	v_pk_mul_f32 v[80:81], v[166:167], v[80:81]
	v_exp_f32_e32 v70, v70
	v_pk_fma_f32 v[66:67], v[164:165], v[66:67], v[80:81] neg_lo:[0,0,1] neg_hi:[0,0,1]
	v_fmamk_f32 v80, v84, 0x3e38aa3b, v191
	v_fmamk_f32 v81, v85, 0x3e38aa3b, v191
	v_exp_f32_e32 v80, v80
	v_exp_f32_e32 v81, v81
	v_exp_f32_e32 v71, v71
	v_fmamk_f32 v72, v72, 0x3e38aa3b, v190
	v_fmamk_f32 v73, v73, 0x3e38aa3b, v190
	v_pk_mul_f32 v[80:81], v[166:167], v[80:81]
	v_exp_f32_e32 v72, v72
	v_pk_fma_f32 v[68:69], v[164:165], v[68:69], v[80:81] neg_lo:[0,0,1] neg_hi:[0,0,1]
	v_fmamk_f32 v80, v86, 0x3e38aa3b, v191
	v_fmamk_f32 v81, v87, 0x3e38aa3b, v191
	v_exp_f32_e32 v80, v80
	v_exp_f32_e32 v81, v81
	v_exp_f32_e32 v73, v73
	v_fmamk_f32 v74, v74, 0x3e38aa3b, v190
	v_fmamk_f32 v75, v75, 0x3e38aa3b, v190
	v_pk_mul_f32 v[80:81], v[166:167], v[80:81]
	v_exp_f32_e32 v74, v74
	v_pk_fma_f32 v[70:71], v[164:165], v[70:71], v[80:81] neg_lo:[0,0,1] neg_hi:[0,0,1]
	v_fmamk_f32 v80, v88, 0x3e38aa3b, v191
	v_fmamk_f32 v81, v89, 0x3e38aa3b, v191
	v_exp_f32_e32 v80, v80
	v_exp_f32_e32 v81, v81
	v_exp_f32_e32 v75, v75
	v_cvt_pk_bf16_f32 v64, v64, v65
	v_cvt_pk_bf16_f32 v65, v66, v67
	v_pk_mul_f32 v[80:81], v[166:167], v[80:81]
	v_cvt_pk_bf16_f32 v66, v68, v69
	v_pk_fma_f32 v[72:73], v[164:165], v[72:73], v[80:81] neg_lo:[0,0,1] neg_hi:[0,0,1]
	v_fmamk_f32 v80, v90, 0x3e38aa3b, v191
	v_fmamk_f32 v81, v91, 0x3e38aa3b, v191
	v_exp_f32_e32 v80, v80
	v_exp_f32_e32 v81, v81
	v_cvt_pk_bf16_f32 v68, v72, v73
	v_fmamk_f32 v76, v76, 0x3e38aa3b, v190
	v_fmamk_f32 v77, v77, 0x3e38aa3b, v190
	v_pk_mul_f32 v[80:81], v[166:167], v[80:81]
	v_exp_f32_e32 v76, v76
	v_pk_fma_f32 v[74:75], v[164:165], v[74:75], v[80:81] neg_lo:[0,0,1] neg_hi:[0,0,1]
	v_fmamk_f32 v80, v92, 0x3e38aa3b, v191
	v_cvt_pk_bf16_f32 v69, v74, v75
	ds_read2_b64 v[72:75], v193 offset0:136 offset1:138
	v_fmamk_f32 v81, v93, 0x3e38aa3b, v191
	v_exp_f32_e32 v80, v80
	v_exp_f32_e32 v81, v81
	v_exp_f32_e32 v77, v77
	v_cvt_pk_bf16_f32 v67, v70, v71
	v_fmamk_f32 v78, v78, 0x3e38aa3b, v190
	v_pk_mul_f32 v[80:81], v[166:167], v[80:81]
	s_waitcnt lgkmcnt(0)
	v_mfma_f32_32x32x16_bf16 v[48:63], v[72:75], v[64:67], v[48:63]
	ds_read2_b64 v[72:75], v193 offset0:140 offset1:142
	v_fma_f32 v76, v164, v76, -v80
	v_fma_f32 v77, v165, v77, -v81
	v_fmamk_f32 v80, v94, 0x3e38aa3b, v191
	v_fmac_f32_e32 v191, 0x3e38aa3b, v95
	v_exp_f32_e32 v80, v80
	v_fmac_f32_e32 v190, 0x3e38aa3b, v79
	v_exp_f32_e32 v81, v191
	v_exp_f32_e32 v78, v78
	v_exp_f32_e32 v79, v190
	v_cvt_pk_bf16_f32 v70, v76, v77
	v_pk_mul_f32 v[80:81], v[166:167], v[80:81]
	s_nop 0
	v_pk_fma_f32 v[78:79], v[164:165], v[78:79], v[80:81] neg_lo:[0,0,1] neg_hi:[0,0,1]
	s_nop 0
	v_cvt_pk_bf16_f32 v71, v78, v79
	s_waitcnt lgkmcnt(0)
	s_nop 0
	v_mfma_f32_32x32x16_bf16 v[48:63], v[72:75], v[68:71], v[48:63]
	ds_read2_b64 v[72:75], v196 offset0:136 offset1:138
	ds_read2_b64 v[76:79], v196 offset0:140 offset1:142
	s_waitcnt lgkmcnt(1)
	v_mfma_f32_32x32x16_bf16 v[32:47], v[72:75], v[64:67], v[32:47]
	ds_read2_b64 v[72:75], v195 offset0:8 offset1:10
	s_waitcnt lgkmcnt(0)
	v_mfma_f32_32x32x16_bf16 v[16:31], v[72:75], v[64:67], v[16:31]
	ds_read2_b64 v[72:75], v195 offset0:12 offset1:14
	s_waitcnt lgkmcnt(0)
	v_mfma_f32_32x32x16_bf16 v[16:31], v[72:75], v[68:71], v[16:31]
	ds_read2_b64 v[72:75], v194 offset0:72 offset1:74
	s_waitcnt lgkmcnt(0)
; #define MFMA(a, b, c) __builtin_amdgcn_mfma_f32_32x32x16_bf16((a), (b), (c), 0, 0, 0)
; DI float bf2f(bfr v) { return __uint_as_float(((unsigned)v) << 16); }
; DI float siluf_(float x) { return x / (1.f + __expf(-x)); }
; DI void attn_unit(const Params& p, int l, int unit, unsigned char* smem) {
;     ...
;         oacc[dvb] = MFMA(ld2x8(sVT + (32 * dvb + l31) * 72 + 32 * kb + 16 + 4 * h), p1, oacc[dvb]);
;       }
;     }
;   }
;   float ss = 0.f;
; #pragma unroll
;   for (int dvb = 0; dvb < 4; ++dvb)
; #pragma unroll
;     for (int r = 0; r < 16; ++r) ss += oacc[dvb][r] * oacc[dvb][r];
;   ss += __shfl_xor(ss, 32);
;   const float rs = rsqrtf(ss * (1.f / 128.f) + EPS) * (1.f - lam_init);
;     ...
; #pragma unroll
;   for (int dvb = 0; dvb < 4; ++dvb)
; #pragma unroll
;     for (int g = 0; g < 4; ++g) {
;       const int dv = 32 * dvb + 8 * g + 4 * h;
;       const s16x4 z4 = *(const s16x4*)(P + rowq * PLD + C_DAZ + hd * 128 + dv);
;       const f32x4 gn = *(const f32x4*)(p.da_norm + l * 128 + dv);
;       float y[4];
;       for (int q = 0; q < 4; ++q) y[q] = oacc[dvb][4 * g + q] * rs * gn[q] * siluf_(bf2f((bfr)z4[q]));
	v_mfma_f32_32x32x16_bf16 v[0:15], v[72:75], v[64:67], v[0:15]
	v_mul_f32_e32 v74, v49, v49
	v_fmac_f32_e32 v74, v48, v48
	v_fmac_f32_e32 v74, v50, v50
	v_fmac_f32_e32 v74, v51, v51
	v_fmac_f32_e32 v74, v52, v52
	v_fmac_f32_e32 v74, v53, v53
	v_fmac_f32_e32 v74, v54, v54
	v_fmac_f32_e32 v74, v55, v55
	v_mfma_f32_32x32x16_bf16 v[32:47], v[76:79], v[68:71], v[32:47]
	v_fmac_f32_e32 v74, v56, v56
	v_fmac_f32_e32 v74, v57, v57
	v_fmac_f32_e32 v74, v58, v58
	v_fmac_f32_e32 v74, v59, v59
	v_fmac_f32_e32 v74, v60, v60
	v_fmac_f32_e32 v74, v61, v61
	v_fmac_f32_e32 v74, v62, v62
	v_fmac_f32_e32 v74, v63, v63
	s_nop 3
	v_fmac_f32_e32 v74, v32, v32
	v_fmac_f32_e32 v74, v33, v33
	v_fmac_f32_e32 v74, v34, v34
	v_fmac_f32_e32 v74, v35, v35
	v_fmac_f32_e32 v74, v36, v36
	v_fmac_f32_e32 v74, v37, v37
	v_fmac_f32_e32 v74, v38, v38
	v_fmac_f32_e32 v74, v39, v39
	v_fmac_f32_e32 v74, v40, v40
	v_fmac_f32_e32 v74, v41, v41
	v_fmac_f32_e32 v74, v42, v42
	v_fmac_f32_e32 v74, v43, v43
	v_fmac_f32_e32 v74, v44, v44
	v_fmac_f32_e32 v74, v45, v45
	v_fmac_f32_e32 v74, v46, v46
	ds_read2_b64 v[64:67], v194 offset0:76 offset1:78
	v_fmac_f32_e32 v74, v47, v47
	v_fmac_f32_e32 v74, v16, v16
	v_fmac_f32_e32 v74, v17, v17
	v_fmac_f32_e32 v74, v18, v18
	v_fmac_f32_e32 v74, v19, v19
	v_fmac_f32_e32 v74, v20, v20
	v_fmac_f32_e32 v74, v21, v21
	v_fmac_f32_e32 v74, v22, v22
	v_fmac_f32_e32 v74, v23, v23
	s_waitcnt lgkmcnt(0)
	v_mfma_f32_32x32x16_bf16 v[0:15], v[64:67], v[68:71], v[0:15]
	v_fmac_f32_e32 v74, v24, v24
	v_fmac_f32_e32 v74, v25, v25
	v_fmac_f32_e32 v74, v26, v26
	v_fmac_f32_e32 v74, v27, v27
	v_fmac_f32_e32 v74, v28, v28
	v_fmac_f32_e32 v74, v29, v29
	v_fmac_f32_e32 v74, v30, v30
	v_fmac_f32_e32 v74, v31, v31
	s_nop 3
	v_fmac_f32_e32 v74, v0, v0
	v_fmac_f32_e32 v74, v1, v1
	v_fmac_f32_e32 v74, v2, v2
	v_fmac_f32_e32 v74, v3, v3
	v_fmac_f32_e32 v74, v4, v4
	v_fmac_f32_e32 v74, v5, v5
	v_pk_mul_f32 v[72:73], v[6:7], v[6:7]
	v_pk_mul_f32 v[70:71], v[8:9], v[8:9]
	v_add_f32_e32 v72, v72, v74
	v_add_f32_e32 v72, v73, v72
	v_add_f32_e32 v70, v70, v72
	v_pk_mul_f32 v[68:69], v[10:11], v[10:11]
	v_add_f32_e32 v70, v71, v70
	v_add_f32_e32 v68, v68, v70
	v_pk_mul_f32 v[66:67], v[12:13], v[12:13]
	v_add_f32_e32 v68, v69, v68
	v_add_f32_e32 v66, v66, v68
	v_pk_mul_f32 v[64:65], v[14:15], v[14:15]
	v_add_f32_e32 v66, v67, v66
	v_add_f32_e32 v64, v64, v66
	v_add_f32_e32 v64, v65, v64
	ds_bpermute_b32 v65, v189, v64
	v_lshlrev_b64 v[68:69], 12, v[160:161]
	v_lshl_add_u64 v[66:67], v[162:163], 0, s[44:45]
	v_lshl_add_u64 v[68:69], s[10:11], 0, v[68:69]
	v_lshl_add_u64 v[72:73], v[68:69], 0, s[44:45]
	s_waitcnt lgkmcnt(0)
	v_add_f32_e32 v64, v64, v65
	v_fmamk_f32 v64, v64, 0x3c000000, v217
	v_cmp_gt_f32_e32 vcc, s37, v64
	v_mul_f32_e32 v65, 0x4b800000, v64
	v_lshl_add_u64 v[68:69], v[66:67], 0, v[208:209]
	v_cndmask_b32_e32 v64, v64, v65, vcc
	v_rsq_f32_e32 v64, v64
	s_mov_b64 s[10:11], 0x3c00
	v_lshl_add_u64 v[66:67], v[68:69], 0, s[10:11]
	s_movk_i32 s10, 0x3000
	v_mul_f32_e32 v65, 0x45800000, v64
	v_cndmask_b32_e32 v64, v64, v65, vcc
	v_add_co_u32_e32 v68, vcc, s10, v68
	v_lshlrev_b32_e32 v65, 2, v188
	s_nop 0
	v_addc_co_u32_e32 v69, vcc, 0, v69, vcc
	flat_load_dwordx2 v[74:75], v[68:69] offset:3072
	v_mul_f32_e32 v64, v244, v64
	global_load_dwordx4 v[68:71], v65, s[18:19]
	v_pk_mul_f32 v[48:49], v[48:49], v[64:65] op_sel_hi:[1,0]
	v_pk_mul_f32 v[50:51], v[50:51], v[64:65] op_sel_hi:[1,0]
	v_pk_mul_f32 v[52:53], v[52:53], v[64:65] op_sel_hi:[1,0]
	v_pk_mul_f32 v[54:55], v[54:55], v[64:65] op_sel_hi:[1,0]
	v_pk_mul_f32 v[56:57], v[56:57], v[64:65] op_sel_hi:[1,0]
	v_pk_mul_f32 v[32:33], v[32:33], v[64:65] op_sel_hi:[1,0]
	v_pk_mul_f32 v[34:35], v[34:35], v[64:65] op_sel_hi:[1,0]
	v_pk_mul_f32 v[36:37], v[36:37], v[64:65] op_sel_hi:[1,0]
	v_pk_mul_f32 v[38:39], v[38:39], v[64:65] op_sel_hi:[1,0]
	v_pk_mul_f32 v[40:41], v[40:41], v[64:65] op_sel_hi:[1,0]
	v_pk_mul_f32 v[16:17], v[16:17], v[64:65] op_sel_hi:[1,0]
	v_pk_mul_f32 v[18:19], v[18:19], v[64:65] op_sel_hi:[1,0]
	v_pk_mul_f32 v[20:21], v[20:21], v[64:65] op_sel_hi:[1,0]
	v_pk_mul_f32 v[22:23], v[22:23], v[64:65] op_sel_hi:[1,0]
	v_pk_mul_f32 v[24:25], v[24:25], v[64:65] op_sel_hi:[1,0]
	v_pk_mul_f32 v[0:1], v[0:1], v[64:65] op_sel_hi:[1,0]
	v_pk_mul_f32 v[2:3], v[2:3], v[64:65] op_sel_hi:[1,0]
	v_pk_mul_f32 v[4:5], v[4:5], v[64:65] op_sel_hi:[1,0]
	v_pk_mul_f32 v[6:7], v[6:7], v[64:65] op_sel_hi:[1,0]
	v_pk_mul_f32 v[8:9], v[8:9], v[64:65] op_sel_hi:[1,0]
	s_waitcnt vmcnt(0) lgkmcnt(0)
; DI float bf2f(bfr v) { return __uint_as_float(((unsigned)v) << 16); }
; DI unsigned pk2(float a, float b) { f2_t v = {a, b}; bf2_t r = __builtin_convertvector(v, bf2_t); return __builtin_bit_cast(unsigned, r); }
; DI float siluf_(float x) { return x / (1.f + __expf(-x)); }
; DI void attn_unit(const Params& p, int l, int unit, unsigned char* smem) {
;     ...
; #pragma unroll
;   for (int dvb = 0; dvb < 4; ++dvb)
; #pragma unroll
;     for (int g = 0; g < 4; ++g) {
;       const int dv = 32 * dvb + 8 * g + 4 * h;
;       const s16x4 z4 = *(const s16x4*)(P + rowq * PLD + C_DAZ + hd * 128 + dv);
;       const f32x4 gn = *(const f32x4*)(p.da_norm + l * 128 + dv);
;       float y[4];
;       for (int q = 0; q < 4; ++q) y[q] = oacc[dvb][4 * g + q] * rs * gn[q] * siluf_(bf2f((bfr)z4[q]));
;       u32x2 w; w[0] = pk2(y[0], y[1]); w[1] = pk2(y[2], y[3]);
;       *(u32x2*)(YS + rowq * DM + 1536 + hd * 128 + dv) = w;
;     }
	v_and_b32_e32 v78, 0xffff0000, v74
	v_lshlrev_b32_e32 v74, 16, v74
	v_mul_f32_e32 v76, 0xbfb8aa3b, v74
	v_pk_mul_f32 v[48:49], v[68:69], v[48:49]
	v_mul_f32_e32 v68, 0xbfb8aa3b, v78
	v_exp_f32_e32 v76, v76
	v_exp_f32_e32 v77, v68
	v_pk_mul_f32 v[50:51], v[70:71], v[50:51]
	v_pk_add_f32 v[68:69], v[76:77], 1.0 op_sel_hi:[1,0]
	s_nop 0
	v_div_scale_f32 v76, s[10:11], v69, v69, v78
	v_rcp_f32_e32 v77, v76
	s_nop 0
	v_fma_f32 v79, -v76, v77, 1.0
	v_fmac_f32_e32 v77, v79, v77
	v_div_scale_f32 v79, vcc, v78, v69, v78
	v_mul_f32_e32 v80, v79, v77
	v_fma_f32 v81, -v76, v80, v79
	v_fmac_f32_e32 v80, v81, v77
	v_fma_f32 v76, -v76, v80, v79
	v_div_fmas_f32 v76, v76, v77, v80
	v_div_fixup_f32 v69, v76, v69, v78
	v_div_scale_f32 v76, s[10:11], v68, v68, v74
	v_rcp_f32_e32 v77, v76
	s_nop 0
	v_fma_f32 v78, -v76, v77, 1.0
	v_fmac_f32_e32 v77, v78, v77
	v_div_scale_f32 v78, vcc, v74, v68, v74
	v_mul_f32_e32 v79, v78, v77
	v_fma_f32 v80, -v76, v79, v78
	v_fmac_f32_e32 v79, v80, v77
	v_fma_f32 v76, -v76, v79, v78
	v_div_fmas_f32 v76, v76, v77, v79
	v_div_fixup_f32 v68, v76, v68, v74
	v_and_b32_e32 v74, 0xffff0000, v75
	v_lshlrev_b32_e32 v75, 16, v75
	v_pk_mul_f32 v[48:49], v[68:69], v[48:49]
	v_mul_f32_e32 v68, 0xbfb8aa3b, v75
	v_mul_f32_e32 v69, 0xbfb8aa3b, v74
	v_exp_f32_e32 v68, v68
	v_exp_f32_e32 v69, v69
	s_nop 0
	v_pk_add_f32 v[68:69], v[68:69], 1.0 op_sel_hi:[1,0]
	s_nop 0
	v_div_scale_f32 v70, s[10:11], v69, v69, v74
	v_rcp_f32_e32 v71, v70
	s_nop 0
	v_fma_f32 v76, -v70, v71, 1.0
	v_fmac_f32_e32 v71, v76, v71
	v_div_scale_f32 v76, vcc, v74, v69, v74
	v_mul_f32_e32 v77, v76, v71
	v_fma_f32 v78, -v70, v77, v76
	v_fmac_f32_e32 v77, v78, v71
	v_fma_f32 v70, -v70, v77, v76
	v_div_fmas_f32 v70, v70, v71, v77
	v_div_fixup_f32 v69, v70, v69, v74
	v_div_scale_f32 v70, s[10:11], v68, v68, v75
	v_rcp_f32_e32 v71, v70
	s_mov_b64 s[10:11], 0x33110c00
	v_fma_f32 v74, -v70, v71, 1.0
	v_fmac_f32_e32 v71, v74, v71
	v_div_scale_f32 v74, vcc, v75, v68, v75
	v_mul_f32_e32 v76, v74, v71
	v_fma_f32 v77, -v70, v76, v74
	v_fmac_f32_e32 v76, v77, v71
	v_fma_f32 v70, -v70, v76, v74
	v_div_fmas_f32 v70, v70, v71, v76
	v_div_fixup_f32 v68, v70, v68, v75
	v_pk_mul_f32 v[50:51], v[68:69], v[50:51]
	v_cvt_pk_bf16_f32 v68, v48, v49
	v_cvt_pk_bf16_f32 v69, v50, v51
	v_lshl_add_u64 v[50:51], v[72:73], 0, v[208:209]
	v_lshl_add_u64 v[48:49], v[50:51], 0, s[10:11]
	s_mov_b32 s10, 0x33110000
	v_add_co_u32_e32 v50, vcc, s10, v50
	s_nop 1
	v_addc_co_u32_e32 v51, vcc, 0, v51, vcc
	flat_store_dwordx2 v[50:51], v[68:69] offset:3072
	flat_load_dwordx2 v[50:51], v[66:67] offset:16
	s_nop 0
	global_load_dwordx4 v[68:71], v65, s[18:19] offset:32
	s_waitcnt vmcnt(0) lgkmcnt(0)
	v_and_b32_e32 v74, 0xffff0000, v50
	v_lshlrev_b32_e32 v50, 16, v50
	v_mul_f32_e32 v72, 0xbfb8aa3b, v50
	v_pk_mul_f32 v[52:53], v[68:69], v[52:53]
	v_mul_f32_e32 v68, 0xbfb8aa3b, v74
	v_exp_f32_e32 v72, v72
	v_exp_f32_e32 v73, v68
	v_pk_mul_f32 v[54:55], v[70:71], v[54:55]
	v_pk_add_f32 v[68:69], v[72:73], 1.0 op_sel_hi:[1,0]
	s_nop 0
	v_div_scale_f32 v72, s[10:11], v69, v69, v74
	v_rcp_f32_e32 v73, v72
	s_nop 0
	v_fma_f32 v75, -v72, v73, 1.0
	v_fmac_f32_e32 v73, v75, v73
	v_div_scale_f32 v75, vcc, v74, v69, v74
	v_mul_f32_e32 v76, v75, v73
	v_fma_f32 v77, -v72, v76, v75
	v_fmac_f32_e32 v76, v77, v73
	v_fma_f32 v72, -v72, v76, v75
	v_div_fmas_f32 v72, v72, v73, v76
	v_div_fixup_f32 v69, v72, v69, v74
	v_div_scale_f32 v72, s[10:11], v68, v68, v50
	v_rcp_f32_e32 v73, v72
	s_nop 0
	v_fma_f32 v74, -v72, v73, 1.0
	v_fmac_f32_e32 v73, v74, v73
	v_div_scale_f32 v74, vcc, v50, v68, v50
	v_mul_f32_e32 v75, v74, v73
	v_fma_f32 v76, -v72, v75, v74
	v_fmac_f32_e32 v75, v76, v73
	v_fma_f32 v72, -v72, v75, v74
	v_div_fmas_f32 v72, v72, v73, v75
	v_div_fixup_f32 v68, v72, v68, v50
	v_pk_mul_f32 v[52:53], v[68:69], v[52:53]
	v_and_b32_e32 v68, 0xffff0000, v51
	v_lshlrev_b32_e32 v69, 16, v51
	v_mul_f32_e32 v50, 0xbfb8aa3b, v69
	v_mul_f32_e32 v51, 0xbfb8aa3b, v68
	v_exp_f32_e32 v50, v50
	v_exp_f32_e32 v51, v51
	v_cvt_pk_bf16_f32 v52, v52, v53
	v_pk_add_f32 v[50:51], v[50:51], 1.0 op_sel_hi:[1,0]
	s_nop 0
	v_div_scale_f32 v70, s[10:11], v51, v51, v68
	v_rcp_f32_e32 v71, v70
	s_nop 0
	v_fma_f32 v72, -v70, v71, 1.0
	v_fmac_f32_e32 v71, v72, v71
	v_div_scale_f32 v72, vcc, v68, v51, v68
	v_mul_f32_e32 v73, v72, v71
	v_fma_f32 v74, -v70, v73, v72
	v_fmac_f32_e32 v73, v74, v71
	v_fma_f32 v70, -v70, v73, v72
	v_div_fmas_f32 v70, v70, v71, v73
	v_div_fixup_f32 v51, v70, v51, v68
	v_div_scale_f32 v68, s[10:11], v50, v50, v69
	v_rcp_f32_e32 v70, v68
	s_nop 0
	v_fma_f32 v71, -v68, v70, 1.0
	v_fmac_f32_e32 v70, v71, v70
	v_div_scale_f32 v71, vcc, v69, v50, v69
	v_mul_f32_e32 v72, v71, v70
	v_fma_f32 v73, -v68, v72, v71
	v_fmac_f32_e32 v72, v73, v70
	v_fma_f32 v68, -v68, v72, v71
	v_div_fmas_f32 v68, v68, v70, v72
	v_div_fixup_f32 v50, v68, v50, v69
	v_pk_mul_f32 v[50:51], v[50:51], v[54:55]
	s_nop 0
	v_cvt_pk_bf16_f32 v53, v50, v51
	flat_store_dwordx2 v[48:49], v[52:53] offset:16
	flat_load_dwordx2 v[54:55], v[66:67] offset:32
	s_nop 0
	global_load_dwordx4 v[50:53], v65, s[18:19] offset:64
	s_waitcnt vmcnt(0) lgkmcnt(0)
; DI float bf2f(bfr v) { return __uint_as_float(((unsigned)v) << 16); }
; DI unsigned pk2(float a, float b) { f2_t v = {a, b}; bf2_t r = __builtin_convertvector(v, bf2_t); return __builtin_bit_cast(unsigned, r); }
; DI float siluf_(float x) { return x / (1.f + __expf(-x)); }
; DI void attn_unit(const Params& p, int l, int unit, unsigned char* smem) {
;     ...
; #pragma unroll
;   for (int dvb = 0; dvb < 4; ++dvb)
; #pragma unroll
;     for (int g = 0; g < 4; ++g) {
;       const int dv = 32 * dvb + 8 * g + 4 * h;
;       const s16x4 z4 = *(const s16x4*)(P + rowq * PLD + C_DAZ + hd * 128 + dv);
;       const f32x4 gn = *(const f32x4*)(p.da_norm + l * 128 + dv);
;       float y[4];
;       for (int q = 0; q < 4; ++q) y[q] = oacc[dvb][4 * g + q] * rs * gn[q] * siluf_(bf2f((bfr)z4[q]));
;       u32x2 w; w[0] = pk2(y[0], y[1]); w[1] = pk2(y[2], y[3]);
;       *(u32x2*)(YS + rowq * DM + 1536 + hd * 128 + dv) = w;
;     }
	v_and_b32_e32 v70, 0xffff0000, v54
	v_lshlrev_b32_e32 v54, 16, v54
	v_mul_f32_e32 v68, 0xbfb8aa3b, v54
	v_pk_mul_f32 v[50:51], v[50:51], v[56:57]
	v_mul_f32_e32 v56, 0xbfb8aa3b, v70
	v_exp_f32_e32 v68, v68
	v_exp_f32_e32 v69, v56
	s_nop 0
	v_pk_add_f32 v[56:57], v[68:69], 1.0 op_sel_hi:[1,0]
	s_nop 0
	v_div_scale_f32 v68, s[10:11], v57, v57, v70
	v_rcp_f32_e32 v69, v68
	s_nop 0
	v_fma_f32 v71, -v68, v69, 1.0
	v_fmac_f32_e32 v69, v71, v69
	v_div_scale_f32 v71, vcc, v70, v57, v70
	v_mul_f32_e32 v72, v71, v69
	v_fma_f32 v73, -v68, v72, v71
	v_fmac_f32_e32 v72, v73, v69
	v_fma_f32 v68, -v68, v72, v71
	v_div_fmas_f32 v68, v68, v69, v72
	v_div_fixup_f32 v57, v68, v57, v70
	v_div_scale_f32 v68, s[10:11], v56, v56, v54
	v_rcp_f32_e32 v69, v68
	s_nop 0
	v_fma_f32 v70, -v68, v69, 1.0
	v_fmac_f32_e32 v69, v70, v69
	v_div_scale_f32 v70, vcc, v54, v56, v54
	v_mul_f32_e32 v71, v70, v69
	v_fma_f32 v72, -v68, v71, v70
	v_fmac_f32_e32 v71, v72, v69
	v_fma_f32 v68, -v68, v71, v70
	v_div_fmas_f32 v68, v68, v69, v71
	v_div_fixup_f32 v56, v68, v56, v54
	v_and_b32_e32 v68, 0xffff0000, v55
	v_lshlrev_b32_e32 v69, 16, v55
	v_mul_f32_e32 v54, 0xbfb8aa3b, v69
	v_mul_f32_e32 v55, 0xbfb8aa3b, v68
	v_exp_f32_e32 v54, v54
	v_exp_f32_e32 v55, v55
	v_pk_mul_f32 v[50:51], v[56:57], v[50:51]
	v_pk_mul_f32 v[56:57], v[58:59], v[64:65] op_sel_hi:[1,0]
	v_cvt_pk_bf16_f32 v50, v50, v51
	v_pk_add_f32 v[54:55], v[54:55], 1.0 op_sel_hi:[1,0]
	v_pk_mul_f32 v[52:53], v[52:53], v[56:57]
	v_div_scale_f32 v56, s[10:11], v55, v55, v68
	v_rcp_f32_e32 v57, v56
	s_nop 0
	v_fma_f32 v58, -v56, v57, 1.0
	v_fmac_f32_e32 v57, v58, v57
	v_div_scale_f32 v58, vcc, v68, v55, v68
	v_mul_f32_e32 v59, v58, v57
	v_fma_f32 v70, -v56, v59, v58
	v_fmac_f32_e32 v59, v70, v57
	v_fma_f32 v56, -v56, v59, v58
	v_div_fmas_f32 v56, v56, v57, v59
	v_div_fixup_f32 v55, v56, v55, v68
	v_div_scale_f32 v56, s[10:11], v54, v54, v69
	v_rcp_f32_e32 v57, v56
	s_nop 0
	v_fma_f32 v58, -v56, v57, 1.0
	v_fmac_f32_e32 v57, v58, v57
	v_div_scale_f32 v58, vcc, v69, v54, v69
	v_mul_f32_e32 v59, v58, v57
	v_fma_f32 v68, -v56, v59, v58
	v_fmac_f32_e32 v59, v68, v57
	v_fma_f32 v56, -v56, v59, v58
	v_div_fmas_f32 v56, v56, v57, v59
	v_div_fixup_f32 v54, v56, v54, v69
	v_pk_mul_f32 v[52:53], v[54:55], v[52:53]
	v_pk_mul_f32 v[58:59], v[60:61], v[64:65] op_sel_hi:[1,0]
	v_cvt_pk_bf16_f32 v51, v52, v53
	flat_store_dwordx2 v[48:49], v[50:51] offset:32
	flat_load_dwordx2 v[54:55], v[66:67] offset:48
	s_nop 0
	global_load_dwordx4 v[50:53], v65, s[18:19] offset:96
	s_waitcnt vmcnt(0) lgkmcnt(0)
	v_and_b32_e32 v68, 0xffff0000, v54
	v_lshlrev_b32_e32 v54, 16, v54
	v_mul_f32_e32 v56, 0xbfb8aa3b, v54
	v_mul_f32_e32 v57, 0xbfb8aa3b, v68
	v_exp_f32_e32 v56, v56
	v_exp_f32_e32 v57, v57
	v_pk_mul_f32 v[50:51], v[50:51], v[58:59]
	v_pk_add_f32 v[56:57], v[56:57], 1.0 op_sel_hi:[1,0]
	s_nop 0
	v_div_scale_f32 v58, s[10:11], v57, v57, v68
	v_rcp_f32_e32 v59, v58
	s_nop 0
	v_fma_f32 v60, -v58, v59, 1.0
	v_fmac_f32_e32 v59, v60, v59
	v_div_scale_f32 v60, vcc, v68, v57, v68
	v_mul_f32_e32 v61, v60, v59
	v_fma_f32 v69, -v58, v61, v60
	v_fmac_f32_e32 v61, v69, v59
	v_fma_f32 v58, -v58, v61, v60
	v_div_fmas_f32 v58, v58, v59, v61
	v_div_fixup_f32 v57, v58, v57, v68
	v_div_scale_f32 v58, s[10:11], v56, v56, v54
	v_rcp_f32_e32 v59, v58
	s_nop 0
	v_fma_f32 v60, -v58, v59, 1.0
	v_fmac_f32_e32 v59, v60, v59
	v_div_scale_f32 v60, vcc, v54, v56, v54
	v_mul_f32_e32 v61, v60, v59
	v_fma_f32 v68, -v58, v61, v60
	v_fmac_f32_e32 v61, v68, v59
	v_fma_f32 v58, -v58, v61, v60
	v_div_fmas_f32 v58, v58, v59, v61
	v_div_fixup_f32 v56, v58, v56, v54
	v_and_b32_e32 v58, 0xffff0000, v55
	v_lshlrev_b32_e32 v59, 16, v55
	v_mul_f32_e32 v54, 0xbfb8aa3b, v59
	v_mul_f32_e32 v55, 0xbfb8aa3b, v58
	v_exp_f32_e32 v54, v54
	v_exp_f32_e32 v55, v55
	v_pk_mul_f32 v[50:51], v[56:57], v[50:51]
	v_pk_mul_f32 v[56:57], v[62:63], v[64:65] op_sel_hi:[1,0]
	v_cvt_pk_bf16_f32 v50, v50, v51
	v_pk_add_f32 v[54:55], v[54:55], 1.0 op_sel_hi:[1,0]
	v_pk_mul_f32 v[52:53], v[52:53], v[56:57]
	v_div_scale_f32 v56, s[10:11], v55, v55, v58
	v_rcp_f32_e32 v57, v56
	s_nop 0
	v_fma_f32 v60, -v56, v57, 1.0
	v_fmac_f32_e32 v57, v60, v57
	v_div_scale_f32 v60, vcc, v58, v55, v58
	v_mul_f32_e32 v61, v60, v57
	v_fma_f32 v62, -v56, v61, v60
	v_fmac_f32_e32 v61, v62, v57
	v_fma_f32 v56, -v56, v61, v60
	v_div_fmas_f32 v56, v56, v57, v61
	v_div_fixup_f32 v55, v56, v55, v58
	v_div_scale_f32 v56, s[10:11], v54, v54, v59
	v_rcp_f32_e32 v57, v56
	s_nop 0
	v_fma_f32 v58, -v56, v57, 1.0
	v_fmac_f32_e32 v57, v58, v57
	v_div_scale_f32 v58, vcc, v59, v54, v59
	v_mul_f32_e32 v60, v58, v57
	v_fma_f32 v61, -v56, v60, v58
	v_fmac_f32_e32 v60, v61, v57
	v_fma_f32 v56, -v56, v60, v58
	v_div_fmas_f32 v56, v56, v57, v60
	v_div_fixup_f32 v54, v56, v54, v59
	v_pk_mul_f32 v[52:53], v[54:55], v[52:53]
	s_nop 0
	v_cvt_pk_bf16_f32 v51, v52, v53
	flat_store_dwordx2 v[48:49], v[50:51] offset:48
	flat_load_dwordx2 v[54:55], v[66:67] offset:64
	s_nop 0
	global_load_dwordx4 v[50:53], v65, s[18:19] offset:128
	s_waitcnt vmcnt(0) lgkmcnt(0)
; DI float bf2f(bfr v) { return __uint_as_float(((unsigned)v) << 16); }
; DI unsigned pk2(float a, float b) { f2_t v = {a, b}; bf2_t r = __builtin_convertvector(v, bf2_t); return __builtin_bit_cast(unsigned, r); }
; DI float siluf_(float x) { return x / (1.f + __expf(-x)); }
; DI void attn_unit(const Params& p, int l, int unit, unsigned char* smem) {
;     ...
; #pragma unroll
;   for (int dvb = 0; dvb < 4; ++dvb)
; #pragma unroll
;     for (int g = 0; g < 4; ++g) {
;       const int dv = 32 * dvb + 8 * g + 4 * h;
;       const s16x4 z4 = *(const s16x4*)(P + rowq * PLD + C_DAZ + hd * 128 + dv);
;       const f32x4 gn = *(const f32x4*)(p.da_norm + l * 128 + dv);
;       float y[4];
;       for (int q = 0; q < 4; ++q) y[q] = oacc[dvb][4 * g + q] * rs * gn[q] * siluf_(bf2f((bfr)z4[q]));
;       u32x2 w; w[0] = pk2(y[0], y[1]); w[1] = pk2(y[2], y[3]);
;       *(u32x2*)(YS + rowq * DM + 1536 + hd * 128 + dv) = w;
;     }
	v_and_b32_e32 v58, 0xffff0000, v54
	v_lshlrev_b32_e32 v54, 16, v54
	v_mul_f32_e32 v56, 0xbfb8aa3b, v54
	v_pk_mul_f32 v[32:33], v[50:51], v[32:33]
	v_mul_f32_e32 v50, 0xbfb8aa3b, v58
	v_exp_f32_e32 v56, v56
	v_exp_f32_e32 v57, v50
	v_pk_mul_f32 v[34:35], v[52:53], v[34:35]
	v_pk_add_f32 v[50:51], v[56:57], 1.0 op_sel_hi:[1,0]
	s_nop 0
	v_div_scale_f32 v56, s[10:11], v51, v51, v58
	v_rcp_f32_e32 v57, v56
	s_nop 0
	v_fma_f32 v59, -v56, v57, 1.0
	v_fmac_f32_e32 v57, v59, v57
	v_div_scale_f32 v59, vcc, v58, v51, v58
	v_mul_f32_e32 v60, v59, v57
	v_fma_f32 v61, -v56, v60, v59
	v_fmac_f32_e32 v60, v61, v57
	v_fma_f32 v56, -v56, v60, v59
	v_div_fmas_f32 v56, v56, v57, v60
	v_div_fixup_f32 v51, v56, v51, v58
	v_div_scale_f32 v56, s[10:11], v50, v50, v54
	v_rcp_f32_e32 v57, v56
	s_nop 0
	v_fma_f32 v58, -v56, v57, 1.0
	v_fmac_f32_e32 v57, v58, v57
	v_div_scale_f32 v58, vcc, v54, v50, v54
	v_mul_f32_e32 v59, v58, v57
	v_fma_f32 v60, -v56, v59, v58
	v_fmac_f32_e32 v59, v60, v57
	v_fma_f32 v56, -v56, v59, v58
	v_div_fmas_f32 v56, v56, v57, v59
	v_div_fixup_f32 v50, v56, v50, v54
	v_and_b32_e32 v54, 0xffff0000, v55
	v_lshlrev_b32_e32 v55, 16, v55
	v_pk_mul_f32 v[32:33], v[50:51], v[32:33]
	v_mul_f32_e32 v50, 0xbfb8aa3b, v55
	v_mul_f32_e32 v51, 0xbfb8aa3b, v54
	v_exp_f32_e32 v50, v50
	v_exp_f32_e32 v51, v51
	v_cvt_pk_bf16_f32 v32, v32, v33
	v_pk_add_f32 v[50:51], v[50:51], 1.0 op_sel_hi:[1,0]
	s_nop 0
	v_div_scale_f32 v52, s[10:11], v51, v51, v54
	v_rcp_f32_e32 v53, v52
	s_nop 0
	v_fma_f32 v56, -v52, v53, 1.0
	v_fmac_f32_e32 v53, v56, v53
	v_div_scale_f32 v56, vcc, v54, v51, v54
	v_mul_f32_e32 v57, v56, v53
	v_fma_f32 v58, -v52, v57, v56
	v_fmac_f32_e32 v57, v58, v53
	v_fma_f32 v52, -v52, v57, v56
	v_div_fmas_f32 v52, v52, v53, v57
	v_div_fixup_f32 v51, v52, v51, v54
	v_div_scale_f32 v52, s[10:11], v50, v50, v55
	v_rcp_f32_e32 v53, v52
	s_nop 0
	v_fma_f32 v54, -v52, v53, 1.0
	v_fmac_f32_e32 v53, v54, v53
	v_div_scale_f32 v54, vcc, v55, v50, v55
	v_mul_f32_e32 v56, v54, v53
	v_fma_f32 v57, -v52, v56, v54
	v_fmac_f32_e32 v56, v57, v53
	v_fma_f32 v52, -v52, v56, v54
	v_div_fmas_f32 v52, v52, v53, v56
	v_div_fixup_f32 v50, v52, v50, v55
	v_pk_mul_f32 v[34:35], v[50:51], v[34:35]
	s_nop 0
	v_cvt_pk_bf16_f32 v33, v34, v35
	flat_store_dwordx2 v[48:49], v[32:33] offset:64
	flat_load_dwordx2 v[50:51], v[66:67] offset:80
	s_nop 0
	global_load_dwordx4 v[32:35], v65, s[18:19] offset:160
	s_waitcnt vmcnt(0) lgkmcnt(0)
	v_and_b32_e32 v54, 0xffff0000, v50
	v_lshlrev_b32_e32 v50, 16, v50
	v_mul_f32_e32 v52, 0xbfb8aa3b, v50
	v_pk_mul_f32 v[32:33], v[32:33], v[36:37]
	v_mul_f32_e32 v36, 0xbfb8aa3b, v54
	v_exp_f32_e32 v52, v52
	v_exp_f32_e32 v53, v36
	v_pk_mul_f32 v[34:35], v[34:35], v[38:39]
	v_pk_add_f32 v[36:37], v[52:53], 1.0 op_sel_hi:[1,0]
	s_nop 0
	v_div_scale_f32 v52, s[10:11], v37, v37, v54
	v_rcp_f32_e32 v53, v52
	s_nop 0
	v_fma_f32 v55, -v52, v53, 1.0
	v_fmac_f32_e32 v53, v55, v53
	v_div_scale_f32 v55, vcc, v54, v37, v54
	v_mul_f32_e32 v56, v55, v53
	v_fma_f32 v57, -v52, v56, v55
	v_fmac_f32_e32 v56, v57, v53
	v_fma_f32 v52, -v52, v56, v55
	v_div_fmas_f32 v52, v52, v53, v56
	v_div_fixup_f32 v37, v52, v37, v54
	v_div_scale_f32 v52, s[10:11], v36, v36, v50
	v_rcp_f32_e32 v53, v52
	s_nop 0
	v_fma_f32 v54, -v52, v53, 1.0
	v_fmac_f32_e32 v53, v54, v53
	v_div_scale_f32 v54, vcc, v50, v36, v50
	v_mul_f32_e32 v55, v54, v53
	v_fma_f32 v56, -v52, v55, v54
	v_fmac_f32_e32 v55, v56, v53
	v_fma_f32 v52, -v52, v55, v54
	v_div_fmas_f32 v52, v52, v53, v55
	v_div_fixup_f32 v36, v52, v36, v50
	v_and_b32_e32 v50, 0xffff0000, v51
	v_lshlrev_b32_e32 v51, 16, v51
	v_pk_mul_f32 v[32:33], v[36:37], v[32:33]
	v_mul_f32_e32 v36, 0xbfb8aa3b, v51
	v_mul_f32_e32 v37, 0xbfb8aa3b, v50
	v_exp_f32_e32 v36, v36
	v_exp_f32_e32 v37, v37
	v_cvt_pk_bf16_f32 v32, v32, v33
	v_pk_add_f32 v[36:37], v[36:37], 1.0 op_sel_hi:[1,0]
	s_nop 0
	v_div_scale_f32 v38, s[10:11], v37, v37, v50
	v_rcp_f32_e32 v39, v38
	s_nop 0
	v_fma_f32 v52, -v38, v39, 1.0
	v_fmac_f32_e32 v39, v52, v39
	v_div_scale_f32 v52, vcc, v50, v37, v50
	v_mul_f32_e32 v53, v52, v39
	v_fma_f32 v54, -v38, v53, v52
	v_fmac_f32_e32 v53, v54, v39
	v_fma_f32 v38, -v38, v53, v52
	v_div_fmas_f32 v38, v38, v39, v53
	v_div_fixup_f32 v37, v38, v37, v50
	v_div_scale_f32 v38, s[10:11], v36, v36, v51
	v_rcp_f32_e32 v39, v38
	s_nop 0
	v_fma_f32 v50, -v38, v39, 1.0
	v_fmac_f32_e32 v39, v50, v39
	v_div_scale_f32 v50, vcc, v51, v36, v51
	v_mul_f32_e32 v52, v50, v39
	v_fma_f32 v53, -v38, v52, v50
	v_fmac_f32_e32 v52, v53, v39
	v_fma_f32 v38, -v38, v52, v50
	v_div_fmas_f32 v38, v38, v39, v52
	v_div_fixup_f32 v36, v38, v36, v51
	v_pk_mul_f32 v[34:35], v[36:37], v[34:35]
	s_nop 0
	v_cvt_pk_bf16_f32 v33, v34, v35
	flat_store_dwordx2 v[48:49], v[32:33] offset:80
	flat_load_dwordx2 v[36:37], v[66:67] offset:96
	s_nop 0
	global_load_dwordx4 v[32:35], v65, s[18:19] offset:192
	s_waitcnt vmcnt(0) lgkmcnt(0)
; DI float bf2f(bfr v) { return __uint_as_float(((unsigned)v) << 16); }
; DI unsigned pk2(float a, float b) { f2_t v = {a, b}; bf2_t r = __builtin_convertvector(v, bf2_t); return __builtin_bit_cast(unsigned, r); }
; DI float siluf_(float x) { return x / (1.f + __expf(-x)); }
; DI void attn_unit(const Params& p, int l, int unit, unsigned char* smem) {
;     ...
; #pragma unroll
;   for (int dvb = 0; dvb < 4; ++dvb)
; #pragma unroll
;     for (int g = 0; g < 4; ++g) {
;       const int dv = 32 * dvb + 8 * g + 4 * h;
;       const s16x4 z4 = *(const s16x4*)(P + rowq * PLD + C_DAZ + hd * 128 + dv);
;       const f32x4 gn = *(const f32x4*)(p.da_norm + l * 128 + dv);
;       float y[4];
;       for (int q = 0; q < 4; ++q) y[q] = oacc[dvb][4 * g + q] * rs * gn[q] * siluf_(bf2f((bfr)z4[q]));
;       u32x2 w; w[0] = pk2(y[0], y[1]); w[1] = pk2(y[2], y[3]);
;       *(u32x2*)(YS + rowq * DM + 1536 + hd * 128 + dv) = w;
;     }
	v_and_b32_e32 v50, 0xffff0000, v36
	v_lshlrev_b32_e32 v36, 16, v36
	v_mul_f32_e32 v38, 0xbfb8aa3b, v36
	v_mul_f32_e32 v39, 0xbfb8aa3b, v50
	v_exp_f32_e32 v38, v38
	v_exp_f32_e32 v39, v39
	v_pk_mul_f32 v[32:33], v[32:33], v[40:41]
	v_pk_add_f32 v[38:39], v[38:39], 1.0 op_sel_hi:[1,0]
	s_nop 0
	v_div_scale_f32 v40, s[10:11], v39, v39, v50
	v_rcp_f32_e32 v41, v40
	s_nop 0
	v_fma_f32 v51, -v40, v41, 1.0
	v_fmac_f32_e32 v41, v51, v41
	v_div_scale_f32 v51, vcc, v50, v39, v50
	v_mul_f32_e32 v52, v51, v41
	v_fma_f32 v53, -v40, v52, v51
	v_fmac_f32_e32 v52, v53, v41
	v_fma_f32 v40, -v40, v52, v51
	v_div_fmas_f32 v40, v40, v41, v52
	v_div_fixup_f32 v39, v40, v39, v50
	v_div_scale_f32 v40, s[10:11], v38, v38, v36
	v_rcp_f32_e32 v41, v40
	s_nop 0
	v_fma_f32 v50, -v40, v41, 1.0
	v_fmac_f32_e32 v41, v50, v41
	v_div_scale_f32 v50, vcc, v36, v38, v36
	v_mul_f32_e32 v51, v50, v41
	v_fma_f32 v52, -v40, v51, v50
	v_fmac_f32_e32 v51, v52, v41
	v_fma_f32 v40, -v40, v51, v50
	v_div_fmas_f32 v40, v40, v41, v51
	v_div_fixup_f32 v38, v40, v38, v36
	v_and_b32_e32 v40, 0xffff0000, v37
	v_lshlrev_b32_e32 v41, 16, v37
	v_mul_f32_e32 v36, 0xbfb8aa3b, v41
	v_mul_f32_e32 v37, 0xbfb8aa3b, v40
	v_exp_f32_e32 v36, v36
	v_exp_f32_e32 v37, v37
	v_pk_mul_f32 v[32:33], v[38:39], v[32:33]
	v_pk_mul_f32 v[38:39], v[42:43], v[64:65] op_sel_hi:[1,0]
	v_cvt_pk_bf16_f32 v32, v32, v33
	v_pk_add_f32 v[36:37], v[36:37], 1.0 op_sel_hi:[1,0]
	v_pk_mul_f32 v[34:35], v[34:35], v[38:39]
	v_div_scale_f32 v38, s[10:11], v37, v37, v40
	v_rcp_f32_e32 v39, v38
	s_nop 0
	v_fma_f32 v42, -v38, v39, 1.0
	v_fmac_f32_e32 v39, v42, v39
	v_div_scale_f32 v42, vcc, v40, v37, v40
	v_mul_f32_e32 v43, v42, v39
	v_fma_f32 v50, -v38, v43, v42
	v_fmac_f32_e32 v43, v50, v39
	v_fma_f32 v38, -v38, v43, v42
	v_div_fmas_f32 v38, v38, v39, v43
	v_div_fixup_f32 v37, v38, v37, v40
	v_div_scale_f32 v38, s[10:11], v36, v36, v41
	v_rcp_f32_e32 v39, v38
	s_nop 0
	v_fma_f32 v40, -v38, v39, 1.0
	v_fmac_f32_e32 v39, v40, v39
	v_div_scale_f32 v40, vcc, v41, v36, v41
	v_mul_f32_e32 v42, v40, v39
	v_fma_f32 v43, -v38, v42, v40
	v_fmac_f32_e32 v42, v43, v39
	v_fma_f32 v38, -v38, v42, v40
	v_div_fmas_f32 v38, v38, v39, v42
	v_div_fixup_f32 v36, v38, v36, v41
	v_pk_mul_f32 v[34:35], v[36:37], v[34:35]
	v_pk_mul_f32 v[40:41], v[44:45], v[64:65] op_sel_hi:[1,0]
	v_cvt_pk_bf16_f32 v33, v34, v35
	flat_store_dwordx2 v[48:49], v[32:33] offset:96
	flat_load_dwordx2 v[36:37], v[66:67] offset:112
	s_nop 0
	global_load_dwordx4 v[32:35], v65, s[18:19] offset:224
	s_waitcnt vmcnt(0) lgkmcnt(0)
	v_and_b32_e32 v42, 0xffff0000, v36
	v_lshlrev_b32_e32 v36, 16, v36
	v_mul_f32_e32 v38, 0xbfb8aa3b, v36
	v_mul_f32_e32 v39, 0xbfb8aa3b, v42
	v_exp_f32_e32 v38, v38
	v_exp_f32_e32 v39, v39
	v_pk_mul_f32 v[32:33], v[32:33], v[40:41]
	v_pk_add_f32 v[38:39], v[38:39], 1.0 op_sel_hi:[1,0]
	s_nop 0
	v_div_scale_f32 v40, s[10:11], v39, v39, v42
	v_rcp_f32_e32 v41, v40
	s_nop 0
	v_fma_f32 v43, -v40, v41, 1.0
	v_fmac_f32_e32 v41, v43, v41
	v_div_scale_f32 v43, vcc, v42, v39, v42
	v_mul_f32_e32 v44, v43, v41
	v_fma_f32 v45, -v40, v44, v43
	v_fmac_f32_e32 v44, v45, v41
	v_fma_f32 v40, -v40, v44, v43
	v_div_fmas_f32 v40, v40, v41, v44
	v_div_fixup_f32 v39, v40, v39, v42
	v_div_scale_f32 v40, s[10:11], v38, v38, v36
	v_rcp_f32_e32 v41, v40
	s_nop 0
	v_fma_f32 v42, -v40, v41, 1.0
	v_fmac_f32_e32 v41, v42, v41
	v_div_scale_f32 v42, vcc, v36, v38, v36
	v_mul_f32_e32 v43, v42, v41
	v_fma_f32 v44, -v40, v43, v42
	v_fmac_f32_e32 v43, v44, v41
	v_fma_f32 v40, -v40, v43, v42
	v_div_fmas_f32 v40, v40, v41, v43
	v_div_fixup_f32 v38, v40, v38, v36
	v_and_b32_e32 v40, 0xffff0000, v37
	v_lshlrev_b32_e32 v41, 16, v37
	v_mul_f32_e32 v36, 0xbfb8aa3b, v41
	v_mul_f32_e32 v37, 0xbfb8aa3b, v40
	v_exp_f32_e32 v36, v36
	v_exp_f32_e32 v37, v37
	v_pk_mul_f32 v[32:33], v[38:39], v[32:33]
	v_pk_mul_f32 v[38:39], v[46:47], v[64:65] op_sel_hi:[1,0]
	v_cvt_pk_bf16_f32 v32, v32, v33
	v_pk_add_f32 v[36:37], v[36:37], 1.0 op_sel_hi:[1,0]
	v_pk_mul_f32 v[34:35], v[34:35], v[38:39]
	v_div_scale_f32 v38, s[10:11], v37, v37, v40
	v_rcp_f32_e32 v39, v38
	s_nop 0
	v_fma_f32 v42, -v38, v39, 1.0
	v_fmac_f32_e32 v39, v42, v39
	v_div_scale_f32 v42, vcc, v40, v37, v40
	v_mul_f32_e32 v43, v42, v39
	v_fma_f32 v44, -v38, v43, v42
	v_fmac_f32_e32 v43, v44, v39
	v_fma_f32 v38, -v38, v43, v42
	v_div_fmas_f32 v38, v38, v39, v43
	v_div_fixup_f32 v37, v38, v37, v40
	v_div_scale_f32 v38, s[10:11], v36, v36, v41
	v_rcp_f32_e32 v39, v38
	s_nop 0
	v_fma_f32 v40, -v38, v39, 1.0
	v_fmac_f32_e32 v39, v40, v39
	v_div_scale_f32 v40, vcc, v41, v36, v41
	v_mul_f32_e32 v42, v40, v39
	v_fma_f32 v43, -v38, v42, v40
	v_fmac_f32_e32 v42, v43, v39
	v_fma_f32 v38, -v38, v42, v40
	v_div_fmas_f32 v38, v38, v39, v42
	v_div_fixup_f32 v36, v38, v36, v41
	v_pk_mul_f32 v[34:35], v[36:37], v[34:35]
	s_nop 0
	v_cvt_pk_bf16_f32 v33, v34, v35
	flat_store_dwordx2 v[48:49], v[32:33] offset:112
	flat_load_dwordx2 v[36:37], v[66:67] offset:128
	s_nop 0
	global_load_dwordx4 v[32:35], v65, s[18:19] offset:256
	s_waitcnt vmcnt(0) lgkmcnt(0)
; DI float bf2f(bfr v) { return __uint_as_float(((unsigned)v) << 16); }
; DI unsigned pk2(float a, float b) { f2_t v = {a, b}; bf2_t r = __builtin_convertvector(v, bf2_t); return __builtin_bit_cast(unsigned, r); }
; DI float siluf_(float x) { return x / (1.f + __expf(-x)); }
; DI void attn_unit(const Params& p, int l, int unit, unsigned char* smem) {
;     ...
; #pragma unroll
;   for (int dvb = 0; dvb < 4; ++dvb)
; #pragma unroll
;     for (int g = 0; g < 4; ++g) {
;       const int dv = 32 * dvb + 8 * g + 4 * h;
;       const s16x4 z4 = *(const s16x4*)(P + rowq * PLD + C_DAZ + hd * 128 + dv);
;       const f32x4 gn = *(const f32x4*)(p.da_norm + l * 128 + dv);
;       float y[4];
;       for (int q = 0; q < 4; ++q) y[q] = oacc[dvb][4 * g + q] * rs * gn[q] * siluf_(bf2f((bfr)z4[q]));
;       u32x2 w; w[0] = pk2(y[0], y[1]); w[1] = pk2(y[2], y[3]);
;       *(u32x2*)(YS + rowq * DM + 1536 + hd * 128 + dv) = w;
;     }
	v_and_b32_e32 v40, 0xffff0000, v36
	v_lshlrev_b32_e32 v36, 16, v36
	v_mul_f32_e32 v38, 0xbfb8aa3b, v36
	v_pk_mul_f32 v[16:17], v[32:33], v[16:17]
	v_mul_f32_e32 v32, 0xbfb8aa3b, v40
	v_exp_f32_e32 v38, v38
	v_exp_f32_e32 v39, v32
	v_pk_mul_f32 v[18:19], v[34:35], v[18:19]
	v_pk_add_f32 v[32:33], v[38:39], 1.0 op_sel_hi:[1,0]
	s_nop 0
	v_div_scale_f32 v38, s[10:11], v33, v33, v40
	v_rcp_f32_e32 v39, v38
	s_nop 0
	v_fma_f32 v41, -v38, v39, 1.0
	v_fmac_f32_e32 v39, v41, v39
	v_div_scale_f32 v41, vcc, v40, v33, v40
	v_mul_f32_e32 v42, v41, v39
	v_fma_f32 v43, -v38, v42, v41
	v_fmac_f32_e32 v42, v43, v39
	v_fma_f32 v38, -v38, v42, v41
	v_div_fmas_f32 v38, v38, v39, v42
	v_div_fixup_f32 v33, v38, v33, v40
	v_div_scale_f32 v38, s[10:11], v32, v32, v36
	v_rcp_f32_e32 v39, v38
	s_nop 0
	v_fma_f32 v40, -v38, v39, 1.0
	v_fmac_f32_e32 v39, v40, v39
	v_div_scale_f32 v40, vcc, v36, v32, v36
	v_mul_f32_e32 v41, v40, v39
	v_fma_f32 v42, -v38, v41, v40
	v_fmac_f32_e32 v41, v42, v39
	v_fma_f32 v38, -v38, v41, v40
	v_div_fmas_f32 v38, v38, v39, v41
	v_div_fixup_f32 v32, v38, v32, v36
	v_and_b32_e32 v36, 0xffff0000, v37
	v_lshlrev_b32_e32 v37, 16, v37
	v_pk_mul_f32 v[16:17], v[32:33], v[16:17]
	v_mul_f32_e32 v32, 0xbfb8aa3b, v37
	v_mul_f32_e32 v33, 0xbfb8aa3b, v36
	v_exp_f32_e32 v32, v32
	v_exp_f32_e32 v33, v33
	v_cvt_pk_bf16_f32 v16, v16, v17
	v_pk_add_f32 v[32:33], v[32:33], 1.0 op_sel_hi:[1,0]
	s_nop 0
	v_div_scale_f32 v34, s[10:11], v33, v33, v36
	v_rcp_f32_e32 v35, v34
	s_nop 0
	v_fma_f32 v38, -v34, v35, 1.0
	v_fmac_f32_e32 v35, v38, v35
	v_div_scale_f32 v38, vcc, v36, v33, v36
	v_mul_f32_e32 v39, v38, v35
	v_fma_f32 v40, -v34, v39, v38
	v_fmac_f32_e32 v39, v40, v35
	v_fma_f32 v34, -v34, v39, v38
	v_div_fmas_f32 v34, v34, v35, v39
	v_div_fixup_f32 v33, v34, v33, v36
	v_div_scale_f32 v34, s[10:11], v32, v32, v37
	v_rcp_f32_e32 v35, v34
	s_nop 0
	v_fma_f32 v36, -v34, v35, 1.0
	v_fmac_f32_e32 v35, v36, v35
	v_div_scale_f32 v36, vcc, v37, v32, v37
	v_mul_f32_e32 v38, v36, v35
	v_fma_f32 v39, -v34, v38, v36
	v_fmac_f32_e32 v38, v39, v35
	v_fma_f32 v34, -v34, v38, v36
	v_div_fmas_f32 v34, v34, v35, v38
	v_div_fixup_f32 v32, v34, v32, v37
	v_pk_mul_f32 v[18:19], v[32:33], v[18:19]
	s_nop 0
	v_cvt_pk_bf16_f32 v17, v18, v19
	flat_store_dwordx2 v[48:49], v[16:17] offset:128
	flat_load_dwordx2 v[32:33], v[66:67] offset:144
	s_nop 0
	global_load_dwordx4 v[16:19], v65, s[18:19] offset:288
	s_waitcnt vmcnt(0) lgkmcnt(0)
	v_and_b32_e32 v36, 0xffff0000, v32
	v_lshlrev_b32_e32 v32, 16, v32
	v_mul_f32_e32 v34, 0xbfb8aa3b, v32
	v_pk_mul_f32 v[16:17], v[16:17], v[20:21]
	v_mul_f32_e32 v20, 0xbfb8aa3b, v36
	v_exp_f32_e32 v34, v34
	v_exp_f32_e32 v35, v20
	v_pk_mul_f32 v[18:19], v[18:19], v[22:23]
	v_pk_add_f32 v[20:21], v[34:35], 1.0 op_sel_hi:[1,0]
	s_nop 0
	v_div_scale_f32 v34, s[10:11], v21, v21, v36
	v_rcp_f32_e32 v35, v34
	s_nop 0
	v_fma_f32 v37, -v34, v35, 1.0
	v_fmac_f32_e32 v35, v37, v35
	v_div_scale_f32 v37, vcc, v36, v21, v36
	v_mul_f32_e32 v38, v37, v35
	v_fma_f32 v39, -v34, v38, v37
	v_fmac_f32_e32 v38, v39, v35
	v_fma_f32 v34, -v34, v38, v37
	v_div_fmas_f32 v34, v34, v35, v38
	v_div_fixup_f32 v21, v34, v21, v36
	v_div_scale_f32 v34, s[10:11], v20, v20, v32
	v_rcp_f32_e32 v35, v34
	s_nop 0
	v_fma_f32 v36, -v34, v35, 1.0
	v_fmac_f32_e32 v35, v36, v35
	v_div_scale_f32 v36, vcc, v32, v20, v32
	v_mul_f32_e32 v37, v36, v35
	v_fma_f32 v38, -v34, v37, v36
	v_fmac_f32_e32 v37, v38, v35
	v_fma_f32 v34, -v34, v37, v36
	v_div_fmas_f32 v34, v34, v35, v37
	v_div_fixup_f32 v20, v34, v20, v32
	v_and_b32_e32 v32, 0xffff0000, v33
	v_lshlrev_b32_e32 v33, 16, v33
	v_pk_mul_f32 v[16:17], v[20:21], v[16:17]
	v_mul_f32_e32 v20, 0xbfb8aa3b, v33
	v_mul_f32_e32 v21, 0xbfb8aa3b, v32
	v_exp_f32_e32 v20, v20
	v_exp_f32_e32 v21, v21
	v_cvt_pk_bf16_f32 v16, v16, v17
	v_pk_add_f32 v[20:21], v[20:21], 1.0 op_sel_hi:[1,0]
	s_nop 0
	v_div_scale_f32 v22, s[10:11], v21, v21, v32
	v_rcp_f32_e32 v23, v22
	s_nop 0
	v_fma_f32 v34, -v22, v23, 1.0
	v_fmac_f32_e32 v23, v34, v23
	v_div_scale_f32 v34, vcc, v32, v21, v32
	v_mul_f32_e32 v35, v34, v23
	v_fma_f32 v36, -v22, v35, v34
	v_fmac_f32_e32 v35, v36, v23
	v_fma_f32 v22, -v22, v35, v34
	v_div_fmas_f32 v22, v22, v23, v35
	v_div_fixup_f32 v21, v22, v21, v32
	v_div_scale_f32 v22, s[10:11], v20, v20, v33
	v_rcp_f32_e32 v23, v22
	s_nop 0
	v_fma_f32 v32, -v22, v23, 1.0
	v_fmac_f32_e32 v23, v32, v23
	v_div_scale_f32 v32, vcc, v33, v20, v33
	v_mul_f32_e32 v34, v32, v23
	v_fma_f32 v35, -v22, v34, v32
	v_fmac_f32_e32 v34, v35, v23
	v_fma_f32 v22, -v22, v34, v32
	v_div_fmas_f32 v22, v22, v23, v34
	v_div_fixup_f32 v20, v22, v20, v33
	v_pk_mul_f32 v[18:19], v[20:21], v[18:19]
	s_nop 0
	v_cvt_pk_bf16_f32 v17, v18, v19
	flat_store_dwordx2 v[48:49], v[16:17] offset:144
	flat_load_dwordx2 v[20:21], v[66:67] offset:160
	s_nop 0
	global_load_dwordx4 v[16:19], v65, s[18:19] offset:320
	s_waitcnt vmcnt(0) lgkmcnt(0)
; DI float bf2f(bfr v) { return __uint_as_float(((unsigned)v) << 16); }
; DI unsigned pk2(float a, float b) { f2_t v = {a, b}; bf2_t r = __builtin_convertvector(v, bf2_t); return __builtin_bit_cast(unsigned, r); }
; DI float siluf_(float x) { return x / (1.f + __expf(-x)); }
; DI void attn_unit(const Params& p, int l, int unit, unsigned char* smem) {
;     ...
; #pragma unroll
;   for (int dvb = 0; dvb < 4; ++dvb)
; #pragma unroll
;     for (int g = 0; g < 4; ++g) {
;       const int dv = 32 * dvb + 8 * g + 4 * h;
;       const s16x4 z4 = *(const s16x4*)(P + rowq * PLD + C_DAZ + hd * 128 + dv);
;       const f32x4 gn = *(const f32x4*)(p.da_norm + l * 128 + dv);
;       float y[4];
;       for (int q = 0; q < 4; ++q) y[q] = oacc[dvb][4 * g + q] * rs * gn[q] * siluf_(bf2f((bfr)z4[q]));
;       u32x2 w; w[0] = pk2(y[0], y[1]); w[1] = pk2(y[2], y[3]);
;       *(u32x2*)(YS + rowq * DM + 1536 + hd * 128 + dv) = w;
;     }
	v_and_b32_e32 v32, 0xffff0000, v20
	v_lshlrev_b32_e32 v20, 16, v20
	v_mul_f32_e32 v22, 0xbfb8aa3b, v20
	v_mul_f32_e32 v23, 0xbfb8aa3b, v32
	v_exp_f32_e32 v22, v22
	v_exp_f32_e32 v23, v23
	v_pk_mul_f32 v[16:17], v[16:17], v[24:25]
	v_pk_add_f32 v[22:23], v[22:23], 1.0 op_sel_hi:[1,0]
	s_nop 0
	v_div_scale_f32 v24, s[10:11], v23, v23, v32
	v_rcp_f32_e32 v25, v24
	s_nop 0
	v_fma_f32 v33, -v24, v25, 1.0
	v_fmac_f32_e32 v25, v33, v25
	v_div_scale_f32 v33, vcc, v32, v23, v32
	v_mul_f32_e32 v34, v33, v25
	v_fma_f32 v35, -v24, v34, v33
	v_fmac_f32_e32 v34, v35, v25
	v_fma_f32 v24, -v24, v34, v33
	v_div_fmas_f32 v24, v24, v25, v34
	v_div_fixup_f32 v23, v24, v23, v32
	v_div_scale_f32 v24, s[10:11], v22, v22, v20
	v_rcp_f32_e32 v25, v24
	s_nop 0
	v_fma_f32 v32, -v24, v25, 1.0
	v_fmac_f32_e32 v25, v32, v25
	v_div_scale_f32 v32, vcc, v20, v22, v20
	v_mul_f32_e32 v33, v32, v25
	v_fma_f32 v34, -v24, v33, v32
	v_fmac_f32_e32 v33, v34, v25
	v_fma_f32 v24, -v24, v33, v32
	v_div_fmas_f32 v24, v24, v25, v33
	v_div_fixup_f32 v22, v24, v22, v20
	v_and_b32_e32 v24, 0xffff0000, v21
	v_lshlrev_b32_e32 v25, 16, v21
	v_mul_f32_e32 v20, 0xbfb8aa3b, v25
	v_mul_f32_e32 v21, 0xbfb8aa3b, v24
	v_exp_f32_e32 v20, v20
	v_exp_f32_e32 v21, v21
	v_pk_mul_f32 v[16:17], v[22:23], v[16:17]
	v_pk_mul_f32 v[22:23], v[26:27], v[64:65] op_sel_hi:[1,0]
	v_cvt_pk_bf16_f32 v16, v16, v17
	v_pk_add_f32 v[20:21], v[20:21], 1.0 op_sel_hi:[1,0]
	v_pk_mul_f32 v[18:19], v[18:19], v[22:23]
	v_div_scale_f32 v22, s[10:11], v21, v21, v24
	v_rcp_f32_e32 v23, v22
	s_nop 0
	v_fma_f32 v26, -v22, v23, 1.0
	v_fmac_f32_e32 v23, v26, v23
	v_div_scale_f32 v26, vcc, v24, v21, v24
	v_mul_f32_e32 v27, v26, v23
	v_fma_f32 v32, -v22, v27, v26
	v_fmac_f32_e32 v27, v32, v23
	v_fma_f32 v22, -v22, v27, v26
	v_div_fmas_f32 v22, v22, v23, v27
	v_div_fixup_f32 v21, v22, v21, v24
	v_div_scale_f32 v22, s[10:11], v20, v20, v25
	v_rcp_f32_e32 v23, v22
	s_nop 0
	v_fma_f32 v24, -v22, v23, 1.0
	v_fmac_f32_e32 v23, v24, v23
	v_div_scale_f32 v24, vcc, v25, v20, v25
	v_mul_f32_e32 v26, v24, v23
	v_fma_f32 v27, -v22, v26, v24
	v_fmac_f32_e32 v26, v27, v23
	v_fma_f32 v22, -v22, v26, v24
	v_div_fmas_f32 v22, v22, v23, v26
	v_div_fixup_f32 v20, v22, v20, v25
	v_pk_mul_f32 v[18:19], v[20:21], v[18:19]
	v_pk_mul_f32 v[24:25], v[28:29], v[64:65] op_sel_hi:[1,0]
	v_cvt_pk_bf16_f32 v17, v18, v19
	flat_store_dwordx2 v[48:49], v[16:17] offset:160
	flat_load_dwordx2 v[20:21], v[66:67] offset:176
	s_nop 0
	global_load_dwordx4 v[16:19], v65, s[18:19] offset:352
	s_waitcnt vmcnt(0) lgkmcnt(0)
	v_and_b32_e32 v26, 0xffff0000, v20
	v_lshlrev_b32_e32 v20, 16, v20
	v_mul_f32_e32 v22, 0xbfb8aa3b, v20
	v_mul_f32_e32 v23, 0xbfb8aa3b, v26
	v_exp_f32_e32 v22, v22
	v_exp_f32_e32 v23, v23
	v_pk_mul_f32 v[16:17], v[16:17], v[24:25]
	v_pk_add_f32 v[22:23], v[22:23], 1.0 op_sel_hi:[1,0]
	s_nop 0
	v_div_scale_f32 v24, s[10:11], v23, v23, v26
	v_rcp_f32_e32 v25, v24
	s_nop 0
	v_fma_f32 v27, -v24, v25, 1.0
	v_fmac_f32_e32 v25, v27, v25
	v_div_scale_f32 v27, vcc, v26, v23, v26
	v_mul_f32_e32 v28, v27, v25
	v_fma_f32 v29, -v24, v28, v27
	v_fmac_f32_e32 v28, v29, v25
	v_fma_f32 v24, -v24, v28, v27
	v_div_fmas_f32 v24, v24, v25, v28
	v_div_fixup_f32 v23, v24, v23, v26
	v_div_scale_f32 v24, s[10:11], v22, v22, v20
	v_rcp_f32_e32 v25, v24
	s_nop 0
	v_fma_f32 v26, -v24, v25, 1.0
	v_fmac_f32_e32 v25, v26, v25
	v_div_scale_f32 v26, vcc, v20, v22, v20
	v_mul_f32_e32 v27, v26, v25
	v_fma_f32 v28, -v24, v27, v26
	v_fmac_f32_e32 v27, v28, v25
	v_fma_f32 v24, -v24, v27, v26
	v_div_fmas_f32 v24, v24, v25, v27
	v_div_fixup_f32 v22, v24, v22, v20
	v_and_b32_e32 v24, 0xffff0000, v21
	v_lshlrev_b32_e32 v25, 16, v21
	v_mul_f32_e32 v20, 0xbfb8aa3b, v25
	v_mul_f32_e32 v21, 0xbfb8aa3b, v24
	v_exp_f32_e32 v20, v20
	v_exp_f32_e32 v21, v21
	v_pk_mul_f32 v[16:17], v[22:23], v[16:17]
	v_pk_mul_f32 v[22:23], v[30:31], v[64:65] op_sel_hi:[1,0]
	v_cvt_pk_bf16_f32 v16, v16, v17
	v_pk_add_f32 v[20:21], v[20:21], 1.0 op_sel_hi:[1,0]
	v_pk_mul_f32 v[18:19], v[18:19], v[22:23]
	v_div_scale_f32 v22, s[10:11], v21, v21, v24
	v_rcp_f32_e32 v23, v22
	s_nop 0
	v_fma_f32 v26, -v22, v23, 1.0
	v_fmac_f32_e32 v23, v26, v23
	v_div_scale_f32 v26, vcc, v24, v21, v24
	v_mul_f32_e32 v27, v26, v23
	v_fma_f32 v28, -v22, v27, v26
	v_fmac_f32_e32 v27, v28, v23
	v_fma_f32 v22, -v22, v27, v26
	v_div_fmas_f32 v22, v22, v23, v27
	v_div_fixup_f32 v21, v22, v21, v24
	v_div_scale_f32 v22, s[10:11], v20, v20, v25
	v_rcp_f32_e32 v23, v22
	s_nop 0
	v_fma_f32 v24, -v22, v23, 1.0
	v_fmac_f32_e32 v23, v24, v23
	v_div_scale_f32 v24, vcc, v25, v20, v25
	v_mul_f32_e32 v26, v24, v23
	v_fma_f32 v27, -v22, v26, v24
	v_fmac_f32_e32 v26, v27, v23
	v_fma_f32 v22, -v22, v26, v24
	v_div_fmas_f32 v22, v22, v23, v26
	v_div_fixup_f32 v20, v22, v20, v25
	v_pk_mul_f32 v[18:19], v[20:21], v[18:19]
	s_nop 0
	v_cvt_pk_bf16_f32 v17, v18, v19
	flat_store_dwordx2 v[48:49], v[16:17] offset:176
	flat_load_dwordx2 v[20:21], v[66:67] offset:192
	s_nop 0
	global_load_dwordx4 v[16:19], v65, s[18:19] offset:384
	s_waitcnt vmcnt(0) lgkmcnt(0)
; DI float bf2f(bfr v) { return __uint_as_float(((unsigned)v) << 16); }
; DI unsigned pk2(float a, float b) { f2_t v = {a, b}; bf2_t r = __builtin_convertvector(v, bf2_t); return __builtin_bit_cast(unsigned, r); }
; DI float siluf_(float x) { return x / (1.f + __expf(-x)); }
; DI void attn_unit(const Params& p, int l, int unit, unsigned char* smem) {
;     ...
; #pragma unroll
;   for (int dvb = 0; dvb < 4; ++dvb)
; #pragma unroll
;     for (int g = 0; g < 4; ++g) {
;       const int dv = 32 * dvb + 8 * g + 4 * h;
;       const s16x4 z4 = *(const s16x4*)(P + rowq * PLD + C_DAZ + hd * 128 + dv);
;       const f32x4 gn = *(const f32x4*)(p.da_norm + l * 128 + dv);
;       float y[4];
;       for (int q = 0; q < 4; ++q) y[q] = oacc[dvb][4 * g + q] * rs * gn[q] * siluf_(bf2f((bfr)z4[q]));
;       u32x2 w; w[0] = pk2(y[0], y[1]); w[1] = pk2(y[2], y[3]);
;       *(u32x2*)(YS + rowq * DM + 1536 + hd * 128 + dv) = w;
;     }
	v_and_b32_e32 v24, 0xffff0000, v20
	v_lshlrev_b32_e32 v20, 16, v20
	v_mul_f32_e32 v22, 0xbfb8aa3b, v20
	v_pk_mul_f32 v[0:1], v[16:17], v[0:1]
	v_mul_f32_e32 v16, 0xbfb8aa3b, v24
	v_exp_f32_e32 v22, v22
	v_exp_f32_e32 v23, v16
	v_pk_mul_f32 v[2:3], v[18:19], v[2:3]
	v_pk_add_f32 v[16:17], v[22:23], 1.0 op_sel_hi:[1,0]
	s_nop 0
	v_div_scale_f32 v22, s[10:11], v17, v17, v24
	v_rcp_f32_e32 v23, v22
	s_nop 0
	v_fma_f32 v25, -v22, v23, 1.0
	v_fmac_f32_e32 v23, v25, v23
	v_div_scale_f32 v25, vcc, v24, v17, v24
	v_mul_f32_e32 v26, v25, v23
	v_fma_f32 v27, -v22, v26, v25
	v_fmac_f32_e32 v26, v27, v23
	v_fma_f32 v22, -v22, v26, v25
	v_div_fmas_f32 v22, v22, v23, v26
	v_div_fixup_f32 v17, v22, v17, v24
	v_div_scale_f32 v22, s[10:11], v16, v16, v20
	v_rcp_f32_e32 v23, v22
	s_nop 0
	v_fma_f32 v24, -v22, v23, 1.0
	v_fmac_f32_e32 v23, v24, v23
	v_div_scale_f32 v24, vcc, v20, v16, v20
	v_mul_f32_e32 v25, v24, v23
	v_fma_f32 v26, -v22, v25, v24
	v_fmac_f32_e32 v25, v26, v23
	v_fma_f32 v22, -v22, v25, v24
	v_div_fmas_f32 v22, v22, v23, v25
	v_div_fixup_f32 v16, v22, v16, v20
	v_and_b32_e32 v20, 0xffff0000, v21
	v_lshlrev_b32_e32 v21, 16, v21
	v_pk_mul_f32 v[0:1], v[16:17], v[0:1]
	v_mul_f32_e32 v16, 0xbfb8aa3b, v21
	v_mul_f32_e32 v17, 0xbfb8aa3b, v20
	v_exp_f32_e32 v16, v16
	v_exp_f32_e32 v17, v17
	v_cvt_pk_bf16_f32 v0, v0, v1
	v_pk_add_f32 v[16:17], v[16:17], 1.0 op_sel_hi:[1,0]
	s_nop 0
	v_div_scale_f32 v18, s[10:11], v17, v17, v20
	v_rcp_f32_e32 v19, v18
	s_nop 0
	v_fma_f32 v22, -v18, v19, 1.0
	v_fmac_f32_e32 v19, v22, v19
	v_div_scale_f32 v22, vcc, v20, v17, v20
	v_mul_f32_e32 v23, v22, v19
	v_fma_f32 v24, -v18, v23, v22
	v_fmac_f32_e32 v23, v24, v19
	v_fma_f32 v18, -v18, v23, v22
	v_div_fmas_f32 v18, v18, v19, v23
	v_div_fixup_f32 v17, v18, v17, v20
	v_div_scale_f32 v18, s[10:11], v16, v16, v21
	v_rcp_f32_e32 v19, v18
	s_nop 0
	v_fma_f32 v20, -v18, v19, 1.0
	v_fmac_f32_e32 v19, v20, v19
	v_div_scale_f32 v20, vcc, v21, v16, v21
	v_mul_f32_e32 v22, v20, v19
	v_fma_f32 v23, -v18, v22, v20
	v_fmac_f32_e32 v22, v23, v19
	v_fma_f32 v18, -v18, v22, v20
	v_div_fmas_f32 v18, v18, v19, v22
	v_div_fixup_f32 v16, v18, v16, v21
	v_pk_mul_f32 v[2:3], v[16:17], v[2:3]
	s_nop 0
	v_cvt_pk_bf16_f32 v1, v2, v3
	flat_store_dwordx2 v[48:49], v[0:1] offset:192
	flat_load_dwordx2 v[16:17], v[66:67] offset:208
	s_nop 0
	global_load_dwordx4 v[0:3], v65, s[18:19] offset:416
	s_waitcnt vmcnt(0) lgkmcnt(0)
	v_and_b32_e32 v20, 0xffff0000, v16
	v_lshlrev_b32_e32 v16, 16, v16
	v_mul_f32_e32 v18, 0xbfb8aa3b, v16
	v_pk_mul_f32 v[0:1], v[0:1], v[4:5]
	v_mul_f32_e32 v4, 0xbfb8aa3b, v20
	v_exp_f32_e32 v18, v18
	v_exp_f32_e32 v19, v4
	v_pk_mul_f32 v[2:3], v[2:3], v[6:7]
	v_pk_add_f32 v[4:5], v[18:19], 1.0 op_sel_hi:[1,0]
	s_nop 0
	v_div_scale_f32 v18, s[10:11], v5, v5, v20
	v_rcp_f32_e32 v19, v18
	s_nop 0
	v_fma_f32 v21, -v18, v19, 1.0
	v_fmac_f32_e32 v19, v21, v19
	v_div_scale_f32 v21, vcc, v20, v5, v20
	v_mul_f32_e32 v22, v21, v19
	v_fma_f32 v23, -v18, v22, v21
	v_fmac_f32_e32 v22, v23, v19
	v_fma_f32 v18, -v18, v22, v21
	v_div_fmas_f32 v18, v18, v19, v22
	v_div_fixup_f32 v5, v18, v5, v20
	v_div_scale_f32 v18, s[10:11], v4, v4, v16
	v_rcp_f32_e32 v19, v18
	s_nop 0
	v_fma_f32 v20, -v18, v19, 1.0
	v_fmac_f32_e32 v19, v20, v19
	v_div_scale_f32 v20, vcc, v16, v4, v16
	v_mul_f32_e32 v21, v20, v19
	v_fma_f32 v22, -v18, v21, v20
	v_fmac_f32_e32 v21, v22, v19
	v_fma_f32 v18, -v18, v21, v20
	v_div_fmas_f32 v18, v18, v19, v21
	v_div_fixup_f32 v4, v18, v4, v16
	v_and_b32_e32 v16, 0xffff0000, v17
	v_lshlrev_b32_e32 v17, 16, v17
	v_pk_mul_f32 v[0:1], v[4:5], v[0:1]
	v_mul_f32_e32 v4, 0xbfb8aa3b, v17
	v_mul_f32_e32 v5, 0xbfb8aa3b, v16
	v_exp_f32_e32 v4, v4
	v_exp_f32_e32 v5, v5
	v_cvt_pk_bf16_f32 v0, v0, v1
	v_pk_add_f32 v[4:5], v[4:5], 1.0 op_sel_hi:[1,0]
	s_nop 0
	v_div_scale_f32 v6, s[10:11], v5, v5, v16
	v_rcp_f32_e32 v7, v6
	s_nop 0
	v_fma_f32 v18, -v6, v7, 1.0
	v_fmac_f32_e32 v7, v18, v7
	v_div_scale_f32 v18, vcc, v16, v5, v16
	v_mul_f32_e32 v19, v18, v7
	v_fma_f32 v20, -v6, v19, v18
	v_fmac_f32_e32 v19, v20, v7
	v_fma_f32 v6, -v6, v19, v18
	v_div_fmas_f32 v6, v6, v7, v19
	v_div_fixup_f32 v5, v6, v5, v16
	v_div_scale_f32 v6, s[10:11], v4, v4, v17
	v_rcp_f32_e32 v7, v6
	s_nop 0
	v_fma_f32 v16, -v6, v7, 1.0
	v_fmac_f32_e32 v7, v16, v7
	v_div_scale_f32 v16, vcc, v17, v4, v17
	v_mul_f32_e32 v18, v16, v7
	v_fma_f32 v19, -v6, v18, v16
	v_fmac_f32_e32 v18, v19, v7
	v_fma_f32 v6, -v6, v18, v16
	v_div_fmas_f32 v6, v6, v7, v18
	v_div_fixup_f32 v4, v6, v4, v17
	v_pk_mul_f32 v[2:3], v[4:5], v[2:3]
	s_nop 0
	v_cvt_pk_bf16_f32 v1, v2, v3
	flat_store_dwordx2 v[48:49], v[0:1] offset:208
	flat_load_dwordx2 v[4:5], v[66:67] offset:224
	s_nop 0
	global_load_dwordx4 v[0:3], v65, s[18:19] offset:448
	s_waitcnt vmcnt(0) lgkmcnt(0)
; DI float bf2f(bfr v) { return __uint_as_float(((unsigned)v) << 16); }
; DI unsigned pk2(float a, float b) { f2_t v = {a, b}; bf2_t r = __builtin_convertvector(v, bf2_t); return __builtin_bit_cast(unsigned, r); }
; DI float siluf_(float x) { return x / (1.f + __expf(-x)); }
; DI void attn_unit(const Params& p, int l, int unit, unsigned char* smem) {
;     ...
; #pragma unroll
;   for (int dvb = 0; dvb < 4; ++dvb)
; #pragma unroll
;     for (int g = 0; g < 4; ++g) {
;       const int dv = 32 * dvb + 8 * g + 4 * h;
;       const s16x4 z4 = *(const s16x4*)(P + rowq * PLD + C_DAZ + hd * 128 + dv);
;       const f32x4 gn = *(const f32x4*)(p.da_norm + l * 128 + dv);
;       float y[4];
;       for (int q = 0; q < 4; ++q) y[q] = oacc[dvb][4 * g + q] * rs * gn[q] * siluf_(bf2f((bfr)z4[q]));
;       u32x2 w; w[0] = pk2(y[0], y[1]); w[1] = pk2(y[2], y[3]);
;       *(u32x2*)(YS + rowq * DM + 1536 + hd * 128 + dv) = w;
;     }
	v_and_b32_e32 v16, 0xffff0000, v4
	v_lshlrev_b32_e32 v4, 16, v4
	v_mul_f32_e32 v6, 0xbfb8aa3b, v4
	v_mul_f32_e32 v7, 0xbfb8aa3b, v16
	v_exp_f32_e32 v6, v6
	v_exp_f32_e32 v7, v7
	v_pk_mul_f32 v[0:1], v[0:1], v[8:9]
	v_pk_add_f32 v[6:7], v[6:7], 1.0 op_sel_hi:[1,0]
	s_nop 0
	v_div_scale_f32 v8, s[10:11], v7, v7, v16
	v_rcp_f32_e32 v9, v8
	s_nop 0
	v_fma_f32 v17, -v8, v9, 1.0
	v_fmac_f32_e32 v9, v17, v9
	v_div_scale_f32 v17, vcc, v16, v7, v16
	v_mul_f32_e32 v18, v17, v9
	v_fma_f32 v19, -v8, v18, v17
	v_fmac_f32_e32 v18, v19, v9
	v_fma_f32 v8, -v8, v18, v17
	v_div_fmas_f32 v8, v8, v9, v18
	v_div_fixup_f32 v7, v8, v7, v16
	v_div_scale_f32 v8, s[10:11], v6, v6, v4
	v_rcp_f32_e32 v9, v8
	s_nop 0
	v_fma_f32 v16, -v8, v9, 1.0
	v_fmac_f32_e32 v9, v16, v9
	v_div_scale_f32 v16, vcc, v4, v6, v4
	v_mul_f32_e32 v17, v16, v9
	v_fma_f32 v18, -v8, v17, v16
	v_fmac_f32_e32 v17, v18, v9
	v_fma_f32 v8, -v8, v17, v16
	v_div_fmas_f32 v8, v8, v9, v17
	v_div_fixup_f32 v6, v8, v6, v4
	v_and_b32_e32 v8, 0xffff0000, v5
	v_lshlrev_b32_e32 v9, 16, v5
	v_mul_f32_e32 v4, 0xbfb8aa3b, v9
	v_mul_f32_e32 v5, 0xbfb8aa3b, v8
	v_exp_f32_e32 v4, v4
	v_exp_f32_e32 v5, v5
	v_pk_mul_f32 v[0:1], v[6:7], v[0:1]
	v_pk_mul_f32 v[6:7], v[10:11], v[64:65] op_sel_hi:[1,0]
	v_cvt_pk_bf16_f32 v0, v0, v1
	v_pk_add_f32 v[4:5], v[4:5], 1.0 op_sel_hi:[1,0]
	v_pk_mul_f32 v[2:3], v[2:3], v[6:7]
	v_div_scale_f32 v6, s[10:11], v5, v5, v8
	v_rcp_f32_e32 v7, v6
	s_nop 0
	v_fma_f32 v10, -v6, v7, 1.0
	v_fmac_f32_e32 v7, v10, v7
	v_div_scale_f32 v10, vcc, v8, v5, v8
	v_mul_f32_e32 v11, v10, v7
	v_fma_f32 v16, -v6, v11, v10
	v_fmac_f32_e32 v11, v16, v7
	v_fma_f32 v6, -v6, v11, v10
	v_div_fmas_f32 v6, v6, v7, v11
	v_div_fixup_f32 v5, v6, v5, v8
	v_div_scale_f32 v6, s[10:11], v4, v4, v9
	v_rcp_f32_e32 v7, v6
	s_nop 0
	v_fma_f32 v8, -v6, v7, 1.0
	v_fmac_f32_e32 v7, v8, v7
	v_div_scale_f32 v8, vcc, v9, v4, v9
	v_mul_f32_e32 v10, v8, v7
	v_fma_f32 v11, -v6, v10, v8
	v_fmac_f32_e32 v10, v11, v7
	v_fma_f32 v6, -v6, v10, v8
	v_div_fmas_f32 v6, v6, v7, v10
	v_div_fixup_f32 v4, v6, v4, v9
	v_pk_mul_f32 v[2:3], v[4:5], v[2:3]
	v_pk_mul_f32 v[8:9], v[12:13], v[64:65] op_sel_hi:[1,0]
	v_cvt_pk_bf16_f32 v1, v2, v3
	flat_store_dwordx2 v[48:49], v[0:1] offset:224
	flat_load_dwordx2 v[0:1], v[66:67] offset:240
	s_nop 0
	global_load_dwordx4 v[2:5], v65, s[18:19] offset:480
	s_waitcnt vmcnt(0) lgkmcnt(0)
	v_and_b32_e32 v10, 0xffff0000, v0
	v_lshlrev_b32_e32 v0, 16, v0
	v_mul_f32_e32 v6, 0xbfb8aa3b, v0
	v_mul_f32_e32 v7, 0xbfb8aa3b, v10
	v_exp_f32_e32 v6, v6
	v_exp_f32_e32 v7, v7
	v_pk_mul_f32 v[2:3], v[2:3], v[8:9]
	v_pk_add_f32 v[6:7], v[6:7], 1.0 op_sel_hi:[1,0]
	s_nop 0
	v_div_scale_f32 v8, s[10:11], v7, v7, v10
	v_rcp_f32_e32 v9, v8
	s_nop 0
	v_fma_f32 v11, -v8, v9, 1.0
	v_fmac_f32_e32 v9, v11, v9
	v_div_scale_f32 v11, vcc, v10, v7, v10
	v_mul_f32_e32 v12, v11, v9
	v_fma_f32 v13, -v8, v12, v11
	v_fmac_f32_e32 v12, v13, v9
	v_fma_f32 v8, -v8, v12, v11
	v_div_fmas_f32 v8, v8, v9, v12
	v_div_fixup_f32 v7, v8, v7, v10
	v_div_scale_f32 v8, s[10:11], v6, v6, v0
	v_rcp_f32_e32 v9, v8
	s_nop 0
	v_fma_f32 v10, -v8, v9, 1.0
	v_fmac_f32_e32 v9, v10, v9
	v_div_scale_f32 v10, vcc, v0, v6, v0
	v_mul_f32_e32 v11, v10, v9
	v_fma_f32 v12, -v8, v11, v10
	v_fmac_f32_e32 v11, v12, v9
	v_fma_f32 v8, -v8, v11, v10
	v_div_fmas_f32 v8, v8, v9, v11
	v_div_fixup_f32 v6, v8, v6, v0
	v_and_b32_e32 v8, 0xffff0000, v1
	v_lshlrev_b32_e32 v9, 16, v1
	v_mul_f32_e32 v0, 0xbfb8aa3b, v9
	v_mul_f32_e32 v1, 0xbfb8aa3b, v8
	v_exp_f32_e32 v0, v0
	v_exp_f32_e32 v1, v1
	v_pk_mul_f32 v[2:3], v[6:7], v[2:3]
	v_pk_mul_f32 v[6:7], v[14:15], v[64:65] op_sel_hi:[1,0]
	v_cvt_pk_bf16_f32 v2, v2, v3
	v_pk_add_f32 v[0:1], v[0:1], 1.0 op_sel_hi:[1,0]
	v_pk_mul_f32 v[4:5], v[4:5], v[6:7]
	v_div_scale_f32 v6, s[10:11], v1, v1, v8
	v_rcp_f32_e32 v7, v6
	s_nop 0
	v_fma_f32 v10, -v6, v7, 1.0
	v_fmac_f32_e32 v7, v10, v7
	v_div_scale_f32 v10, vcc, v8, v1, v8
	v_mul_f32_e32 v11, v10, v7
	v_fma_f32 v12, -v6, v11, v10
	v_fmac_f32_e32 v11, v12, v7
	v_fma_f32 v6, -v6, v11, v10
	v_div_fmas_f32 v6, v6, v7, v11
	v_div_fixup_f32 v1, v6, v1, v8
	v_div_scale_f32 v6, s[10:11], v0, v0, v9
	v_rcp_f32_e32 v7, v6
	s_nop 0
	v_fma_f32 v8, -v6, v7, 1.0
	v_fmac_f32_e32 v7, v8, v7
	v_div_scale_f32 v8, vcc, v9, v0, v9
	v_mul_f32_e32 v10, v8, v7
	v_fma_f32 v11, -v6, v10, v8
	v_fmac_f32_e32 v10, v11, v7
	v_fma_f32 v6, -v6, v10, v8
	v_div_fmas_f32 v6, v6, v7, v10
	v_div_fixup_f32 v0, v6, v0, v9
	v_pk_mul_f32 v[0:1], v[0:1], v[4:5]
	s_nop 0
	v_cvt_pk_bf16_f32 v3, v0, v1
	flat_store_dwordx2 v[48:49], v[2:3] offset:240
	s_branch .LBB0_511
